# all plain global stores made agent-scope write-through (sc1) so the grid-barrier release fences have no dirty L2 lines to flush
# baseline (speedup 1.0000x reference)
; #define GAS __attribute__((address_space(1)))
; #define LAS __attribute__((address_space(3)))
; #define LDS_WAIT() asm volatile("s_waitcnt lgkmcnt(0)" ::: "memory")
; __device__ __forceinline__ unsigned pk2(float lo, float hi) { return f2bf(lo) | (f2bf(hi) << 16); }
; __device__ __forceinline__ void p0_transpose_item(const float* W, int N, bf16* WT, int ldt, int rowmode, LAS float* scr, int kb, int nb, int lane, const float* kgain) {
;     const int k0 = 64 * kb, n0 = 32 * nb;
;     const int lk = lane >> 3, ln = (lane & 7) * 4;
; #pragma unroll
;     for (int i = 0; i < 8; ++i) { const int kk = 8 * i + lk; f32x4 v = __builtin_nontemporal_load((const GAS f32x4*)(W + (size_t)(k0 + kk) * N + n0 + ln)); if (kgain) v = v * kgain[k0 + kk];
;         scr[kk * 33 + ln] = v[0]; scr[kk * 33 + ln + 1] = v[1]; scr[kk * 33 + ln + 2] = v[2]; scr[kk * 33 + ln + 3] = v[3]; }
;     LDS_WAIT(); asm volatile("" ::: "memory");
;     const int c = lane & 7;
; #pragma unroll
;     for (int j = 0; j < 4; ++j) { const int n = (lane >> 3) + 8 * j; const LAS float* s = scr + (8 * c) * 33 + n;
;         v4u o; o.x = pk2(s[0 * 33], s[1 * 33]); o.y = pk2(s[2 * 33], s[3 * 33]); o.z = pk2(s[4 * 33], s[5 * 33]); o.w = pk2(s[6 * 33], s[7 * 33]);
;         const int ng = n0 + n; int row;
;         if (rowmode == 0) row = ng;
;         else if (rowmode == 3) { const int np = ng - (PW + 4 * HW); row = np < 0 ? ng : (PW + 4 * HW) + ((np & (D - 1)) >> 7) * 256 + (np >= D ? 128 : 0) + (np & 127); }
;         else row = (ng >> 7) * 256 + (rowmode == 2 ? 128 : 0) + (ng & 127);
.LBB0_14:
	s_mul_hi_i32 s4, s23, 0x38e38e39
	s_lshr_b32 s5, s4, 31
	s_ashr_i32 s4, s4, 7
	s_add_i32 s4, s4, s5
	s_mul_i32 s5, s4, 0xffffb800
	s_lshl_b32 s6, s4, 6
	s_lshl_b32 s8, s4, 12
	s_add_i32 s4, s15, s5
	s_ashr_i32 s7, s6, 31
	s_sub_i32 s8, s17, s8
	s_ashr_i32 s5, s4, 31
	v_or_b32_e32 v46, s6, v22
	v_or_b32_e32 v48, s6, v32
	v_or_b32_e32 v50, s6, v31
	v_or_b32_e32 v51, s6, v30
	v_or_b32_e32 v54, s6, v21
	v_or_b32_e32 v55, s6, v20
	v_or_b32_e32 v58, s6, v18
	v_or_b32_e32 v59, s6, v17
	v_lshl_add_u64 v[6:7], s[6:7], 1, v[4:5]
	s_and_b32 s6, s8, 0x1f00
	v_lshl_add_u64 v[44:45], s[4:5], 2, v[2:3]
	s_xor_b32 s5, s6, 0x1000
	v_mad_i64_i32 v[46:47], s[6:7], v46, s19, v[44:45]
	v_mad_i64_i32 v[48:49], s[6:7], v48, s19, v[44:45]
	v_mad_i64_i32 v[52:53], s[6:7], v50, s19, v[44:45]
	v_mad_i64_i32 v[56:57], s[6:7], v51, s19, v[44:45]
	v_mad_i64_i32 v[60:61], s[6:7], v54, s19, v[44:45]
	v_mad_i64_i32 v[64:65], s[6:7], v55, s19, v[44:45]
	v_mad_i64_i32 v[68:69], s[6:7], v58, s19, v[44:45]
	v_mad_i64_i32 v[72:73], s[6:7], v59, s19, v[44:45]
	global_load_dwordx4 v[44:47], v[46:47], off nt
	s_nop 0
	global_load_dwordx4 v[48:51], v[48:49], off nt
	s_nop 0
	global_load_dwordx4 v[52:55], v[52:53], off nt
	s_nop 0
	global_load_dwordx4 v[56:59], v[56:57], off nt
	s_nop 0
	global_load_dwordx4 v[60:63], v[60:61], off nt
	s_nop 0
	global_load_dwordx4 v[64:67], v[64:65], off nt
	s_nop 0
	global_load_dwordx4 v[68:71], v[68:69], off nt
	s_nop 0
	global_load_dwordx4 v[72:75], v[72:73], off nt
	v_add_u32_e32 v76, s4, v22
	s_add_i32 s6, s5, 0x2800
	v_add_u32_e32 v78, 8, v76
	v_add_u32_e32 v79, 16, v76
	v_add_u32_e32 v81, 24, v76
	s_cmpk_gt_u32 s4, 0x37ff
	v_and_b32_e32 v77, 0x67, v76
	v_and_b32_e32 v80, 0x6f, v78
	v_and_b32_e32 v82, 0x77, v79
	v_and_b32_e32 v83, 0x7f, v81
	s_cselect_b32 s4, 0x80, 0
	v_or_b32_e32 v77, s4, v77
	v_or_b32_e32 v80, s4, v80
	v_or_b32_e32 v82, s4, v82
	v_or_b32_e32 v83, s4, v83
	v_or_b32_e32 v77, s6, v77
	v_or_b32_e32 v80, s6, v80
	v_cmp_gt_i32_e32 vcc, s20, v78
	v_or_b32_e32 v82, s6, v82
	v_cmp_gt_i32_e64 s[4:5], s20, v79
	v_or_b32_e32 v83, s6, v83
	v_cmp_gt_i32_e64 s[6:7], s20, v81
	v_cmp_gt_i32_e64 s[8:9], s20, v76
	v_cndmask_b32_e32 v78, v80, v78, vcc
	v_cndmask_b32_e64 v80, v82, v79, s[4:5]
	v_cndmask_b32_e64 v76, v77, v76, s[8:9]
	v_cndmask_b32_e64 v82, v83, v81, s[6:7]
	v_ashrrev_i32_e32 v77, 31, v76
	v_ashrrev_i32_e32 v79, 31, v78
	v_ashrrev_i32_e32 v81, 31, v80
	v_ashrrev_i32_e32 v83, 31, v82
	v_lshlrev_b64 v[76:77], 13, v[76:77]
	v_lshlrev_b64 v[78:79], 13, v[78:79]
	v_lshlrev_b64 v[80:81], 13, v[80:81]
	v_lshlrev_b64 v[82:83], 13, v[82:83]
	v_lshl_add_u64 v[76:77], v[6:7], 0, v[76:77]
	v_lshl_add_u64 v[78:79], v[6:7], 0, v[78:79]
	v_lshl_add_u64 v[80:81], v[6:7], 0, v[80:81]
	v_lshl_add_u64 v[6:7], v[6:7], 0, v[82:83]
	s_add_i32 s23, s23, s82
	s_add_i32 s15, s15, s16
	s_add_i32 s17, s17, s18
	s_cmp_lt_i32 s23, 0x9000
	s_waitcnt vmcnt(7)
	ds_write2_b32 v23, v44, v45 offset1:1
	ds_write2_b32 v23, v46, v47 offset0:2 offset1:3
	s_waitcnt vmcnt(6)
	ds_write2_b32 v24, v48, v49 offset1:1
	ds_write2_b32 v25, v50, v51 offset1:1
	s_waitcnt vmcnt(5)
	ds_write2_b32 v26, v52, v53 offset1:1
	ds_write2_b32 v27, v54, v55 offset1:1
	s_waitcnt vmcnt(4)
	ds_write2_b32 v28, v56, v57 offset1:1
	ds_write2_b32 v29, v58, v59 offset1:1
	s_waitcnt vmcnt(3)
	ds_write2_b32 v34, v60, v61 offset1:1
	ds_write2_b32 v35, v62, v63 offset1:1
	s_waitcnt vmcnt(2)
	ds_write2_b32 v36, v64, v65 offset1:1
	ds_write2_b32 v37, v66, v67 offset0:2 offset1:3
	s_waitcnt vmcnt(1)
	ds_write2_b32 v38, v68, v69 offset1:1
	ds_write2_b32 v39, v70, v71 offset1:1
	s_waitcnt vmcnt(0)
	ds_write2_b32 v42, v72, v73 offset1:1
	ds_write2_b32 v43, v74, v75 offset1:1
	s_waitcnt lgkmcnt(0)
; #define GAS __attribute__((address_space(1)))
; #define LAS __attribute__((address_space(3)))
; __device__ __forceinline__ unsigned f2bf(float f) { unsigned u = __builtin_bit_cast(unsigned, f); return (u + 0x7fffu + ((u >> 16) & 1u)) >> 16; }
; __device__ __forceinline__ unsigned pk2(float lo, float hi) { return f2bf(lo) | (f2bf(hi) << 16); }
; __device__ __forceinline__ void p0_transpose_item(const float* W, int N, bf16* WT, int ldt, int rowmode, LAS float* scr, int kb, int nb, int lane, const float* kgain) {
;     ...
;     for (int j = 0; j < 4; ++j) { const int n = (lane >> 3) + 8 * j; const LAS float* s = scr + (8 * c) * 33 + n;
;         v4u o; o.x = pk2(s[0 * 33], s[1 * 33]); o.y = pk2(s[2 * 33], s[3 * 33]); o.z = pk2(s[4 * 33], s[5 * 33]); o.w = pk2(s[6 * 33], s[7 * 33]);
;         const int ng = n0 + n; int row;
;         if (rowmode == 0) row = ng;
;         else if (rowmode == 3) { const int np = ng - (PW + 4 * HW); row = np < 0 ? ng : (PW + 4 * HW) + ((np & (D - 1)) >> 7) * 256 + (np >= D ? 128 : 0) + (np & 127); }
;         else row = (ng >> 7) * 256 + (rowmode == 2 ? 128 : 0) + (ng & 127);
;         *(GAS v4u*)(WT + (size_t)row * ldt + k0 + 8 * c) = o; }
	ds_read2_b32 v[44:45], v13 offset0:33 offset1:41
	ds_read2_b32 v[46:47], v13 offset1:8
	ds_read2_b32 v[48:49], v13 offset0:66 offset1:74
	ds_read2_b32 v[50:51], v13 offset0:99 offset1:107
	ds_read2_b32 v[52:53], v13 offset0:132 offset1:140
	ds_read2_b32 v[54:55], v13 offset0:165 offset1:173
	ds_read2_b32 v[56:57], v13 offset0:198 offset1:206
	ds_read2_b32 v[58:59], v13 offset0:231 offset1:239
	ds_read2_b32 v[60:61], v13 offset0:16 offset1:24
	ds_read2_b32 v[62:63], v13 offset0:49 offset1:57
	ds_read2_b32 v[64:65], v13 offset0:115 offset1:123
	ds_read2_b32 v[66:67], v13 offset0:82 offset1:90
	ds_read2_b32 v[68:69], v13 offset0:181 offset1:189
	ds_read2_b32 v[70:71], v13 offset0:148 offset1:156
	ds_read2_b32 v[72:73], v13 offset0:247 offset1:255
	ds_read2_b32 v[74:75], v13 offset0:214 offset1:222
	s_waitcnt lgkmcnt(14)
	v_bfe_u32 v82, v46, 16, 1
	v_bfe_u32 v85, v45, 16, 1
	s_waitcnt lgkmcnt(13)
	v_bfe_u32 v86, v48, 16, 1
	v_bfe_u32 v87, v49, 16, 1
	s_waitcnt lgkmcnt(12)
	v_bfe_u32 v88, v50, 16, 1
	v_bfe_u32 v89, v51, 16, 1
	s_waitcnt lgkmcnt(11)
	v_bfe_u32 v90, v52, 16, 1
	v_bfe_u32 v91, v53, 16, 1
	s_waitcnt lgkmcnt(10)
	v_bfe_u32 v92, v54, 16, 1
	v_bfe_u32 v93, v55, 16, 1
	s_waitcnt lgkmcnt(9)
	v_bfe_u32 v94, v56, 16, 1
	v_bfe_u32 v83, v47, 16, 1
	v_bfe_u32 v84, v44, 16, 1
	v_bfe_u32 v95, v57, 16, 1
	s_waitcnt lgkmcnt(8)
	v_bfe_u32 v96, v58, 16, 1
	v_bfe_u32 v97, v59, 16, 1
	s_waitcnt lgkmcnt(6)
	v_bfe_u32 v98, v62, 16, 1
	v_bfe_u32 v99, v63, 16, 1
	v_bfe_u32 v100, v60, 16, 1
	v_bfe_u32 v101, v61, 16, 1
	s_waitcnt lgkmcnt(5)
	v_bfe_u32 v102, v64, 16, 1
	v_bfe_u32 v103, v65, 16, 1
	s_waitcnt lgkmcnt(4)
	v_bfe_u32 v104, v66, 16, 1
	v_bfe_u32 v105, v67, 16, 1
	s_waitcnt lgkmcnt(3)
	v_bfe_u32 v106, v68, 16, 1
	v_bfe_u32 v107, v69, 16, 1
	s_waitcnt lgkmcnt(2)
	v_bfe_u32 v108, v70, 16, 1
	v_bfe_u32 v109, v71, 16, 1
	s_waitcnt lgkmcnt(1)
	v_bfe_u32 v110, v72, 16, 1
	v_bfe_u32 v111, v73, 16, 1
	s_waitcnt lgkmcnt(0)
	v_bfe_u32 v112, v74, 16, 1
	v_bfe_u32 v113, v75, 16, 1
	v_add3_u32 v46, v46, v82, s21
	v_add3_u32 v82, v45, v85, s21
	v_add3_u32 v45, v48, v86, s21
	v_add3_u32 v48, v49, v87, s21
	v_add3_u32 v49, v50, v88, s21
	v_add3_u32 v50, v51, v89, s21
	v_add3_u32 v51, v52, v90, s21
	v_add3_u32 v52, v53, v91, s21
	v_add3_u32 v53, v54, v92, s21
	v_add3_u32 v54, v55, v93, s21
	v_add3_u32 v55, v56, v94, s21
	v_add3_u32 v47, v47, v83, s21
	v_add3_u32 v44, v44, v84, s21
	v_add3_u32 v56, v57, v95, s21
	v_add3_u32 v57, v58, v96, s21
	v_add3_u32 v58, v59, v97, s21
	v_add3_u32 v59, v62, v98, s21
	v_add3_u32 v62, v63, v99, s21
	v_add3_u32 v60, v60, v100, s21
	v_add3_u32 v61, v61, v101, s21
	v_add3_u32 v63, v64, v102, s21
	v_add3_u32 v64, v65, v103, s21
	v_add3_u32 v65, v66, v104, s21
	v_add3_u32 v66, v67, v105, s21
	v_add3_u32 v67, v68, v106, s21
	v_add3_u32 v68, v69, v107, s21
	v_add3_u32 v69, v70, v108, s21
	v_add3_u32 v70, v71, v109, s21
	v_add3_u32 v71, v72, v110, s21
	v_add3_u32 v72, v73, v111, s21
	v_add3_u32 v73, v74, v112, s21
	v_add3_u32 v74, v75, v113, s21
	v_lshrrev_b32_e32 v46, 16, v46
	v_lshrrev_b32_e32 v45, 16, v45
	v_lshrrev_b32_e32 v51, 16, v51
	v_lshrrev_b32_e32 v55, 16, v55
	v_lshrrev_b32_e32 v75, 16, v47
	v_lshrrev_b32_e32 v83, 16, v48
	v_lshrrev_b32_e32 v52, 16, v52
	v_lshrrev_b32_e32 v56, 16, v56
	v_lshrrev_b32_e32 v60, 16, v60
	v_lshrrev_b32_e32 v65, 16, v65
	v_lshrrev_b32_e32 v69, 16, v69
	v_lshrrev_b32_e32 v73, 16, v73
	v_lshrrev_b32_e32 v61, 16, v61
	v_lshrrev_b32_e32 v66, 16, v66
	v_lshrrev_b32_e32 v70, 16, v70
	v_lshrrev_b32_e32 v74, 16, v74
	v_and_or_b32 v44, v44, s22, v46
	v_and_or_b32 v45, v49, s22, v45
	v_and_or_b32 v46, v53, s22, v51
	v_and_or_b32 v47, v57, s22, v55
	v_and_or_b32 v48, v82, s22, v75
	v_and_or_b32 v49, v50, s22, v83
	v_and_or_b32 v50, v54, s22, v52
	v_and_or_b32 v51, v58, s22, v56
	v_and_or_b32 v52, v59, s22, v60
	v_and_or_b32 v53, v63, s22, v65
	v_and_or_b32 v54, v67, s22, v69
	v_and_or_b32 v55, v71, s22, v73
	v_and_or_b32 v56, v62, s22, v61
	v_and_or_b32 v57, v64, s22, v66
	v_and_or_b32 v58, v68, s22, v70
	v_and_or_b32 v59, v72, s22, v74
	global_store_dwordx4 v[76:77], v[44:47], off sc1
	global_store_dwordx4 v[78:79], v[48:51], off sc1
	global_store_dwordx4 v[80:81], v[52:55], off sc1
	global_store_dwordx4 v[6:7], v[56:59], off sc1
	s_waitcnt lgkmcnt(0)
	s_cbranch_scc1 .LBB0_14
	v_mov_b32_e32 v23, v32
	v_mov_b32_e32 v24, v31
	v_mov_b32_e32 v25, v30
	v_mov_b32_e32 v26, v21
	v_mov_b32_e32 v27, v20
	v_mov_b32_e32 v28, v18
	v_mov_b32_e32 v29, v17

; #define GAS __attribute__((address_space(1)))
; #define LAS __attribute__((address_space(3)))
; #define LDS_WAIT() asm volatile("s_waitcnt lgkmcnt(0)" ::: "memory")
; __device__ __forceinline__ void p0_transpose_item(const float* W, int N, bf16* WT, int ldt, int rowmode, LAS float* scr, int kb, int nb, int lane, const float* kgain) {
;     ...
;     const int lk = lane >> 3, ln = (lane & 7) * 4;
; #pragma unroll
;     for (int i = 0; i < 8; ++i) { const int kk = 8 * i + lk; f32x4 v = __builtin_nontemporal_load((const GAS f32x4*)(W + (size_t)(k0 + kk) * N + n0 + ln)); if (kgain) v = v * kgain[k0 + kk];
;         scr[kk * 33 + ln] = v[0]; scr[kk * 33 + ln + 1] = v[1]; scr[kk * 33 + ln + 2] = v[2]; scr[kk * 33 + ln + 3] = v[3]; }
;     LDS_WAIT(); asm volatile("" ::: "memory");
;     const int c = lane & 7;
; #pragma unroll
;     for (int j = 0; j < 4; ++j) { const int n = (lane >> 3) + 8 * j; const LAS float* s = scr + (8 * c) * 33 + n;
.LBB0_20:
	s_ashr_i32 s18, s17, 31
	s_lshr_b32 s18, s18, 28
	s_add_i32 s18, s17, s18
	s_ashr_i32 s19, s18, 4
	s_lshl_b32 s18, s19, 6
	s_lshl_b32 s19, s19, 9
	s_sub_i32 s20, s6, s19
	v_or_b32_e32 v14, s18, v22
	v_or_b32_e32 v16, s18, v23
	v_or_b32_e32 v18, s18, v24
	v_or_b32_e32 v20, s18, v25
	v_or_b32_e32 v42, s18, v26
	v_or_b32_e32 v44, s18, v27
	v_or_b32_e32 v46, s18, v28
	v_or_b32_e32 v48, s18, v29
	s_ashr_i32 s21, s20, 31
	v_ashrrev_i32_e32 v15, 31, v14
	v_ashrrev_i32_e32 v17, 31, v16
	v_ashrrev_i32_e32 v19, 31, v18
	v_ashrrev_i32_e32 v21, 31, v20
	v_ashrrev_i32_e32 v43, 31, v42
	v_ashrrev_i32_e32 v45, 31, v44
	v_ashrrev_i32_e32 v47, 31, v46
	v_ashrrev_i32_e32 v49, 31, v48
	v_add_u32_e32 v50, s20, v22
	v_lshl_add_u64 v[52:53], s[20:21], 2, v[6:7]
	v_lshlrev_b64 v[14:15], 11, v[14:15]
	v_lshlrev_b64 v[16:17], 11, v[16:17]
	v_lshlrev_b64 v[18:19], 11, v[18:19]
	v_lshlrev_b64 v[20:21], 11, v[20:21]
	v_lshlrev_b64 v[42:43], 11, v[42:43]
	v_lshlrev_b64 v[44:45], 11, v[44:45]
	v_lshlrev_b64 v[46:47], 11, v[46:47]
	v_lshlrev_b64 v[48:49], 11, v[48:49]
	v_ashrrev_i32_e32 v51, 31, v50
	v_lshl_add_u64 v[14:15], v[52:53], 0, v[14:15]
	v_lshl_add_u64 v[54:55], v[52:53], 0, v[16:17]
	v_lshl_add_u64 v[56:57], v[52:53], 0, v[18:19]
	v_lshl_add_u64 v[58:59], v[52:53], 0, v[20:21]
	v_lshl_add_u64 v[60:61], v[52:53], 0, v[42:43]
	v_lshl_add_u64 v[62:63], v[52:53], 0, v[44:45]
	v_lshl_add_u64 v[64:65], v[52:53], 0, v[46:47]
	v_add_u32_e32 v68, 8, v50
	v_add_u32_e32 v70, 16, v50
	v_add_u32_e32 v72, 24, v50
	v_lshl_add_u64 v[74:75], v[52:53], 0, v[48:49]
	v_lshlrev_b64 v[76:77], 10, v[50:51]
	global_load_dwordx4 v[14:17], v[14:15], off nt
	s_nop 0
	global_load_dwordx4 v[18:21], v[54:55], off nt
	global_load_dwordx4 v[42:45], v[56:57], off nt
	global_load_dwordx4 v[46:49], v[58:59], off nt
	global_load_dwordx4 v[50:53], v[60:61], off nt
	s_nop 0
	global_load_dwordx4 v[54:57], v[62:63], off nt
	global_load_dwordx4 v[58:61], v[64:65], off nt
	s_nop 0
	global_load_dwordx4 v[62:65], v[74:75], off nt
	s_ashr_i32 s19, s18, 31
	v_ashrrev_i32_e32 v69, 31, v68
	v_ashrrev_i32_e32 v71, 31, v70
	v_ashrrev_i32_e32 v73, 31, v72
	v_lshl_add_u64 v[66:67], s[18:19], 1, v[8:9]
	v_lshlrev_b64 v[68:69], 10, v[68:69]
	v_lshlrev_b64 v[70:71], 10, v[70:71]
	v_lshlrev_b64 v[72:73], 10, v[72:73]
	v_lshl_add_u64 v[74:75], v[66:67], 0, v[76:77]
	v_lshl_add_u64 v[68:69], v[66:67], 0, v[68:69]
	v_lshl_add_u64 v[70:71], v[66:67], 0, v[70:71]
	v_lshl_add_u64 v[66:67], v[66:67], 0, v[72:73]
	s_add_i32 s17, s17, s82
	s_add_i32 s6, s6, s8
	s_cmpk_lt_i32 s17, 0x80
	s_waitcnt vmcnt(7)
	ds_write2_b32 v34, v14, v15 offset1:1
	ds_write2_b32 v34, v16, v17 offset0:2 offset1:3
	s_waitcnt vmcnt(6)
	ds_write2_b32 v35, v18, v19 offset1:1
	ds_write2_b32 v35, v20, v21 offset0:2 offset1:3
	s_waitcnt vmcnt(5)
	ds_write2_b32 v36, v42, v43 offset1:1
	ds_write2_b32 v36, v44, v45 offset0:2 offset1:3
	s_waitcnt vmcnt(4)
	ds_write2_b32 v37, v46, v47 offset1:1
	ds_write2_b32 v37, v48, v49 offset0:2 offset1:3
	s_waitcnt vmcnt(3)
	ds_write2_b32 v38, v50, v51 offset1:1
	ds_write2_b32 v38, v52, v53 offset0:2 offset1:3
	s_waitcnt vmcnt(2)
	ds_write2_b32 v39, v54, v55 offset1:1
	ds_write2_b32 v39, v56, v57 offset0:2 offset1:3
	s_waitcnt vmcnt(1)
	ds_write2_b32 v40, v58, v59 offset1:1
	ds_write2_b32 v40, v60, v61 offset0:2 offset1:3
	s_waitcnt vmcnt(0)
	ds_write2_b32 v41, v62, v63 offset1:1
	ds_write2_b32 v41, v64, v65 offset0:2 offset1:3
	s_waitcnt lgkmcnt(0)
	ds_read2_b32 v[14:15], v30 offset1:33
	ds_read2_b32 v[16:17], v30 offset0:66 offset1:99
	ds_read2_b32 v[18:19], v30 offset0:132 offset1:165
	ds_read2_b32 v[20:21], v30 offset0:198 offset1:231
	ds_read2_b32 v[42:43], v31 offset1:33
	ds_read2_b32 v[44:45], v31 offset0:66 offset1:99
	ds_read2_b32 v[46:47], v31 offset0:132 offset1:165
	ds_read2_b32 v[48:49], v31 offset0:198 offset1:231
	ds_read2_b32 v[50:51], v32 offset1:33
	ds_read2_b32 v[52:53], v32 offset0:66 offset1:99
	ds_read2_b32 v[54:55], v32 offset0:132 offset1:165
	ds_read2_b32 v[56:57], v32 offset0:198 offset1:231
	ds_read2_b32 v[58:59], v33 offset1:33
	ds_read2_b32 v[60:61], v33 offset0:66 offset1:99
	ds_read2_b32 v[62:63], v33 offset0:132 offset1:165
	ds_read2_b32 v[64:65], v33 offset0:198 offset1:231
	s_waitcnt lgkmcnt(14)
; #define GAS __attribute__((address_space(1)))
; #define LAS __attribute__((address_space(3)))
; __device__ __forceinline__ unsigned f2bf(float f) { unsigned u = __builtin_bit_cast(unsigned, f); return (u + 0x7fffu + ((u >> 16) & 1u)) >> 16; }
; __device__ __forceinline__ unsigned pk2(float lo, float hi) { return f2bf(lo) | (f2bf(hi) << 16); }
; __device__ __forceinline__ void p0_transpose_item(const float* W, int N, bf16* WT, int ldt, int rowmode, LAS float* scr, int kb, int nb, int lane, const float* kgain) {
;     ...
;     for (int j = 0; j < 4; ++j) { const int n = (lane >> 3) + 8 * j; const LAS float* s = scr + (8 * c) * 33 + n;
;         v4u o; o.x = pk2(s[0 * 33], s[1 * 33]); o.y = pk2(s[2 * 33], s[3 * 33]); o.z = pk2(s[4 * 33], s[5 * 33]); o.w = pk2(s[6 * 33], s[7 * 33]);
;         const int ng = n0 + n; int row;
;         if (rowmode == 0) row = ng;
;         else if (rowmode == 3) { const int np = ng - (PW + 4 * HW); row = np < 0 ? ng : (PW + 4 * HW) + ((np & (D - 1)) >> 7) * 256 + (np >= D ? 128 : 0) + (np & 127); }
;         else row = (ng >> 7) * 256 + (rowmode == 2 ? 128 : 0) + (ng & 127);
;         *(GAS v4u*)(WT + (size_t)row * ldt + k0 + 8 * c) = o; }
	v_bfe_u32 v13, v14, 16, 1
	v_bfe_u32 v72, v15, 16, 1
	v_bfe_u32 v73, v16, 16, 1
	v_bfe_u32 v76, v17, 16, 1
	s_waitcnt lgkmcnt(13)
	v_bfe_u32 v77, v18, 16, 1
	v_bfe_u32 v78, v19, 16, 1
	s_waitcnt lgkmcnt(12)
	v_bfe_u32 v79, v20, 16, 1
	v_bfe_u32 v80, v21, 16, 1
	s_waitcnt lgkmcnt(11)
	v_bfe_u32 v81, v42, 16, 1
	v_bfe_u32 v82, v43, 16, 1
	s_waitcnt lgkmcnt(10)
	v_bfe_u32 v83, v44, 16, 1
	v_bfe_u32 v84, v45, 16, 1
	s_waitcnt lgkmcnt(9)
	v_bfe_u32 v85, v46, 16, 1
	v_bfe_u32 v86, v47, 16, 1
	s_waitcnt lgkmcnt(8)
	v_bfe_u32 v87, v48, 16, 1
	v_bfe_u32 v88, v49, 16, 1
	s_waitcnt lgkmcnt(7)
	v_bfe_u32 v89, v50, 16, 1
	v_bfe_u32 v90, v51, 16, 1
	s_waitcnt lgkmcnt(6)
	v_bfe_u32 v91, v52, 16, 1
	v_bfe_u32 v92, v53, 16, 1
	s_waitcnt lgkmcnt(5)
	v_bfe_u32 v93, v54, 16, 1
	v_bfe_u32 v94, v55, 16, 1
	s_waitcnt lgkmcnt(4)
	v_bfe_u32 v95, v56, 16, 1
	s_waitcnt lgkmcnt(3)
	v_bfe_u32 v98, v58, 16, 1
	s_waitcnt lgkmcnt(2)
	v_bfe_u32 v100, v60, 16, 1
	s_waitcnt lgkmcnt(1)
	v_bfe_u32 v102, v62, 16, 1
	s_waitcnt lgkmcnt(0)
	v_bfe_u32 v104, v64, 16, 1
	v_add3_u32 v13, v14, v13, s14
	v_add3_u32 v14, v15, v72, s14
	v_add3_u32 v15, v16, v73, s14
	v_add3_u32 v16, v17, v76, s14
	v_add3_u32 v17, v18, v77, s14
	v_add3_u32 v18, v19, v78, s14
	v_add3_u32 v19, v20, v79, s14
	v_bfe_u32 v96, v57, 16, 1
	v_bfe_u32 v97, v59, 16, 1
	v_bfe_u32 v99, v61, 16, 1
	v_bfe_u32 v101, v63, 16, 1
	v_bfe_u32 v103, v65, 16, 1
	v_add3_u32 v20, v21, v80, s14
	v_add3_u32 v21, v42, v81, s14
	v_add3_u32 v42, v43, v82, s14
	v_add3_u32 v43, v44, v83, s14
	v_add3_u32 v44, v45, v84, s14
	v_add3_u32 v45, v46, v85, s14
	v_add3_u32 v46, v47, v86, s14
	v_add3_u32 v47, v48, v87, s14
	v_add3_u32 v48, v49, v88, s14
	v_add3_u32 v49, v50, v89, s14
	v_add3_u32 v50, v51, v90, s14
	v_add3_u32 v51, v52, v91, s14
	v_add3_u32 v52, v53, v92, s14
	v_add3_u32 v53, v54, v93, s14
	v_add3_u32 v54, v55, v94, s14
	v_add3_u32 v55, v56, v95, s14
	v_add3_u32 v58, v58, v98, s14
	v_add3_u32 v60, v60, v100, s14
	v_add3_u32 v62, v62, v102, s14
	v_add3_u32 v64, v64, v104, s14
	v_lshrrev_b32_e32 v13, 16, v13
	v_lshrrev_b32_e32 v15, 16, v15
	v_lshrrev_b32_e32 v17, 16, v17
	v_lshrrev_b32_e32 v19, 16, v19
	v_add3_u32 v56, v57, v96, s14
	v_add3_u32 v57, v59, v97, s14
	v_add3_u32 v59, v61, v99, s14
	v_add3_u32 v61, v63, v101, s14
	v_add3_u32 v63, v65, v103, s14
	v_lshrrev_b32_e32 v21, 16, v21
	v_lshrrev_b32_e32 v43, 16, v43
	v_lshrrev_b32_e32 v45, 16, v45
	v_lshrrev_b32_e32 v47, 16, v47
	v_lshrrev_b32_e32 v49, 16, v49
	v_lshrrev_b32_e32 v51, 16, v51
	v_lshrrev_b32_e32 v53, 16, v53
	v_lshrrev_b32_e32 v55, 16, v55
	v_lshrrev_b32_e32 v58, 16, v58
	v_lshrrev_b32_e32 v60, 16, v60
	v_lshrrev_b32_e32 v62, 16, v62
	v_lshrrev_b32_e32 v64, 16, v64
	v_and_or_b32 v14, v14, s15, v13
	v_and_or_b32 v15, v16, s15, v15
	v_and_or_b32 v16, v18, s15, v17
	v_and_or_b32 v17, v20, s15, v19
	v_and_or_b32 v18, v42, s15, v21
	v_and_or_b32 v19, v44, s15, v43
	v_and_or_b32 v20, v46, s15, v45
	v_and_or_b32 v21, v48, s15, v47
	v_and_or_b32 v42, v50, s15, v49
	v_and_or_b32 v43, v52, s15, v51
	v_and_or_b32 v44, v54, s15, v53
	v_and_or_b32 v45, v56, s15, v55
	v_and_or_b32 v46, v57, s15, v58
	v_and_or_b32 v47, v59, s15, v60
	v_and_or_b32 v48, v61, s15, v62
	v_and_or_b32 v49, v63, s15, v64
	global_store_dwordx4 v[74:75], v[14:17], off sc1
	global_store_dwordx4 v[68:69], v[18:21], off sc1
	global_store_dwordx4 v[70:71], v[42:45], off sc1
	global_store_dwordx4 v[66:67], v[46:49], off sc1
	s_waitcnt lgkmcnt(0)
	s_cbranch_scc1 .LBB0_20
	s_branch .LBB0_17

; #define GAS __attribute__((address_space(1)))
; #define LAS __attribute__((address_space(3)))
; #define LDS_WAIT() asm volatile("s_waitcnt lgkmcnt(0)" ::: "memory")
; __device__ __forceinline__ void p0_transpose_item(const float* W, int N, bf16* WT, int ldt, int rowmode, LAS float* scr, int kb, int nb, int lane, const float* kgain) {
;     ...
;     const int lk = lane >> 3, ln = (lane & 7) * 4;
; #pragma unroll
;     for (int i = 0; i < 8; ++i) { const int kk = 8 * i + lk; f32x4 v = __builtin_nontemporal_load((const GAS f32x4*)(W + (size_t)(k0 + kk) * N + n0 + ln)); if (kgain) v = v * kgain[k0 + kk];
;         scr[kk * 33 + ln] = v[0]; scr[kk * 33 + ln + 1] = v[1]; scr[kk * 33 + ln + 2] = v[2]; scr[kk * 33 + ln + 3] = v[3]; }
;     LDS_WAIT(); asm volatile("" ::: "memory");
;     const int c = lane & 7;
; #pragma unroll
;     for (int j = 0; j < 4; ++j) { const int n = (lane >> 3) + 8 * j; const LAS float* s = scr + (8 * c) * 33 + n;
.LBB0_24:
	s_ashr_i32 s7, s6, 31
	s_lshr_b32 s7, s7, 25
	s_add_i32 s7, s6, s7
	s_ashr_i32 s7, s7, 7
	s_lshl_b32 s14, s7, 6
	s_lshl_b32 s7, s7, 12
	s_sub_i32 s16, s5, s7
	v_or_b32_e32 v6, s14, v22
	v_or_b32_e32 v8, s14, v23
	v_or_b32_e32 v14, s14, v24
	v_or_b32_e32 v16, s14, v25
	v_or_b32_e32 v18, s14, v26
	v_or_b32_e32 v20, s14, v27
	v_or_b32_e32 v42, s14, v28
	v_or_b32_e32 v44, s14, v29
	s_ashr_i32 s17, s16, 31
	v_ashrrev_i32_e32 v7, 31, v6
	v_ashrrev_i32_e32 v9, 31, v8
	v_ashrrev_i32_e32 v15, 31, v14
	v_ashrrev_i32_e32 v17, 31, v16
	v_ashrrev_i32_e32 v19, 31, v18
	v_ashrrev_i32_e32 v21, 31, v20
	v_ashrrev_i32_e32 v43, 31, v42
	v_ashrrev_i32_e32 v45, 31, v44
	v_add_u32_e32 v46, s16, v22
	v_lshl_add_u64 v[48:49], s[16:17], 2, v[2:3]
	v_lshlrev_b64 v[6:7], 14, v[6:7]
	v_lshlrev_b64 v[8:9], 14, v[8:9]
	v_lshlrev_b64 v[14:15], 14, v[14:15]
	v_lshlrev_b64 v[16:17], 14, v[16:17]
	v_lshlrev_b64 v[18:19], 14, v[18:19]
	v_lshlrev_b64 v[20:21], 14, v[20:21]
	v_lshlrev_b64 v[42:43], 14, v[42:43]
	v_lshlrev_b64 v[44:45], 14, v[44:45]
	v_ashrrev_i32_e32 v47, 31, v46
	v_lshl_add_u64 v[6:7], v[48:49], 0, v[6:7]
	v_lshl_add_u64 v[50:51], v[48:49], 0, v[8:9]
	v_lshl_add_u64 v[52:53], v[48:49], 0, v[14:15]
	v_lshl_add_u64 v[54:55], v[48:49], 0, v[16:17]
	v_lshl_add_u64 v[56:57], v[48:49], 0, v[18:19]
	v_lshl_add_u64 v[58:59], v[48:49], 0, v[20:21]
	v_lshl_add_u64 v[60:61], v[48:49], 0, v[42:43]
	v_add_u32_e32 v64, 8, v46
	v_add_u32_e32 v66, 16, v46
	v_add_u32_e32 v68, 24, v46
	v_lshl_add_u64 v[70:71], v[48:49], 0, v[44:45]
	v_lshlrev_b64 v[72:73], 13, v[46:47]
	global_load_dwordx4 v[6:9], v[6:7], off nt
	s_nop 0
	global_load_dwordx4 v[14:17], v[50:51], off nt
	global_load_dwordx4 v[18:21], v[52:53], off nt
	global_load_dwordx4 v[42:45], v[54:55], off nt
	global_load_dwordx4 v[46:49], v[56:57], off nt
	s_nop 0
	global_load_dwordx4 v[50:53], v[58:59], off nt
	global_load_dwordx4 v[54:57], v[60:61], off nt
	s_nop 0
	global_load_dwordx4 v[58:61], v[70:71], off nt
	s_ashr_i32 s15, s14, 31
	v_ashrrev_i32_e32 v65, 31, v64
	v_ashrrev_i32_e32 v67, 31, v66
	v_ashrrev_i32_e32 v69, 31, v68
	v_lshl_add_u64 v[62:63], s[14:15], 1, v[4:5]
	v_lshlrev_b64 v[64:65], 13, v[64:65]
	v_lshlrev_b64 v[66:67], 13, v[66:67]
	v_lshlrev_b64 v[68:69], 13, v[68:69]
	v_lshl_add_u64 v[70:71], v[62:63], 0, v[72:73]
	v_lshl_add_u64 v[64:65], v[62:63], 0, v[64:65]
	v_lshl_add_u64 v[66:67], v[62:63], 0, v[66:67]
	v_lshl_add_u64 v[62:63], v[62:63], 0, v[68:69]
	s_add_i32 s6, s6, s82
	s_add_i32 s5, s5, s8
	s_cmpk_lt_i32 s6, 0x1000
	s_waitcnt vmcnt(7)
	ds_write2_b32 v34, v6, v7 offset1:1
	ds_write2_b32 v34, v8, v9 offset0:2 offset1:3
	s_waitcnt vmcnt(6)
	ds_write2_b32 v35, v14, v15 offset1:1
	ds_write2_b32 v35, v16, v17 offset0:2 offset1:3
	s_waitcnt vmcnt(5)
	ds_write2_b32 v36, v18, v19 offset1:1
	ds_write2_b32 v36, v20, v21 offset0:2 offset1:3
	s_waitcnt vmcnt(4)
	ds_write2_b32 v37, v42, v43 offset1:1
	ds_write2_b32 v37, v44, v45 offset0:2 offset1:3
	s_waitcnt vmcnt(3)
	ds_write2_b32 v38, v46, v47 offset1:1
	ds_write2_b32 v38, v48, v49 offset0:2 offset1:3
	s_waitcnt vmcnt(2)
	ds_write2_b32 v39, v50, v51 offset1:1
	ds_write2_b32 v39, v52, v53 offset0:2 offset1:3
	s_waitcnt vmcnt(1)
	ds_write2_b32 v40, v54, v55 offset1:1
	ds_write2_b32 v40, v56, v57 offset0:2 offset1:3
	s_waitcnt vmcnt(0)
	ds_write2_b32 v41, v58, v59 offset1:1
	ds_write2_b32 v41, v60, v61 offset0:2 offset1:3
	s_waitcnt lgkmcnt(0)
	ds_read2_b32 v[6:7], v30 offset1:33
	ds_read2_b32 v[8:9], v30 offset0:66 offset1:99
	ds_read2_b32 v[14:15], v30 offset0:132 offset1:165
	ds_read2_b32 v[16:17], v30 offset0:198 offset1:231
	ds_read2_b32 v[18:19], v31 offset1:33
	ds_read2_b32 v[20:21], v31 offset0:66 offset1:99
	ds_read2_b32 v[42:43], v31 offset0:132 offset1:165
	ds_read2_b32 v[44:45], v31 offset0:198 offset1:231
	ds_read2_b32 v[46:47], v32 offset1:33
	ds_read2_b32 v[48:49], v32 offset0:66 offset1:99
	ds_read2_b32 v[50:51], v32 offset0:132 offset1:165
	ds_read2_b32 v[52:53], v32 offset0:198 offset1:231
	ds_read2_b32 v[54:55], v33 offset1:33
	ds_read2_b32 v[56:57], v33 offset0:66 offset1:99
	ds_read2_b32 v[58:59], v33 offset0:132 offset1:165
	ds_read2_b32 v[60:61], v33 offset0:198 offset1:231
	s_waitcnt lgkmcnt(14)
	v_bfe_u32 v13, v6, 16, 1
	v_bfe_u32 v69, v8, 16, 1
	s_waitcnt lgkmcnt(13)
	v_bfe_u32 v73, v14, 16, 1
	v_bfe_u32 v74, v15, 16, 1
	s_waitcnt lgkmcnt(12)
	v_bfe_u32 v75, v16, 16, 1
	v_bfe_u32 v68, v7, 16, 1
	v_bfe_u32 v72, v9, 16, 1
	v_bfe_u32 v76, v17, 16, 1
	s_waitcnt lgkmcnt(11)
	v_bfe_u32 v77, v18, 16, 1
	v_bfe_u32 v78, v19, 16, 1
	s_waitcnt lgkmcnt(10)
	v_bfe_u32 v79, v20, 16, 1
	v_bfe_u32 v80, v21, 16, 1
	s_waitcnt lgkmcnt(9)
	v_bfe_u32 v81, v42, 16, 1
	v_bfe_u32 v82, v43, 16, 1
	s_waitcnt lgkmcnt(8)
	v_bfe_u32 v83, v44, 16, 1
	v_bfe_u32 v84, v45, 16, 1
	s_waitcnt lgkmcnt(7)
	v_bfe_u32 v85, v46, 16, 1
	v_bfe_u32 v86, v47, 16, 1
	s_waitcnt lgkmcnt(6)
	v_bfe_u32 v87, v48, 16, 1
	v_bfe_u32 v88, v49, 16, 1
	s_waitcnt lgkmcnt(5)
	v_bfe_u32 v89, v50, 16, 1
	v_bfe_u32 v90, v51, 16, 1
	s_waitcnt lgkmcnt(4)
	v_bfe_u32 v91, v52, 16, 1
	s_waitcnt lgkmcnt(3)
	v_bfe_u32 v94, v54, 16, 1
	s_waitcnt lgkmcnt(2)
	v_bfe_u32 v96, v56, 16, 1
	s_waitcnt lgkmcnt(1)
	v_bfe_u32 v98, v58, 16, 1
	s_waitcnt lgkmcnt(0)
; #define GAS __attribute__((address_space(1)))
; #define LAS __attribute__((address_space(3)))
; __device__ __forceinline__ unsigned pk2(float lo, float hi) { return f2bf(lo) | (f2bf(hi) << 16); }
; __device__ __forceinline__ void p0_transpose_item(const float* W, int N, bf16* WT, int ldt, int rowmode, LAS float* scr, int kb, int nb, int lane, const float* kgain) {
;     ...
;     const int lk = lane >> 3, ln = (lane & 7) * 4;
; #pragma unroll
;     for (int i = 0; i < 8; ++i) { const int kk = 8 * i + lk; f32x4 v = __builtin_nontemporal_load((const GAS f32x4*)(W + (size_t)(k0 + kk) * N + n0 + ln)); if (kgain) v = v * kgain[k0 + kk];
;         scr[kk * 33 + ln] = v[0]; scr[kk * 33 + ln + 1] = v[1]; scr[kk * 33 + ln + 2] = v[2]; scr[kk * 33 + ln + 3] = v[3]; }
;     ...
;     for (int j = 0; j < 4; ++j) { const int n = (lane >> 3) + 8 * j; const LAS float* s = scr + (8 * c) * 33 + n;
;         v4u o; o.x = pk2(s[0 * 33], s[1 * 33]); o.y = pk2(s[2 * 33], s[3 * 33]); o.z = pk2(s[4 * 33], s[5 * 33]); o.w = pk2(s[6 * 33], s[7 * 33]);
;         const int ng = n0 + n; int row;
;         if (rowmode == 0) row = ng;
;         else if (rowmode == 3) { const int np = ng - (PW + 4 * HW); row = np < 0 ? ng : (PW + 4 * HW) + ((np & (D - 1)) >> 7) * 256 + (np >= D ? 128 : 0) + (np & 127); }
;         else row = (ng >> 7) * 256 + (rowmode == 2 ? 128 : 0) + (ng & 127);
;         *(GAS v4u*)(WT + (size_t)row * ldt + k0 + 8 * c) = o; }
	v_bfe_u32 v100, v60, 16, 1
	v_add3_u32 v6, v6, v13, s1
	v_add3_u32 v8, v8, v69, s1
	v_add3_u32 v13, v14, v73, s1
	v_add3_u32 v14, v15, v74, s1
	v_add3_u32 v15, v16, v75, s1
	v_bfe_u32 v92, v53, 16, 1
	v_bfe_u32 v93, v55, 16, 1
	v_bfe_u32 v95, v57, 16, 1
	v_bfe_u32 v97, v59, 16, 1
	v_bfe_u32 v99, v61, 16, 1
	v_add3_u32 v7, v7, v68, s1
	v_add3_u32 v9, v9, v72, s1
	v_add3_u32 v16, v17, v76, s1
	v_add3_u32 v17, v18, v77, s1
	v_add3_u32 v18, v19, v78, s1
	v_add3_u32 v19, v20, v79, s1
	v_add3_u32 v20, v21, v80, s1
	v_add3_u32 v21, v42, v81, s1
	v_add3_u32 v42, v43, v82, s1
	v_add3_u32 v43, v44, v83, s1
	v_add3_u32 v44, v45, v84, s1
	v_add3_u32 v45, v46, v85, s1
	v_add3_u32 v46, v47, v86, s1
	v_add3_u32 v47, v48, v87, s1
	v_add3_u32 v48, v49, v88, s1
	v_add3_u32 v49, v50, v89, s1
	v_add3_u32 v50, v51, v90, s1
	v_add3_u32 v51, v52, v91, s1
	v_add3_u32 v54, v54, v94, s1
	v_add3_u32 v56, v56, v96, s1
	v_add3_u32 v58, v58, v98, s1
	v_add3_u32 v60, v60, v100, s1
	v_lshrrev_b32_e32 v6, 16, v6
	v_lshrrev_b32_e32 v8, 16, v8
	v_lshrrev_b32_e32 v13, 16, v13
	v_lshrrev_b32_e32 v15, 16, v15
	v_add3_u32 v52, v53, v92, s1
	v_add3_u32 v53, v55, v93, s1
	v_add3_u32 v55, v57, v95, s1
	v_add3_u32 v57, v59, v97, s1
	v_add3_u32 v59, v61, v99, s1
	v_lshrrev_b32_e32 v17, 16, v17
	v_lshrrev_b32_e32 v19, 16, v19
	v_lshrrev_b32_e32 v21, 16, v21
	v_lshrrev_b32_e32 v43, 16, v43
	v_lshrrev_b32_e32 v45, 16, v45
	v_lshrrev_b32_e32 v47, 16, v47
	v_lshrrev_b32_e32 v49, 16, v49
	v_lshrrev_b32_e32 v51, 16, v51
	v_lshrrev_b32_e32 v54, 16, v54
	v_lshrrev_b32_e32 v56, 16, v56
	v_lshrrev_b32_e32 v58, 16, v58
	v_lshrrev_b32_e32 v60, 16, v60
	v_and_or_b32 v6, v7, s4, v6
	v_and_or_b32 v7, v9, s4, v8
	v_and_or_b32 v8, v14, s4, v13
	v_and_or_b32 v9, v16, s4, v15
	v_and_or_b32 v14, v18, s4, v17
	v_and_or_b32 v15, v20, s4, v19
	v_and_or_b32 v16, v42, s4, v21
	v_and_or_b32 v17, v44, s4, v43
	v_and_or_b32 v18, v46, s4, v45
	v_and_or_b32 v19, v48, s4, v47
	v_and_or_b32 v20, v50, s4, v49
	v_and_or_b32 v21, v52, s4, v51
	v_and_or_b32 v42, v53, s4, v54
	v_and_or_b32 v43, v55, s4, v56
	v_and_or_b32 v44, v57, s4, v58
	v_and_or_b32 v45, v59, s4, v60
	global_store_dwordx4 v[70:71], v[6:9], off sc1
	global_store_dwordx4 v[64:65], v[14:17], off sc1
	global_store_dwordx4 v[66:67], v[18:21], off sc1
	global_store_dwordx4 v[62:63], v[42:45], off sc1
	s_waitcnt lgkmcnt(0)
	s_cbranch_scc1 .LBB0_24
	v_mov_b32_e32 v13, 0
	v_lshl_add_u64 v[4:5], v[10:11], 1, s[68:69]
	s_mov_b64 s[4:5], 0x9301000
	v_lshl_add_u64 v[2:3], s[36:37], 0, v[12:13]
	v_lshl_add_u64 v[4:5], v[4:5], 0, s[4:5]
	s_movk_i32 s1, 0x7fff
	s_mov_b32 s4, 0xffff0000
	s_mov_b32 s5, s80
.LBB0_26:
	s_ashr_i32 s6, s5, 31
	s_lshr_b32 s6, s6, 25
	s_add_i32 s6, s5, s6
	s_ashr_i32 s7, s6, 7
	s_lshl_b32 s6, s7, 6
	s_lshl_b32 s7, s7, 12
	s_sub_i32 s14, s0, s7
	v_or_b32_e32 v6, s6, v22
	v_or_b32_e32 v8, s6, v23
	v_or_b32_e32 v14, s6, v24
	v_or_b32_e32 v16, s6, v25
	v_or_b32_e32 v18, s6, v26
	v_or_b32_e32 v20, s6, v27
	v_or_b32_e32 v42, s6, v28
	v_or_b32_e32 v44, s6, v29
	s_ashr_i32 s15, s14, 31
	v_ashrrev_i32_e32 v7, 31, v6
	v_ashrrev_i32_e32 v9, 31, v8
	v_ashrrev_i32_e32 v15, 31, v14
	v_ashrrev_i32_e32 v17, 31, v16
	v_ashrrev_i32_e32 v19, 31, v18
	v_ashrrev_i32_e32 v21, 31, v20
	v_ashrrev_i32_e32 v43, 31, v42
	v_ashrrev_i32_e32 v45, 31, v44
	v_add_u32_e32 v46, s14, v22
	v_lshl_add_u64 v[48:49], s[14:15], 2, v[2:3]
	v_lshlrev_b64 v[6:7], 14, v[6:7]
	v_lshlrev_b64 v[8:9], 14, v[8:9]
	v_lshlrev_b64 v[14:15], 14, v[14:15]
	v_lshlrev_b64 v[16:17], 14, v[16:17]
	v_lshlrev_b64 v[18:19], 14, v[18:19]
	v_lshlrev_b64 v[20:21], 14, v[20:21]
	v_lshlrev_b64 v[42:43], 14, v[42:43]
	v_lshlrev_b64 v[44:45], 14, v[44:45]
	v_ashrrev_i32_e32 v47, 31, v46
	v_lshl_add_u64 v[6:7], v[48:49], 0, v[6:7]
	v_lshl_add_u64 v[50:51], v[48:49], 0, v[8:9]
	v_lshl_add_u64 v[52:53], v[48:49], 0, v[14:15]
	v_lshl_add_u64 v[54:55], v[48:49], 0, v[16:17]
	v_lshl_add_u64 v[56:57], v[48:49], 0, v[18:19]
	v_lshl_add_u64 v[58:59], v[48:49], 0, v[20:21]
	v_lshl_add_u64 v[60:61], v[48:49], 0, v[42:43]
	v_add_u32_e32 v64, 8, v46
	v_add_u32_e32 v66, 16, v46
	v_add_u32_e32 v68, 24, v46
	v_lshl_add_u64 v[70:71], v[48:49], 0, v[44:45]
	v_lshlrev_b64 v[72:73], 13, v[46:47]
	global_load_dwordx4 v[6:9], v[6:7], off nt
	s_nop 0
	global_load_dwordx4 v[14:17], v[50:51], off nt
	global_load_dwordx4 v[18:21], v[52:53], off nt
	global_load_dwordx4 v[42:45], v[54:55], off nt
	global_load_dwordx4 v[46:49], v[56:57], off nt
	s_nop 0
	global_load_dwordx4 v[50:53], v[58:59], off nt
	global_load_dwordx4 v[54:57], v[60:61], off nt
	s_nop 0
	global_load_dwordx4 v[58:61], v[70:71], off nt
	s_ashr_i32 s7, s6, 31
	v_ashrrev_i32_e32 v65, 31, v64
	v_ashrrev_i32_e32 v67, 31, v66
	v_ashrrev_i32_e32 v69, 31, v68
	v_lshl_add_u64 v[62:63], s[6:7], 1, v[4:5]
	v_lshlrev_b64 v[64:65], 13, v[64:65]
	v_lshlrev_b64 v[66:67], 13, v[66:67]
	v_lshlrev_b64 v[68:69], 13, v[68:69]
	v_lshl_add_u64 v[70:71], v[62:63], 0, v[72:73]
	v_lshl_add_u64 v[64:65], v[62:63], 0, v[64:65]
	v_lshl_add_u64 v[66:67], v[62:63], 0, v[66:67]
	v_lshl_add_u64 v[62:63], v[62:63], 0, v[68:69]
	s_add_i32 s5, s5, s82
	s_add_i32 s0, s0, s8
	s_cmpk_lt_i32 s5, 0x1000
	s_waitcnt vmcnt(7)
; #define GAS __attribute__((address_space(1)))
; #define LAS __attribute__((address_space(3)))
; #define LDS_WAIT() asm volatile("s_waitcnt lgkmcnt(0)" ::: "memory")
; __device__ __forceinline__ unsigned pk2(float lo, float hi) { return f2bf(lo) | (f2bf(hi) << 16); }
; __device__ __forceinline__ void p0_transpose_item(const float* W, int N, bf16* WT, int ldt, int rowmode, LAS float* scr, int kb, int nb, int lane, const float* kgain) {
;     ...
;         scr[kk * 33 + ln] = v[0]; scr[kk * 33 + ln + 1] = v[1]; scr[kk * 33 + ln + 2] = v[2]; scr[kk * 33 + ln + 3] = v[3]; }
;     LDS_WAIT(); asm volatile("" ::: "memory");
;     const int c = lane & 7;
; #pragma unroll
;     for (int j = 0; j < 4; ++j) { const int n = (lane >> 3) + 8 * j; const LAS float* s = scr + (8 * c) * 33 + n;
;         v4u o; o.x = pk2(s[0 * 33], s[1 * 33]); o.y = pk2(s[2 * 33], s[3 * 33]); o.z = pk2(s[4 * 33], s[5 * 33]); o.w = pk2(s[6 * 33], s[7 * 33]);
;         const int ng = n0 + n; int row;
;         if (rowmode == 0) row = ng;
;         else if (rowmode == 3) { const int np = ng - (PW + 4 * HW); row = np < 0 ? ng : (PW + 4 * HW) + ((np & (D - 1)) >> 7) * 256 + (np >= D ? 128 : 0) + (np & 127); }
;         else row = (ng >> 7) * 256 + (rowmode == 2 ? 128 : 0) + (ng & 127);
;         *(GAS v4u*)(WT + (size_t)row * ldt + k0 + 8 * c) = o; }
	ds_write2_b32 v34, v6, v7 offset1:1
	ds_write2_b32 v34, v8, v9 offset0:2 offset1:3
	s_waitcnt vmcnt(6)
	ds_write2_b32 v35, v14, v15 offset1:1
	ds_write2_b32 v35, v16, v17 offset0:2 offset1:3
	s_waitcnt vmcnt(5)
	ds_write2_b32 v36, v18, v19 offset1:1
	ds_write2_b32 v36, v20, v21 offset0:2 offset1:3
	s_waitcnt vmcnt(4)
	ds_write2_b32 v37, v42, v43 offset1:1
	ds_write2_b32 v37, v44, v45 offset0:2 offset1:3
	s_waitcnt vmcnt(3)
	ds_write2_b32 v38, v46, v47 offset1:1
	ds_write2_b32 v38, v48, v49 offset0:2 offset1:3
	s_waitcnt vmcnt(2)
	ds_write2_b32 v39, v50, v51 offset1:1
	ds_write2_b32 v39, v52, v53 offset0:2 offset1:3
	s_waitcnt vmcnt(1)
	ds_write2_b32 v40, v54, v55 offset1:1
	ds_write2_b32 v40, v56, v57 offset0:2 offset1:3
	s_waitcnt vmcnt(0)
	ds_write2_b32 v41, v58, v59 offset1:1
	ds_write2_b32 v41, v60, v61 offset0:2 offset1:3
	s_waitcnt lgkmcnt(0)
	ds_read2_b32 v[6:7], v30 offset1:33
	ds_read2_b32 v[8:9], v30 offset0:66 offset1:99
	ds_read2_b32 v[14:15], v30 offset0:132 offset1:165
	ds_read2_b32 v[16:17], v30 offset0:198 offset1:231
	ds_read2_b32 v[18:19], v31 offset1:33
	ds_read2_b32 v[20:21], v31 offset0:66 offset1:99
	ds_read2_b32 v[42:43], v31 offset0:132 offset1:165
	ds_read2_b32 v[44:45], v31 offset0:198 offset1:231
	ds_read2_b32 v[46:47], v32 offset1:33
	ds_read2_b32 v[48:49], v32 offset0:66 offset1:99
	ds_read2_b32 v[50:51], v32 offset0:132 offset1:165
	ds_read2_b32 v[52:53], v32 offset0:198 offset1:231
	ds_read2_b32 v[54:55], v33 offset1:33
	ds_read2_b32 v[56:57], v33 offset0:66 offset1:99
	ds_read2_b32 v[58:59], v33 offset0:132 offset1:165
	ds_read2_b32 v[60:61], v33 offset0:198 offset1:231
	s_waitcnt lgkmcnt(14)
	v_bfe_u32 v13, v6, 16, 1
	v_bfe_u32 v69, v8, 16, 1
	s_waitcnt lgkmcnt(13)
	v_bfe_u32 v73, v14, 16, 1
	v_bfe_u32 v74, v15, 16, 1
	s_waitcnt lgkmcnt(12)
	v_bfe_u32 v75, v16, 16, 1
	v_bfe_u32 v68, v7, 16, 1
	v_bfe_u32 v72, v9, 16, 1
	v_bfe_u32 v76, v17, 16, 1
	s_waitcnt lgkmcnt(11)
	v_bfe_u32 v77, v18, 16, 1
	v_bfe_u32 v78, v19, 16, 1
	s_waitcnt lgkmcnt(10)
	v_bfe_u32 v79, v20, 16, 1
	v_bfe_u32 v80, v21, 16, 1
	s_waitcnt lgkmcnt(9)
	v_bfe_u32 v81, v42, 16, 1
	v_bfe_u32 v82, v43, 16, 1
	s_waitcnt lgkmcnt(8)
	v_bfe_u32 v83, v44, 16, 1
	v_bfe_u32 v84, v45, 16, 1
	s_waitcnt lgkmcnt(7)
	v_bfe_u32 v85, v46, 16, 1
	v_bfe_u32 v86, v47, 16, 1
	s_waitcnt lgkmcnt(6)
	v_bfe_u32 v87, v48, 16, 1
	v_bfe_u32 v88, v49, 16, 1
	s_waitcnt lgkmcnt(5)
	v_bfe_u32 v89, v50, 16, 1
	v_bfe_u32 v90, v51, 16, 1
	s_waitcnt lgkmcnt(4)
	v_bfe_u32 v91, v52, 16, 1
	s_waitcnt lgkmcnt(3)
	v_bfe_u32 v94, v54, 16, 1
	s_waitcnt lgkmcnt(2)
	v_bfe_u32 v96, v56, 16, 1
	s_waitcnt lgkmcnt(1)
	v_bfe_u32 v98, v58, 16, 1
	s_waitcnt lgkmcnt(0)
	v_bfe_u32 v100, v60, 16, 1
	v_add3_u32 v6, v6, v13, s1
	v_add3_u32 v8, v8, v69, s1
	v_add3_u32 v13, v14, v73, s1
	v_add3_u32 v14, v15, v74, s1
	v_add3_u32 v15, v16, v75, s1
	v_bfe_u32 v92, v53, 16, 1
	v_bfe_u32 v93, v55, 16, 1
	v_bfe_u32 v95, v57, 16, 1
	v_bfe_u32 v97, v59, 16, 1
	v_bfe_u32 v99, v61, 16, 1
	v_add3_u32 v7, v7, v68, s1
	v_add3_u32 v9, v9, v72, s1
	v_add3_u32 v16, v17, v76, s1
	v_add3_u32 v17, v18, v77, s1
	v_add3_u32 v18, v19, v78, s1
	v_add3_u32 v19, v20, v79, s1
	v_add3_u32 v20, v21, v80, s1
	v_add3_u32 v21, v42, v81, s1
	v_add3_u32 v42, v43, v82, s1
	v_add3_u32 v43, v44, v83, s1
	v_add3_u32 v44, v45, v84, s1
	v_add3_u32 v45, v46, v85, s1
	v_add3_u32 v46, v47, v86, s1
	v_add3_u32 v47, v48, v87, s1
	v_add3_u32 v48, v49, v88, s1
	v_add3_u32 v49, v50, v89, s1
	v_add3_u32 v50, v51, v90, s1
	v_add3_u32 v51, v52, v91, s1
	v_add3_u32 v54, v54, v94, s1
	v_add3_u32 v56, v56, v96, s1
	v_add3_u32 v58, v58, v98, s1
	v_add3_u32 v60, v60, v100, s1
	v_lshrrev_b32_e32 v6, 16, v6
	v_lshrrev_b32_e32 v8, 16, v8
	v_lshrrev_b32_e32 v13, 16, v13
	v_lshrrev_b32_e32 v15, 16, v15
	v_add3_u32 v52, v53, v92, s1
	v_add3_u32 v53, v55, v93, s1
	v_add3_u32 v55, v57, v95, s1
	v_add3_u32 v57, v59, v97, s1
	v_add3_u32 v59, v61, v99, s1
	v_lshrrev_b32_e32 v17, 16, v17
	v_lshrrev_b32_e32 v19, 16, v19
	v_lshrrev_b32_e32 v21, 16, v21
	v_lshrrev_b32_e32 v43, 16, v43
	v_lshrrev_b32_e32 v45, 16, v45
	v_lshrrev_b32_e32 v47, 16, v47
	v_lshrrev_b32_e32 v49, 16, v49
	v_lshrrev_b32_e32 v51, 16, v51
	v_lshrrev_b32_e32 v54, 16, v54
	v_lshrrev_b32_e32 v56, 16, v56
	v_lshrrev_b32_e32 v58, 16, v58
	v_lshrrev_b32_e32 v60, 16, v60
	v_and_or_b32 v6, v7, s4, v6
	v_and_or_b32 v7, v9, s4, v8
	v_and_or_b32 v8, v14, s4, v13
	v_and_or_b32 v9, v16, s4, v15
	v_and_or_b32 v14, v18, s4, v17
	v_and_or_b32 v15, v20, s4, v19
	v_and_or_b32 v16, v42, s4, v21
	v_and_or_b32 v17, v44, s4, v43
	v_and_or_b32 v18, v46, s4, v45
	v_and_or_b32 v19, v48, s4, v47
	v_and_or_b32 v20, v50, s4, v49
	v_and_or_b32 v21, v52, s4, v51
	v_and_or_b32 v42, v53, s4, v54
	v_and_or_b32 v43, v55, s4, v56
	v_and_or_b32 v44, v57, s4, v58
	v_and_or_b32 v45, v59, s4, v60
	global_store_dwordx4 v[70:71], v[6:9], off sc1
	global_store_dwordx4 v[64:65], v[14:17], off sc1
	global_store_dwordx4 v[66:67], v[18:21], off sc1
	global_store_dwordx4 v[62:63], v[42:45], off sc1
	s_waitcnt lgkmcnt(0)
	s_cbranch_scc1 .LBB0_26

; #define GAS __attribute__((address_space(1)))
; #define LDS_WAIT() asm volatile("s_waitcnt lgkmcnt(0)" ::: "memory")
; __device__ __forceinline__ void p0_transpose_item(const float* W, int N, bf16* WT, int ldt, int rowmode, LAS float* scr, int kb, int nb, int lane, const float* kgain) {
;     ...
;     const int lk = lane >> 3, ln = (lane & 7) * 4;
; #pragma unroll
;     for (int i = 0; i < 8; ++i) { const int kk = 8 * i + lk; f32x4 v = __builtin_nontemporal_load((const GAS f32x4*)(W + (size_t)(k0 + kk) * N + n0 + ln)); if (kgain) v = v * kgain[k0 + kk];
;         scr[kk * 33 + ln] = v[0]; scr[kk * 33 + ln + 1] = v[1]; scr[kk * 33 + ln + 2] = v[2]; scr[kk * 33 + ln + 3] = v[3]; }
;     LDS_WAIT(); asm volatile("" ::: "memory");
.LBB0_29:
	s_ashr_i32 s6, s5, 31
	s_lshr_b32 s6, s6, 25
	s_add_i32 s6, s5, s6
	s_ashr_i32 s7, s6, 7
	s_lshl_b32 s6, s7, 6
	s_lshl_b32 s7, s7, 12
	s_sub_i32 s14, s0, s7
	v_or_b32_e32 v6, s6, v22
	v_or_b32_e32 v8, s6, v23
	v_or_b32_e32 v14, s6, v24
	v_or_b32_e32 v16, s6, v25
	v_or_b32_e32 v18, s6, v26
	v_or_b32_e32 v20, s6, v27
	v_or_b32_e32 v42, s6, v28
	v_or_b32_e32 v44, s6, v29
	s_ashr_i32 s15, s14, 31
	v_ashrrev_i32_e32 v7, 31, v6
	v_ashrrev_i32_e32 v9, 31, v8
	v_ashrrev_i32_e32 v15, 31, v14
	v_ashrrev_i32_e32 v17, 31, v16
	v_ashrrev_i32_e32 v19, 31, v18
	v_ashrrev_i32_e32 v21, 31, v20
	v_ashrrev_i32_e32 v43, 31, v42
	v_ashrrev_i32_e32 v45, 31, v44
	v_add_u32_e32 v46, s14, v22
	v_lshl_add_u64 v[48:49], s[14:15], 2, v[2:3]
	v_lshlrev_b64 v[6:7], 14, v[6:7]
	v_lshlrev_b64 v[8:9], 14, v[8:9]
	v_lshlrev_b64 v[14:15], 14, v[14:15]
	v_lshlrev_b64 v[16:17], 14, v[16:17]
	v_lshlrev_b64 v[18:19], 14, v[18:19]
	v_lshlrev_b64 v[20:21], 14, v[20:21]
	v_lshlrev_b64 v[42:43], 14, v[42:43]
	v_lshlrev_b64 v[44:45], 14, v[44:45]
	v_ashrrev_i32_e32 v47, 31, v46
	v_lshl_add_u64 v[6:7], v[48:49], 0, v[6:7]
	v_lshl_add_u64 v[50:51], v[48:49], 0, v[8:9]
	v_lshl_add_u64 v[52:53], v[48:49], 0, v[14:15]
	v_lshl_add_u64 v[54:55], v[48:49], 0, v[16:17]
	v_lshl_add_u64 v[56:57], v[48:49], 0, v[18:19]
	v_lshl_add_u64 v[58:59], v[48:49], 0, v[20:21]
	v_lshl_add_u64 v[60:61], v[48:49], 0, v[42:43]
	v_add_u32_e32 v64, 8, v46
	v_add_u32_e32 v66, 16, v46
	v_add_u32_e32 v68, 24, v46
	v_lshl_add_u64 v[70:71], v[48:49], 0, v[44:45]
	v_lshlrev_b64 v[72:73], 13, v[46:47]
	global_load_dwordx4 v[6:9], v[6:7], off nt
	s_nop 0
	global_load_dwordx4 v[14:17], v[50:51], off nt
	global_load_dwordx4 v[18:21], v[52:53], off nt
	global_load_dwordx4 v[42:45], v[54:55], off nt
	global_load_dwordx4 v[46:49], v[56:57], off nt
	s_nop 0
	global_load_dwordx4 v[50:53], v[58:59], off nt
	global_load_dwordx4 v[54:57], v[60:61], off nt
	s_nop 0
	global_load_dwordx4 v[58:61], v[70:71], off nt
	s_ashr_i32 s7, s6, 31
	v_ashrrev_i32_e32 v65, 31, v64
	v_ashrrev_i32_e32 v67, 31, v66
	v_ashrrev_i32_e32 v69, 31, v68
	v_lshl_add_u64 v[62:63], s[6:7], 1, v[4:5]
	v_lshlrev_b64 v[64:65], 13, v[64:65]
	v_lshlrev_b64 v[66:67], 13, v[66:67]
	v_lshlrev_b64 v[68:69], 13, v[68:69]
	v_lshl_add_u64 v[70:71], v[62:63], 0, v[72:73]
	v_lshl_add_u64 v[64:65], v[62:63], 0, v[64:65]
	v_lshl_add_u64 v[66:67], v[62:63], 0, v[66:67]
	v_lshl_add_u64 v[62:63], v[62:63], 0, v[68:69]
	s_add_i32 s5, s5, s82
	s_add_i32 s0, s0, s8
	s_cmpk_lt_i32 s5, 0x2000
	s_waitcnt vmcnt(7)
	ds_write2_b32 v34, v6, v7 offset1:1
	ds_write2_b32 v34, v8, v9 offset0:2 offset1:3
	s_waitcnt vmcnt(6)
	ds_write2_b32 v35, v14, v15 offset1:1
	ds_write2_b32 v35, v16, v17 offset0:2 offset1:3
	s_waitcnt vmcnt(5)
	ds_write2_b32 v36, v18, v19 offset1:1
	ds_write2_b32 v36, v20, v21 offset0:2 offset1:3
	s_waitcnt vmcnt(4)
	ds_write2_b32 v37, v42, v43 offset1:1
	ds_write2_b32 v37, v44, v45 offset0:2 offset1:3
	s_waitcnt vmcnt(3)
	ds_write2_b32 v38, v46, v47 offset1:1
	ds_write2_b32 v38, v48, v49 offset0:2 offset1:3
	s_waitcnt vmcnt(2)
	ds_write2_b32 v39, v50, v51 offset1:1
	ds_write2_b32 v39, v52, v53 offset0:2 offset1:3
	s_waitcnt vmcnt(1)
	ds_write2_b32 v40, v54, v55 offset1:1
	ds_write2_b32 v40, v56, v57 offset0:2 offset1:3
	s_waitcnt vmcnt(0)
	ds_write2_b32 v41, v58, v59 offset1:1
	ds_write2_b32 v41, v60, v61 offset0:2 offset1:3
	s_waitcnt lgkmcnt(0)
; #define GAS __attribute__((address_space(1)))
; #define LAS __attribute__((address_space(3)))
; __device__ __forceinline__ unsigned pk2(float lo, float hi) { return f2bf(lo) | (f2bf(hi) << 16); }
; __device__ __forceinline__ void p0_transpose_item(const float* W, int N, bf16* WT, int ldt, int rowmode, LAS float* scr, int kb, int nb, int lane, const float* kgain) {
;     ...
;     for (int j = 0; j < 4; ++j) { const int n = (lane >> 3) + 8 * j; const LAS float* s = scr + (8 * c) * 33 + n;
;         v4u o; o.x = pk2(s[0 * 33], s[1 * 33]); o.y = pk2(s[2 * 33], s[3 * 33]); o.z = pk2(s[4 * 33], s[5 * 33]); o.w = pk2(s[6 * 33], s[7 * 33]);
;         const int ng = n0 + n; int row;
;         if (rowmode == 0) row = ng;
;         else if (rowmode == 3) { const int np = ng - (PW + 4 * HW); row = np < 0 ? ng : (PW + 4 * HW) + ((np & (D - 1)) >> 7) * 256 + (np >= D ? 128 : 0) + (np & 127); }
;         else row = (ng >> 7) * 256 + (rowmode == 2 ? 128 : 0) + (ng & 127);
;         *(GAS v4u*)(WT + (size_t)row * ldt + k0 + 8 * c) = o; }
	ds_read2_b32 v[6:7], v30 offset1:33
	ds_read2_b32 v[8:9], v30 offset0:66 offset1:99
	ds_read2_b32 v[14:15], v30 offset0:132 offset1:165
	ds_read2_b32 v[16:17], v30 offset0:198 offset1:231
	ds_read2_b32 v[18:19], v31 offset1:33
	ds_read2_b32 v[20:21], v31 offset0:66 offset1:99
	ds_read2_b32 v[42:43], v31 offset0:132 offset1:165
	ds_read2_b32 v[44:45], v31 offset0:198 offset1:231
	ds_read2_b32 v[46:47], v32 offset1:33
	ds_read2_b32 v[48:49], v32 offset0:66 offset1:99
	ds_read2_b32 v[50:51], v32 offset0:132 offset1:165
	ds_read2_b32 v[52:53], v32 offset0:198 offset1:231
	ds_read2_b32 v[54:55], v33 offset1:33
	ds_read2_b32 v[56:57], v33 offset0:66 offset1:99
	ds_read2_b32 v[58:59], v33 offset0:132 offset1:165
	ds_read2_b32 v[60:61], v33 offset0:198 offset1:231
	s_waitcnt lgkmcnt(14)
	v_bfe_u32 v13, v6, 16, 1
	v_bfe_u32 v69, v8, 16, 1
	s_waitcnt lgkmcnt(13)
	v_bfe_u32 v73, v14, 16, 1
	v_bfe_u32 v74, v15, 16, 1
	s_waitcnt lgkmcnt(12)
	v_bfe_u32 v75, v16, 16, 1
	v_bfe_u32 v68, v7, 16, 1
	v_bfe_u32 v72, v9, 16, 1
	v_bfe_u32 v76, v17, 16, 1
	s_waitcnt lgkmcnt(11)
	v_bfe_u32 v77, v18, 16, 1
	v_bfe_u32 v78, v19, 16, 1
	s_waitcnt lgkmcnt(10)
	v_bfe_u32 v79, v20, 16, 1
	v_bfe_u32 v80, v21, 16, 1
	s_waitcnt lgkmcnt(9)
	v_bfe_u32 v81, v42, 16, 1
	v_bfe_u32 v82, v43, 16, 1
	s_waitcnt lgkmcnt(8)
	v_bfe_u32 v83, v44, 16, 1
	v_bfe_u32 v84, v45, 16, 1
	s_waitcnt lgkmcnt(7)
	v_bfe_u32 v85, v46, 16, 1
	v_bfe_u32 v86, v47, 16, 1
	s_waitcnt lgkmcnt(6)
	v_bfe_u32 v87, v48, 16, 1
	v_bfe_u32 v88, v49, 16, 1
	s_waitcnt lgkmcnt(5)
	v_bfe_u32 v89, v50, 16, 1
	v_bfe_u32 v90, v51, 16, 1
	s_waitcnt lgkmcnt(4)
	v_bfe_u32 v91, v52, 16, 1
	s_waitcnt lgkmcnt(3)
	v_bfe_u32 v94, v54, 16, 1
	s_waitcnt lgkmcnt(2)
	v_bfe_u32 v96, v56, 16, 1
	s_waitcnt lgkmcnt(1)
	v_bfe_u32 v98, v58, 16, 1
	s_waitcnt lgkmcnt(0)
	v_bfe_u32 v100, v60, 16, 1
	v_add3_u32 v6, v6, v13, s1
	v_add3_u32 v8, v8, v69, s1
	v_add3_u32 v13, v14, v73, s1
	v_add3_u32 v14, v15, v74, s1
	v_add3_u32 v15, v16, v75, s1
	v_bfe_u32 v92, v53, 16, 1
	v_bfe_u32 v93, v55, 16, 1
	v_bfe_u32 v95, v57, 16, 1
	v_bfe_u32 v97, v59, 16, 1
	v_bfe_u32 v99, v61, 16, 1
	v_add3_u32 v7, v7, v68, s1
	v_add3_u32 v9, v9, v72, s1
	v_add3_u32 v16, v17, v76, s1
	v_add3_u32 v17, v18, v77, s1
	v_add3_u32 v18, v19, v78, s1
	v_add3_u32 v19, v20, v79, s1
	v_add3_u32 v20, v21, v80, s1
	v_add3_u32 v21, v42, v81, s1
	v_add3_u32 v42, v43, v82, s1
	v_add3_u32 v43, v44, v83, s1
	v_add3_u32 v44, v45, v84, s1
	v_add3_u32 v45, v46, v85, s1
	v_add3_u32 v46, v47, v86, s1
	v_add3_u32 v47, v48, v87, s1
	v_add3_u32 v48, v49, v88, s1
	v_add3_u32 v49, v50, v89, s1
	v_add3_u32 v50, v51, v90, s1
	v_add3_u32 v51, v52, v91, s1
	v_add3_u32 v54, v54, v94, s1
	v_add3_u32 v56, v56, v96, s1
	v_add3_u32 v58, v58, v98, s1
	v_add3_u32 v60, v60, v100, s1
	v_lshrrev_b32_e32 v6, 16, v6
	v_lshrrev_b32_e32 v8, 16, v8
	v_lshrrev_b32_e32 v13, 16, v13
	v_lshrrev_b32_e32 v15, 16, v15
	v_add3_u32 v52, v53, v92, s1
	v_add3_u32 v53, v55, v93, s1
	v_add3_u32 v55, v57, v95, s1
	v_add3_u32 v57, v59, v97, s1
	v_add3_u32 v59, v61, v99, s1
	v_lshrrev_b32_e32 v17, 16, v17
	v_lshrrev_b32_e32 v19, 16, v19
	v_lshrrev_b32_e32 v21, 16, v21
	v_lshrrev_b32_e32 v43, 16, v43
	v_lshrrev_b32_e32 v45, 16, v45
	v_lshrrev_b32_e32 v47, 16, v47
	v_lshrrev_b32_e32 v49, 16, v49
	v_lshrrev_b32_e32 v51, 16, v51
	v_lshrrev_b32_e32 v54, 16, v54
	v_lshrrev_b32_e32 v56, 16, v56
	v_lshrrev_b32_e32 v58, 16, v58
	v_lshrrev_b32_e32 v60, 16, v60
	v_and_or_b32 v6, v7, s4, v6
	v_and_or_b32 v7, v9, s4, v8
	v_and_or_b32 v8, v14, s4, v13
	v_and_or_b32 v9, v16, s4, v15
	v_and_or_b32 v14, v18, s4, v17
	v_and_or_b32 v15, v20, s4, v19
	v_and_or_b32 v16, v42, s4, v21
	v_and_or_b32 v17, v44, s4, v43
	v_and_or_b32 v18, v46, s4, v45
	v_and_or_b32 v19, v48, s4, v47
	v_and_or_b32 v20, v50, s4, v49
	v_and_or_b32 v21, v52, s4, v51
	v_and_or_b32 v42, v53, s4, v54
	v_and_or_b32 v43, v55, s4, v56
	v_and_or_b32 v44, v57, s4, v58
	v_and_or_b32 v45, v59, s4, v60
	global_store_dwordx4 v[70:71], v[6:9], off sc1
	global_store_dwordx4 v[64:65], v[14:17], off sc1
	global_store_dwordx4 v[66:67], v[18:21], off sc1
	global_store_dwordx4 v[62:63], v[42:45], off sc1
	s_waitcnt lgkmcnt(0)
	s_cbranch_scc1 .LBB0_29

; #define GAS __attribute__((address_space(1)))
; #define LAS __attribute__((address_space(3)))
; __device__ __forceinline__ unsigned pk2(float lo, float hi) { return f2bf(lo) | (f2bf(hi) << 16); }
; __device__ __forceinline__ void p0_transpose_item(const float* W, int N, bf16* WT, int ldt, int rowmode, LAS float* scr, int kb, int nb, int lane, const float* kgain) {
;     ...
;     for (int j = 0; j < 4; ++j) { const int n = (lane >> 3) + 8 * j; const LAS float* s = scr + (8 * c) * 33 + n;
;         v4u o; o.x = pk2(s[0 * 33], s[1 * 33]); o.y = pk2(s[2 * 33], s[3 * 33]); o.z = pk2(s[4 * 33], s[5 * 33]); o.w = pk2(s[6 * 33], s[7 * 33]);
;         const int ng = n0 + n; int row;
;         if (rowmode == 0) row = ng;
;         else if (rowmode == 3) { const int np = ng - (PW + 4 * HW); row = np < 0 ? ng : (PW + 4 * HW) + ((np & (D - 1)) >> 7) * 256 + (np >= D ? 128 : 0) + (np & 127); }
;         else row = (ng >> 7) * 256 + (rowmode == 2 ? 128 : 0) + (ng & 127);
;         *(GAS v4u*)(WT + (size_t)row * ldt + k0 + 8 * c) = o; }
.LBB0_32:
	s_waitcnt vmcnt(0)
	ds_write2_b32 v41, v2, v3 offset1:1
	ds_write2_b32 v41, v4, v5 offset0:2 offset1:3
	s_waitcnt lgkmcnt(0)
	ds_read2_b32 v[2:3], v30 offset1:33
	ds_read2_b32 v[18:19], v30 offset0:198 offset1:231
	s_mulk_i32 s20, 0xaa00
	s_add_i32 s1, s14, s20
	s_and_b32 s0, s0, 0x60
	s_waitcnt lgkmcnt(1)
	v_bfe_u32 v4, v2, 16, 1
	v_add3_u32 v2, v2, v4, s17
	ds_read2_b32 v[4:5], v30 offset0:66 offset1:99
	v_bfe_u32 v8, v3, 16, 1
	v_add3_u32 v3, v3, v8, s17
	ds_read2_b32 v[8:9], v30 offset0:132 offset1:165
	v_lshrrev_b32_e32 v2, 16, v2
	v_and_or_b32 v2, v3, s18, v2
	s_waitcnt lgkmcnt(1)
	v_bfe_u32 v3, v4, 16, 1
	v_add3_u32 v3, v4, v3, s17
	v_bfe_u32 v4, v5, 16, 1
	v_lshrrev_b32_e32 v3, 16, v3
	v_add3_u32 v4, v5, v4, s17
	v_and_or_b32 v3, v4, s18, v3
	s_waitcnt lgkmcnt(0)
	v_bfe_u32 v4, v8, 16, 1
	v_add3_u32 v4, v8, v4, s17
	v_bfe_u32 v5, v9, 16, 1
	v_lshrrev_b32_e32 v4, 16, v4
	v_add3_u32 v5, v9, v5, s17
	v_and_or_b32 v4, v5, s18, v4
	v_bfe_u32 v5, v18, 16, 1
	v_add3_u32 v5, v18, v5, s17
	v_bfe_u32 v8, v19, 16, 1
	v_lshrrev_b32_e32 v5, 16, v5
	v_add3_u32 v8, v19, v8, s17
	s_and_b32 s1, s1, 0xffffff00
	v_and_or_b32 v5, v8, s18, v5
	v_or_b32_e32 v8, s0, v22
	v_or_b32_e32 v8, s1, v8
	s_ashr_i32 s7, s6, 31
	ds_read2_b32 v[18:19], v31 offset1:33
	v_ashrrev_i32_e32 v9, 31, v8
	v_lshl_add_u64 v[6:7], s[6:7], 1, v[16:17]
	v_lshlrev_b64 v[8:9], 13, v[8:9]
	v_lshl_add_u64 v[8:9], v[6:7], 0, v[8:9]
	global_store_dwordx4 v[8:9], v[2:5], off sc1
	ds_read2_b32 v[4:5], v31 offset0:66 offset1:99
	ds_read2_b32 v[8:9], v31 offset0:132 offset1:165
	s_waitcnt lgkmcnt(2)
	v_bfe_u32 v2, v18, 16, 1
	v_add3_u32 v2, v18, v2, s17
	v_bfe_u32 v3, v19, 16, 1
	v_lshrrev_b32_e32 v2, 16, v2
	v_add3_u32 v3, v19, v3, s17
	v_and_or_b32 v2, v3, s18, v2
	s_waitcnt lgkmcnt(1)
	v_bfe_u32 v3, v4, 16, 1
	v_add3_u32 v3, v4, v3, s17
	v_bfe_u32 v4, v5, 16, 1
	ds_read2_b32 v[18:19], v31 offset0:198 offset1:231
	v_lshrrev_b32_e32 v3, 16, v3
	v_add3_u32 v4, v5, v4, s17
	v_and_or_b32 v3, v4, s18, v3
	s_waitcnt lgkmcnt(1)
	v_bfe_u32 v4, v8, 16, 1
	v_add3_u32 v4, v8, v4, s17
	v_bfe_u32 v5, v9, 16, 1
	v_lshrrev_b32_e32 v4, 16, v4
	v_add3_u32 v5, v9, v5, s17
	v_and_or_b32 v4, v5, s18, v4
	s_waitcnt lgkmcnt(0)
	v_bfe_u32 v5, v18, 16, 1
	v_add3_u32 v5, v18, v5, s17
	v_bfe_u32 v8, v19, 16, 1
	v_lshrrev_b32_e32 v5, 16, v5
	v_add3_u32 v8, v19, v8, s17
	v_and_or_b32 v5, v8, s18, v5
	v_or_b32_e32 v8, s0, v23
	v_or_b32_e32 v8, s1, v8
	ds_read2_b32 v[18:19], v32 offset1:33
	v_ashrrev_i32_e32 v9, 31, v8
	v_lshlrev_b64 v[8:9], 13, v[8:9]
	v_lshl_add_u64 v[8:9], v[6:7], 0, v[8:9]
	global_store_dwordx4 v[8:9], v[2:5], off sc1
	ds_read2_b32 v[4:5], v32 offset0:66 offset1:99
	ds_read2_b32 v[8:9], v32 offset0:132 offset1:165
	s_waitcnt lgkmcnt(2)
	v_bfe_u32 v2, v18, 16, 1
	v_add3_u32 v2, v18, v2, s17
	v_bfe_u32 v3, v19, 16, 1
	v_lshrrev_b32_e32 v2, 16, v2
	v_add3_u32 v3, v19, v3, s17
	v_and_or_b32 v2, v3, s18, v2
	s_waitcnt lgkmcnt(1)
	v_bfe_u32 v3, v4, 16, 1
	v_add3_u32 v3, v4, v3, s17
	v_bfe_u32 v4, v5, 16, 1
	ds_read2_b32 v[18:19], v32 offset0:198 offset1:231
	v_lshrrev_b32_e32 v3, 16, v3
	v_add3_u32 v4, v5, v4, s17
	v_and_or_b32 v3, v4, s18, v3
	s_waitcnt lgkmcnt(1)
	v_bfe_u32 v4, v8, 16, 1
	v_add3_u32 v4, v8, v4, s17
	v_bfe_u32 v5, v9, 16, 1
	v_lshrrev_b32_e32 v4, 16, v4
	v_add3_u32 v5, v9, v5, s17
	v_and_or_b32 v4, v5, s18, v4
	s_waitcnt lgkmcnt(0)
	v_bfe_u32 v5, v18, 16, 1
	v_add3_u32 v5, v18, v5, s17
	v_bfe_u32 v8, v19, 16, 1
	v_lshrrev_b32_e32 v5, 16, v5
	v_add3_u32 v8, v19, v8, s17
	v_and_or_b32 v5, v8, s18, v5
	v_or_b32_e32 v8, s0, v24
	v_or_b32_e32 v8, s1, v8
	v_ashrrev_i32_e32 v9, 31, v8
	v_lshlrev_b64 v[8:9], 13, v[8:9]
	v_lshl_add_u64 v[8:9], v[6:7], 0, v[8:9]
	global_store_dwordx4 v[8:9], v[2:5], off sc1
	ds_read2_b32 v[2:3], v33 offset1:33
	ds_read2_b32 v[4:5], v33 offset0:66 offset1:99
	ds_read2_b32 v[8:9], v33 offset0:132 offset1:165
	ds_read2_b32 v[18:19], v33 offset0:198 offset1:231
	v_or_b32_e32 v13, s0, v25
	v_or_b32_e32 v20, s1, v13
	s_waitcnt lgkmcnt(3)
	v_bfe_u32 v13, v3, 16, 1
	v_add3_u32 v3, v3, v13, s17
	v_bfe_u32 v13, v2, 16, 1
	v_add3_u32 v2, v2, v13, s17
	v_lshrrev_b32_e32 v2, 16, v2
	v_and_or_b32 v2, v3, s18, v2
	s_waitcnt lgkmcnt(2)
	v_bfe_u32 v3, v5, 16, 1
	v_add3_u32 v3, v5, v3, s17
	v_bfe_u32 v5, v4, 16, 1
	v_add3_u32 v4, v4, v5, s17
	v_lshrrev_b32_e32 v4, 16, v4
	s_waitcnt lgkmcnt(1)
	v_bfe_u32 v5, v8, 16, 1
	v_and_or_b32 v3, v3, s18, v4
	v_bfe_u32 v4, v9, 16, 1
	v_add3_u32 v5, v8, v5, s17
	v_add3_u32 v4, v9, v4, s17
	v_lshrrev_b32_e32 v5, 16, v5
	s_waitcnt lgkmcnt(0)
	v_bfe_u32 v8, v18, 16, 1
	v_and_or_b32 v4, v4, s18, v5
	v_bfe_u32 v5, v19, 16, 1
	v_add3_u32 v8, v18, v8, s17
	v_add3_u32 v5, v19, v5, s17
	v_lshrrev_b32_e32 v8, 16, v8
	v_ashrrev_i32_e32 v21, 31, v20
	v_and_or_b32 v5, v5, s18, v8
	v_lshlrev_b64 v[8:9], 13, v[20:21]
	v_lshl_add_u64 v[6:7], v[6:7], 0, v[8:9]
	global_store_dwordx4 v[6:7], v[2:5], off sc1
	s_waitcnt lgkmcnt(0)
	s_add_i32 s19, s19, s82
	s_add_i32 s9, s9, s8
	s_add_i32 s14, s14, s15
	s_cmpk_lt_i32 s19, 0x5600
	s_cbranch_scc0 .LBB0_49

; #define GAS __attribute__((address_space(1)))
; #define LDS_WAIT() asm volatile("s_waitcnt lgkmcnt(0)" ::: "memory")
; __device__ __forceinline__ void p0_transpose_item(const float* W, int N, bf16* WT, int ldt, int rowmode, LAS float* scr, int kb, int nb, int lane, const float* kgain) {
;     ...
;     const int lk = lane >> 3, ln = (lane & 7) * 4;
; #pragma unroll
;     for (int i = 0; i < 8; ++i) { const int kk = 8 * i + lk; f32x4 v = __builtin_nontemporal_load((const GAS f32x4*)(W + (size_t)(k0 + kk) * N + n0 + ln)); if (kgain) v = v * kgain[k0 + kk];
;         scr[kk * 33 + ln] = v[0]; scr[kk * 33 + ln + 1] = v[1]; scr[kk * 33 + ln + 2] = v[2]; scr[kk * 33 + ln + 3] = v[3]; }
;     LDS_WAIT(); asm volatile("" ::: "memory");
.LBB0_53:
	s_mul_hi_i32 s16, s15, 0x2fa0be83
	s_lshr_b32 s17, s16, 31
	s_ashr_i32 s16, s16, 6
	s_add_i32 s17, s16, s17
	s_lshl_b32 s16, s17, 6
	s_mul_i32 s18, s17, 0xffffd500
	s_mul_i32 s19, s17, 0xffffaa00
	s_add_i32 s18, s4, s18
	v_or_b32_e32 v6, s16, v22
	v_or_b32_e32 v8, s16, v23
	v_or_b32_e32 v14, s16, v24
	v_or_b32_e32 v16, s16, v25
	v_or_b32_e32 v18, s16, v26
	v_or_b32_e32 v20, s16, v27
	v_or_b32_e32 v42, s16, v28
	v_or_b32_e32 v44, s16, v29
	s_ashr_i32 s17, s16, 31
	s_add_i32 s20, s5, s19
	s_ashr_i32 s19, s18, 31
	v_ashrrev_i32_e32 v7, 31, v6
	v_ashrrev_i32_e32 v9, 31, v8
	v_ashrrev_i32_e32 v15, 31, v14
	v_ashrrev_i32_e32 v17, 31, v16
	v_ashrrev_i32_e32 v19, 31, v18
	v_ashrrev_i32_e32 v21, 31, v20
	v_ashrrev_i32_e32 v43, 31, v42
	v_ashrrev_i32_e32 v45, 31, v44
	v_lshl_add_u64 v[62:63], s[16:17], 1, v[4:5]
	s_and_b32 s16, s18, 0x60
	v_lshl_add_u64 v[46:47], s[18:19], 2, v[2:3]
	v_lshl_add_u64 v[48:49], v[6:7], 2, s[0:1]
	v_lshl_add_u64 v[50:51], v[8:9], 2, s[0:1]
	v_lshl_add_u64 v[52:53], v[14:15], 2, s[0:1]
	v_lshl_add_u64 v[54:55], v[16:17], 2, s[0:1]
	v_lshl_add_u64 v[56:57], v[18:19], 2, s[0:1]
	v_lshl_add_u64 v[58:59], v[20:21], 2, s[0:1]
	v_lshl_add_u64 v[60:61], v[42:43], 2, s[0:1]
	v_lshl_add_u64 v[64:65], v[44:45], 2, s[0:1]
	s_and_b32 s20, s20, 0xffffff00
	v_or_b32_e32 v9, s16, v22
	v_or_b32_e32 v13, s16, v23
	v_or_b32_e32 v15, s16, v24
	v_or_b32_e32 v17, s16, v25
	v_mad_i64_i32 v[6:7], s[16:17], v6, s7, v[46:47]
	global_load_dword v66, v[48:49], off
	global_load_dword v68, v[50:51], off
	global_load_dword v70, v[52:53], off
	global_load_dword v72, v[54:55], off
	global_load_dword v74, v[56:57], off
	global_load_dword v76, v[58:59], off
	global_load_dword v78, v[60:61], off
	v_or_b32_e32 v80, s20, v9
	global_load_dword v64, v[64:65], off
	v_mad_i64_i32 v[48:49], s[16:17], v8, s7, v[46:47]
	v_mad_i64_i32 v[50:51], s[16:17], v14, s7, v[46:47]
	v_mad_i64_i32 v[52:53], s[16:17], v16, s7, v[46:47]
	v_mad_i64_i32 v[54:55], s[16:17], v18, s7, v[46:47]
	v_mad_i64_i32 v[56:57], s[16:17], v20, s7, v[46:47]
	v_mad_i64_i32 v[58:59], s[16:17], v42, s7, v[46:47]
	v_mad_i64_i32 v[60:61], s[16:17], v44, s7, v[46:47]
	v_or_b32_e32 v84, s20, v15
	v_or_b32_e32 v86, s20, v17
	global_load_dwordx4 v[6:9], v[6:7], off nt
	s_nop 0
	global_load_dwordx4 v[14:17], v[48:49], off nt
	global_load_dwordx4 v[18:21], v[50:51], off nt
	global_load_dwordx4 v[42:45], v[52:53], off nt
	s_nop 0
	global_load_dwordx4 v[46:49], v[54:55], off nt
	global_load_dwordx4 v[50:53], v[56:57], off nt
	s_nop 0
	global_load_dwordx4 v[54:57], v[58:59], off nt
	s_nop 0
	global_load_dwordx4 v[58:61], v[60:61], off nt
	v_or_b32_e32 v82, s20, v13
	v_ashrrev_i32_e32 v81, 31, v80
	v_ashrrev_i32_e32 v83, 31, v82
	v_ashrrev_i32_e32 v85, 31, v84
	v_ashrrev_i32_e32 v87, 31, v86
	v_lshlrev_b64 v[80:81], 13, v[80:81]
	v_lshlrev_b64 v[82:83], 13, v[82:83]
	v_lshlrev_b64 v[84:85], 13, v[84:85]
	v_lshlrev_b64 v[86:87], 13, v[86:87]
	v_lshl_add_u64 v[80:81], v[62:63], 0, v[80:81]
	v_lshl_add_u64 v[82:83], v[62:63], 0, v[82:83]
	v_lshl_add_u64 v[84:85], v[62:63], 0, v[84:85]
	v_lshl_add_u64 v[62:63], v[62:63], 0, v[86:87]
	s_add_i32 s15, s15, s82
	s_add_i32 s4, s4, s8
	s_add_i32 s5, s5, s6
	s_cmpk_gt_i32 s15, 0x16d7
	s_waitcnt vmcnt(7)
	v_pk_mul_f32 v[6:7], v[6:7], v[66:67] op_sel_hi:[1,0]
	v_pk_mul_f32 v[8:9], v[8:9], v[66:67] op_sel_hi:[1,0]
	s_waitcnt vmcnt(6)
	v_pk_mul_f32 v[16:17], v[16:17], v[68:69] op_sel_hi:[1,0]
	v_pk_mul_f32 v[14:15], v[14:15], v[68:69] op_sel_hi:[1,0]
	s_waitcnt vmcnt(5)
	v_pk_mul_f32 v[20:21], v[20:21], v[70:71] op_sel_hi:[1,0]
	v_pk_mul_f32 v[18:19], v[18:19], v[70:71] op_sel_hi:[1,0]
	s_waitcnt vmcnt(4)
	v_pk_mul_f32 v[44:45], v[44:45], v[72:73] op_sel_hi:[1,0]
	v_pk_mul_f32 v[42:43], v[42:43], v[72:73] op_sel_hi:[1,0]
	s_waitcnt vmcnt(3)
	v_pk_mul_f32 v[48:49], v[48:49], v[74:75] op_sel_hi:[1,0]
	v_pk_mul_f32 v[46:47], v[46:47], v[74:75] op_sel_hi:[1,0]
	s_waitcnt vmcnt(2)
	v_pk_mul_f32 v[52:53], v[52:53], v[76:77] op_sel_hi:[1,0]
	v_pk_mul_f32 v[50:51], v[50:51], v[76:77] op_sel_hi:[1,0]
	s_waitcnt vmcnt(1)
	v_pk_mul_f32 v[56:57], v[56:57], v[78:79] op_sel_hi:[1,0]
	v_pk_mul_f32 v[54:55], v[54:55], v[78:79] op_sel_hi:[1,0]
	s_waitcnt vmcnt(0)
; #define GAS __attribute__((address_space(1)))
; #define LAS __attribute__((address_space(3)))
; #define LDS_WAIT() asm volatile("s_waitcnt lgkmcnt(0)" ::: "memory")
; __device__ __forceinline__ unsigned pk2(float lo, float hi) { return f2bf(lo) | (f2bf(hi) << 16); }
; __device__ __forceinline__ void p0_transpose_item(const float* W, int N, bf16* WT, int ldt, int rowmode, LAS float* scr, int kb, int nb, int lane, const float* kgain) {
;     ...
;     for (int i = 0; i < 8; ++i) { const int kk = 8 * i + lk; f32x4 v = __builtin_nontemporal_load((const GAS f32x4*)(W + (size_t)(k0 + kk) * N + n0 + ln)); if (kgain) v = v * kgain[k0 + kk];
;         scr[kk * 33 + ln] = v[0]; scr[kk * 33 + ln + 1] = v[1]; scr[kk * 33 + ln + 2] = v[2]; scr[kk * 33 + ln + 3] = v[3]; }
;     LDS_WAIT(); asm volatile("" ::: "memory");
;     const int c = lane & 7;
; #pragma unroll
;     for (int j = 0; j < 4; ++j) { const int n = (lane >> 3) + 8 * j; const LAS float* s = scr + (8 * c) * 33 + n;
;         v4u o; o.x = pk2(s[0 * 33], s[1 * 33]); o.y = pk2(s[2 * 33], s[3 * 33]); o.z = pk2(s[4 * 33], s[5 * 33]); o.w = pk2(s[6 * 33], s[7 * 33]);
;         const int ng = n0 + n; int row;
;         if (rowmode == 0) row = ng;
;         else if (rowmode == 3) { const int np = ng - (PW + 4 * HW); row = np < 0 ? ng : (PW + 4 * HW) + ((np & (D - 1)) >> 7) * 256 + (np >= D ? 128 : 0) + (np & 127); }
;         else row = (ng >> 7) * 256 + (rowmode == 2 ? 128 : 0) + (ng & 127);
;         *(GAS v4u*)(WT + (size_t)row * ldt + k0 + 8 * c) = o; }
	v_pk_mul_f32 v[60:61], v[60:61], v[64:65] op_sel_hi:[1,0]
	v_pk_mul_f32 v[58:59], v[58:59], v[64:65] op_sel_hi:[1,0]
	ds_write2_b32 v34, v6, v7 offset1:1
	ds_write2_b32 v34, v8, v9 offset0:2 offset1:3
	ds_write2_b32 v35, v14, v15 offset1:1
	ds_write2_b32 v35, v16, v17 offset0:2 offset1:3
	ds_write2_b32 v36, v18, v19 offset1:1
	ds_write2_b32 v36, v20, v21 offset0:2 offset1:3
	ds_write2_b32 v37, v42, v43 offset1:1
	ds_write2_b32 v37, v44, v45 offset0:2 offset1:3
	ds_write2_b32 v38, v46, v47 offset1:1
	ds_write2_b32 v38, v48, v49 offset0:2 offset1:3
	ds_write2_b32 v39, v50, v51 offset1:1
	ds_write2_b32 v39, v52, v53 offset0:2 offset1:3
	ds_write2_b32 v40, v54, v55 offset1:1
	ds_write2_b32 v40, v56, v57 offset0:2 offset1:3
	ds_write2_b32 v41, v58, v59 offset1:1
	ds_write2_b32 v41, v60, v61 offset0:2 offset1:3
	s_waitcnt lgkmcnt(0)
	ds_read2_b32 v[6:7], v30 offset1:33
	ds_read2_b32 v[8:9], v30 offset0:66 offset1:99
	ds_read2_b32 v[14:15], v30 offset0:132 offset1:165
	ds_read2_b32 v[16:17], v30 offset0:198 offset1:231
	ds_read2_b32 v[18:19], v31 offset1:33
	ds_read2_b32 v[20:21], v31 offset0:66 offset1:99
	ds_read2_b32 v[42:43], v31 offset0:132 offset1:165
	ds_read2_b32 v[44:45], v31 offset0:198 offset1:231
	ds_read2_b32 v[46:47], v32 offset1:33
	ds_read2_b32 v[48:49], v32 offset0:66 offset1:99
	ds_read2_b32 v[50:51], v32 offset0:132 offset1:165
	ds_read2_b32 v[52:53], v32 offset0:198 offset1:231
	ds_read2_b32 v[54:55], v33 offset1:33
	ds_read2_b32 v[56:57], v33 offset0:66 offset1:99
	ds_read2_b32 v[58:59], v33 offset0:132 offset1:165
	ds_read2_b32 v[60:61], v33 offset0:198 offset1:231
	s_waitcnt lgkmcnt(14)
	v_bfe_u32 v13, v6, 16, 1
	v_bfe_u32 v65, v8, 16, 1
	s_waitcnt lgkmcnt(13)
	v_bfe_u32 v67, v14, 16, 1
	v_bfe_u32 v68, v15, 16, 1
	s_waitcnt lgkmcnt(12)
	v_bfe_u32 v69, v16, 16, 1
	v_bfe_u32 v64, v7, 16, 1
	v_bfe_u32 v66, v9, 16, 1
	v_bfe_u32 v70, v17, 16, 1
	s_waitcnt lgkmcnt(11)
	v_bfe_u32 v71, v18, 16, 1
	v_bfe_u32 v72, v19, 16, 1
	s_waitcnt lgkmcnt(10)
	v_bfe_u32 v73, v20, 16, 1
	v_bfe_u32 v74, v21, 16, 1
	s_waitcnt lgkmcnt(9)
	v_bfe_u32 v75, v42, 16, 1
	v_bfe_u32 v76, v43, 16, 1
	s_waitcnt lgkmcnt(8)
	v_bfe_u32 v77, v44, 16, 1
	v_bfe_u32 v78, v45, 16, 1
	s_waitcnt lgkmcnt(7)
	v_bfe_u32 v79, v46, 16, 1
	v_bfe_u32 v86, v47, 16, 1
	s_waitcnt lgkmcnt(6)
	v_bfe_u32 v87, v48, 16, 1
	v_bfe_u32 v88, v49, 16, 1
	s_waitcnt lgkmcnt(5)
	v_bfe_u32 v89, v50, 16, 1
	v_bfe_u32 v90, v51, 16, 1
	s_waitcnt lgkmcnt(4)
	v_bfe_u32 v91, v52, 16, 1
	s_waitcnt lgkmcnt(3)
	v_bfe_u32 v94, v54, 16, 1
	s_waitcnt lgkmcnt(2)
	v_bfe_u32 v96, v56, 16, 1
	s_waitcnt lgkmcnt(1)
	v_bfe_u32 v98, v58, 16, 1
	s_waitcnt lgkmcnt(0)
	v_bfe_u32 v100, v60, 16, 1
	v_add3_u32 v6, v6, v13, s9
	v_add3_u32 v8, v8, v65, s9
	v_add3_u32 v13, v14, v67, s9
	v_add3_u32 v14, v15, v68, s9
	v_add3_u32 v15, v16, v69, s9
	v_bfe_u32 v92, v53, 16, 1
	v_bfe_u32 v93, v55, 16, 1
	v_bfe_u32 v95, v57, 16, 1
	v_bfe_u32 v97, v59, 16, 1
	v_bfe_u32 v99, v61, 16, 1
	v_add3_u32 v7, v7, v64, s9
	v_add3_u32 v9, v9, v66, s9
	v_add3_u32 v16, v17, v70, s9
	v_add3_u32 v17, v18, v71, s9
	v_add3_u32 v18, v19, v72, s9
	v_add3_u32 v19, v20, v73, s9
	v_add3_u32 v20, v21, v74, s9
	v_add3_u32 v21, v42, v75, s9
	v_add3_u32 v42, v43, v76, s9
	v_add3_u32 v43, v44, v77, s9
	v_add3_u32 v44, v45, v78, s9
	v_add3_u32 v45, v46, v79, s9
	v_add3_u32 v46, v47, v86, s9
	v_add3_u32 v47, v48, v87, s9
	v_add3_u32 v48, v49, v88, s9
	v_add3_u32 v49, v50, v89, s9
	v_add3_u32 v50, v51, v90, s9
	v_add3_u32 v51, v52, v91, s9
	v_add3_u32 v54, v54, v94, s9
	v_add3_u32 v56, v56, v96, s9
	v_add3_u32 v58, v58, v98, s9
	v_add3_u32 v60, v60, v100, s9
	v_lshrrev_b32_e32 v6, 16, v6
	v_lshrrev_b32_e32 v8, 16, v8
	v_lshrrev_b32_e32 v13, 16, v13
	v_lshrrev_b32_e32 v15, 16, v15
	v_add3_u32 v52, v53, v92, s9
	v_add3_u32 v53, v55, v93, s9
	v_add3_u32 v55, v57, v95, s9
	v_add3_u32 v57, v59, v97, s9
	v_add3_u32 v59, v61, v99, s9
	v_lshrrev_b32_e32 v17, 16, v17
	v_lshrrev_b32_e32 v19, 16, v19
	v_lshrrev_b32_e32 v21, 16, v21
	v_lshrrev_b32_e32 v43, 16, v43
	v_lshrrev_b32_e32 v45, 16, v45
	v_lshrrev_b32_e32 v47, 16, v47
	v_lshrrev_b32_e32 v49, 16, v49
	v_lshrrev_b32_e32 v51, 16, v51
	v_lshrrev_b32_e32 v54, 16, v54
	v_lshrrev_b32_e32 v56, 16, v56
	v_lshrrev_b32_e32 v58, 16, v58
	v_lshrrev_b32_e32 v60, 16, v60
	v_and_or_b32 v6, v7, s14, v6
	v_and_or_b32 v7, v9, s14, v8
	v_and_or_b32 v8, v14, s14, v13
	v_and_or_b32 v9, v16, s14, v15
	v_and_or_b32 v14, v18, s14, v17
	v_and_or_b32 v15, v20, s14, v19
	v_and_or_b32 v16, v42, s14, v21
	v_and_or_b32 v17, v44, s14, v43
	v_and_or_b32 v18, v46, s14, v45
	v_and_or_b32 v19, v48, s14, v47
	v_and_or_b32 v20, v50, s14, v49
	v_and_or_b32 v21, v52, s14, v51
	v_and_or_b32 v42, v53, s14, v54
	v_and_or_b32 v43, v55, s14, v56
	v_and_or_b32 v44, v57, s14, v58
	v_and_or_b32 v45, v59, s14, v60
	global_store_dwordx4 v[80:81], v[6:9], off sc1
	global_store_dwordx4 v[82:83], v[14:17], off sc1
	global_store_dwordx4 v[84:85], v[18:21], off sc1
	global_store_dwordx4 v[62:63], v[42:45], off sc1
	s_waitcnt lgkmcnt(0)
	s_cbranch_scc0 .LBB0_53

; #define GAS __attribute__((address_space(1)))
; #define LAS __attribute__((address_space(3)))
; __device__ __forceinline__ unsigned pk2(float lo, float hi) { return f2bf(lo) | (f2bf(hi) << 16); }
; __device__ __forceinline__ void p0_transpose_item(const float* W, int N, bf16* WT, int ldt, int rowmode, LAS float* scr, int kb, int nb, int lane, const float* kgain) {
;     ...
;     for (int j = 0; j < 4; ++j) { const int n = (lane >> 3) + 8 * j; const LAS float* s = scr + (8 * c) * 33 + n;
;         v4u o; o.x = pk2(s[0 * 33], s[1 * 33]); o.y = pk2(s[2 * 33], s[3 * 33]); o.z = pk2(s[4 * 33], s[5 * 33]); o.w = pk2(s[6 * 33], s[7 * 33]);
;         const int ng = n0 + n; int row;
;         if (rowmode == 0) row = ng;
;         else if (rowmode == 3) { const int np = ng - (PW + 4 * HW); row = np < 0 ? ng : (PW + 4 * HW) + ((np & (D - 1)) >> 7) * 256 + (np >= D ? 128 : 0) + (np & 127); }
;         else row = (ng >> 7) * 256 + (rowmode == 2 ? 128 : 0) + (ng & 127);
;         *(GAS v4u*)(WT + (size_t)row * ldt + k0 + 8 * c) = o; }
.LBB0_56:
	s_waitcnt vmcnt(0)
	ds_write2_b32 v41, v2, v3 offset1:1
	ds_write2_b32 v41, v4, v5 offset0:2 offset1:3
	s_waitcnt lgkmcnt(0)
	ds_read2_b32 v[2:3], v30 offset1:33
	ds_read2_b32 v[14:15], v30 offset0:198 offset1:231
	s_mulk_i32 s20, 0xaa00
	s_add_i32 s1, s14, s20
	s_and_b32 s1, s1, 0xffffff00
	s_waitcnt lgkmcnt(1)
	v_bfe_u32 v4, v2, 16, 1
	v_add3_u32 v2, v2, v4, s17
	ds_read2_b32 v[4:5], v30 offset0:66 offset1:99
	v_bfe_u32 v8, v3, 16, 1
	v_add3_u32 v3, v3, v8, s17
	ds_read2_b32 v[8:9], v30 offset0:132 offset1:165
	v_lshrrev_b32_e32 v2, 16, v2
	v_and_or_b32 v2, v3, s18, v2
	s_waitcnt lgkmcnt(1)
	v_bfe_u32 v3, v4, 16, 1
	v_add3_u32 v3, v4, v3, s17
	v_bfe_u32 v4, v5, 16, 1
	v_lshrrev_b32_e32 v3, 16, v3
	v_add3_u32 v4, v5, v4, s17
	v_and_or_b32 v3, v4, s18, v3
	s_waitcnt lgkmcnt(0)
	v_bfe_u32 v4, v8, 16, 1
	v_add3_u32 v4, v8, v4, s17
	v_bfe_u32 v5, v9, 16, 1
	v_lshrrev_b32_e32 v4, 16, v4
	v_add3_u32 v5, v9, v5, s17
	v_and_or_b32 v4, v5, s18, v4
	v_bfe_u32 v5, v14, 16, 1
	v_add3_u32 v5, v14, v5, s17
	v_bfe_u32 v8, v15, 16, 1
	v_lshrrev_b32_e32 v5, 16, v5
	v_add3_u32 v8, v15, v8, s17
	s_and_b32 s0, s0, 0x60
	s_bitset1_b32 s1, 7
	v_and_or_b32 v5, v8, s18, v5
	v_or_b32_e32 v8, s0, v22
	v_or_b32_e32 v8, s1, v8
	s_ashr_i32 s7, s6, 31
	ds_read2_b32 v[14:15], v31 offset1:33
	v_ashrrev_i32_e32 v9, 31, v8
	v_lshl_add_u64 v[6:7], s[6:7], 1, v[10:11]
	v_lshlrev_b64 v[8:9], 13, v[8:9]
	v_lshl_add_u64 v[8:9], v[6:7], 0, v[8:9]
	global_store_dwordx4 v[8:9], v[2:5], off sc1
	ds_read2_b32 v[4:5], v31 offset0:66 offset1:99
	ds_read2_b32 v[8:9], v31 offset0:132 offset1:165
	s_waitcnt lgkmcnt(2)
	v_bfe_u32 v2, v14, 16, 1
	v_add3_u32 v2, v14, v2, s17
	v_bfe_u32 v3, v15, 16, 1
	v_lshrrev_b32_e32 v2, 16, v2
	v_add3_u32 v3, v15, v3, s17
	v_and_or_b32 v2, v3, s18, v2
	s_waitcnt lgkmcnt(1)
	v_bfe_u32 v3, v4, 16, 1
	v_add3_u32 v3, v4, v3, s17
	v_bfe_u32 v4, v5, 16, 1
	ds_read2_b32 v[14:15], v31 offset0:198 offset1:231
	v_lshrrev_b32_e32 v3, 16, v3
	v_add3_u32 v4, v5, v4, s17
	v_and_or_b32 v3, v4, s18, v3
	s_waitcnt lgkmcnt(1)
	v_bfe_u32 v4, v8, 16, 1
	v_add3_u32 v4, v8, v4, s17
	v_bfe_u32 v5, v9, 16, 1
	v_lshrrev_b32_e32 v4, 16, v4
	v_add3_u32 v5, v9, v5, s17
	v_and_or_b32 v4, v5, s18, v4
	s_waitcnt lgkmcnt(0)
	v_bfe_u32 v5, v14, 16, 1
	v_add3_u32 v5, v14, v5, s17
	v_bfe_u32 v8, v15, 16, 1
	v_lshrrev_b32_e32 v5, 16, v5
	v_add3_u32 v8, v15, v8, s17
	v_and_or_b32 v5, v8, s18, v5
	v_or_b32_e32 v8, s0, v23
	v_or_b32_e32 v8, s1, v8
	ds_read2_b32 v[14:15], v32 offset1:33
	v_ashrrev_i32_e32 v9, 31, v8
	v_lshlrev_b64 v[8:9], 13, v[8:9]
	v_lshl_add_u64 v[8:9], v[6:7], 0, v[8:9]
	global_store_dwordx4 v[8:9], v[2:5], off sc1
	ds_read2_b32 v[4:5], v32 offset0:66 offset1:99
	ds_read2_b32 v[8:9], v32 offset0:132 offset1:165
	s_waitcnt lgkmcnt(2)
	v_bfe_u32 v2, v14, 16, 1
	v_add3_u32 v2, v14, v2, s17
	v_bfe_u32 v3, v15, 16, 1
	v_lshrrev_b32_e32 v2, 16, v2
	v_add3_u32 v3, v15, v3, s17
	v_and_or_b32 v2, v3, s18, v2
	s_waitcnt lgkmcnt(1)
	v_bfe_u32 v3, v4, 16, 1
	v_add3_u32 v3, v4, v3, s17
	v_bfe_u32 v4, v5, 16, 1
	ds_read2_b32 v[14:15], v32 offset0:198 offset1:231
	v_lshrrev_b32_e32 v3, 16, v3
	v_add3_u32 v4, v5, v4, s17
	v_and_or_b32 v3, v4, s18, v3
	s_waitcnt lgkmcnt(1)
	v_bfe_u32 v4, v8, 16, 1
	v_add3_u32 v4, v8, v4, s17
	v_bfe_u32 v5, v9, 16, 1
	v_lshrrev_b32_e32 v4, 16, v4
	v_add3_u32 v5, v9, v5, s17
	v_and_or_b32 v4, v5, s18, v4
	s_waitcnt lgkmcnt(0)
	v_bfe_u32 v5, v14, 16, 1
	v_add3_u32 v5, v14, v5, s17
	v_bfe_u32 v8, v15, 16, 1
	v_lshrrev_b32_e32 v5, 16, v5
	v_add3_u32 v8, v15, v8, s17
	v_and_or_b32 v5, v8, s18, v5
	v_or_b32_e32 v8, s0, v24
	v_or_b32_e32 v8, s1, v8
	v_ashrrev_i32_e32 v9, 31, v8
	v_lshlrev_b64 v[8:9], 13, v[8:9]
	v_lshl_add_u64 v[8:9], v[6:7], 0, v[8:9]
	global_store_dwordx4 v[8:9], v[2:5], off sc1
	ds_read2_b32 v[2:3], v33 offset1:33
	ds_read2_b32 v[4:5], v33 offset0:66 offset1:99
	ds_read2_b32 v[8:9], v33 offset0:132 offset1:165
	ds_read2_b32 v[14:15], v33 offset0:198 offset1:231
	v_or_b32_e32 v16, s0, v25
	s_waitcnt lgkmcnt(3)
	v_bfe_u32 v17, v3, 16, 1
	v_add3_u32 v3, v3, v17, s17
	v_bfe_u32 v17, v2, 16, 1
	v_add3_u32 v2, v2, v17, s17
	v_lshrrev_b32_e32 v2, 16, v2
	v_and_or_b32 v2, v3, s18, v2
	s_waitcnt lgkmcnt(2)
	v_bfe_u32 v3, v5, 16, 1
	v_add3_u32 v3, v5, v3, s17
	v_bfe_u32 v5, v4, 16, 1
	v_add3_u32 v4, v4, v5, s17
	v_lshrrev_b32_e32 v4, 16, v4
	s_waitcnt lgkmcnt(1)
	v_bfe_u32 v5, v8, 16, 1
	v_and_or_b32 v3, v3, s18, v4
	v_bfe_u32 v4, v9, 16, 1
	v_add3_u32 v5, v8, v5, s17
	v_add3_u32 v4, v9, v4, s17
	v_lshrrev_b32_e32 v5, 16, v5
	s_waitcnt lgkmcnt(0)
	v_bfe_u32 v8, v14, 16, 1
	v_or_b32_e32 v16, s1, v16
	v_and_or_b32 v4, v4, s18, v5
	v_bfe_u32 v5, v15, 16, 1
	v_add3_u32 v8, v14, v8, s17
	v_add3_u32 v5, v15, v5, s17
	v_lshrrev_b32_e32 v8, 16, v8
	v_ashrrev_i32_e32 v17, 31, v16
	v_and_or_b32 v5, v5, s18, v8
	v_lshlrev_b64 v[8:9], 13, v[16:17]
	v_lshl_add_u64 v[6:7], v[6:7], 0, v[8:9]
	global_store_dwordx4 v[6:7], v[2:5], off sc1
	s_waitcnt lgkmcnt(0)
	s_add_i32 s19, s19, s82
	s_add_i32 s9, s9, s8
	s_add_i32 s14, s14, s15
	s_cmpk_lt_i32 s19, 0x5600
	s_cbranch_scc0 .LBB0_73

; #define GAS __attribute__((address_space(1)))
; __global__ void __launch_bounds__(NWAVES * 64, 2) fwd(Args args) {
;     ...
;         for (int m = gw; m < T; m += NGW) {
;             const GAS f32x4* xr = (const GAS f32x4*)(x + (size_t)m * D) + F.lane; const GAS f32x4* gr = (const GAS f32x4*)g_mix + F.lane;
;             f32x4 v[16]; float s = 0.f;
; #pragma unroll
;             for (int j = 0; j < 16; ++j) { v[j] = __builtin_nontemporal_load(xr + 64 * j); s += (v[j][0] * v[j][0] + v[j][1] * v[j][1]) + (v[j][2] * v[j][2] + v[j][3] * v[j][3]); }
;             const float r = 1.0f / sqrtf(wave_sum(s) * (1.0f / D) + EPS);
.LBB0_75:
	v_add_co_u32_e64 v18, s[4:5], s8, v98
	v_add_co_u32_e32 v62, vcc, 0xffffd000, v98
	s_nop 0
	v_addc_co_u32_e64 v19, s[4:5], -1, v99, s[4:5]
	v_add_co_u32_e64 v20, s[4:5], s9, v98
	v_addc_co_u32_e32 v63, vcc, -1, v99, vcc
	s_nop 0
	v_addc_co_u32_e64 v21, s[4:5], -1, v99, s[4:5]
	global_load_dwordx4 v[14:17], v[98:99], off offset:-3072 nt
	global_load_dwordx4 v[10:13], v[98:99], off offset:-2048 nt
	global_load_dwordx4 v[6:9], v[98:99], off offset:-1024 nt
	global_load_dwordx4 v[2:5], v[98:99], off nt
	global_load_dwordx4 v[30:33], v[70:71], off
	global_load_dwordx4 v[46:49], v[18:19], off offset:-3072 nt
	global_load_dwordx4 v[34:37], v[18:19], off offset:-1024 nt
	global_load_dwordx4 v[50:53], v[18:19], off offset:-2048 nt
	global_load_dwordx4 v[38:41], v[18:19], off nt
	global_load_dwordx4 v[26:29], v[20:21], off offset:-2048 nt
	global_load_dwordx4 v[42:45], v[20:21], off offset:-3072 nt
	global_load_dwordx4 v[22:25], v[20:21], off offset:-1024 nt
	s_nop 0
	global_load_dwordx4 v[18:21], v[98:99], off offset:-4096 nt
	global_load_dwordx4 v[66:69], v[62:63], off offset:-3072 nt
	global_load_dwordx4 v[58:61], v[62:63], off offset:-2048 nt
	global_load_dwordx4 v[54:57], v[62:63], off nt
	s_nop 0
	global_load_dwordx4 v[62:65], v[62:63], off offset:-1024 nt
	v_add_co_u32_e64 v100, s[4:5], s9, v96
	s_add_i32 s16, s16, s82
	s_nop 0
	v_addc_co_u32_e64 v101, s[4:5], -1, v97, s[4:5]
	v_lshl_add_u64 v[98:99], v[98:99], 0, s[6:7]
	s_cmpk_gt_i32 s16, 0x1fff
	s_waitcnt vmcnt(11)
	v_pk_mul_f32 v[114:115], v[48:49], v[48:49]
	s_waitcnt vmcnt(10)
	v_mul_f32_e32 v144, v34, v34
	v_mul_f32_e32 v147, v35, v35
	s_waitcnt vmcnt(8)
	v_pk_mul_f32 v[116:117], v[40:41], v[40:41]
	v_pk_mul_f32 v[104:105], v[38:39], v[38:39]
	s_waitcnt vmcnt(7)
	v_mul_f32_e32 v146, v26, v26
	v_mul_f32_e32 v150, v27, v27
	v_mul_f32_e32 v153, v28, v28
	s_waitcnt vmcnt(6)
	v_mul_f32_e32 v124, v43, v43
	v_mul_f32_e32 v126, v45, v45
	v_mov_b32_e32 v158, v26
	v_mov_b32_e32 v159, v28
	v_mov_b32_e32 v28, v27
	s_waitcnt vmcnt(3)
	v_pk_mul_f32 v[26:27], v[68:69], v[68:69]
	v_pk_mul_f32 v[160:161], v[66:67], v[66:67]
	s_waitcnt vmcnt(2)
	v_pk_mul_f32 v[164:165], v[60:61], v[60:61]
	v_pk_mul_f32 v[166:167], v[58:59], v[58:59]
	v_pk_mul_f32 v[108:109], v[12:13], v[12:13]
	v_pk_mul_f32 v[110:111], v[10:11], v[10:11]
	v_mul_f32_e32 v112, v7, v7
	v_mul_f32_e32 v134, v9, v9
	v_mul_f32_e32 v151, v36, v36
	v_mov_b32_e32 v136, v34
	v_mov_b32_e32 v137, v36
	v_mov_b32_e32 v36, v35
	v_mov_b32_e32 v34, v38
	v_mov_b32_e32 v35, v40
	v_mov_b32_e32 v40, v39
	v_mov_b32_e32 v38, v42
	v_mov_b32_e32 v39, v44
	v_pk_mov_b32 v[176:177], v[104:105], v[116:117] op_sel:[1,0]
	v_mov_b32_e32 v105, v117
	v_pk_fma_f32 v[116:117], v[42:43], v[42:43], v[124:125] op_sel_hi:[1,1,0]
	v_pk_fma_f32 v[178:179], v[44:45], v[44:45], v[126:127] op_sel_hi:[1,1,0]
	v_mov_b32_e32 v44, v43
	v_pk_mov_b32 v[42:43], v[160:161], v[26:27] op_sel:[1,0]
	v_mov_b32_e32 v161, v27
	v_pk_mov_b32 v[26:27], v[166:167], v[164:165] op_sel:[1,0]
	v_mov_b32_e32 v167, v165
	v_mul_f32_e32 v156, v5, v5
	v_mov_b32_e32 v102, v30
	v_mov_b32_e32 v103, v32
	v_mov_b32_e32 v32, v31
	v_pk_mul_f32 v[30:31], v[46:47], v[46:47]
	v_mul_f32_e32 v118, v51, v51
	v_mul_f32_e32 v120, v53, v53
	v_pk_mov_b32 v[132:133], v[110:111], v[108:109] op_sel:[1,0]
	v_mov_b32_e32 v111, v109
	v_pk_fma_f32 v[108:109], v[6:7], v[6:7], v[112:113] op_sel_hi:[1,1,0]
	v_pk_fma_f32 v[112:113], v[8:9], v[8:9], v[134:135] op_sel_hi:[1,1,0]
	s_waitcnt vmcnt(1)
	v_mul_f32_e32 v169, v55, v55
	v_mul_f32_e32 v171, v56, v56
	s_waitcnt vmcnt(0)
	v_mul_f32_e32 v168, v63, v63
	v_mul_f32_e32 v170, v65, v65
	v_pk_add_f32 v[42:43], v[42:43], v[160:161]
	v_pk_add_f32 v[26:27], v[26:27], v[166:167]
	v_mov_b32_e32 v134, v46
	v_mov_b32_e32 v135, v48
	v_mov_b32_e32 v48, v47
	v_mov_b32_e32 v46, v50
	v_mov_b32_e32 v47, v52
	v_mul_f32_e32 v163, v54, v54
	v_mul_f32_e32 v184, v57, v57
	v_pk_mov_b32 v[172:173], v[30:31], v[114:115] op_sel:[1,0]
	v_mov_b32_e32 v31, v115
	v_pk_fma_f32 v[114:115], v[50:51], v[50:51], v[118:119] op_sel_hi:[1,1,0]
	v_pk_fma_f32 v[174:175], v[52:53], v[52:53], v[120:121] op_sel_hi:[1,1,0]
	v_mov_b32_e32 v113, v156
	v_mov_b32_e32 v156, v54
	v_mov_b32_e32 v157, v56
	v_mov_b32_e32 v56, v55
	v_mov_b32_e32 v52, v51
	v_pk_fma_f32 v[50:51], v[62:63], v[62:63], v[168:169] op_sel_hi:[1,1,0]
	v_pk_fma_f32 v[54:55], v[64:65], v[64:65], v[170:171] op_sel_hi:[1,1,0]
	v_pk_add_f32 v[42:43], v[42:43], v[42:43] op_sel:[0,1] op_sel_hi:[1,0]
	v_pk_add_f32 v[26:27], v[26:27], v[26:27] op_sel:[0,1] op_sel_hi:[1,0]
	v_mov_b32_e32 v51, v171
	v_mov_b32_e32 v55, v184
	v_mov_b32_e32 v43, v163
	v_mov_b32_e32 v27, v169
	v_pk_add_f32 v[50:51], v[50:51], v[54:55]
	v_pk_add_f32 v[26:27], v[42:43], v[26:27]
	v_pk_add_f32 v[30:31], v[172:173], v[30:31]
	v_pk_add_f32 v[26:27], v[26:27], v[50:51]
	v_mul_f32_e32 v152, v37, v37
	v_pk_add_f32 v[30:31], v[30:31], v[30:31] op_sel:[0,1] op_sel_hi:[1,0]
	v_pk_add_f32 v[26:27], v[26:27], v[26:27] op_sel:[0,1] op_sel_hi:[1,0]
	v_mov_b32_e32 v115, v151
	v_mov_b32_e32 v175, v152
	v_mov_b32_e32 v31, v147
	v_mov_b32_e32 v27, v144
	v_pk_add_f32 v[110:111], v[132:133], v[110:111]
	v_mov_b32_e32 v132, v66
	v_mov_b32_e32 v133, v68
	v_mov_b32_e32 v68, v67
	v_mov_b32_e32 v66, v58
	v_mov_b32_e32 v67, v60
	v_mov_b32_e32 v60, v59
	v_mov_b32_e32 v58, v62
	v_mov_b32_e32 v59, v64
	v_mov_b32_e32 v64, v63
	v_pk_add_f32 v[62:63], v[114:115], v[174:175]
	v_pk_add_f32 v[26:27], v[26:27], v[30:31]
	v_pk_add_f32 v[104:105], v[176:177], v[104:105]
	v_pk_add_f32 v[26:27], v[26:27], v[62:63]
	v_mul_f32_e32 v155, v4, v4
	v_mul_f32_e32 v154, v29, v29
	v_pk_add_f32 v[104:105], v[104:105], v[104:105] op_sel:[0,1] op_sel_hi:[1,0]
; #define GAS __attribute__((address_space(1)))
; __device__ __forceinline__ unsigned pk2(float lo, float hi) { return f2bf(lo) | (f2bf(hi) << 16); }
; __device__ __forceinline__ float wave_sum(float v) {
; #pragma unroll
;     for (int o = 1; o < 64; o <<= 1) v += __shfl_xor(v, o);
;     return v;
; }
; __global__ void __launch_bounds__(NWAVES * 64, 2) fwd(Args args) {
;     ...
;             const float r = 1.0f / sqrtf(wave_sum(s) * (1.0f / D) + EPS);
;             GAS v2u* o8 = (GAS v2u*)(U + (size_t)m * D) + F.lane;
; #pragma unroll
;             for (int j = 0; j < 16; ++j) { const f32x4 gg = gr[64 * j]; v2u w; w.x = pk2(v[j][0] * r * gg[0], v[j][1] * r * gg[1]); w.y = pk2(v[j][2] * r * gg[2], v[j][3] * r * gg[3]); o8[64 * j] = w; }
	v_pk_add_f32 v[26:27], v[26:27], v[26:27] op_sel:[0,1] op_sel_hi:[1,0]
	v_pk_mul_f32 v[122:123], v[24:25], v[24:25]
	v_pk_mul_f32 v[106:107], v[22:23], v[22:23]
	v_mov_b32_e32 v109, v155
	v_mov_b32_e32 v117, v153
	v_mov_b32_e32 v179, v154
	v_mov_b32_e32 v105, v150
	v_mov_b32_e32 v27, v146
	v_pk_mov_b32 v[180:181], v[106:107], v[122:123] op_sel:[1,0]
	v_mov_b32_e32 v107, v123
	v_pk_add_f32 v[108:109], v[108:109], v[112:113]
	v_pk_add_f32 v[112:113], v[116:117], v[178:179]
	v_pk_add_f32 v[26:27], v[26:27], v[104:105]
	v_mul_f32_e32 v128, v19, v19
	v_mul_f32_e32 v130, v21, v21
	v_pk_add_f32 v[106:107], v[180:181], v[106:107]
	v_pk_add_f32 v[26:27], v[26:27], v[112:113]
	v_mul_f32_e32 v141, v14, v14
	v_mul_f32_e32 v143, v15, v15
	v_mul_f32_e32 v148, v16, v16
	v_mul_f32_e32 v149, v17, v17
	v_pk_fma_f32 v[122:123], v[18:19], v[18:19], v[128:129] op_sel_hi:[1,1,0]
	v_pk_fma_f32 v[182:183], v[20:21], v[20:21], v[130:131] op_sel_hi:[1,1,0]
	v_pk_add_f32 v[106:107], v[106:107], v[106:107] op_sel:[0,1] op_sel_hi:[1,0]
	v_pk_add_f32 v[26:27], v[26:27], v[26:27] op_sel:[0,1] op_sel_hi:[1,0]
	v_mov_b32_e32 v123, v148
	v_mov_b32_e32 v183, v149
	v_mov_b32_e32 v107, v143
	v_mov_b32_e32 v27, v141
	v_pk_add_f32 v[114:115], v[122:123], v[182:183]
	v_pk_add_f32 v[26:27], v[26:27], v[106:107]
	v_mul_f32_e32 v142, v2, v2
	v_pk_add_f32 v[26:27], v[26:27], v[114:115]
	v_mul_f32_e32 v145, v3, v3
	v_pk_add_f32 v[110:111], v[110:111], v[110:111] op_sel:[0,1] op_sel_hi:[1,0]
	v_pk_add_f32 v[26:27], v[26:27], v[26:27] op_sel:[0,1] op_sel_hi:[1,0]
	v_mov_b32_e32 v111, v145
	v_mov_b32_e32 v27, v142
	v_pk_add_f32 v[26:27], v[26:27], v[110:111]
	s_nop 0
	v_pk_add_f32 v[26:27], v[26:27], v[108:109]
	s_nop 0
	v_add_f32_e32 v26, v26, v27
	ds_bpermute_b32 v27, v119, v26
	s_waitcnt lgkmcnt(0)
	v_add_f32_e32 v26, v26, v27
	ds_bpermute_b32 v27, v121, v26
	s_waitcnt lgkmcnt(0)
	v_add_f32_e32 v26, v26, v27
	ds_bpermute_b32 v27, v125, v26
	s_waitcnt lgkmcnt(0)
	v_add_f32_e32 v26, v26, v27
	ds_bpermute_b32 v27, v127, v26
	s_waitcnt lgkmcnt(0)
	v_add_f32_e32 v26, v26, v27
	ds_bpermute_b32 v27, v129, v26
	s_waitcnt lgkmcnt(0)
	v_add_f32_e32 v26, v26, v27
	ds_bpermute_b32 v27, v131, v26
	s_waitcnt lgkmcnt(0)
	v_add_f32_e32 v26, v26, v27
	v_fmamk_f32 v26, v26, 0x39800000, v138
	v_mul_f32_e32 v27, 0x4f800000, v26
	v_cmp_gt_f32_e32 vcc, s14, v26
	s_nop 1
	v_cndmask_b32_e32 v26, v26, v27, vcc
	v_sqrt_f32_e32 v27, v26
	s_nop 0
	v_add_u32_e32 v30, -1, v27
	v_add_u32_e32 v31, 1, v27
	v_fma_f32 v42, -v30, v27, v26
	v_fma_f32 v43, -v31, v27, v26
	v_cmp_ge_f32_e64 s[4:5], 0, v42
	s_nop 1
	v_cndmask_b32_e64 v27, v27, v30, s[4:5]
	v_cmp_lt_f32_e64 s[4:5], 0, v43
	s_nop 1
	v_cndmask_b32_e64 v27, v27, v31, s[4:5]
	v_mul_f32_e32 v30, 0x37800000, v27
	v_cndmask_b32_e32 v27, v27, v30, vcc
	v_cmp_class_f32_e32 vcc, v26, v139
	s_nop 1
	v_cndmask_b32_e32 v26, v27, v26, vcc
	v_div_scale_f32 v27, s[4:5], v26, v26, 1.0
	v_rcp_f32_e32 v31, v27
	v_div_scale_f32 v30, vcc, 1.0, v26, 1.0
	v_fma_f32 v42, -v27, v31, 1.0
	v_fmac_f32_e32 v31, v42, v31
	v_mul_f32_e32 v42, v30, v31
	v_fma_f32 v43, -v27, v42, v30
	v_fmac_f32_e32 v42, v43, v31
	v_fma_f32 v27, -v27, v42, v30
	v_div_fmas_f32 v27, v27, v31, v42
	v_div_fixup_f32 v26, v27, v26, 1.0
	v_pk_mul_f32 v[50:51], v[26:27], v[68:69] op_sel_hi:[0,1]
	v_pk_mul_f32 v[42:43], v[26:27], v[132:133] op_sel_hi:[0,1]
	v_pk_mul_f32 v[32:33], v[32:33], v[50:51]
	v_pk_mul_f32 v[104:105], v[26:27], v[34:35] op_sel_hi:[0,1]
	v_pk_mul_f32 v[34:35], v[102:103], v[42:43]
	v_and_b32_sdwa v43, v33, v140 dst_sel:DWORD dst_unused:UNUSED_PAD src0_sel:WORD_1 src1_sel:DWORD
	v_and_b32_sdwa v50, v32, v140 dst_sel:DWORD dst_unused:UNUSED_PAD src0_sel:WORD_1 src1_sel:DWORD
	v_pk_mul_f32 v[54:55], v[26:27], v[66:67] op_sel_hi:[0,1]
	v_pk_mul_f32 v[60:61], v[26:27], v[60:61] op_sel_hi:[0,1]
	v_pk_mul_f32 v[58:59], v[26:27], v[58:59] op_sel_hi:[0,1]
	v_pk_mul_f32 v[62:63], v[26:27], v[64:65] op_sel_hi:[0,1]
	v_pk_mul_f32 v[64:65], v[26:27], v[156:157] op_sel_hi:[0,1]
	v_pk_mul_f32 v[56:57], v[26:27], v[56:57] op_sel_hi:[0,1]
	v_pk_mul_f32 v[66:67], v[26:27], v[134:135] op_sel_hi:[0,1]
	v_pk_mul_f32 v[48:49], v[26:27], v[48:49] op_sel_hi:[0,1]
	v_pk_mul_f32 v[46:47], v[26:27], v[46:47] op_sel_hi:[0,1]
	v_pk_mul_f32 v[52:53], v[26:27], v[52:53] op_sel_hi:[0,1]
	v_pk_mul_f32 v[68:69], v[26:27], v[136:137] op_sel_hi:[0,1]
	v_pk_mul_f32 v[36:37], v[26:27], v[36:37] op_sel_hi:[0,1]
	v_pk_mul_f32 v[40:41], v[26:27], v[40:41] op_sel_hi:[0,1]
	v_pk_mul_f32 v[38:39], v[26:27], v[38:39] op_sel_hi:[0,1]
	v_pk_mul_f32 v[44:45], v[26:27], v[44:45] op_sel_hi:[0,1]
	v_pk_mul_f32 v[30:31], v[26:27], v[158:159] op_sel_hi:[0,1]
	v_and_b32_sdwa v27, v35, v140 dst_sel:DWORD dst_unused:UNUSED_PAD src0_sel:WORD_1 src1_sel:DWORD
	v_and_b32_sdwa v42, v34, v140 dst_sel:DWORD dst_unused:UNUSED_PAD src0_sel:WORD_1 src1_sel:DWORD
	v_add3_u32 v33, v33, v43, s15
	v_add3_u32 v32, v32, v50, s15
	v_add3_u32 v34, v34, v42, s15
	v_add3_u32 v27, v35, v27, s15
	v_and_b32_e32 v33, 0xffff0000, v33
	v_and_b32_e32 v32, 0xffff0000, v32
	v_or_b32_sdwa v33, v33, v27 dst_sel:DWORD dst_unused:UNUSED_PAD src0_sel:DWORD src1_sel:WORD_1
	v_or_b32_sdwa v32, v32, v34 dst_sel:DWORD dst_unused:UNUSED_PAD src0_sel:DWORD src1_sel:WORD_1
	global_store_dwordx2 v[100:101], v[32:33], off offset:-3584 sc1
	global_load_dwordx4 v[32:35], v[70:71], off offset:1024
	s_waitcnt vmcnt(0)
; #define GAS __attribute__((address_space(1)))
; __device__ __forceinline__ unsigned pk2(float lo, float hi) { return f2bf(lo) | (f2bf(hi) << 16); }
; __global__ void __launch_bounds__(NWAVES * 64, 2) fwd(Args args) {
;     ...
;             GAS v2u* o8 = (GAS v2u*)(U + (size_t)m * D) + F.lane;
; #pragma unroll
;             for (int j = 0; j < 16; ++j) { const f32x4 gg = gr[64 * j]; v2u w; w.x = pk2(v[j][0] * r * gg[0], v[j][1] * r * gg[1]); w.y = pk2(v[j][2] * r * gg[2], v[j][3] * r * gg[3]); o8[64 * j] = w; }
	v_mov_b32_e32 v42, v32
	v_mov_b32_e32 v43, v34
	v_mov_b32_e32 v34, v33
	v_pk_mul_f32 v[32:33], v[42:43], v[54:55]
	v_pk_mul_f32 v[34:35], v[34:35], v[60:61]
	v_and_b32_sdwa v27, v33, v140 dst_sel:DWORD dst_unused:UNUSED_PAD src0_sel:WORD_1 src1_sel:DWORD
	v_and_b32_sdwa v43, v35, v140 dst_sel:DWORD dst_unused:UNUSED_PAD src0_sel:WORD_1 src1_sel:DWORD
	v_and_b32_sdwa v50, v34, v140 dst_sel:DWORD dst_unused:UNUSED_PAD src0_sel:WORD_1 src1_sel:DWORD
	v_and_b32_sdwa v42, v32, v140 dst_sel:DWORD dst_unused:UNUSED_PAD src0_sel:WORD_1 src1_sel:DWORD
	v_add3_u32 v27, v33, v27, s15
	v_add3_u32 v33, v35, v43, s15
	v_add3_u32 v34, v34, v50, s15
	v_add3_u32 v32, v32, v42, s15
	v_and_b32_e32 v33, 0xffff0000, v33
	v_and_b32_e32 v34, 0xffff0000, v34
	v_or_b32_sdwa v33, v33, v27 dst_sel:DWORD dst_unused:UNUSED_PAD src0_sel:DWORD src1_sel:WORD_1
	v_or_b32_sdwa v32, v34, v32 dst_sel:DWORD dst_unused:UNUSED_PAD src0_sel:DWORD src1_sel:WORD_1
	global_store_dwordx2 v[100:101], v[32:33], off offset:-3072 sc1
	global_load_dwordx4 v[32:35], v[70:71], off offset:2048
	s_waitcnt vmcnt(0)
	v_mov_b32_e32 v42, v32
	v_mov_b32_e32 v43, v34
	v_mov_b32_e32 v34, v33
	v_pk_mul_f32 v[32:33], v[42:43], v[58:59]
	v_pk_mul_f32 v[34:35], v[34:35], v[62:63]
	v_and_b32_sdwa v27, v33, v140 dst_sel:DWORD dst_unused:UNUSED_PAD src0_sel:WORD_1 src1_sel:DWORD
	v_and_b32_sdwa v43, v35, v140 dst_sel:DWORD dst_unused:UNUSED_PAD src0_sel:WORD_1 src1_sel:DWORD
	v_and_b32_sdwa v50, v34, v140 dst_sel:DWORD dst_unused:UNUSED_PAD src0_sel:WORD_1 src1_sel:DWORD
	v_and_b32_sdwa v42, v32, v140 dst_sel:DWORD dst_unused:UNUSED_PAD src0_sel:WORD_1 src1_sel:DWORD
	v_add3_u32 v27, v33, v27, s15
	v_add3_u32 v33, v35, v43, s15
	v_add3_u32 v34, v34, v50, s15
	v_add3_u32 v32, v32, v42, s15
	v_and_b32_e32 v33, 0xffff0000, v33
	v_and_b32_e32 v34, 0xffff0000, v34
	v_or_b32_sdwa v33, v33, v27 dst_sel:DWORD dst_unused:UNUSED_PAD src0_sel:DWORD src1_sel:WORD_1
	v_or_b32_sdwa v32, v34, v32 dst_sel:DWORD dst_unused:UNUSED_PAD src0_sel:DWORD src1_sel:WORD_1
	global_store_dwordx2 v[100:101], v[32:33], off offset:-2560 sc1
	global_load_dwordx4 v[32:35], v[70:71], off offset:3072
	s_waitcnt vmcnt(0)
	v_mov_b32_e32 v42, v32
	v_mov_b32_e32 v43, v34
	v_mov_b32_e32 v34, v33
	v_pk_mul_f32 v[32:33], v[42:43], v[64:65]
	v_pk_mul_f32 v[34:35], v[34:35], v[56:57]
	v_and_b32_sdwa v27, v33, v140 dst_sel:DWORD dst_unused:UNUSED_PAD src0_sel:WORD_1 src1_sel:DWORD
	v_and_b32_sdwa v43, v35, v140 dst_sel:DWORD dst_unused:UNUSED_PAD src0_sel:WORD_1 src1_sel:DWORD
	v_and_b32_sdwa v50, v34, v140 dst_sel:DWORD dst_unused:UNUSED_PAD src0_sel:WORD_1 src1_sel:DWORD
	v_and_b32_sdwa v42, v32, v140 dst_sel:DWORD dst_unused:UNUSED_PAD src0_sel:WORD_1 src1_sel:DWORD
	v_add3_u32 v27, v33, v27, s15
	v_add3_u32 v33, v35, v43, s15
	v_add3_u32 v34, v34, v50, s15
	v_add3_u32 v32, v32, v42, s15
	v_and_b32_e32 v33, 0xffff0000, v33
	v_and_b32_e32 v34, 0xffff0000, v34
	v_or_b32_sdwa v33, v33, v27 dst_sel:DWORD dst_unused:UNUSED_PAD src0_sel:DWORD src1_sel:WORD_1
	v_or_b32_sdwa v32, v34, v32 dst_sel:DWORD dst_unused:UNUSED_PAD src0_sel:DWORD src1_sel:WORD_1
	global_store_dwordx2 v[100:101], v[32:33], off offset:-2048 sc1
	global_load_dwordx4 v[32:35], v[72:73], off
	s_waitcnt vmcnt(0)
	v_mov_b32_e32 v42, v32
	v_mov_b32_e32 v43, v34
	v_mov_b32_e32 v34, v33
	v_pk_mul_f32 v[32:33], v[42:43], v[66:67]
	v_pk_mul_f32 v[34:35], v[34:35], v[48:49]
	v_and_b32_sdwa v27, v33, v140 dst_sel:DWORD dst_unused:UNUSED_PAD src0_sel:WORD_1 src1_sel:DWORD
	v_and_b32_sdwa v43, v35, v140 dst_sel:DWORD dst_unused:UNUSED_PAD src0_sel:WORD_1 src1_sel:DWORD
	v_and_b32_sdwa v48, v34, v140 dst_sel:DWORD dst_unused:UNUSED_PAD src0_sel:WORD_1 src1_sel:DWORD
	v_and_b32_sdwa v42, v32, v140 dst_sel:DWORD dst_unused:UNUSED_PAD src0_sel:WORD_1 src1_sel:DWORD
	v_add3_u32 v27, v33, v27, s15
	v_add3_u32 v33, v35, v43, s15
	v_add3_u32 v34, v34, v48, s15
	v_add3_u32 v32, v32, v42, s15
	v_and_b32_e32 v33, 0xffff0000, v33
	v_and_b32_e32 v34, 0xffff0000, v34
	v_or_b32_sdwa v33, v33, v27 dst_sel:DWORD dst_unused:UNUSED_PAD src0_sel:DWORD src1_sel:WORD_1
	v_or_b32_sdwa v32, v34, v32 dst_sel:DWORD dst_unused:UNUSED_PAD src0_sel:DWORD src1_sel:WORD_1
	global_store_dwordx2 v[100:101], v[32:33], off offset:-1536 sc1
	global_load_dwordx4 v[32:35], v[74:75], off
	s_waitcnt vmcnt(0)
	v_mov_b32_e32 v42, v32
	v_mov_b32_e32 v43, v34
	v_mov_b32_e32 v34, v33
	v_pk_mul_f32 v[32:33], v[42:43], v[46:47]
	v_pk_mul_f32 v[34:35], v[34:35], v[52:53]
	v_and_b32_sdwa v27, v33, v140 dst_sel:DWORD dst_unused:UNUSED_PAD src0_sel:WORD_1 src1_sel:DWORD
	v_and_b32_sdwa v43, v35, v140 dst_sel:DWORD dst_unused:UNUSED_PAD src0_sel:WORD_1 src1_sel:DWORD
	v_and_b32_sdwa v46, v34, v140 dst_sel:DWORD dst_unused:UNUSED_PAD src0_sel:WORD_1 src1_sel:DWORD
	v_and_b32_sdwa v42, v32, v140 dst_sel:DWORD dst_unused:UNUSED_PAD src0_sel:WORD_1 src1_sel:DWORD
	v_add3_u32 v27, v33, v27, s15
	v_add3_u32 v33, v35, v43, s15
	v_add3_u32 v34, v34, v46, s15
	v_add3_u32 v32, v32, v42, s15
	v_and_b32_e32 v33, 0xffff0000, v33
	v_and_b32_e32 v34, 0xffff0000, v34
	v_or_b32_sdwa v33, v33, v27 dst_sel:DWORD dst_unused:UNUSED_PAD src0_sel:DWORD src1_sel:WORD_1
	v_or_b32_sdwa v32, v34, v32 dst_sel:DWORD dst_unused:UNUSED_PAD src0_sel:DWORD src1_sel:WORD_1
	global_store_dwordx2 v[100:101], v[32:33], off offset:-1024 sc1
	global_load_dwordx4 v[32:35], v[76:77], off
	s_waitcnt vmcnt(0)
; #define GAS __attribute__((address_space(1)))
; __device__ __forceinline__ unsigned pk2(float lo, float hi) { return f2bf(lo) | (f2bf(hi) << 16); }
; __global__ void __launch_bounds__(NWAVES * 64, 2) fwd(Args args) {
;     ...
;             GAS v2u* o8 = (GAS v2u*)(U + (size_t)m * D) + F.lane;
; #pragma unroll
;             for (int j = 0; j < 16; ++j) { const f32x4 gg = gr[64 * j]; v2u w; w.x = pk2(v[j][0] * r * gg[0], v[j][1] * r * gg[1]); w.y = pk2(v[j][2] * r * gg[2], v[j][3] * r * gg[3]); o8[64 * j] = w; }
	v_mov_b32_e32 v42, v32
	v_mov_b32_e32 v43, v34
	v_mov_b32_e32 v34, v33
	v_pk_mul_f32 v[32:33], v[42:43], v[68:69]
	v_pk_mul_f32 v[34:35], v[34:35], v[36:37]
	v_and_b32_sdwa v27, v33, v140 dst_sel:DWORD dst_unused:UNUSED_PAD src0_sel:WORD_1 src1_sel:DWORD
	v_and_b32_sdwa v37, v35, v140 dst_sel:DWORD dst_unused:UNUSED_PAD src0_sel:WORD_1 src1_sel:DWORD
	v_and_b32_sdwa v42, v34, v140 dst_sel:DWORD dst_unused:UNUSED_PAD src0_sel:WORD_1 src1_sel:DWORD
	v_and_b32_sdwa v36, v32, v140 dst_sel:DWORD dst_unused:UNUSED_PAD src0_sel:WORD_1 src1_sel:DWORD
	v_add3_u32 v27, v33, v27, s15
	v_add3_u32 v33, v35, v37, s15
	v_add3_u32 v34, v34, v42, s15
	v_add3_u32 v32, v32, v36, s15
	v_and_b32_e32 v33, 0xffff0000, v33
	v_and_b32_e32 v34, 0xffff0000, v34
	v_or_b32_sdwa v33, v33, v27 dst_sel:DWORD dst_unused:UNUSED_PAD src0_sel:DWORD src1_sel:WORD_1
	v_or_b32_sdwa v32, v34, v32 dst_sel:DWORD dst_unused:UNUSED_PAD src0_sel:DWORD src1_sel:WORD_1
	global_store_dwordx2 v[100:101], v[32:33], off offset:-512 sc1
	global_load_dwordx4 v[32:35], v[78:79], off
	s_waitcnt vmcnt(0)
	v_mov_b32_e32 v36, v32
	v_mov_b32_e32 v37, v34
	v_mov_b32_e32 v34, v33
	v_pk_mul_f32 v[32:33], v[36:37], v[104:105]
	v_pk_mul_f32 v[34:35], v[34:35], v[40:41]
	v_and_b32_sdwa v27, v33, v140 dst_sel:DWORD dst_unused:UNUSED_PAD src0_sel:WORD_1 src1_sel:DWORD
	v_and_b32_sdwa v37, v35, v140 dst_sel:DWORD dst_unused:UNUSED_PAD src0_sel:WORD_1 src1_sel:DWORD
	v_and_b32_sdwa v40, v34, v140 dst_sel:DWORD dst_unused:UNUSED_PAD src0_sel:WORD_1 src1_sel:DWORD
	v_and_b32_sdwa v36, v32, v140 dst_sel:DWORD dst_unused:UNUSED_PAD src0_sel:WORD_1 src1_sel:DWORD
	v_add3_u32 v27, v33, v27, s15
	v_add3_u32 v33, v35, v37, s15
	v_add3_u32 v34, v34, v40, s15
	v_add3_u32 v32, v32, v36, s15
	v_and_b32_e32 v33, 0xffff0000, v33
	v_and_b32_e32 v34, 0xffff0000, v34
	v_or_b32_sdwa v33, v33, v27 dst_sel:DWORD dst_unused:UNUSED_PAD src0_sel:DWORD src1_sel:WORD_1
	v_or_b32_sdwa v32, v34, v32 dst_sel:DWORD dst_unused:UNUSED_PAD src0_sel:DWORD src1_sel:WORD_1
	global_store_dwordx2 v[96:97], v[32:33], off offset:-4096 sc1
	global_load_dwordx4 v[32:35], v[80:81], off
	s_waitcnt vmcnt(0)
	v_mov_b32_e32 v36, v32
	v_mov_b32_e32 v37, v34
	v_mov_b32_e32 v34, v33
	v_pk_mul_f32 v[32:33], v[36:37], v[38:39]
	v_pk_mul_f32 v[34:35], v[34:35], v[44:45]
	v_and_b32_sdwa v27, v33, v140 dst_sel:DWORD dst_unused:UNUSED_PAD src0_sel:WORD_1 src1_sel:DWORD
	v_and_b32_sdwa v37, v35, v140 dst_sel:DWORD dst_unused:UNUSED_PAD src0_sel:WORD_1 src1_sel:DWORD
	v_and_b32_sdwa v38, v34, v140 dst_sel:DWORD dst_unused:UNUSED_PAD src0_sel:WORD_1 src1_sel:DWORD
	v_and_b32_sdwa v36, v32, v140 dst_sel:DWORD dst_unused:UNUSED_PAD src0_sel:WORD_1 src1_sel:DWORD
	v_add3_u32 v27, v33, v27, s15
	v_add3_u32 v33, v35, v37, s15
	v_add3_u32 v34, v34, v38, s15
	v_add3_u32 v32, v32, v36, s15
	v_and_b32_e32 v33, 0xffff0000, v33
	v_and_b32_e32 v34, 0xffff0000, v34
	v_or_b32_sdwa v33, v33, v27 dst_sel:DWORD dst_unused:UNUSED_PAD src0_sel:DWORD src1_sel:WORD_1
	v_or_b32_sdwa v32, v34, v32 dst_sel:DWORD dst_unused:UNUSED_PAD src0_sel:DWORD src1_sel:WORD_1
	global_store_dwordx2 v[96:97], v[32:33], off offset:-3584 sc1
	global_load_dwordx4 v[32:35], v[82:83], off
	v_pk_mul_f32 v[28:29], v[26:27], v[28:29] op_sel_hi:[0,1]
	s_waitcnt vmcnt(0)
	v_mov_b32_e32 v37, v34
	v_mov_b32_e32 v34, v33
	v_mov_b32_e32 v36, v32
	v_pk_mul_f32 v[28:29], v[34:35], v[28:29]
	v_pk_mul_f32 v[30:31], v[36:37], v[30:31]
	v_and_b32_sdwa v33, v29, v140 dst_sel:DWORD dst_unused:UNUSED_PAD src0_sel:WORD_1 src1_sel:DWORD
	v_and_b32_sdwa v34, v28, v140 dst_sel:DWORD dst_unused:UNUSED_PAD src0_sel:WORD_1 src1_sel:DWORD
	v_and_b32_sdwa v27, v31, v140 dst_sel:DWORD dst_unused:UNUSED_PAD src0_sel:WORD_1 src1_sel:DWORD
	v_and_b32_sdwa v32, v30, v140 dst_sel:DWORD dst_unused:UNUSED_PAD src0_sel:WORD_1 src1_sel:DWORD
	v_add3_u32 v29, v29, v33, s15
	v_add3_u32 v28, v28, v34, s15
	v_add3_u32 v30, v30, v32, s15
	v_add3_u32 v27, v31, v27, s15
	v_and_b32_e32 v29, 0xffff0000, v29
	v_and_b32_e32 v28, 0xffff0000, v28
	v_or_b32_sdwa v29, v29, v27 dst_sel:DWORD dst_unused:UNUSED_PAD src0_sel:DWORD src1_sel:WORD_1
	v_or_b32_sdwa v28, v28, v30 dst_sel:DWORD dst_unused:UNUSED_PAD src0_sel:DWORD src1_sel:WORD_1
	global_store_dwordx2 v[96:97], v[28:29], off offset:-3072 sc1
	global_load_dwordx4 v[28:31], v[84:85], off
	v_mov_b32_e32 v32, v22
	v_mov_b32_e32 v33, v24
	v_mov_b32_e32 v24, v23
	v_pk_mul_f32 v[22:23], v[26:27], v[32:33] op_sel_hi:[0,1]
	v_pk_mul_f32 v[24:25], v[26:27], v[24:25] op_sel_hi:[0,1]
	s_waitcnt vmcnt(0)
	v_mov_b32_e32 v33, v30
	v_mov_b32_e32 v30, v29
	v_mov_b32_e32 v32, v28
	v_pk_mul_f32 v[24:25], v[30:31], v[24:25]
	v_pk_mul_f32 v[22:23], v[32:33], v[22:23]
	v_and_b32_sdwa v29, v25, v140 dst_sel:DWORD dst_unused:UNUSED_PAD src0_sel:WORD_1 src1_sel:DWORD
	v_and_b32_sdwa v30, v24, v140 dst_sel:DWORD dst_unused:UNUSED_PAD src0_sel:WORD_1 src1_sel:DWORD
	v_and_b32_sdwa v27, v23, v140 dst_sel:DWORD dst_unused:UNUSED_PAD src0_sel:WORD_1 src1_sel:DWORD
	v_and_b32_sdwa v28, v22, v140 dst_sel:DWORD dst_unused:UNUSED_PAD src0_sel:WORD_1 src1_sel:DWORD
	v_add3_u32 v25, v25, v29, s15
	v_add3_u32 v24, v24, v30, s15
	v_add3_u32 v22, v22, v28, s15
	v_add3_u32 v23, v23, v27, s15
	v_and_b32_e32 v25, 0xffff0000, v25
	v_and_b32_e32 v24, 0xffff0000, v24
	v_or_b32_sdwa v23, v25, v23 dst_sel:DWORD dst_unused:UNUSED_PAD src0_sel:DWORD src1_sel:WORD_1
	v_or_b32_sdwa v22, v24, v22 dst_sel:DWORD dst_unused:UNUSED_PAD src0_sel:DWORD src1_sel:WORD_1
	global_store_dwordx2 v[96:97], v[22:23], off offset:-2560 sc1
	global_load_dwordx4 v[22:25], v[86:87], off
	v_mov_b32_e32 v28, v18
	v_mov_b32_e32 v29, v20
	v_mov_b32_e32 v20, v19
	v_pk_mul_f32 v[18:19], v[26:27], v[28:29] op_sel_hi:[0,1]
	v_pk_mul_f32 v[20:21], v[26:27], v[20:21] op_sel_hi:[0,1]
	s_waitcnt vmcnt(0)
; #define GAS __attribute__((address_space(1)))
; __device__ __forceinline__ unsigned pk2(float lo, float hi) { return f2bf(lo) | (f2bf(hi) << 16); }
; __global__ void __launch_bounds__(NWAVES * 64, 2) fwd(Args args) {
;     ...
;             GAS v2u* o8 = (GAS v2u*)(U + (size_t)m * D) + F.lane;
; #pragma unroll
;             for (int j = 0; j < 16; ++j) { const f32x4 gg = gr[64 * j]; v2u w; w.x = pk2(v[j][0] * r * gg[0], v[j][1] * r * gg[1]); w.y = pk2(v[j][2] * r * gg[2], v[j][3] * r * gg[3]); o8[64 * j] = w; }
	v_mov_b32_e32 v29, v24
	v_mov_b32_e32 v24, v23
	v_mov_b32_e32 v28, v22
	v_pk_mul_f32 v[20:21], v[24:25], v[20:21]
	v_pk_mul_f32 v[18:19], v[28:29], v[18:19]
	v_and_b32_sdwa v24, v21, v140 dst_sel:DWORD dst_unused:UNUSED_PAD src0_sel:WORD_1 src1_sel:DWORD
	v_and_b32_sdwa v25, v20, v140 dst_sel:DWORD dst_unused:UNUSED_PAD src0_sel:WORD_1 src1_sel:DWORD
	v_and_b32_sdwa v22, v19, v140 dst_sel:DWORD dst_unused:UNUSED_PAD src0_sel:WORD_1 src1_sel:DWORD
	v_and_b32_sdwa v23, v18, v140 dst_sel:DWORD dst_unused:UNUSED_PAD src0_sel:WORD_1 src1_sel:DWORD
	v_add3_u32 v21, v21, v24, s15
	v_add3_u32 v20, v20, v25, s15
	v_add3_u32 v18, v18, v23, s15
	v_add3_u32 v19, v19, v22, s15
	v_and_b32_e32 v21, 0xffff0000, v21
	v_and_b32_e32 v20, 0xffff0000, v20
	v_or_b32_sdwa v19, v21, v19 dst_sel:DWORD dst_unused:UNUSED_PAD src0_sel:DWORD src1_sel:WORD_1
	v_or_b32_sdwa v18, v20, v18 dst_sel:DWORD dst_unused:UNUSED_PAD src0_sel:DWORD src1_sel:WORD_1
	global_store_dwordx2 v[96:97], v[18:19], off offset:-2048 sc1
	global_load_dwordx4 v[18:21], v[88:89], off
	v_mov_b32_e32 v22, v14
	v_mov_b32_e32 v23, v16
	v_mov_b32_e32 v16, v15
	v_pk_mul_f32 v[14:15], v[26:27], v[22:23] op_sel_hi:[0,1]
	v_pk_mul_f32 v[16:17], v[26:27], v[16:17] op_sel_hi:[0,1]
	s_waitcnt vmcnt(0)
	v_mov_b32_e32 v23, v20
	v_mov_b32_e32 v20, v19
	v_mov_b32_e32 v22, v18
	v_pk_mul_f32 v[16:17], v[20:21], v[16:17]
	v_pk_mul_f32 v[14:15], v[22:23], v[14:15]
	v_and_b32_sdwa v20, v17, v140 dst_sel:DWORD dst_unused:UNUSED_PAD src0_sel:WORD_1 src1_sel:DWORD
	v_and_b32_sdwa v21, v16, v140 dst_sel:DWORD dst_unused:UNUSED_PAD src0_sel:WORD_1 src1_sel:DWORD
	v_and_b32_sdwa v18, v15, v140 dst_sel:DWORD dst_unused:UNUSED_PAD src0_sel:WORD_1 src1_sel:DWORD
	v_and_b32_sdwa v19, v14, v140 dst_sel:DWORD dst_unused:UNUSED_PAD src0_sel:WORD_1 src1_sel:DWORD
	v_add3_u32 v17, v17, v20, s15
	v_add3_u32 v16, v16, v21, s15
	v_add3_u32 v14, v14, v19, s15
	v_add3_u32 v15, v15, v18, s15
	v_and_b32_e32 v17, 0xffff0000, v17
	v_and_b32_e32 v16, 0xffff0000, v16
	v_or_b32_sdwa v15, v17, v15 dst_sel:DWORD dst_unused:UNUSED_PAD src0_sel:DWORD src1_sel:WORD_1
	v_or_b32_sdwa v14, v16, v14 dst_sel:DWORD dst_unused:UNUSED_PAD src0_sel:DWORD src1_sel:WORD_1
	global_store_dwordx2 v[96:97], v[14:15], off offset:-1536 sc1
	global_load_dwordx4 v[14:17], v[90:91], off
	v_mov_b32_e32 v18, v10
	v_mov_b32_e32 v19, v12
	v_mov_b32_e32 v12, v11
	v_pk_mul_f32 v[10:11], v[26:27], v[18:19] op_sel_hi:[0,1]
	v_pk_mul_f32 v[12:13], v[26:27], v[12:13] op_sel_hi:[0,1]
	s_waitcnt vmcnt(0)
	v_mov_b32_e32 v19, v16
	v_mov_b32_e32 v16, v15
	v_mov_b32_e32 v18, v14
	v_pk_mul_f32 v[12:13], v[16:17], v[12:13]
	v_pk_mul_f32 v[10:11], v[18:19], v[10:11]
	v_and_b32_sdwa v16, v13, v140 dst_sel:DWORD dst_unused:UNUSED_PAD src0_sel:WORD_1 src1_sel:DWORD
	v_and_b32_sdwa v17, v12, v140 dst_sel:DWORD dst_unused:UNUSED_PAD src0_sel:WORD_1 src1_sel:DWORD
	v_and_b32_sdwa v14, v11, v140 dst_sel:DWORD dst_unused:UNUSED_PAD src0_sel:WORD_1 src1_sel:DWORD
	v_and_b32_sdwa v15, v10, v140 dst_sel:DWORD dst_unused:UNUSED_PAD src0_sel:WORD_1 src1_sel:DWORD
	v_add3_u32 v13, v13, v16, s15
	v_add3_u32 v12, v12, v17, s15
	v_add3_u32 v10, v10, v15, s15
	v_add3_u32 v11, v11, v14, s15
	v_and_b32_e32 v13, 0xffff0000, v13
	v_and_b32_e32 v12, 0xffff0000, v12
	v_or_b32_sdwa v11, v13, v11 dst_sel:DWORD dst_unused:UNUSED_PAD src0_sel:DWORD src1_sel:WORD_1
	v_or_b32_sdwa v10, v12, v10 dst_sel:DWORD dst_unused:UNUSED_PAD src0_sel:DWORD src1_sel:WORD_1
	global_store_dwordx2 v[96:97], v[10:11], off offset:-1024 sc1
	global_load_dwordx4 v[10:13], v[92:93], off
	v_mov_b32_e32 v14, v6
	v_mov_b32_e32 v15, v8
	v_mov_b32_e32 v8, v7
	v_pk_mul_f32 v[6:7], v[26:27], v[14:15] op_sel_hi:[0,1]
	v_pk_mul_f32 v[8:9], v[26:27], v[8:9] op_sel_hi:[0,1]
	s_waitcnt vmcnt(0)
	v_mov_b32_e32 v15, v12
	v_mov_b32_e32 v12, v11
	v_mov_b32_e32 v14, v10
	v_pk_mul_f32 v[8:9], v[12:13], v[8:9]
	v_pk_mul_f32 v[6:7], v[14:15], v[6:7]
	v_and_b32_sdwa v12, v9, v140 dst_sel:DWORD dst_unused:UNUSED_PAD src0_sel:WORD_1 src1_sel:DWORD
	v_and_b32_sdwa v13, v8, v140 dst_sel:DWORD dst_unused:UNUSED_PAD src0_sel:WORD_1 src1_sel:DWORD
	v_and_b32_sdwa v10, v7, v140 dst_sel:DWORD dst_unused:UNUSED_PAD src0_sel:WORD_1 src1_sel:DWORD
	v_and_b32_sdwa v11, v6, v140 dst_sel:DWORD dst_unused:UNUSED_PAD src0_sel:WORD_1 src1_sel:DWORD
	v_add3_u32 v9, v9, v12, s15
	v_add3_u32 v8, v8, v13, s15
	v_add3_u32 v6, v6, v11, s15
	v_add3_u32 v7, v7, v10, s15
	v_and_b32_e32 v9, 0xffff0000, v9
	v_and_b32_e32 v8, 0xffff0000, v8
	v_or_b32_sdwa v7, v9, v7 dst_sel:DWORD dst_unused:UNUSED_PAD src0_sel:DWORD src1_sel:WORD_1
	v_or_b32_sdwa v6, v8, v6 dst_sel:DWORD dst_unused:UNUSED_PAD src0_sel:DWORD src1_sel:WORD_1
	global_store_dwordx2 v[96:97], v[6:7], off offset:-512 sc1
	global_load_dwordx4 v[6:9], v[94:95], off
	v_mov_b32_e32 v10, v2
	v_mov_b32_e32 v11, v4
	v_mov_b32_e32 v4, v3
	v_pk_mul_f32 v[2:3], v[26:27], v[10:11] op_sel_hi:[0,1]
	v_pk_mul_f32 v[4:5], v[26:27], v[4:5] op_sel_hi:[0,1]
	s_waitcnt vmcnt(0)
	v_mov_b32_e32 v11, v8
	v_mov_b32_e32 v8, v7
	v_mov_b32_e32 v10, v6
	v_pk_mul_f32 v[4:5], v[8:9], v[4:5]
	v_pk_mul_f32 v[2:3], v[10:11], v[2:3]
	v_and_b32_sdwa v8, v5, v140 dst_sel:DWORD dst_unused:UNUSED_PAD src0_sel:WORD_1 src1_sel:DWORD
	v_and_b32_sdwa v9, v4, v140 dst_sel:DWORD dst_unused:UNUSED_PAD src0_sel:WORD_1 src1_sel:DWORD
	v_and_b32_sdwa v6, v3, v140 dst_sel:DWORD dst_unused:UNUSED_PAD src0_sel:WORD_1 src1_sel:DWORD
	v_and_b32_sdwa v7, v2, v140 dst_sel:DWORD dst_unused:UNUSED_PAD src0_sel:WORD_1 src1_sel:DWORD
	v_add3_u32 v5, v5, v8, s15
	v_add3_u32 v4, v4, v9, s15
	v_add3_u32 v2, v2, v7, s15
	v_add3_u32 v3, v3, v6, s15
	v_and_b32_e32 v5, 0xffff0000, v5
	v_and_b32_e32 v4, 0xffff0000, v4
	v_or_b32_sdwa v3, v5, v3 dst_sel:DWORD dst_unused:UNUSED_PAD src0_sel:DWORD src1_sel:WORD_1
	v_or_b32_sdwa v2, v4, v2 dst_sel:DWORD dst_unused:UNUSED_PAD src0_sel:DWORD src1_sel:WORD_1
	global_store_dwordx2 v[96:97], v[2:3], off sc1
	v_lshl_add_u64 v[96:97], v[96:97], 0, s[0:1]
	s_cbranch_scc0 .LBB0_75

; __device__ __forceinline__ unsigned cvt_pk_bf16(float lo, float hi) { const cvt_f2 v = {lo, hi}; return __builtin_bit_cast(unsigned, __builtin_convertvector(v, cvt_b2)); }
;     __device__ __forceinline__ void operator()(const f32x4 (&acc)[2][2][4][2], const Unit& u, int wr, int wc, int fr, int fq) const {
;     ...
;             const int gc0 = (u.pn - 40) * HALF + wc * 32 + 8 * fq; bf16* RT = PROJ + (size_t)6 * T * 2048; bf16* GBt = RT + (size_t)T * 4096;
; #pragma unroll
;             for (int ai = 0; ai < 2; ++ai)
; #pragma unroll
;                 for (int m = 0; m < 4; ++m) { const size_t ro = (size_t)(row0 + ai * HALF + m * 16) * D + gc0; float rt[8], gb[8];
; #pragma unroll
;                     for (int n = 0; n < 2; ++n)
; #pragma unroll
;                         for (int j = 0; j < 4; ++j) { const float a = fminf(fmaxf(acc[ai][0][m][n][j], -30.f), 30.f), b = fminf(fmaxf(acc[ai][1][m][n][j], -30.f), 30.f);
;                             const float ea = __expf(-a), eb = __expf(-b); gb[4 * n + j] = __builtin_amdgcn_rcpf(1.0f + eb); rt[4 * n + j] = (1.0f + eb) * __builtin_amdgcn_rcpf(1.0f + ea); }
;                     pg8::u32x4 w; w.x = cvt_pk_bf16(rt[0], rt[1]); w.y = cvt_pk_bf16(rt[2], rt[3]); w.z = cvt_pk_bf16(rt[4], rt[5]); w.w = cvt_pk_bf16(rt[6], rt[7]);
;                     *(pg8::u32x4*)(RT + ro) = w;
;                     w.x = cvt_pk_bf16(gb[0], gb[1]); w.y = cvt_pk_bf16(gb[2], gb[3]); w.z = cvt_pk_bf16(gb[4], gb[5]); w.w = cvt_pk_bf16(gb[6], gb[7]);
;                     *(pg8::u32x4*)(GBt + ro) = w; }
.LBB0_146:
	s_and_b64 vcc, exec, s[0:1]
	s_cbranch_vccz .LBB0_222
	v_max_f32_e32 v126, v126, v126
	v_max_f32_e32 v127, v127, v127
	v_med3_f32 v126, v126, s91, v171
	v_med3_f32 v127, v127, s91, v171
	v_mul_f32_e32 v126, 0xbfb8aa3b, v126
	v_mul_f32_e32 v127, 0xbfb8aa3b, v127
	v_exp_f32_e32 v126, v126
	v_exp_f32_e32 v127, v127
	v_max_f32_e32 v122, v122, v122
	v_max_f32_e32 v123, v123, v123
	v_med3_f32 v122, v122, s91, v171
	v_med3_f32 v123, v123, s91, v171
	v_mul_f32_e32 v122, 0xbfb8aa3b, v122
	v_mul_f32_e32 v123, 0xbfb8aa3b, v123
	v_exp_f32_e32 v122, v122
	v_add_f32_e32 v126, 1.0, v126
	v_exp_f32_e32 v123, v123
	v_add_f32_e32 v127, 1.0, v127
	v_rcp_f32_e32 v126, v126
	v_rcp_f32_e32 v127, v127
	v_pk_add_f32 v[122:123], v[122:123], 1.0 op_sel_hi:[1,0]
	v_max_f32_e32 v118, v118, v118
	v_rcp_f32_e32 v132, v122
	v_pk_mul_f32 v[126:127], v[126:127], v[122:123]
	v_max_f32_e32 v122, v128, v128
	v_med3_f32 v122, v122, s91, v171
	v_mul_f32_e32 v122, 0xbfb8aa3b, v122
	v_exp_f32_e32 v122, v122
	v_max_f32_e32 v119, v119, v119
	v_med3_f32 v118, v118, s91, v171
	v_med3_f32 v119, v119, s91, v171
	v_add_f32_e32 v122, 1.0, v122
	v_rcp_f32_e32 v128, v122
	v_max_f32_e32 v122, v129, v129
	v_med3_f32 v122, v122, s91, v171
	v_mul_f32_e32 v122, 0xbfb8aa3b, v122
	v_mul_f32_e32 v118, 0xbfb8aa3b, v118
	v_mul_f32_e32 v119, 0xbfb8aa3b, v119
	v_exp_f32_e32 v122, v122
	v_exp_f32_e32 v118, v118
	v_exp_f32_e32 v119, v119
	v_max_f32_e32 v124, v124, v124
	v_max_f32_e32 v125, v125, v125
	v_max_f32_e32 v114, v114, v114
	v_max_f32_e32 v115, v115, v115
	v_med3_f32 v124, v124, s91, v171
	v_med3_f32 v125, v125, s91, v171
	v_med3_f32 v114, v114, s91, v171
	v_med3_f32 v115, v115, s91, v171
	v_mul_f32_e32 v124, 0xbfb8aa3b, v124
	v_mul_f32_e32 v125, 0xbfb8aa3b, v125
	v_mul_f32_e32 v114, 0xbfb8aa3b, v114
	v_mul_f32_e32 v115, 0xbfb8aa3b, v115
	v_exp_f32_e32 v124, v124
	v_exp_f32_e32 v125, v125
	v_add_f32_e32 v122, 1.0, v122
	v_exp_f32_e32 v114, v114
	v_add_f32_e32 v118, 1.0, v118
	v_exp_f32_e32 v115, v115
	v_add_f32_e32 v119, 1.0, v119
	v_rcp_f32_e32 v129, v122
	v_rcp_f32_e32 v118, v118
	v_rcp_f32_e32 v119, v119
	v_rcp_f32_e32 v133, v123
	v_pk_add_f32 v[122:123], v[124:125], 1.0 op_sel_hi:[1,0]
	v_pk_add_f32 v[114:115], v[114:115], 1.0 op_sel_hi:[1,0]
	v_rcp_f32_e32 v134, v122
	v_pk_mul_f32 v[124:125], v[128:129], v[122:123]
	v_rcp_f32_e32 v122, v123
	v_rcp_f32_e32 v123, v114
	v_pk_mul_f32 v[118:119], v[118:119], v[114:115]
	v_max_f32_e32 v114, v120, v120
	v_med3_f32 v114, v114, s91, v171
	v_mul_f32_e32 v114, 0xbfb8aa3b, v114
	v_exp_f32_e32 v114, v114
	v_max_f32_e32 v116, v116, v116
	v_max_f32_e32 v117, v117, v117
	v_med3_f32 v116, v116, s91, v171
	v_add_f32_e32 v114, 1.0, v114
	v_rcp_f32_e32 v120, v114
	v_max_f32_e32 v114, v121, v121
	v_med3_f32 v114, v114, s91, v171
	v_mul_f32_e32 v114, 0xbfb8aa3b, v114
	v_exp_f32_e32 v114, v114
	v_med3_f32 v117, v117, s91, v171
	v_max_f32_e32 v110, v110, v110
	v_max_f32_e32 v111, v111, v111
	v_mul_f32_e32 v116, 0xbfb8aa3b, v116
	v_mul_f32_e32 v117, 0xbfb8aa3b, v117
	v_med3_f32 v110, v110, s91, v171
	v_med3_f32 v111, v111, s91, v171
	v_exp_f32_e32 v116, v116
	v_exp_f32_e32 v117, v117
	v_mul_f32_e32 v110, 0xbfb8aa3b, v110
	v_mul_f32_e32 v111, 0xbfb8aa3b, v111
	v_add_f32_e32 v114, 1.0, v114
	v_exp_f32_e32 v110, v110
	v_exp_f32_e32 v111, v111
	v_rcp_f32_e32 v121, v114
	v_max_f32_e32 v106, v106, v106
	v_max_f32_e32 v107, v107, v107
	v_med3_f32 v106, v106, s91, v171
	v_med3_f32 v107, v107, s91, v171
	v_ashrrev_i32_e32 v157, 31, v156
	v_rcp_f32_e32 v128, v115
	v_pk_add_f32 v[114:115], v[116:117], 1.0 op_sel_hi:[1,0]
	v_mul_f32_e32 v106, 0xbfb8aa3b, v106
	v_mul_f32_e32 v107, 0xbfb8aa3b, v107
	v_lshl_add_u32 v146, s54, 7, v166
	v_lshlrev_b64 v[130:131], 12, v[156:157]
	v_rcp_f32_e32 v129, v114
	v_rcp_f32_e32 v135, v115
	v_exp_f32_e32 v106, v106
	v_add_f32_e32 v110, 1.0, v110
	v_exp_f32_e32 v107, v107
	v_add_f32_e32 v111, 1.0, v111
	v_pk_mul_f32 v[120:121], v[120:121], v[114:115]
	v_lshl_add_u64 v[114:115], v[130:131], 0, v[146:147]
	v_rcp_f32_e32 v110, v110
	v_rcp_f32_e32 v111, v111
	v_lshlrev_b64 v[114:115], 1, v[114:115]
	v_cvt_pk_bf16_f32 v116, v126, v127
	v_cvt_pk_bf16_f32 v117, v124, v125
	v_cvt_pk_bf16_f32 v118, v118, v119
	v_cvt_pk_bf16_f32 v119, v120, v121
	v_lshl_add_u64 v[120:121], s[40:41], 0, v[114:115]
	global_store_dwordx4 v[120:121], v[116:119], off sc1
	v_lshl_add_u64 v[120:121], s[42:43], 0, v[114:115]
	v_pk_add_f32 v[106:107], v[106:107], 1.0 op_sel_hi:[1,0]
	v_cvt_pk_bf16_f32 v116, v132, v133
	v_cvt_pk_bf16_f32 v117, v134, v122
	v_cvt_pk_bf16_f32 v118, v123, v128
	v_cvt_pk_bf16_f32 v119, v129, v135
	global_store_dwordx4 v[120:121], v[116:119], off sc1
	v_pk_mul_f32 v[110:111], v[110:111], v[106:107]
	v_max_f32_e32 v102, v102, v102
	v_rcp_f32_e32 v118, v106
	v_max_f32_e32 v106, v112, v112
	v_med3_f32 v106, v106, s91, v171
	v_mul_f32_e32 v106, 0xbfb8aa3b, v106
	v_exp_f32_e32 v106, v106
	v_max_f32_e32 v103, v103, v103
	v_med3_f32 v102, v102, s91, v171
	v_med3_f32 v103, v103, s91, v171
	v_add_f32_e32 v106, 1.0, v106
	v_rcp_f32_e32 v112, v106
	v_max_f32_e32 v106, v113, v113
	v_med3_f32 v106, v106, s91, v171
	v_mul_f32_e32 v106, 0xbfb8aa3b, v106
	v_mul_f32_e32 v102, 0xbfb8aa3b, v102
	v_mul_f32_e32 v103, 0xbfb8aa3b, v103
	v_exp_f32_e32 v106, v106
	v_exp_f32_e32 v102, v102
	v_exp_f32_e32 v103, v103
	v_max_f32_e32 v108, v108, v108
	v_max_f32_e32 v109, v109, v109
	v_max_f32_e32 v98, v98, v98
	v_max_f32_e32 v99, v99, v99
	v_med3_f32 v108, v108, s91, v171
	v_med3_f32 v109, v109, s91, v171
	v_med3_f32 v98, v98, s91, v171
	v_med3_f32 v99, v99, s91, v171
	v_mul_f32_e32 v108, 0xbfb8aa3b, v108
	v_mul_f32_e32 v109, 0xbfb8aa3b, v109
	v_mul_f32_e32 v98, 0xbfb8aa3b, v98
; __device__ __forceinline__ unsigned cvt_pk_bf16(float lo, float hi) { const cvt_f2 v = {lo, hi}; return __builtin_bit_cast(unsigned, __builtin_convertvector(v, cvt_b2)); }
;     __device__ __forceinline__ void operator()(const f32x4 (&acc)[2][2][4][2], const Unit& u, int wr, int wc, int fr, int fq) const {
;     ...
;                 for (int m = 0; m < 4; ++m) { const size_t ro = (size_t)(row0 + ai * HALF + m * 16) * D + gc0; float rt[8], gb[8];
; #pragma unroll
;                     for (int n = 0; n < 2; ++n)
; #pragma unroll
;                         for (int j = 0; j < 4; ++j) { const float a = fminf(fmaxf(acc[ai][0][m][n][j], -30.f), 30.f), b = fminf(fmaxf(acc[ai][1][m][n][j], -30.f), 30.f);
;                             const float ea = __expf(-a), eb = __expf(-b); gb[4 * n + j] = __builtin_amdgcn_rcpf(1.0f + eb); rt[4 * n + j] = (1.0f + eb) * __builtin_amdgcn_rcpf(1.0f + ea); }
;                     pg8::u32x4 w; w.x = cvt_pk_bf16(rt[0], rt[1]); w.y = cvt_pk_bf16(rt[2], rt[3]); w.z = cvt_pk_bf16(rt[4], rt[5]); w.w = cvt_pk_bf16(rt[6], rt[7]);
;                     *(pg8::u32x4*)(RT + ro) = w;
;                     w.x = cvt_pk_bf16(gb[0], gb[1]); w.y = cvt_pk_bf16(gb[2], gb[3]); w.z = cvt_pk_bf16(gb[4], gb[5]); w.w = cvt_pk_bf16(gb[6], gb[7]);
;                     *(pg8::u32x4*)(GBt + ro) = w; }
	v_mul_f32_e32 v99, 0xbfb8aa3b, v99
	v_exp_f32_e32 v108, v108
	v_exp_f32_e32 v109, v109
	v_add_f32_e32 v106, 1.0, v106
	v_exp_f32_e32 v98, v98
	v_add_f32_e32 v102, 1.0, v102
	v_exp_f32_e32 v99, v99
	v_add_f32_e32 v103, 1.0, v103
	v_rcp_f32_e32 v113, v106
	v_rcp_f32_e32 v102, v102
	v_rcp_f32_e32 v103, v103
	v_rcp_f32_e32 v119, v107
	v_pk_add_f32 v[106:107], v[108:109], 1.0 op_sel_hi:[1,0]
	v_pk_add_f32 v[98:99], v[98:99], 1.0 op_sel_hi:[1,0]
	v_pk_mul_f32 v[108:109], v[112:113], v[106:107]
	v_rcp_f32_e32 v113, v98
	v_pk_mul_f32 v[102:103], v[102:103], v[98:99]
	v_max_f32_e32 v98, v104, v104
	v_med3_f32 v98, v98, s91, v171
	v_mul_f32_e32 v98, 0xbfb8aa3b, v98
	v_exp_f32_e32 v98, v98
	v_max_f32_e32 v100, v100, v100
	v_max_f32_e32 v101, v101, v101
	v_med3_f32 v100, v100, s91, v171
	v_add_f32_e32 v98, 1.0, v98
	v_rcp_f32_e32 v104, v98
	v_max_f32_e32 v98, v105, v105
	v_med3_f32 v98, v98, s91, v171
	v_mul_f32_e32 v98, 0xbfb8aa3b, v98
	v_exp_f32_e32 v98, v98
	v_med3_f32 v101, v101, s91, v171
	v_max_f32_e32 v94, v94, v94
	v_max_f32_e32 v95, v95, v95
	v_mul_f32_e32 v100, 0xbfb8aa3b, v100
	v_mul_f32_e32 v101, 0xbfb8aa3b, v101
	v_med3_f32 v94, v94, s91, v171
	v_med3_f32 v95, v95, s91, v171
	v_exp_f32_e32 v100, v100
	v_exp_f32_e32 v101, v101
	v_mul_f32_e32 v94, 0xbfb8aa3b, v94
	v_mul_f32_e32 v95, 0xbfb8aa3b, v95
	v_exp_f32_e32 v94, v94
	v_exp_f32_e32 v95, v95
	v_add_f32_e32 v98, 1.0, v98
	v_max_f32_e32 v90, v90, v90
	v_max_f32_e32 v91, v91, v91
	v_or_b32_e32 v116, 16, v156
	v_rcp_f32_e32 v105, v98
	v_med3_f32 v90, v90, s91, v171
	v_med3_f32 v91, v91, s91, v171
	v_ashrrev_i32_e32 v117, 31, v116
	v_rcp_f32_e32 v121, v99
	v_pk_add_f32 v[98:99], v[100:101], 1.0 op_sel_hi:[1,0]
	v_mul_f32_e32 v90, 0xbfb8aa3b, v90
	v_mul_f32_e32 v91, 0xbfb8aa3b, v91
	v_lshlrev_b64 v[116:117], 12, v[116:117]
	v_rcp_f32_e32 v120, v106
	v_rcp_f32_e32 v112, v107
	v_rcp_f32_e32 v122, v98
	v_rcp_f32_e32 v123, v99
	v_exp_f32_e32 v90, v90
	v_add_f32_e32 v94, 1.0, v94
	v_exp_f32_e32 v91, v91
	v_add_f32_e32 v95, 1.0, v95
	v_lshl_add_u64 v[106:107], v[116:117], 0, v[146:147]
	v_rcp_f32_e32 v94, v94
	v_rcp_f32_e32 v95, v95
	v_pk_mul_f32 v[104:105], v[104:105], v[98:99]
	v_cvt_pk_bf16_f32 v100, v102, v103
	v_lshlrev_b64 v[102:103], 1, v[106:107]
	v_cvt_pk_bf16_f32 v98, v110, v111
	v_cvt_pk_bf16_f32 v99, v108, v109
	v_cvt_pk_bf16_f32 v101, v104, v105
	v_lshl_add_u64 v[104:105], s[40:41], 0, v[102:103]
	global_store_dwordx4 v[104:105], v[98:101], off sc1
	v_lshl_add_u64 v[102:103], s[42:43], 0, v[102:103]
	v_pk_add_f32 v[90:91], v[90:91], 1.0 op_sel_hi:[1,0]
	v_cvt_pk_bf16_f32 v98, v118, v119
	v_cvt_pk_bf16_f32 v99, v120, v112
	v_cvt_pk_bf16_f32 v100, v113, v121
	v_cvt_pk_bf16_f32 v101, v122, v123
	global_store_dwordx4 v[102:103], v[98:101], off sc1
	v_pk_mul_f32 v[94:95], v[94:95], v[90:91]
	v_max_f32_e32 v86, v86, v86
	v_rcp_f32_e32 v100, v90
	v_max_f32_e32 v90, v96, v96
	v_med3_f32 v90, v90, s91, v171
	v_mul_f32_e32 v90, 0xbfb8aa3b, v90
	v_exp_f32_e32 v90, v90
	v_max_f32_e32 v87, v87, v87
	v_med3_f32 v86, v86, s91, v171
	v_med3_f32 v87, v87, s91, v171
	v_add_f32_e32 v90, 1.0, v90
	v_rcp_f32_e32 v96, v90
	v_max_f32_e32 v90, v97, v97
	v_med3_f32 v90, v90, s91, v171
	v_mul_f32_e32 v90, 0xbfb8aa3b, v90
	v_mul_f32_e32 v86, 0xbfb8aa3b, v86
	v_mul_f32_e32 v87, 0xbfb8aa3b, v87
	v_exp_f32_e32 v90, v90
	v_exp_f32_e32 v86, v86
	v_exp_f32_e32 v87, v87
	v_max_f32_e32 v92, v92, v92
	v_max_f32_e32 v93, v93, v93
	v_max_f32_e32 v82, v82, v82
	v_max_f32_e32 v83, v83, v83
	v_med3_f32 v92, v92, s91, v171
	v_med3_f32 v93, v93, s91, v171
	v_med3_f32 v82, v82, s91, v171
	v_med3_f32 v83, v83, s91, v171
	v_mul_f32_e32 v92, 0xbfb8aa3b, v92
	v_mul_f32_e32 v93, 0xbfb8aa3b, v93
	v_mul_f32_e32 v82, 0xbfb8aa3b, v82
	v_mul_f32_e32 v83, 0xbfb8aa3b, v83
	v_exp_f32_e32 v92, v92
	v_exp_f32_e32 v93, v93
	v_add_f32_e32 v90, 1.0, v90
	v_exp_f32_e32 v82, v82
	v_add_f32_e32 v86, 1.0, v86
	v_exp_f32_e32 v83, v83
	v_add_f32_e32 v87, 1.0, v87
	v_rcp_f32_e32 v97, v90
	v_rcp_f32_e32 v86, v86
	v_rcp_f32_e32 v87, v87
	v_rcp_f32_e32 v101, v91
	v_pk_add_f32 v[90:91], v[92:93], 1.0 op_sel_hi:[1,0]
	v_pk_add_f32 v[82:83], v[82:83], 1.0 op_sel_hi:[1,0]
	v_pk_mul_f32 v[92:93], v[96:97], v[90:91]
	v_rcp_f32_e32 v97, v82
	v_pk_mul_f32 v[86:87], v[86:87], v[82:83]
	v_max_f32_e32 v82, v88, v88
	v_med3_f32 v82, v82, s91, v171
	v_mul_f32_e32 v82, 0xbfb8aa3b, v82
	v_exp_f32_e32 v82, v82
	v_max_f32_e32 v84, v84, v84
	v_max_f32_e32 v85, v85, v85
	v_med3_f32 v84, v84, s91, v171
	v_add_f32_e32 v82, 1.0, v82
	v_rcp_f32_e32 v88, v82
	v_max_f32_e32 v82, v89, v89
	v_med3_f32 v82, v82, s91, v171
	v_mul_f32_e32 v82, 0xbfb8aa3b, v82
	v_exp_f32_e32 v82, v82
	v_med3_f32 v85, v85, s91, v171
	v_max_f32_e32 v78, v78, v78
	v_max_f32_e32 v79, v79, v79
	v_mul_f32_e32 v84, 0xbfb8aa3b, v84
	v_mul_f32_e32 v85, 0xbfb8aa3b, v85
	v_med3_f32 v78, v78, s91, v171
	v_med3_f32 v79, v79, s91, v171
	v_exp_f32_e32 v84, v84
	v_exp_f32_e32 v85, v85
	v_mul_f32_e32 v78, 0xbfb8aa3b, v78
	v_mul_f32_e32 v79, 0xbfb8aa3b, v79
	v_exp_f32_e32 v78, v78
	v_exp_f32_e32 v79, v79
	v_add_f32_e32 v82, 1.0, v82
	v_max_f32_e32 v74, v74, v74
	v_max_f32_e32 v75, v75, v75
	v_or_b32_e32 v98, 32, v156
	v_rcp_f32_e32 v89, v82
	v_med3_f32 v74, v74, s91, v171
	v_med3_f32 v75, v75, s91, v171
	v_ashrrev_i32_e32 v99, 31, v98
	v_rcp_f32_e32 v103, v83
	v_pk_add_f32 v[82:83], v[84:85], 1.0 op_sel_hi:[1,0]
	v_mul_f32_e32 v74, 0xbfb8aa3b, v74
	v_mul_f32_e32 v75, 0xbfb8aa3b, v75
	v_lshlrev_b64 v[98:99], 12, v[98:99]
	v_rcp_f32_e32 v102, v90
	v_rcp_f32_e32 v96, v91
	v_rcp_f32_e32 v104, v82
	v_rcp_f32_e32 v105, v83
	v_exp_f32_e32 v74, v74
	v_add_f32_e32 v78, 1.0, v78
	v_exp_f32_e32 v75, v75
	v_add_f32_e32 v79, 1.0, v79
; __device__ __forceinline__ unsigned cvt_pk_bf16(float lo, float hi) { const cvt_f2 v = {lo, hi}; return __builtin_bit_cast(unsigned, __builtin_convertvector(v, cvt_b2)); }
;     __device__ __forceinline__ void operator()(const f32x4 (&acc)[2][2][4][2], const Unit& u, int wr, int wc, int fr, int fq) const {
;     ...
;                 for (int m = 0; m < 4; ++m) { const size_t ro = (size_t)(row0 + ai * HALF + m * 16) * D + gc0; float rt[8], gb[8];
; #pragma unroll
;                     for (int n = 0; n < 2; ++n)
; #pragma unroll
;                         for (int j = 0; j < 4; ++j) { const float a = fminf(fmaxf(acc[ai][0][m][n][j], -30.f), 30.f), b = fminf(fmaxf(acc[ai][1][m][n][j], -30.f), 30.f);
;                             const float ea = __expf(-a), eb = __expf(-b); gb[4 * n + j] = __builtin_amdgcn_rcpf(1.0f + eb); rt[4 * n + j] = (1.0f + eb) * __builtin_amdgcn_rcpf(1.0f + ea); }
;                     pg8::u32x4 w; w.x = cvt_pk_bf16(rt[0], rt[1]); w.y = cvt_pk_bf16(rt[2], rt[3]); w.z = cvt_pk_bf16(rt[4], rt[5]); w.w = cvt_pk_bf16(rt[6], rt[7]);
;                     *(pg8::u32x4*)(RT + ro) = w;
;                     w.x = cvt_pk_bf16(gb[0], gb[1]); w.y = cvt_pk_bf16(gb[2], gb[3]); w.z = cvt_pk_bf16(gb[4], gb[5]); w.w = cvt_pk_bf16(gb[6], gb[7]);
;                     *(pg8::u32x4*)(GBt + ro) = w; }
	v_lshl_add_u64 v[90:91], v[98:99], 0, v[146:147]
	v_rcp_f32_e32 v78, v78
	v_rcp_f32_e32 v79, v79
	v_pk_mul_f32 v[88:89], v[88:89], v[82:83]
	v_cvt_pk_bf16_f32 v84, v86, v87
	v_lshlrev_b64 v[86:87], 1, v[90:91]
	v_cvt_pk_bf16_f32 v82, v94, v95
	v_cvt_pk_bf16_f32 v83, v92, v93
	v_cvt_pk_bf16_f32 v85, v88, v89
	v_lshl_add_u64 v[88:89], s[40:41], 0, v[86:87]
	global_store_dwordx4 v[88:89], v[82:85], off sc1
	v_lshl_add_u64 v[86:87], s[42:43], 0, v[86:87]
	v_pk_add_f32 v[74:75], v[74:75], 1.0 op_sel_hi:[1,0]
	v_cvt_pk_bf16_f32 v82, v100, v101
	v_cvt_pk_bf16_f32 v83, v102, v96
	v_cvt_pk_bf16_f32 v84, v97, v103
	v_cvt_pk_bf16_f32 v85, v104, v105
	global_store_dwordx4 v[86:87], v[82:85], off sc1
	v_pk_mul_f32 v[78:79], v[78:79], v[74:75]
	v_max_f32_e32 v70, v70, v70
	v_rcp_f32_e32 v84, v74
	v_max_f32_e32 v74, v80, v80
	v_med3_f32 v74, v74, s91, v171
	v_mul_f32_e32 v74, 0xbfb8aa3b, v74
	v_exp_f32_e32 v74, v74
	v_max_f32_e32 v71, v71, v71
	v_med3_f32 v70, v70, s91, v171
	v_med3_f32 v71, v71, s91, v171
	v_add_f32_e32 v74, 1.0, v74
	v_rcp_f32_e32 v80, v74
	v_max_f32_e32 v74, v81, v81
	v_med3_f32 v74, v74, s91, v171
	v_mul_f32_e32 v74, 0xbfb8aa3b, v74
	v_mul_f32_e32 v70, 0xbfb8aa3b, v70
	v_mul_f32_e32 v71, 0xbfb8aa3b, v71
	v_exp_f32_e32 v74, v74
	v_exp_f32_e32 v70, v70
	v_exp_f32_e32 v71, v71
	v_max_f32_e32 v76, v76, v76
	v_max_f32_e32 v77, v77, v77
	v_max_f32_e32 v66, v66, v66
	v_max_f32_e32 v67, v67, v67
	v_med3_f32 v76, v76, s91, v171
	v_med3_f32 v77, v77, s91, v171
	v_med3_f32 v66, v66, s91, v171
	v_med3_f32 v67, v67, s91, v171
	v_mul_f32_e32 v76, 0xbfb8aa3b, v76
	v_mul_f32_e32 v77, 0xbfb8aa3b, v77
	v_mul_f32_e32 v66, 0xbfb8aa3b, v66
	v_mul_f32_e32 v67, 0xbfb8aa3b, v67
	v_exp_f32_e32 v76, v76
	v_exp_f32_e32 v77, v77
	v_add_f32_e32 v74, 1.0, v74
	v_exp_f32_e32 v66, v66
	v_add_f32_e32 v70, 1.0, v70
	v_exp_f32_e32 v67, v67
	v_add_f32_e32 v71, 1.0, v71
	v_rcp_f32_e32 v81, v74
	v_rcp_f32_e32 v70, v70
	v_rcp_f32_e32 v71, v71
	v_rcp_f32_e32 v85, v75
	v_pk_add_f32 v[74:75], v[76:77], 1.0 op_sel_hi:[1,0]
	v_pk_add_f32 v[66:67], v[66:67], 1.0 op_sel_hi:[1,0]
	v_pk_mul_f32 v[76:77], v[80:81], v[74:75]
	v_rcp_f32_e32 v81, v66
	v_pk_mul_f32 v[70:71], v[70:71], v[66:67]
	v_max_f32_e32 v66, v72, v72
	v_med3_f32 v66, v66, s91, v171
	v_mul_f32_e32 v66, 0xbfb8aa3b, v66
	v_exp_f32_e32 v66, v66
	v_max_f32_e32 v68, v68, v68
	v_max_f32_e32 v69, v69, v69
	v_med3_f32 v68, v68, s91, v171
	v_add_f32_e32 v66, 1.0, v66
	v_rcp_f32_e32 v72, v66
	v_max_f32_e32 v66, v73, v73
	v_med3_f32 v66, v66, s91, v171
	v_mul_f32_e32 v66, 0xbfb8aa3b, v66
	v_exp_f32_e32 v66, v66
	v_med3_f32 v69, v69, s91, v171
	v_max_f32_e32 v62, v62, v62
	v_max_f32_e32 v63, v63, v63
	v_mul_f32_e32 v68, 0xbfb8aa3b, v68
	v_mul_f32_e32 v69, 0xbfb8aa3b, v69
	v_med3_f32 v62, v62, s91, v171
	v_med3_f32 v63, v63, s91, v171
	v_exp_f32_e32 v68, v68
	v_exp_f32_e32 v69, v69
	v_mul_f32_e32 v62, 0xbfb8aa3b, v62
	v_mul_f32_e32 v63, 0xbfb8aa3b, v63
	v_exp_f32_e32 v62, v62
	v_exp_f32_e32 v63, v63
	v_add_f32_e32 v66, 1.0, v66
	v_max_f32_e32 v58, v58, v58
	v_max_f32_e32 v59, v59, v59
	v_or_b32_e32 v82, 48, v156
	v_rcp_f32_e32 v73, v66
	v_med3_f32 v58, v58, s91, v171
	v_med3_f32 v59, v59, s91, v171
	v_ashrrev_i32_e32 v83, 31, v82
	v_rcp_f32_e32 v87, v67
	v_pk_add_f32 v[66:67], v[68:69], 1.0 op_sel_hi:[1,0]
	v_mul_f32_e32 v58, 0xbfb8aa3b, v58
	v_mul_f32_e32 v59, 0xbfb8aa3b, v59
	v_lshlrev_b64 v[82:83], 12, v[82:83]
	v_rcp_f32_e32 v86, v74
	v_rcp_f32_e32 v80, v75
	v_rcp_f32_e32 v88, v66
	v_rcp_f32_e32 v89, v67
	v_exp_f32_e32 v58, v58
	v_add_f32_e32 v62, 1.0, v62
	v_exp_f32_e32 v59, v59
	v_add_f32_e32 v63, 1.0, v63
	v_lshl_add_u64 v[74:75], v[82:83], 0, v[146:147]
	v_rcp_f32_e32 v62, v62
	v_rcp_f32_e32 v63, v63
	v_pk_mul_f32 v[72:73], v[72:73], v[66:67]
	v_cvt_pk_bf16_f32 v68, v70, v71
	v_lshlrev_b64 v[70:71], 1, v[74:75]
	v_cvt_pk_bf16_f32 v66, v78, v79
	v_cvt_pk_bf16_f32 v67, v76, v77
	v_cvt_pk_bf16_f32 v69, v72, v73
	v_lshl_add_u64 v[72:73], s[40:41], 0, v[70:71]
	global_store_dwordx4 v[72:73], v[66:69], off sc1
	v_lshl_add_u64 v[70:71], s[42:43], 0, v[70:71]
	v_pk_add_f32 v[58:59], v[58:59], 1.0 op_sel_hi:[1,0]
	v_cvt_pk_bf16_f32 v66, v84, v85
	v_cvt_pk_bf16_f32 v67, v86, v80
	v_cvt_pk_bf16_f32 v68, v81, v87
	v_cvt_pk_bf16_f32 v69, v88, v89
	global_store_dwordx4 v[70:71], v[66:69], off sc1
	v_pk_mul_f32 v[62:63], v[62:63], v[58:59]
	v_max_f32_e32 v54, v54, v54
	v_rcp_f32_e32 v66, v58
	v_max_f32_e32 v58, v64, v64
	v_med3_f32 v58, v58, s91, v171
	v_mul_f32_e32 v58, 0xbfb8aa3b, v58
	v_exp_f32_e32 v58, v58
	v_max_f32_e32 v55, v55, v55
	v_med3_f32 v54, v54, s91, v171
	v_med3_f32 v55, v55, s91, v171
	v_add_f32_e32 v58, 1.0, v58
	v_rcp_f32_e32 v64, v58
	v_max_f32_e32 v58, v65, v65
	v_med3_f32 v58, v58, s91, v171
	v_mul_f32_e32 v58, 0xbfb8aa3b, v58
	v_mul_f32_e32 v54, 0xbfb8aa3b, v54
	v_mul_f32_e32 v55, 0xbfb8aa3b, v55
	v_exp_f32_e32 v58, v58
	v_exp_f32_e32 v54, v54
	v_exp_f32_e32 v55, v55
	v_max_f32_e32 v60, v60, v60
	v_max_f32_e32 v61, v61, v61
	v_max_f32_e32 v50, v50, v50
	v_max_f32_e32 v51, v51, v51
	v_med3_f32 v60, v60, s91, v171
	v_med3_f32 v61, v61, s91, v171
	v_med3_f32 v50, v50, s91, v171
	v_med3_f32 v51, v51, s91, v171
	v_mul_f32_e32 v60, 0xbfb8aa3b, v60
	v_mul_f32_e32 v61, 0xbfb8aa3b, v61
	v_mul_f32_e32 v50, 0xbfb8aa3b, v50
	v_mul_f32_e32 v51, 0xbfb8aa3b, v51
	v_exp_f32_e32 v60, v60
	v_exp_f32_e32 v61, v61
	v_add_f32_e32 v58, 1.0, v58
	v_exp_f32_e32 v50, v50
	v_add_f32_e32 v54, 1.0, v54
	v_exp_f32_e32 v51, v51
	v_add_f32_e32 v55, 1.0, v55
	v_rcp_f32_e32 v65, v58
	v_rcp_f32_e32 v54, v54
	v_rcp_f32_e32 v55, v55
	v_rcp_f32_e32 v67, v59
	v_pk_add_f32 v[58:59], v[60:61], 1.0 op_sel_hi:[1,0]
	v_pk_add_f32 v[50:51], v[50:51], 1.0 op_sel_hi:[1,0]
; __device__ __forceinline__ unsigned cvt_pk_bf16(float lo, float hi) { const cvt_f2 v = {lo, hi}; return __builtin_bit_cast(unsigned, __builtin_convertvector(v, cvt_b2)); }
;     __device__ __forceinline__ void operator()(const f32x4 (&acc)[2][2][4][2], const Unit& u, int wr, int wc, int fr, int fq) const {
;     ...
;                 for (int m = 0; m < 4; ++m) { const size_t ro = (size_t)(row0 + ai * HALF + m * 16) * D + gc0; float rt[8], gb[8];
; #pragma unroll
;                     for (int n = 0; n < 2; ++n)
; #pragma unroll
;                         for (int j = 0; j < 4; ++j) { const float a = fminf(fmaxf(acc[ai][0][m][n][j], -30.f), 30.f), b = fminf(fmaxf(acc[ai][1][m][n][j], -30.f), 30.f);
;                             const float ea = __expf(-a), eb = __expf(-b); gb[4 * n + j] = __builtin_amdgcn_rcpf(1.0f + eb); rt[4 * n + j] = (1.0f + eb) * __builtin_amdgcn_rcpf(1.0f + ea); }
;                     pg8::u32x4 w; w.x = cvt_pk_bf16(rt[0], rt[1]); w.y = cvt_pk_bf16(rt[2], rt[3]); w.z = cvt_pk_bf16(rt[4], rt[5]); w.w = cvt_pk_bf16(rt[6], rt[7]);
;                     *(pg8::u32x4*)(RT + ro) = w;
;                     w.x = cvt_pk_bf16(gb[0], gb[1]); w.y = cvt_pk_bf16(gb[2], gb[3]); w.z = cvt_pk_bf16(gb[4], gb[5]); w.w = cvt_pk_bf16(gb[6], gb[7]);
;                     *(pg8::u32x4*)(GBt + ro) = w; }
	v_rcp_f32_e32 v68, v58
	v_pk_mul_f32 v[60:61], v[64:65], v[58:59]
	v_rcp_f32_e32 v58, v59
	v_rcp_f32_e32 v59, v50
	v_pk_mul_f32 v[54:55], v[54:55], v[50:51]
	v_max_f32_e32 v50, v56, v56
	v_med3_f32 v50, v50, s91, v171
	v_mul_f32_e32 v50, 0xbfb8aa3b, v50
	v_exp_f32_e32 v50, v50
	v_max_f32_e32 v52, v52, v52
	v_max_f32_e32 v53, v53, v53
	v_med3_f32 v52, v52, s91, v171
	v_add_f32_e32 v50, 1.0, v50
	v_rcp_f32_e32 v56, v50
	v_max_f32_e32 v50, v57, v57
	v_med3_f32 v50, v50, s91, v171
	v_mul_f32_e32 v50, 0xbfb8aa3b, v50
	v_exp_f32_e32 v50, v50
	v_med3_f32 v53, v53, s91, v171
	v_max_f32_e32 v46, v46, v46
	v_max_f32_e32 v47, v47, v47
	v_mul_f32_e32 v52, 0xbfb8aa3b, v52
	v_mul_f32_e32 v53, 0xbfb8aa3b, v53
	v_med3_f32 v46, v46, s91, v171
	v_med3_f32 v47, v47, s91, v171
	v_exp_f32_e32 v52, v52
	v_exp_f32_e32 v53, v53
	v_mul_f32_e32 v46, 0xbfb8aa3b, v46
	v_mul_f32_e32 v47, 0xbfb8aa3b, v47
	v_exp_f32_e32 v46, v46
	v_exp_f32_e32 v47, v47
	v_add_f32_e32 v50, 1.0, v50
	v_max_f32_e32 v42, v42, v42
	v_max_f32_e32 v43, v43, v43
	v_rcp_f32_e32 v57, v50
	v_med3_f32 v42, v42, s91, v171
	v_med3_f32 v43, v43, s91, v171
	v_rcp_f32_e32 v64, v51
	v_pk_add_f32 v[50:51], v[52:53], 1.0 op_sel_hi:[1,0]
	v_mul_f32_e32 v42, 0xbfb8aa3b, v42
	v_mul_f32_e32 v43, 0xbfb8aa3b, v43
	v_rcp_f32_e32 v65, v50
	v_rcp_f32_e32 v69, v51
	v_exp_f32_e32 v42, v42
	v_add_f32_e32 v46, 1.0, v46
	v_exp_f32_e32 v43, v43
	v_add_f32_e32 v47, 1.0, v47
	s_mov_b64 s[0:1], 0x100000
	v_rcp_f32_e32 v46, v46
	v_rcp_f32_e32 v47, v47
	v_pk_mul_f32 v[56:57], v[56:57], v[50:51]
	v_cvt_pk_bf16_f32 v52, v54, v55
	v_lshl_add_u64 v[54:55], v[114:115], 0, s[0:1]
	v_cvt_pk_bf16_f32 v50, v62, v63
	v_cvt_pk_bf16_f32 v51, v60, v61
	v_cvt_pk_bf16_f32 v53, v56, v57
	v_lshl_add_u64 v[56:57], s[40:41], 0, v[54:55]
	global_store_dwordx4 v[56:57], v[50:53], off sc1
	v_lshl_add_u64 v[54:55], s[42:43], 0, v[54:55]
	v_pk_add_f32 v[42:43], v[42:43], 1.0 op_sel_hi:[1,0]
	v_cvt_pk_bf16_f32 v50, v66, v67
	v_cvt_pk_bf16_f32 v51, v68, v58
	v_cvt_pk_bf16_f32 v52, v59, v64
	v_cvt_pk_bf16_f32 v53, v65, v69
	global_store_dwordx4 v[54:55], v[50:53], off sc1
	v_pk_mul_f32 v[46:47], v[46:47], v[42:43]
	v_max_f32_e32 v38, v38, v38
	v_rcp_f32_e32 v50, v42
	v_max_f32_e32 v42, v48, v48
	v_med3_f32 v42, v42, s91, v171
	v_mul_f32_e32 v42, 0xbfb8aa3b, v42
	v_exp_f32_e32 v42, v42
	v_max_f32_e32 v39, v39, v39
	v_med3_f32 v38, v38, s91, v171
	v_med3_f32 v39, v39, s91, v171
	v_add_f32_e32 v42, 1.0, v42
	v_rcp_f32_e32 v48, v42
	v_max_f32_e32 v42, v49, v49
	v_med3_f32 v42, v42, s91, v171
	v_mul_f32_e32 v42, 0xbfb8aa3b, v42
	v_mul_f32_e32 v38, 0xbfb8aa3b, v38
	v_mul_f32_e32 v39, 0xbfb8aa3b, v39
	v_exp_f32_e32 v42, v42
	v_exp_f32_e32 v38, v38
	v_exp_f32_e32 v39, v39
	v_max_f32_e32 v44, v44, v44
	v_max_f32_e32 v45, v45, v45
	v_max_f32_e32 v34, v34, v34
	v_max_f32_e32 v35, v35, v35
	v_med3_f32 v44, v44, s91, v171
	v_med3_f32 v45, v45, s91, v171
	v_med3_f32 v34, v34, s91, v171
	v_med3_f32 v35, v35, s91, v171
	v_mul_f32_e32 v44, 0xbfb8aa3b, v44
	v_mul_f32_e32 v45, 0xbfb8aa3b, v45
	v_mul_f32_e32 v34, 0xbfb8aa3b, v34
	v_mul_f32_e32 v35, 0xbfb8aa3b, v35
	v_exp_f32_e32 v44, v44
	v_exp_f32_e32 v45, v45
	v_add_f32_e32 v42, 1.0, v42
	v_exp_f32_e32 v34, v34
	v_add_f32_e32 v38, 1.0, v38
	v_exp_f32_e32 v35, v35
	v_add_f32_e32 v39, 1.0, v39
	v_rcp_f32_e32 v49, v42
	v_rcp_f32_e32 v38, v38
	v_rcp_f32_e32 v39, v39
	v_rcp_f32_e32 v51, v43
	v_pk_add_f32 v[42:43], v[44:45], 1.0 op_sel_hi:[1,0]
	v_pk_add_f32 v[34:35], v[34:35], 1.0 op_sel_hi:[1,0]
	v_rcp_f32_e32 v52, v42
	v_pk_mul_f32 v[44:45], v[48:49], v[42:43]
	v_rcp_f32_e32 v42, v43
	v_rcp_f32_e32 v43, v34
	v_pk_mul_f32 v[38:39], v[38:39], v[34:35]
	v_max_f32_e32 v34, v40, v40
	v_med3_f32 v34, v34, s91, v171
	v_mul_f32_e32 v34, 0xbfb8aa3b, v34
	v_exp_f32_e32 v34, v34
	v_max_f32_e32 v36, v36, v36
	v_max_f32_e32 v37, v37, v37
	v_med3_f32 v36, v36, s91, v171
	v_add_f32_e32 v34, 1.0, v34
	v_rcp_f32_e32 v40, v34
	v_max_f32_e32 v34, v41, v41
	v_med3_f32 v34, v34, s91, v171
	v_mul_f32_e32 v34, 0xbfb8aa3b, v34
	v_exp_f32_e32 v34, v34
	v_med3_f32 v37, v37, s91, v171
	v_max_f32_e32 v30, v30, v30
	v_max_f32_e32 v31, v31, v31
	v_mul_f32_e32 v36, 0xbfb8aa3b, v36
	v_mul_f32_e32 v37, 0xbfb8aa3b, v37
	v_med3_f32 v30, v30, s91, v171
	v_med3_f32 v31, v31, s91, v171
	v_exp_f32_e32 v36, v36
	v_exp_f32_e32 v37, v37
	v_mul_f32_e32 v30, 0xbfb8aa3b, v30
	v_mul_f32_e32 v31, 0xbfb8aa3b, v31
	v_exp_f32_e32 v30, v30
	v_exp_f32_e32 v31, v31
	v_add_f32_e32 v34, 1.0, v34
	v_max_f32_e32 v26, v26, v26
	v_max_f32_e32 v27, v27, v27
	v_rcp_f32_e32 v41, v34
	v_med3_f32 v26, v26, s91, v171
	v_med3_f32 v27, v27, s91, v171
	v_rcp_f32_e32 v48, v35
	v_pk_add_f32 v[34:35], v[36:37], 1.0 op_sel_hi:[1,0]
	v_mul_f32_e32 v26, 0xbfb8aa3b, v26
	v_mul_f32_e32 v27, 0xbfb8aa3b, v27
	v_rcp_f32_e32 v49, v34
	v_rcp_f32_e32 v53, v35
	v_exp_f32_e32 v26, v26
	v_add_f32_e32 v30, 1.0, v30
	v_exp_f32_e32 v27, v27
	v_add_f32_e32 v31, 1.0, v31
	s_mov_b64 s[0:1], 0x120000
	v_rcp_f32_e32 v30, v30
	v_rcp_f32_e32 v31, v31
	v_pk_mul_f32 v[40:41], v[40:41], v[34:35]
	v_cvt_pk_bf16_f32 v36, v38, v39
	v_lshl_add_u64 v[38:39], v[114:115], 0, s[0:1]
	v_cvt_pk_bf16_f32 v34, v46, v47
	v_cvt_pk_bf16_f32 v35, v44, v45
	v_cvt_pk_bf16_f32 v37, v40, v41
	v_lshl_add_u64 v[40:41], s[40:41], 0, v[38:39]
	global_store_dwordx4 v[40:41], v[34:37], off sc1
	v_lshl_add_u64 v[38:39], s[42:43], 0, v[38:39]
	v_pk_add_f32 v[26:27], v[26:27], 1.0 op_sel_hi:[1,0]
	v_cvt_pk_bf16_f32 v34, v50, v51
	v_cvt_pk_bf16_f32 v35, v52, v42
	v_cvt_pk_bf16_f32 v36, v43, v48
	v_cvt_pk_bf16_f32 v37, v49, v53
	global_store_dwordx4 v[38:39], v[34:37], off sc1
	v_pk_mul_f32 v[30:31], v[30:31], v[26:27]
	v_max_f32_e32 v22, v22, v22
; __device__ __forceinline__ unsigned cvt_pk_bf16(float lo, float hi) { const cvt_f2 v = {lo, hi}; return __builtin_bit_cast(unsigned, __builtin_convertvector(v, cvt_b2)); }
;     __device__ __forceinline__ void operator()(const f32x4 (&acc)[2][2][4][2], const Unit& u, int wr, int wc, int fr, int fq) const {
;     ...
;                 for (int m = 0; m < 4; ++m) { const size_t ro = (size_t)(row0 + ai * HALF + m * 16) * D + gc0; float rt[8], gb[8];
; #pragma unroll
;                     for (int n = 0; n < 2; ++n)
; #pragma unroll
;                         for (int j = 0; j < 4; ++j) { const float a = fminf(fmaxf(acc[ai][0][m][n][j], -30.f), 30.f), b = fminf(fmaxf(acc[ai][1][m][n][j], -30.f), 30.f);
;                             const float ea = __expf(-a), eb = __expf(-b); gb[4 * n + j] = __builtin_amdgcn_rcpf(1.0f + eb); rt[4 * n + j] = (1.0f + eb) * __builtin_amdgcn_rcpf(1.0f + ea); }
;                     pg8::u32x4 w; w.x = cvt_pk_bf16(rt[0], rt[1]); w.y = cvt_pk_bf16(rt[2], rt[3]); w.z = cvt_pk_bf16(rt[4], rt[5]); w.w = cvt_pk_bf16(rt[6], rt[7]);
;                     *(pg8::u32x4*)(RT + ro) = w;
;                     w.x = cvt_pk_bf16(gb[0], gb[1]); w.y = cvt_pk_bf16(gb[2], gb[3]); w.z = cvt_pk_bf16(gb[4], gb[5]); w.w = cvt_pk_bf16(gb[6], gb[7]);
;                     *(pg8::u32x4*)(GBt + ro) = w; }
	v_rcp_f32_e32 v34, v26
	v_max_f32_e32 v26, v32, v32
	v_med3_f32 v26, v26, s91, v171
	v_mul_f32_e32 v26, 0xbfb8aa3b, v26
	v_exp_f32_e32 v26, v26
	v_max_f32_e32 v23, v23, v23
	v_med3_f32 v22, v22, s91, v171
	v_med3_f32 v23, v23, s91, v171
	v_add_f32_e32 v26, 1.0, v26
	v_rcp_f32_e32 v32, v26
	v_max_f32_e32 v26, v33, v33
	v_med3_f32 v26, v26, s91, v171
	v_mul_f32_e32 v26, 0xbfb8aa3b, v26
	v_mul_f32_e32 v22, 0xbfb8aa3b, v22
	v_mul_f32_e32 v23, 0xbfb8aa3b, v23
	v_exp_f32_e32 v26, v26
	v_exp_f32_e32 v22, v22
	v_exp_f32_e32 v23, v23
	v_max_f32_e32 v28, v28, v28
	v_max_f32_e32 v29, v29, v29
	v_max_f32_e32 v18, v18, v18
	v_max_f32_e32 v19, v19, v19
	v_med3_f32 v28, v28, s91, v171
	v_med3_f32 v29, v29, s91, v171
	v_med3_f32 v18, v18, s91, v171
	v_med3_f32 v19, v19, s91, v171
	v_mul_f32_e32 v28, 0xbfb8aa3b, v28
	v_mul_f32_e32 v29, 0xbfb8aa3b, v29
	v_mul_f32_e32 v18, 0xbfb8aa3b, v18
	v_mul_f32_e32 v19, 0xbfb8aa3b, v19
	v_exp_f32_e32 v28, v28
	v_exp_f32_e32 v29, v29
	v_add_f32_e32 v26, 1.0, v26
	v_exp_f32_e32 v18, v18
	v_add_f32_e32 v22, 1.0, v22
	v_exp_f32_e32 v19, v19
	v_add_f32_e32 v23, 1.0, v23
	v_rcp_f32_e32 v33, v26
	v_rcp_f32_e32 v22, v22
	v_rcp_f32_e32 v23, v23
	v_rcp_f32_e32 v35, v27
	v_pk_add_f32 v[26:27], v[28:29], 1.0 op_sel_hi:[1,0]
	v_pk_add_f32 v[18:19], v[18:19], 1.0 op_sel_hi:[1,0]
	v_rcp_f32_e32 v36, v26
	v_pk_mul_f32 v[28:29], v[32:33], v[26:27]
	v_rcp_f32_e32 v26, v27
	v_rcp_f32_e32 v27, v18
	v_pk_mul_f32 v[22:23], v[22:23], v[18:19]
	v_max_f32_e32 v18, v24, v24
	v_med3_f32 v18, v18, s91, v171
	v_mul_f32_e32 v18, 0xbfb8aa3b, v18
	v_exp_f32_e32 v18, v18
	v_max_f32_e32 v20, v20, v20
	v_max_f32_e32 v21, v21, v21
	v_med3_f32 v20, v20, s91, v171
	v_add_f32_e32 v18, 1.0, v18
	v_rcp_f32_e32 v24, v18
	v_max_f32_e32 v18, v25, v25
	v_med3_f32 v18, v18, s91, v171
	v_mul_f32_e32 v18, 0xbfb8aa3b, v18
	v_exp_f32_e32 v18, v18
	v_med3_f32 v21, v21, s91, v171
	v_max_f32_e32 v14, v14, v14
	v_max_f32_e32 v15, v15, v15
	v_mul_f32_e32 v20, 0xbfb8aa3b, v20
	v_mul_f32_e32 v21, 0xbfb8aa3b, v21
	v_med3_f32 v14, v14, s91, v171
	v_med3_f32 v15, v15, s91, v171
	v_exp_f32_e32 v20, v20
	v_exp_f32_e32 v21, v21
	v_mul_f32_e32 v14, 0xbfb8aa3b, v14
	v_mul_f32_e32 v15, 0xbfb8aa3b, v15
	v_exp_f32_e32 v14, v14
	v_exp_f32_e32 v15, v15
	v_add_f32_e32 v18, 1.0, v18
	v_max_f32_e32 v10, v10, v10
	v_max_f32_e32 v11, v11, v11
	v_rcp_f32_e32 v25, v18
	v_med3_f32 v10, v10, s91, v171
	v_med3_f32 v11, v11, s91, v171
	v_rcp_f32_e32 v32, v19
	v_pk_add_f32 v[18:19], v[20:21], 1.0 op_sel_hi:[1,0]
	v_mul_f32_e32 v10, 0xbfb8aa3b, v10
	v_mul_f32_e32 v11, 0xbfb8aa3b, v11
	v_rcp_f32_e32 v33, v18
	v_rcp_f32_e32 v37, v19
	v_exp_f32_e32 v10, v10
	v_add_f32_e32 v14, 1.0, v14
	v_exp_f32_e32 v11, v11
	v_add_f32_e32 v15, 1.0, v15
	s_mov_b64 s[0:1], 0x140000
	v_rcp_f32_e32 v14, v14
	v_rcp_f32_e32 v15, v15
	v_pk_mul_f32 v[24:25], v[24:25], v[18:19]
	v_cvt_pk_bf16_f32 v20, v22, v23
	v_lshl_add_u64 v[22:23], v[114:115], 0, s[0:1]
	v_cvt_pk_bf16_f32 v18, v30, v31
	v_cvt_pk_bf16_f32 v19, v28, v29
	v_cvt_pk_bf16_f32 v21, v24, v25
	v_lshl_add_u64 v[24:25], s[40:41], 0, v[22:23]
	global_store_dwordx4 v[24:25], v[18:21], off sc1
	v_lshl_add_u64 v[22:23], s[42:43], 0, v[22:23]
	v_pk_add_f32 v[10:11], v[10:11], 1.0 op_sel_hi:[1,0]
	v_cvt_pk_bf16_f32 v18, v34, v35
	v_cvt_pk_bf16_f32 v19, v36, v26
	v_cvt_pk_bf16_f32 v20, v27, v32
	v_cvt_pk_bf16_f32 v21, v33, v37
	global_store_dwordx4 v[22:23], v[18:21], off sc1
	v_pk_mul_f32 v[14:15], v[14:15], v[10:11]
	v_max_f32_e32 v6, v6, v6
	v_rcp_f32_e32 v18, v10
	v_max_f32_e32 v10, v16, v16
	v_med3_f32 v10, v10, s91, v171
	v_mul_f32_e32 v10, 0xbfb8aa3b, v10
	v_exp_f32_e32 v10, v10
	v_max_f32_e32 v7, v7, v7
	v_med3_f32 v6, v6, s91, v171
	v_med3_f32 v7, v7, s91, v171
	v_add_f32_e32 v10, 1.0, v10
	v_rcp_f32_e32 v16, v10
	v_max_f32_e32 v10, v17, v17
	v_med3_f32 v10, v10, s91, v171
	v_mul_f32_e32 v10, 0xbfb8aa3b, v10
	v_mul_f32_e32 v6, 0xbfb8aa3b, v6
	v_mul_f32_e32 v7, 0xbfb8aa3b, v7
	v_exp_f32_e32 v10, v10
	v_exp_f32_e32 v6, v6
	v_exp_f32_e32 v7, v7
	v_max_f32_e32 v12, v12, v12
	v_max_f32_e32 v13, v13, v13
	v_max_f32_e32 v2, v2, v2
	v_max_f32_e32 v3, v3, v3
	v_med3_f32 v12, v12, s91, v171
	v_med3_f32 v13, v13, s91, v171
	v_med3_f32 v2, v2, s91, v171
	v_med3_f32 v3, v3, s91, v171
	v_mul_f32_e32 v12, 0xbfb8aa3b, v12
	v_mul_f32_e32 v13, 0xbfb8aa3b, v13
	v_mul_f32_e32 v2, 0xbfb8aa3b, v2
	v_mul_f32_e32 v3, 0xbfb8aa3b, v3
	v_exp_f32_e32 v12, v12
	v_exp_f32_e32 v13, v13
	v_add_f32_e32 v10, 1.0, v10
	v_exp_f32_e32 v2, v2
	v_add_f32_e32 v6, 1.0, v6
	v_exp_f32_e32 v3, v3
	v_add_f32_e32 v7, 1.0, v7
	v_rcp_f32_e32 v17, v10
	v_rcp_f32_e32 v6, v6
	v_rcp_f32_e32 v7, v7
	v_rcp_f32_e32 v19, v11
	v_pk_add_f32 v[10:11], v[12:13], 1.0 op_sel_hi:[1,0]
	v_pk_add_f32 v[2:3], v[2:3], 1.0 op_sel_hi:[1,0]
	v_rcp_f32_e32 v20, v10
	v_pk_mul_f32 v[12:13], v[16:17], v[10:11]
	v_rcp_f32_e32 v10, v11
	v_rcp_f32_e32 v11, v2
	v_pk_mul_f32 v[6:7], v[6:7], v[2:3]
	v_max_f32_e32 v2, v8, v8
	v_med3_f32 v2, v2, s91, v171
	v_mul_f32_e32 v2, 0xbfb8aa3b, v2
	v_exp_f32_e32 v2, v2
	v_max_f32_e32 v4, v4, v4
	v_max_f32_e32 v5, v5, v5
	v_med3_f32 v4, v4, s91, v171
	v_add_f32_e32 v2, 1.0, v2
	v_rcp_f32_e32 v8, v2
	v_max_f32_e32 v2, v9, v9
	v_med3_f32 v2, v2, s91, v171
	v_mul_f32_e32 v2, 0xbfb8aa3b, v2
	v_exp_f32_e32 v2, v2
	v_med3_f32 v5, v5, s91, v171
	v_mul_f32_e32 v4, 0xbfb8aa3b, v4
	v_mul_f32_e32 v5, 0xbfb8aa3b, v5
	v_exp_f32_e32 v4, v4
	v_exp_f32_e32 v5, v5
	v_add_f32_e32 v2, 1.0, v2
	v_rcp_f32_e32 v9, v2
	v_rcp_f32_e32 v16, v3
	v_pk_add_f32 v[2:3], v[4:5], 1.0 op_sel_hi:[1,0]
	s_mov_b64 s[0:1], 0x160000
	v_rcp_f32_e32 v17, v2
	v_rcp_f32_e32 v21, v3
	v_pk_mul_f32 v[8:9], v[8:9], v[2:3]
	v_cvt_pk_bf16_f32 v4, v6, v7
	v_lshl_add_u64 v[6:7], v[114:115], 0, s[0:1]
	v_cvt_pk_bf16_f32 v2, v14, v15
	v_cvt_pk_bf16_f32 v3, v12, v13
	v_cvt_pk_bf16_f32 v5, v8, v9
	v_lshl_add_u64 v[8:9], s[40:41], 0, v[6:7]
	global_store_dwordx4 v[8:9], v[2:5], off sc1
	v_lshl_add_u64 v[6:7], s[42:43], 0, v[6:7]
	s_nop 0
	v_cvt_pk_bf16_f32 v2, v18, v19
	v_cvt_pk_bf16_f32 v3, v20, v10
	v_cvt_pk_bf16_f32 v4, v11, v16
	v_cvt_pk_bf16_f32 v5, v17, v21
	global_store_dwordx4 v[6:7], v[2:5], off sc1
	s_andn2_b64 vcc, exec, s[4:5]
	s_mov_b64 s[0:1], -1
	s_cbranch_vccnz .LBB0_139
	s_branch .LBB0_223

; __device__ __forceinline__ unsigned cvt_pk_bf16(float lo, float hi) { const cvt_f2 v = {lo, hi}; return __builtin_bit_cast(unsigned, __builtin_convertvector(v, cvt_b2)); }
; __device__ __forceinline__ float fsigmoid(float x) { return __builtin_amdgcn_rcpf(1.0f + __expf(-x)); }
;     __device__ __forceinline__ void operator()(const f32x4 (&acc)[2][2][4][2], const Unit& u, int wr, int wc, int fr, int fq) const {
;     ...
;             for (int m = 0; m < 4; ++m) { bf16* rowp = base + (size_t)(row0 + ai * HALF + m * 16) * ldc + col0;
; #pragma unroll
;                 for (int bj = 0; bj < 2; ++bj) { f32x4 v0 = acc[ai][bj][m][0], v1 = acc[ai][bj][m][1];
;                     if (act != 0) {
; #pragma unroll
;                         for (int j = 0; j < 4; ++j) { const float s0 = fsigmoid(v0[j]), s1 = fsigmoid(v1[j]); v0[j] = act == 1 ? v0[j] * s0 : s0; v1[j] = act == 1 ? v1[j] * s1 : s1; } }
;                     pg8::u32x4 w; w.x = cvt_pk_bf16(v0[0], v0[1]); w.y = cvt_pk_bf16(v0[2], v0[3]); w.z = cvt_pk_bf16(v1[0], v1[1]); w.w = cvt_pk_bf16(v1[2], v1[3]);
;                     *(pg8::u32x4*)(rowp + bj * HALF) = w; } }
.LBB0_156:
	s_xor_b64 s[36:37], s[36:37], -1
	s_lshl_b64 s[8:9], s[8:9], 1
	v_readlane_b32 s44, v244, 11
	v_readlane_b32 s45, v244, 12
	s_add_u32 s8, s44, s8
	s_addc_u32 s9, s45, s9
	v_lshl_add_u64 v[158:159], v[146:147], 1, s[8:9]
	v_mad_i64_i32 v[160:161], s[8:9], s0, v156, 0
	v_lshl_add_u64 v[160:161], v[160:161], 1, v[158:159]
	v_cvt_pk_bf16_f32 v130, v130, v131
	v_cvt_pk_bf16_f32 v131, v132, v133
	v_cvt_pk_bf16_f32 v132, v134, v135
	v_cvt_pk_bf16_f32 v133, v136, v137
	global_store_dwordx4 v[160:161], v[130:133], off sc1
	s_andn2_b64 vcc, exec, s[36:37]
	s_nop 0
	v_cndmask_b32_e64 v130, 0, 1, s[36:37]
	v_cmp_ne_u32_e64 s[8:9], 1, v130
	s_mov_b64 s[36:37], -1
	s_cbranch_vccnz .LBB0_158
	v_mov_b64_e32 v[136:137], v[116:117]
	v_mov_b64_e32 v[132:133], v[124:125]
	s_mov_b64 s[36:37], 0
	v_mov_b64_e32 v[134:135], v[114:115]
	v_mov_b64_e32 v[130:131], v[122:123]

; __device__ __forceinline__ unsigned cvt_pk_bf16(float lo, float hi) { const cvt_f2 v = {lo, hi}; return __builtin_bit_cast(unsigned, __builtin_convertvector(v, cvt_b2)); }
;     __device__ __forceinline__ void operator()(const f32x4 (&acc)[2][2][4][2], const Unit& u, int wr, int wc, int fr, int fq) const {
;     ...
;                     pg8::u32x4 w; w.x = cvt_pk_bf16(v0[0], v0[1]); w.y = cvt_pk_bf16(v0[2], v0[3]); w.z = cvt_pk_bf16(v1[0], v1[1]); w.w = cvt_pk_bf16(v1[2], v1[3]);
;                     *(pg8::u32x4*)(rowp + bj * HALF) = w; } }
.LBB0_160:
	v_cvt_pk_bf16_f32 v130, v130, v131
	v_cvt_pk_bf16_f32 v131, v132, v133
	v_cvt_pk_bf16_f32 v132, v134, v135
	v_cvt_pk_bf16_f32 v133, v136, v137
	s_and_b64 vcc, exec, s[8:9]
	s_mov_b64 s[36:37], -1
	global_store_dwordx4 v[160:161], v[130:133], off offset:256 sc1
	s_cbranch_vccnz .LBB0_162
	v_mov_b64_e32 v[136:137], v[104:105]
	v_mov_b64_e32 v[132:133], v[112:113]
	s_mov_b64 s[36:37], 0
	v_mov_b64_e32 v[134:135], v[102:103]
	v_mov_b64_e32 v[130:131], v[110:111]

; __device__ __forceinline__ unsigned cvt_pk_bf16(float lo, float hi) { const cvt_f2 v = {lo, hi}; return __builtin_bit_cast(unsigned, __builtin_convertvector(v, cvt_b2)); }
; __device__ __forceinline__ float fsigmoid(float x) { return __builtin_amdgcn_rcpf(1.0f + __expf(-x)); }
;     __device__ __forceinline__ void operator()(const f32x4 (&acc)[2][2][4][2], const Unit& u, int wr, int wc, int fr, int fq) const {
;     ...
;             for (int m = 0; m < 4; ++m) { bf16* rowp = base + (size_t)(row0 + ai * HALF + m * 16) * ldc + col0;
; #pragma unroll
;                 for (int bj = 0; bj < 2; ++bj) { f32x4 v0 = acc[ai][bj][m][0], v1 = acc[ai][bj][m][1];
;                     if (act != 0) {
; #pragma unroll
;                         for (int j = 0; j < 4; ++j) { const float s0 = fsigmoid(v0[j]), s1 = fsigmoid(v1[j]); v0[j] = act == 1 ? v0[j] * s0 : s0; v1[j] = act == 1 ? v1[j] * s1 : s1; } }
;                     pg8::u32x4 w; w.x = cvt_pk_bf16(v0[0], v0[1]); w.y = cvt_pk_bf16(v0[2], v0[3]); w.z = cvt_pk_bf16(v1[0], v1[1]); w.w = cvt_pk_bf16(v1[2], v1[3]);
;                     *(pg8::u32x4*)(rowp + bj * HALF) = w; } }
.LBB0_164:
	v_or_b32_e32 v157, 16, v156
	v_mad_i64_i32 v[160:161], s[36:37], s0, v157, 0
	v_lshl_add_u64 v[160:161], v[160:161], 1, v[158:159]
	v_cvt_pk_bf16_f32 v130, v130, v131
	v_cvt_pk_bf16_f32 v131, v132, v133
	v_cvt_pk_bf16_f32 v132, v134, v135
	v_cvt_pk_bf16_f32 v133, v136, v137
	s_and_b64 vcc, exec, s[8:9]
	s_mov_b64 s[36:37], -1
	global_store_dwordx4 v[160:161], v[130:133], off sc1
	s_cbranch_vccnz .LBB0_166
	v_mov_b64_e32 v[136:137], v[100:101]
	v_mov_b64_e32 v[132:133], v[108:109]
	s_mov_b64 s[36:37], 0
	v_mov_b64_e32 v[134:135], v[98:99]
	v_mov_b64_e32 v[130:131], v[106:107]

; __device__ __forceinline__ unsigned cvt_pk_bf16(float lo, float hi) { const cvt_f2 v = {lo, hi}; return __builtin_bit_cast(unsigned, __builtin_convertvector(v, cvt_b2)); }
;     __device__ __forceinline__ void operator()(const f32x4 (&acc)[2][2][4][2], const Unit& u, int wr, int wc, int fr, int fq) const {
;     ...
;                     pg8::u32x4 w; w.x = cvt_pk_bf16(v0[0], v0[1]); w.y = cvt_pk_bf16(v0[2], v0[3]); w.z = cvt_pk_bf16(v1[0], v1[1]); w.w = cvt_pk_bf16(v1[2], v1[3]);
;                     *(pg8::u32x4*)(rowp + bj * HALF) = w; } }
.LBB0_168:
	v_cvt_pk_bf16_f32 v130, v130, v131
	v_cvt_pk_bf16_f32 v131, v132, v133
	v_cvt_pk_bf16_f32 v132, v134, v135
	v_cvt_pk_bf16_f32 v133, v136, v137
	s_and_b64 vcc, exec, s[8:9]
	s_mov_b64 s[36:37], -1
	global_store_dwordx4 v[160:161], v[130:133], off offset:256 sc1
	s_cbranch_vccnz .LBB0_170
	v_mov_b64_e32 v[136:137], v[88:89]
	v_mov_b64_e32 v[132:133], v[96:97]
	s_mov_b64 s[36:37], 0
	v_mov_b64_e32 v[134:135], v[86:87]
	v_mov_b64_e32 v[130:131], v[94:95]

; __device__ __forceinline__ unsigned cvt_pk_bf16(float lo, float hi) { const cvt_f2 v = {lo, hi}; return __builtin_bit_cast(unsigned, __builtin_convertvector(v, cvt_b2)); }
; __device__ __forceinline__ float fsigmoid(float x) { return __builtin_amdgcn_rcpf(1.0f + __expf(-x)); }
;     __device__ __forceinline__ void operator()(const f32x4 (&acc)[2][2][4][2], const Unit& u, int wr, int wc, int fr, int fq) const {
;     ...
;             for (int m = 0; m < 4; ++m) { bf16* rowp = base + (size_t)(row0 + ai * HALF + m * 16) * ldc + col0;
; #pragma unroll
;                 for (int bj = 0; bj < 2; ++bj) { f32x4 v0 = acc[ai][bj][m][0], v1 = acc[ai][bj][m][1];
;                     if (act != 0) {
; #pragma unroll
;                         for (int j = 0; j < 4; ++j) { const float s0 = fsigmoid(v0[j]), s1 = fsigmoid(v1[j]); v0[j] = act == 1 ? v0[j] * s0 : s0; v1[j] = act == 1 ? v1[j] * s1 : s1; } }
;                     pg8::u32x4 w; w.x = cvt_pk_bf16(v0[0], v0[1]); w.y = cvt_pk_bf16(v0[2], v0[3]); w.z = cvt_pk_bf16(v1[0], v1[1]); w.w = cvt_pk_bf16(v1[2], v1[3]);
;                     *(pg8::u32x4*)(rowp + bj * HALF) = w; } }
.LBB0_172:
	v_or_b32_e32 v157, 32, v156
	v_mad_i64_i32 v[160:161], s[36:37], s0, v157, 0
	v_lshl_add_u64 v[160:161], v[160:161], 1, v[158:159]
	v_cvt_pk_bf16_f32 v130, v130, v131
	v_cvt_pk_bf16_f32 v131, v132, v133
	v_cvt_pk_bf16_f32 v132, v134, v135
	v_cvt_pk_bf16_f32 v133, v136, v137
	s_and_b64 vcc, exec, s[8:9]
	s_mov_b64 s[36:37], -1
	global_store_dwordx4 v[160:161], v[130:133], off sc1
	s_cbranch_vccnz .LBB0_174
	v_mov_b64_e32 v[136:137], v[84:85]
	v_mov_b64_e32 v[132:133], v[92:93]
	s_mov_b64 s[36:37], 0
	v_mov_b64_e32 v[134:135], v[82:83]
	v_mov_b64_e32 v[130:131], v[90:91]

; __device__ __forceinline__ unsigned cvt_pk_bf16(float lo, float hi) { const cvt_f2 v = {lo, hi}; return __builtin_bit_cast(unsigned, __builtin_convertvector(v, cvt_b2)); }
;     __device__ __forceinline__ void operator()(const f32x4 (&acc)[2][2][4][2], const Unit& u, int wr, int wc, int fr, int fq) const {
;     ...
;                     pg8::u32x4 w; w.x = cvt_pk_bf16(v0[0], v0[1]); w.y = cvt_pk_bf16(v0[2], v0[3]); w.z = cvt_pk_bf16(v1[0], v1[1]); w.w = cvt_pk_bf16(v1[2], v1[3]);
;                     *(pg8::u32x4*)(rowp + bj * HALF) = w; } }
.LBB0_176:
	v_cvt_pk_bf16_f32 v130, v130, v131
	v_cvt_pk_bf16_f32 v131, v132, v133
	v_cvt_pk_bf16_f32 v132, v134, v135
	v_cvt_pk_bf16_f32 v133, v136, v137
	s_and_b64 vcc, exec, s[8:9]
	s_mov_b64 s[36:37], -1
	global_store_dwordx4 v[160:161], v[130:133], off offset:256 sc1
	s_cbranch_vccnz .LBB0_178
	v_mov_b64_e32 v[136:137], v[72:73]
	v_mov_b64_e32 v[132:133], v[80:81]
	s_mov_b64 s[36:37], 0
	v_mov_b64_e32 v[134:135], v[70:71]
	v_mov_b64_e32 v[130:131], v[78:79]

; __device__ __forceinline__ unsigned cvt_pk_bf16(float lo, float hi) { const cvt_f2 v = {lo, hi}; return __builtin_bit_cast(unsigned, __builtin_convertvector(v, cvt_b2)); }
; __device__ __forceinline__ float fsigmoid(float x) { return __builtin_amdgcn_rcpf(1.0f + __expf(-x)); }
;     __device__ __forceinline__ void operator()(const f32x4 (&acc)[2][2][4][2], const Unit& u, int wr, int wc, int fr, int fq) const {
;     ...
;             for (int m = 0; m < 4; ++m) { bf16* rowp = base + (size_t)(row0 + ai * HALF + m * 16) * ldc + col0;
; #pragma unroll
;                 for (int bj = 0; bj < 2; ++bj) { f32x4 v0 = acc[ai][bj][m][0], v1 = acc[ai][bj][m][1];
;                     if (act != 0) {
; #pragma unroll
;                         for (int j = 0; j < 4; ++j) { const float s0 = fsigmoid(v0[j]), s1 = fsigmoid(v1[j]); v0[j] = act == 1 ? v0[j] * s0 : s0; v1[j] = act == 1 ? v1[j] * s1 : s1; } }
;                     pg8::u32x4 w; w.x = cvt_pk_bf16(v0[0], v0[1]); w.y = cvt_pk_bf16(v0[2], v0[3]); w.z = cvt_pk_bf16(v1[0], v1[1]); w.w = cvt_pk_bf16(v1[2], v1[3]);
;                     *(pg8::u32x4*)(rowp + bj * HALF) = w; } }
.LBB0_180:
	v_or_b32_e32 v157, 48, v156
	v_mad_i64_i32 v[160:161], s[36:37], s0, v157, 0
	v_lshl_add_u64 v[160:161], v[160:161], 1, v[158:159]
	v_cvt_pk_bf16_f32 v130, v130, v131
	v_cvt_pk_bf16_f32 v131, v132, v133
	v_cvt_pk_bf16_f32 v132, v134, v135
	v_cvt_pk_bf16_f32 v133, v136, v137
	s_and_b64 vcc, exec, s[8:9]
	s_mov_b64 s[36:37], -1
	global_store_dwordx4 v[160:161], v[130:133], off sc1
	s_cbranch_vccnz .LBB0_182
	v_mov_b64_e32 v[136:137], v[68:69]
	v_mov_b64_e32 v[132:133], v[76:77]
	s_mov_b64 s[36:37], 0
	v_mov_b64_e32 v[134:135], v[66:67]
	v_mov_b64_e32 v[130:131], v[74:75]

; __device__ __forceinline__ unsigned cvt_pk_bf16(float lo, float hi) { const cvt_f2 v = {lo, hi}; return __builtin_bit_cast(unsigned, __builtin_convertvector(v, cvt_b2)); }
;     __device__ __forceinline__ void operator()(const f32x4 (&acc)[2][2][4][2], const Unit& u, int wr, int wc, int fr, int fq) const {
;     ...
;                     pg8::u32x4 w; w.x = cvt_pk_bf16(v0[0], v0[1]); w.y = cvt_pk_bf16(v0[2], v0[3]); w.z = cvt_pk_bf16(v1[0], v1[1]); w.w = cvt_pk_bf16(v1[2], v1[3]);
;                     *(pg8::u32x4*)(rowp + bj * HALF) = w; } }
.LBB0_184:
	v_cvt_pk_bf16_f32 v130, v130, v131
	v_cvt_pk_bf16_f32 v131, v132, v133
	v_cvt_pk_bf16_f32 v132, v134, v135
	v_cvt_pk_bf16_f32 v133, v136, v137
	s_and_b64 vcc, exec, s[8:9]
	s_mov_b64 s[36:37], -1
	global_store_dwordx4 v[160:161], v[130:133], off offset:256 sc1
	s_cbranch_vccnz .LBB0_186
	v_mov_b64_e32 v[136:137], v[56:57]
	v_mov_b64_e32 v[132:133], v[64:65]
	s_mov_b64 s[36:37], 0
	v_mov_b64_e32 v[134:135], v[54:55]
	v_mov_b64_e32 v[130:131], v[62:63]

; __device__ __forceinline__ unsigned cvt_pk_bf16(float lo, float hi) { const cvt_f2 v = {lo, hi}; return __builtin_bit_cast(unsigned, __builtin_convertvector(v, cvt_b2)); }
; __device__ __forceinline__ float fsigmoid(float x) { return __builtin_amdgcn_rcpf(1.0f + __expf(-x)); }
;     __device__ __forceinline__ void operator()(const f32x4 (&acc)[2][2][4][2], const Unit& u, int wr, int wc, int fr, int fq) const {
;     ...
;             for (int m = 0; m < 4; ++m) { bf16* rowp = base + (size_t)(row0 + ai * HALF + m * 16) * ldc + col0;
; #pragma unroll
;                 for (int bj = 0; bj < 2; ++bj) { f32x4 v0 = acc[ai][bj][m][0], v1 = acc[ai][bj][m][1];
;                     if (act != 0) {
; #pragma unroll
;                         for (int j = 0; j < 4; ++j) { const float s0 = fsigmoid(v0[j]), s1 = fsigmoid(v1[j]); v0[j] = act == 1 ? v0[j] * s0 : s0; v1[j] = act == 1 ? v1[j] * s1 : s1; } }
;                     pg8::u32x4 w; w.x = cvt_pk_bf16(v0[0], v0[1]); w.y = cvt_pk_bf16(v0[2], v0[3]); w.z = cvt_pk_bf16(v1[0], v1[1]); w.w = cvt_pk_bf16(v1[2], v1[3]);
;                     *(pg8::u32x4*)(rowp + bj * HALF) = w; } }
.LBB0_188:
	v_add_u32_e32 v157, 0x80, v156
	v_mad_i64_i32 v[160:161], s[36:37], s0, v157, 0
	v_lshl_add_u64 v[160:161], v[160:161], 1, v[158:159]
	v_cvt_pk_bf16_f32 v130, v130, v131
	v_cvt_pk_bf16_f32 v131, v132, v133
	v_cvt_pk_bf16_f32 v132, v134, v135
	v_cvt_pk_bf16_f32 v133, v136, v137
	s_and_b64 vcc, exec, s[8:9]
	s_mov_b64 s[36:37], -1
	global_store_dwordx4 v[160:161], v[130:133], off sc1
	s_cbranch_vccnz .LBB0_190
	v_mov_b64_e32 v[136:137], v[52:53]
	v_mov_b64_e32 v[132:133], v[60:61]
	s_mov_b64 s[36:37], 0
	v_mov_b64_e32 v[134:135], v[50:51]
	v_mov_b64_e32 v[130:131], v[58:59]

; __device__ __forceinline__ unsigned cvt_pk_bf16(float lo, float hi) { const cvt_f2 v = {lo, hi}; return __builtin_bit_cast(unsigned, __builtin_convertvector(v, cvt_b2)); }
;     __device__ __forceinline__ void operator()(const f32x4 (&acc)[2][2][4][2], const Unit& u, int wr, int wc, int fr, int fq) const {
;     ...
;                     pg8::u32x4 w; w.x = cvt_pk_bf16(v0[0], v0[1]); w.y = cvt_pk_bf16(v0[2], v0[3]); w.z = cvt_pk_bf16(v1[0], v1[1]); w.w = cvt_pk_bf16(v1[2], v1[3]);
;                     *(pg8::u32x4*)(rowp + bj * HALF) = w; } }
.LBB0_192:
	v_cvt_pk_bf16_f32 v130, v130, v131
	v_cvt_pk_bf16_f32 v131, v132, v133
	v_cvt_pk_bf16_f32 v132, v134, v135
	v_cvt_pk_bf16_f32 v133, v136, v137
	s_and_b64 vcc, exec, s[8:9]
	s_mov_b64 s[36:37], -1
	global_store_dwordx4 v[160:161], v[130:133], off offset:256 sc1
	s_cbranch_vccnz .LBB0_194
	v_mov_b64_e32 v[136:137], v[40:41]
	v_mov_b64_e32 v[132:133], v[48:49]
	s_mov_b64 s[36:37], 0
	v_mov_b64_e32 v[134:135], v[38:39]
	v_mov_b64_e32 v[130:131], v[46:47]

; __device__ __forceinline__ unsigned cvt_pk_bf16(float lo, float hi) { const cvt_f2 v = {lo, hi}; return __builtin_bit_cast(unsigned, __builtin_convertvector(v, cvt_b2)); }
; __device__ __forceinline__ float fsigmoid(float x) { return __builtin_amdgcn_rcpf(1.0f + __expf(-x)); }
;     __device__ __forceinline__ void operator()(const f32x4 (&acc)[2][2][4][2], const Unit& u, int wr, int wc, int fr, int fq) const {
;     ...
;             for (int m = 0; m < 4; ++m) { bf16* rowp = base + (size_t)(row0 + ai * HALF + m * 16) * ldc + col0;
; #pragma unroll
;                 for (int bj = 0; bj < 2; ++bj) { f32x4 v0 = acc[ai][bj][m][0], v1 = acc[ai][bj][m][1];
;                     if (act != 0) {
; #pragma unroll
;                         for (int j = 0; j < 4; ++j) { const float s0 = fsigmoid(v0[j]), s1 = fsigmoid(v1[j]); v0[j] = act == 1 ? v0[j] * s0 : s0; v1[j] = act == 1 ? v1[j] * s1 : s1; } }
;                     pg8::u32x4 w; w.x = cvt_pk_bf16(v0[0], v0[1]); w.y = cvt_pk_bf16(v0[2], v0[3]); w.z = cvt_pk_bf16(v1[0], v1[1]); w.w = cvt_pk_bf16(v1[2], v1[3]);
;                     *(pg8::u32x4*)(rowp + bj * HALF) = w; } }
.LBB0_196:
	v_add_u32_e32 v157, 0x90, v156
	v_mad_i64_i32 v[160:161], s[36:37], s0, v157, 0
	v_lshl_add_u64 v[160:161], v[160:161], 1, v[158:159]
	v_cvt_pk_bf16_f32 v130, v130, v131
	v_cvt_pk_bf16_f32 v131, v132, v133
	v_cvt_pk_bf16_f32 v132, v134, v135
	v_cvt_pk_bf16_f32 v133, v136, v137
	s_and_b64 vcc, exec, s[8:9]
	s_mov_b64 s[36:37], -1
	global_store_dwordx4 v[160:161], v[130:133], off sc1
	s_cbranch_vccnz .LBB0_198
	v_mov_b64_e32 v[136:137], v[36:37]
	v_mov_b64_e32 v[132:133], v[44:45]
	s_mov_b64 s[36:37], 0
	v_mov_b64_e32 v[134:135], v[34:35]
	v_mov_b64_e32 v[130:131], v[42:43]

; __device__ __forceinline__ unsigned cvt_pk_bf16(float lo, float hi) { const cvt_f2 v = {lo, hi}; return __builtin_bit_cast(unsigned, __builtin_convertvector(v, cvt_b2)); }
;     __device__ __forceinline__ void operator()(const f32x4 (&acc)[2][2][4][2], const Unit& u, int wr, int wc, int fr, int fq) const {
;     ...
;                     pg8::u32x4 w; w.x = cvt_pk_bf16(v0[0], v0[1]); w.y = cvt_pk_bf16(v0[2], v0[3]); w.z = cvt_pk_bf16(v1[0], v1[1]); w.w = cvt_pk_bf16(v1[2], v1[3]);
;                     *(pg8::u32x4*)(rowp + bj * HALF) = w; } }
.LBB0_200:
	v_cvt_pk_bf16_f32 v130, v130, v131
	v_cvt_pk_bf16_f32 v131, v132, v133
	v_cvt_pk_bf16_f32 v132, v134, v135
	v_cvt_pk_bf16_f32 v133, v136, v137
	s_and_b64 vcc, exec, s[8:9]
	s_mov_b64 s[36:37], -1
	global_store_dwordx4 v[160:161], v[130:133], off offset:256 sc1
	s_cbranch_vccnz .LBB0_202
	v_mov_b64_e32 v[136:137], v[24:25]
	v_mov_b64_e32 v[132:133], v[32:33]
	s_mov_b64 s[36:37], 0
	v_mov_b64_e32 v[134:135], v[22:23]
	v_mov_b64_e32 v[130:131], v[30:31]

; __device__ __forceinline__ unsigned cvt_pk_bf16(float lo, float hi) { const cvt_f2 v = {lo, hi}; return __builtin_bit_cast(unsigned, __builtin_convertvector(v, cvt_b2)); }
; __device__ __forceinline__ float fsigmoid(float x) { return __builtin_amdgcn_rcpf(1.0f + __expf(-x)); }
;     __device__ __forceinline__ void operator()(const f32x4 (&acc)[2][2][4][2], const Unit& u, int wr, int wc, int fr, int fq) const {
;     ...
;             for (int m = 0; m < 4; ++m) { bf16* rowp = base + (size_t)(row0 + ai * HALF + m * 16) * ldc + col0;
; #pragma unroll
;                 for (int bj = 0; bj < 2; ++bj) { f32x4 v0 = acc[ai][bj][m][0], v1 = acc[ai][bj][m][1];
;                     if (act != 0) {
; #pragma unroll
;                         for (int j = 0; j < 4; ++j) { const float s0 = fsigmoid(v0[j]), s1 = fsigmoid(v1[j]); v0[j] = act == 1 ? v0[j] * s0 : s0; v1[j] = act == 1 ? v1[j] * s1 : s1; } }
;                     pg8::u32x4 w; w.x = cvt_pk_bf16(v0[0], v0[1]); w.y = cvt_pk_bf16(v0[2], v0[3]); w.z = cvt_pk_bf16(v1[0], v1[1]); w.w = cvt_pk_bf16(v1[2], v1[3]);
;                     *(pg8::u32x4*)(rowp + bj * HALF) = w; } }
.LBB0_204:
	v_add_u32_e32 v157, 0xa0, v156
	v_mad_i64_i32 v[160:161], s[36:37], s0, v157, 0
	v_lshl_add_u64 v[160:161], v[160:161], 1, v[158:159]
	v_cvt_pk_bf16_f32 v130, v130, v131
	v_cvt_pk_bf16_f32 v131, v132, v133
	v_cvt_pk_bf16_f32 v132, v134, v135
	v_cvt_pk_bf16_f32 v133, v136, v137
	s_and_b64 vcc, exec, s[8:9]
	s_mov_b64 s[36:37], -1
	global_store_dwordx4 v[160:161], v[130:133], off sc1
	s_cbranch_vccnz .LBB0_206
	v_mov_b64_e32 v[136:137], v[20:21]
	v_mov_b64_e32 v[132:133], v[28:29]
	s_mov_b64 s[36:37], 0
	v_mov_b64_e32 v[134:135], v[18:19]
	v_mov_b64_e32 v[130:131], v[26:27]

; __device__ __forceinline__ unsigned cvt_pk_bf16(float lo, float hi) { const cvt_f2 v = {lo, hi}; return __builtin_bit_cast(unsigned, __builtin_convertvector(v, cvt_b2)); }
;     __device__ __forceinline__ void operator()(const f32x4 (&acc)[2][2][4][2], const Unit& u, int wr, int wc, int fr, int fq) const {
;     ...
;                     pg8::u32x4 w; w.x = cvt_pk_bf16(v0[0], v0[1]); w.y = cvt_pk_bf16(v0[2], v0[3]); w.z = cvt_pk_bf16(v1[0], v1[1]); w.w = cvt_pk_bf16(v1[2], v1[3]);
;                     *(pg8::u32x4*)(rowp + bj * HALF) = w; } }
.LBB0_208:
	v_cvt_pk_bf16_f32 v130, v130, v131
	v_cvt_pk_bf16_f32 v131, v132, v133
	v_cvt_pk_bf16_f32 v132, v134, v135
	v_cvt_pk_bf16_f32 v133, v136, v137
	s_and_b64 vcc, exec, s[8:9]
	s_mov_b64 s[36:37], -1
	global_store_dwordx4 v[160:161], v[130:133], off offset:256 sc1
	s_cbranch_vccnz .LBB0_210
	v_mov_b64_e32 v[136:137], v[8:9]
	v_mov_b64_e32 v[132:133], v[16:17]
	s_mov_b64 s[36:37], 0
	v_mov_b64_e32 v[134:135], v[6:7]
	v_mov_b64_e32 v[130:131], v[14:15]

; __device__ __forceinline__ unsigned cvt_pk_bf16(float lo, float hi) { const cvt_f2 v = {lo, hi}; return __builtin_bit_cast(unsigned, __builtin_convertvector(v, cvt_b2)); }
; __device__ __forceinline__ float fsigmoid(float x) { return __builtin_amdgcn_rcpf(1.0f + __expf(-x)); }
;     __device__ __forceinline__ void operator()(const f32x4 (&acc)[2][2][4][2], const Unit& u, int wr, int wc, int fr, int fq) const {
;     ...
;             for (int m = 0; m < 4; ++m) { bf16* rowp = base + (size_t)(row0 + ai * HALF + m * 16) * ldc + col0;
; #pragma unroll
;                 for (int bj = 0; bj < 2; ++bj) { f32x4 v0 = acc[ai][bj][m][0], v1 = acc[ai][bj][m][1];
;                     if (act != 0) {
; #pragma unroll
;                         for (int j = 0; j < 4; ++j) { const float s0 = fsigmoid(v0[j]), s1 = fsigmoid(v1[j]); v0[j] = act == 1 ? v0[j] * s0 : s0; v1[j] = act == 1 ? v1[j] * s1 : s1; } }
;                     pg8::u32x4 w; w.x = cvt_pk_bf16(v0[0], v0[1]); w.y = cvt_pk_bf16(v0[2], v0[3]); w.z = cvt_pk_bf16(v1[0], v1[1]); w.w = cvt_pk_bf16(v1[2], v1[3]);
;                     *(pg8::u32x4*)(rowp + bj * HALF) = w; } }
.LBB0_212:
	v_add_u32_e32 v157, 0xb0, v156
	v_mad_i64_i32 v[160:161], s[0:1], s0, v157, 0
	v_lshl_add_u64 v[158:159], v[160:161], 1, v[158:159]
	v_cvt_pk_bf16_f32 v130, v130, v131
	v_cvt_pk_bf16_f32 v131, v132, v133
	v_cvt_pk_bf16_f32 v132, v134, v135
	v_cvt_pk_bf16_f32 v133, v136, v137
	s_and_b64 vcc, exec, s[8:9]
	s_mov_b64 s[0:1], -1
	global_store_dwordx4 v[158:159], v[130:133], off sc1
	s_cbranch_vccnz .LBB0_214
	v_mov_b64_e32 v[136:137], v[4:5]
	v_mov_b64_e32 v[132:133], v[12:13]
	s_mov_b64 s[0:1], 0
	v_mov_b64_e32 v[134:135], v[2:3]
	v_mov_b64_e32 v[130:131], v[10:11]

; __device__ __forceinline__ unsigned cvt_pk_bf16(float lo, float hi) { const cvt_f2 v = {lo, hi}; return __builtin_bit_cast(unsigned, __builtin_convertvector(v, cvt_b2)); }
;     __device__ __forceinline__ void operator()(const f32x4 (&acc)[2][2][4][2], const Unit& u, int wr, int wc, int fr, int fq) const {
;     ...
;                     pg8::u32x4 w; w.x = cvt_pk_bf16(v0[0], v0[1]); w.y = cvt_pk_bf16(v0[2], v0[3]); w.z = cvt_pk_bf16(v1[0], v1[1]); w.w = cvt_pk_bf16(v1[2], v1[3]);
;                     *(pg8::u32x4*)(rowp + bj * HALF) = w; } }
.LBB0_216:
	v_cvt_pk_bf16_f32 v130, v130, v131
	v_cvt_pk_bf16_f32 v131, v132, v133
	v_cvt_pk_bf16_f32 v132, v134, v135
	v_cvt_pk_bf16_f32 v133, v136, v137
	global_store_dwordx4 v[158:159], v[130:133], off offset:256 sc1
	s_branch .LBB0_221

;     __device__ __forceinline__ void operator()(const f32x4 (&acc)[2][2][4][2], const Unit& u, int wr, int wc, int fr, int fq) const {
;     ...
;         if (cls == 2) {
;             float lb[2][8];
; #pragma unroll
;             for (int bj = 0; bj < 2; ++bj) {
;                 const f32x4 p0a = *(const f32x4*)(lbp + col0 + bj * HALF), p0b = *(const f32x4*)(lbp + col0 + bj * HALF + 4);
;                 const f32x4 p1a = *(const f32x4*)(lbp + HW + col0 + bj * HALF), p1b = *(const f32x4*)(lbp + HW + col0 + bj * HALF + 4);
; #pragma unroll
;                 for (int j = 0; j < 4; ++j) { lb[bj][j] = __builtin_amdgcn_rcpf(1.0f + __expf(p1a[j] - p0a[j])); lb[bj][4 + j] = __builtin_amdgcn_rcpf(1.0f + __expf(p1b[j] - p0b[j])); }
;             }
; #pragma unroll
;             for (int ai = 0; ai < 2; ++ai)
; #pragma unroll
;                 for (int m = 0; m < 4; ++m) { const size_t ro = (size_t)(row0 + ai * HALF + m * 16) * 2048 + col0;
; #pragma unroll
;                     for (int bj = 0; bj < 2; ++bj) { float gl[8];
; #pragma unroll
;                         for (int n = 0; n < 2; ++n)
; #pragma unroll
;                             for (int j = 0; j < 4; ++j) { const float x = fminf(fmaxf(acc[ai][bj][m][n][j], -80.f), 80.f); const float e = __expf(-x); const float sg = __builtin_amdgcn_rcpf(1.0f + e); const float l = lb[bj][4 * n + j];
;                                 const float f = l + (1.0f - l) * sg; gl[4 * n + j] = __log2f(f); }
.LBB0_219:
	s_and_b64 vcc, exec, s[6:7]
	s_cbranch_vccz .LBB0_221
	v_lshlrev_b64 v[130:131], 2, v[146:147]
	v_lshl_add_u64 v[180:181], s[62:63], 0, v[130:131]
	v_lshl_add_u64 v[188:189], s[22:23], 0, v[130:131]
	global_load_dwordx4 v[130:133], v[180:181], off offset:16
	global_load_dwordx4 v[134:137], v[180:181], off
	global_load_dwordx4 v[158:161], v[188:189], off
	global_load_dwordx4 v[172:175], v[188:189], off offset:16
	global_load_dwordx4 v[176:179], v[180:181], off offset:528
	s_nop 0
	global_load_dwordx4 v[180:183], v[180:181], off offset:512
	s_nop 0
	global_load_dwordx4 v[184:187], v[188:189], off offset:512
	s_nop 0
	global_load_dwordx4 v[188:191], v[188:189], off offset:528
	v_max_f32_e32 v203, v105, v105
	v_med3_f32 v203, v203, s90, v170
	v_mul_f32_e32 v203, 0xbfb8aa3b, v203
	v_exp_f32_e32 v203, v203
	s_mov_b64 s[0:1], 0x80000
	v_add_f32_e32 v203, 1.0, v203
	v_rcp_f32_e32 v203, v203
	s_waitcnt vmcnt(0)
	v_sub_f32_e32 v135, v159, v135
	v_sub_f32_e32 v130, v172, v130
	v_sub_f32_e32 v131, v173, v131
	v_sub_f32_e32 v132, v174, v132
	v_sub_f32_e32 v157, v184, v180
	v_sub_f32_e32 v133, v175, v133
	v_sub_f32_e32 v173, v187, v183
	v_mul_f32_e32 v157, 0x3fb8aa3b, v157
	v_sub_f32_e32 v174, v191, v179
	v_mul_f32_e32 v130, 0x3fb8aa3b, v130
	v_mul_f32_e32 v131, 0x3fb8aa3b, v131
	v_mul_f32_e32 v132, 0x3fb8aa3b, v132
	v_mul_f32_e32 v133, 0x3fb8aa3b, v133
	v_mul_f32_e32 v173, 0x3fb8aa3b, v173
	v_exp_f32_e32 v157, v157
	v_sub_f32_e32 v159, v185, v181
	v_mul_f32_e32 v174, 0x3fb8aa3b, v174
	v_exp_f32_e32 v130, v130
	v_exp_f32_e32 v131, v131
	v_exp_f32_e32 v132, v132
	v_exp_f32_e32 v133, v133
	v_exp_f32_e32 v173, v173
	v_sub_f32_e32 v172, v190, v178
	v_mul_f32_e32 v159, 0x3fb8aa3b, v159
	v_exp_f32_e32 v174, v174
	v_sub_f32_e32 v137, v161, v137
	v_mul_f32_e32 v172, 0x3fb8aa3b, v172
	v_exp_f32_e32 v159, v159
	v_mul_f32_e32 v137, 0x3fb8aa3b, v137
	v_exp_f32_e32 v172, v172
	v_add_f32_e32 v157, 1.0, v157
	v_exp_f32_e32 v137, v137
	v_add_f32_e32 v130, 1.0, v130
	v_add_f32_e32 v131, 1.0, v131
	v_add_f32_e32 v132, 1.0, v132
	v_add_f32_e32 v133, 1.0, v133
	v_add_f32_e32 v184, 1.0, v173
	v_rcp_f32_e32 v173, v157
	v_ashrrev_i32_e32 v157, 31, v156
	v_sub_f32_e32 v134, v158, v134
	v_sub_f32_e32 v136, v160, v136
	v_sub_f32_e32 v158, v188, v176
	v_sub_f32_e32 v160, v189, v177
	v_add_f32_e32 v185, 1.0, v174
	v_rcp_f32_e32 v177, v130
	v_rcp_f32_e32 v175, v131
	v_rcp_f32_e32 v176, v132
	v_rcp_f32_e32 v174, v133
	v_lshl_add_u64 v[132:133], v[146:147], 1, s[86:87]
	v_lshlrev_b64 v[130:131], 12, v[156:157]
	v_max_f32_e32 v146, v128, v128
	v_max_f32_e32 v157, v129, v129
	v_sub_f32_e32 v161, v186, v182
	v_mul_f32_e32 v136, 0x3fb8aa3b, v136
	v_add_f32_e32 v182, 1.0, v159
	v_med3_f32 v146, v146, s90, v170
	v_med3_f32 v157, v157, s90, v170
	v_exp_f32_e32 v136, v136
	v_add_f32_e32 v183, 1.0, v172
	v_rcp_f32_e32 v172, v182
	v_mul_f32_e32 v146, 0xbfb8aa3b, v146
	v_mul_f32_e32 v157, 0xbfb8aa3b, v157
	v_max_f32_e32 v182, v118, v118
	v_add_f32_e32 v137, 1.0, v137
	v_exp_f32_e32 v146, v146
	v_exp_f32_e32 v157, v157
	v_med3_f32 v182, v182, s90, v170
	v_rcp_f32_e32 v178, v137
	v_rcp_f32_e32 v137, v183
	v_mul_f32_e32 v182, 0xbfb8aa3b, v182
	v_max_f32_e32 v183, v119, v119
	v_max_f32_e32 v186, v120, v120
	v_mul_f32_e32 v134, 0x3fb8aa3b, v134
	v_mul_f32_e32 v135, 0x3fb8aa3b, v135
	v_mul_f32_e32 v158, 0x3fb8aa3b, v158
	v_exp_f32_e32 v182, v182
	v_med3_f32 v183, v183, s90, v170
	v_med3_f32 v186, v186, s90, v170
	v_max_f32_e32 v187, v121, v121
	v_exp_f32_e32 v134, v134
	v_exp_f32_e32 v135, v135
	v_exp_f32_e32 v158, v158
	v_add_f32_e32 v136, 1.0, v136
	v_mul_f32_e32 v183, 0xbfb8aa3b, v183
	v_mul_f32_e32 v186, 0xbfb8aa3b, v186
	v_med3_f32 v187, v187, s90, v170
	v_rcp_f32_e32 v179, v136
	v_add_f32_e32 v146, 1.0, v146
	v_add_f32_e32 v157, 1.0, v157
	v_exp_f32_e32 v183, v183
	v_exp_f32_e32 v186, v186
	v_mul_f32_e32 v187, 0xbfb8aa3b, v187
	v_rcp_f32_e32 v146, v146
	v_rcp_f32_e32 v157, v157
	v_exp_f32_e32 v187, v187
	v_mul_f32_e32 v160, 0x3fb8aa3b, v160
	v_add_f32_e32 v182, 1.0, v182
	v_exp_f32_e32 v160, v160
	v_add_f32_e32 v134, 1.0, v134
	v_add_f32_e32 v135, 1.0, v135
	v_add_f32_e32 v158, 1.0, v158
	v_rcp_f32_e32 v182, v182
	v_rcp_f32_e32 v181, v134
	v_rcp_f32_e32 v180, v135
	v_rcp_f32_e32 v159, v158
	v_rcp_f32_e32 v158, v185
	v_max_f32_e32 v134, v126, v126
	v_max_f32_e32 v135, v127, v127
	v_sub_f32_e32 v185, 1.0, v179
	v_sub_f32_e32 v192, 1.0, v178
	v_add_f32_e32 v183, 1.0, v183
	v_add_f32_e32 v186, 1.0, v186
	v_med3_f32 v134, v134, s90, v170
	v_med3_f32 v135, v135, s90, v170
	v_fma_f32 v146, v146, v185, v179
	v_fma_f32 v157, v157, v192, v178
	v_rcp_f32_e32 v183, v183
	v_rcp_f32_e32 v186, v186
	v_add_f32_e32 v187, 1.0, v187
	v_mul_f32_e32 v134, 0xbfb8aa3b, v134
	v_mul_f32_e32 v135, 0xbfb8aa3b, v135
	v_log_f32_e32 v146, v146
	v_log_f32_e32 v157, v157
	v_sub_f32_e32 v195, 1.0, v177
	v_rcp_f32_e32 v187, v187
	v_add_f32_e32 v160, 1.0, v160
	v_exp_f32_e32 v134, v134
	v_exp_f32_e32 v135, v135
	v_fma_f32 v182, v182, v195, v177
	v_rcp_f32_e32 v136, v160
	v_rcp_f32_e32 v160, v184
	v_log_f32_e32 v184, v182
	v_sub_f32_e32 v182, 1.0, v175
	v_sub_f32_e32 v191, 1.0, v176
	v_fma_f32 v183, v183, v182, v175
	v_fma_f32 v186, v186, v191, v176
	v_sub_f32_e32 v194, 1.0, v174
	v_log_f32_e32 v183, v183
	v_log_f32_e32 v189, v186
	v_fma_f32 v186, v187, v194, v174
	v_cvt_pk_bf16_f32 v187, v146, v157
	v_max_f32_e32 v146, v124, v124
	v_mul_f32_e32 v161, 0x3fb8aa3b, v161
	v_add_f32_e32 v134, 1.0, v134
	v_add_f32_e32 v135, 1.0, v135
	v_med3_f32 v146, v146, s90, v170
	v_max_f32_e32 v157, v125, v125
	v_exp_f32_e32 v161, v161
	v_rcp_f32_e32 v134, v134
	v_rcp_f32_e32 v135, v135
	v_mul_f32_e32 v146, 0xbfb8aa3b, v146
; __device__ __forceinline__ unsigned cvt_pk_bf16(float lo, float hi) { const cvt_f2 v = {lo, hi}; return __builtin_bit_cast(unsigned, __builtin_convertvector(v, cvt_b2)); }
;     __device__ __forceinline__ void operator()(const f32x4 (&acc)[2][2][4][2], const Unit& u, int wr, int wc, int fr, int fq) const {
;     ...
;             for (int ai = 0; ai < 2; ++ai)
; #pragma unroll
;                 for (int m = 0; m < 4; ++m) { const size_t ro = (size_t)(row0 + ai * HALF + m * 16) * 2048 + col0;
; #pragma unroll
;                     for (int bj = 0; bj < 2; ++bj) { float gl[8];
; #pragma unroll
;                         for (int n = 0; n < 2; ++n)
; #pragma unroll
;                             for (int j = 0; j < 4; ++j) { const float x = fminf(fmaxf(acc[ai][bj][m][n][j], -80.f), 80.f); const float e = __expf(-x); const float sg = __builtin_amdgcn_rcpf(1.0f + e); const float l = lb[bj][4 * n + j];
;                                 const float f = l + (1.0f - l) * sg; gl[4 * n + j] = __log2f(f); }
;                         pg8::u32x4 w; w.x = cvt_pk_bf16(gl[0], gl[1]); w.y = cvt_pk_bf16(gl[2], gl[3]); w.z = cvt_pk_bf16(gl[4], gl[5]); w.w = cvt_pk_bf16(gl[6], gl[7]);
;                         *(pg8::u32x4*)(G + ro + bj * HALF) = w;
;                         } }
	v_med3_f32 v157, v157, s90, v170
	v_exp_f32_e32 v146, v146
	v_mul_f32_e32 v157, 0xbfb8aa3b, v157
	v_cvt_pk_bf16_f32 v188, v184, v183
	v_exp_f32_e32 v184, v157
	v_sub_f32_e32 v190, 1.0, v181
	v_sub_f32_e32 v193, 1.0, v180
	v_add_f32_e32 v161, 1.0, v161
	v_fma_f32 v134, v134, v190, v181
	v_fma_f32 v135, v135, v193, v180
	v_rcp_f32_e32 v161, v161
	v_log_f32_e32 v134, v134
	v_log_f32_e32 v135, v135
	v_log_f32_e32 v196, v186
	v_add_f32_e32 v146, 1.0, v146
	v_rcp_f32_e32 v146, v146
	v_add_f32_e32 v184, 1.0, v184
	v_rcp_f32_e32 v184, v184
	v_lshl_add_u64 v[130:131], v[132:133], 0, v[130:131]
	v_cvt_pk_bf16_f32 v186, v134, v135
	v_cvt_pk_bf16_f32 v189, v189, v196
	v_sub_f32_e32 v157, 1.0, v161
	global_store_dwordx4 v[130:131], v[186:189], off sc1
	v_fma_f32 v146, v146, v157, v161
	v_log_f32_e32 v197, v146
	v_sub_f32_e32 v186, 1.0, v160
	v_fma_f32 v146, v184, v186, v160
	v_log_f32_e32 v198, v146
	v_max_f32_e32 v146, v114, v114
	v_med3_f32 v146, v146, s90, v170
	v_mul_f32_e32 v146, 0xbfb8aa3b, v146
	v_max_f32_e32 v184, v115, v115
	v_exp_f32_e32 v146, v146
	v_med3_f32 v184, v184, s90, v170
	v_mul_f32_e32 v184, 0xbfb8aa3b, v184
	v_exp_f32_e32 v184, v184
	v_add_f32_e32 v146, 1.0, v146
	v_rcp_f32_e32 v146, v146
	v_sub_f32_e32 v189, 1.0, v159
	v_add_f32_e32 v184, 1.0, v184
	v_rcp_f32_e32 v184, v184
	v_fma_f32 v146, v146, v189, v159
	v_log_f32_e32 v199, v146
	v_sub_f32_e32 v146, 1.0, v136
	v_fma_f32 v184, v184, v146, v136
	v_log_f32_e32 v200, v184
	v_max_f32_e32 v184, v116, v116
	v_med3_f32 v184, v184, s90, v170
	v_max_f32_e32 v134, v122, v122
	v_max_f32_e32 v135, v123, v123
	v_mul_f32_e32 v184, 0xbfb8aa3b, v184
	v_max_f32_e32 v188, v117, v117
	v_med3_f32 v134, v134, s90, v170
	v_med3_f32 v135, v135, s90, v170
	v_exp_f32_e32 v184, v184
	v_med3_f32 v188, v188, s90, v170
	v_mul_f32_e32 v134, 0xbfb8aa3b, v134
	v_mul_f32_e32 v135, 0xbfb8aa3b, v135
	v_mul_f32_e32 v188, 0xbfb8aa3b, v188
	v_exp_f32_e32 v134, v134
	v_exp_f32_e32 v135, v135
	v_exp_f32_e32 v188, v188
	v_add_f32_e32 v184, 1.0, v184
	v_rcp_f32_e32 v196, v184
	v_add_f32_e32 v134, 1.0, v134
	v_add_f32_e32 v135, 1.0, v135
	v_add_f32_e32 v188, 1.0, v188
	v_rcp_f32_e32 v134, v134
	v_rcp_f32_e32 v135, v135
	v_rcp_f32_e32 v201, v188
	v_sub_f32_e32 v184, 1.0, v137
	v_fma_f32 v188, v196, v184, v137
	v_sub_f32_e32 v183, 1.0, v173
	v_sub_f32_e32 v187, 1.0, v172
	v_log_f32_e32 v202, v188
	v_sub_f32_e32 v188, 1.0, v158
	v_fma_f32 v134, v134, v183, v173
	v_fma_f32 v135, v135, v187, v172
	v_fma_f32 v196, v201, v188, v158
	v_log_f32_e32 v134, v134
	v_log_f32_e32 v135, v135
	v_log_f32_e32 v201, v196
	v_cvt_pk_bf16_f32 v197, v197, v198
	v_cvt_pk_bf16_f32 v198, v199, v200
	v_cvt_pk_bf16_f32 v196, v134, v135
	v_cvt_pk_bf16_f32 v199, v202, v201
	global_store_dwordx4 v[130:131], v[196:199], off offset:256 sc1
	v_max_f32_e32 v200, v102, v102
	v_max_f32_e32 v201, v103, v103
	v_max_f32_e32 v196, v110, v110
	v_max_f32_e32 v197, v111, v111
	v_max_f32_e32 v198, v112, v112
	v_max_f32_e32 v199, v113, v113
	v_med3_f32 v196, v196, s90, v170
	v_med3_f32 v197, v197, s90, v170
	v_med3_f32 v198, v198, s90, v170
	v_med3_f32 v199, v199, s90, v170
	v_mul_f32_e32 v196, 0xbfb8aa3b, v196
	v_mul_f32_e32 v197, 0xbfb8aa3b, v197
	v_mul_f32_e32 v198, 0xbfb8aa3b, v198
	v_mul_f32_e32 v199, 0xbfb8aa3b, v199
	v_exp_f32_e32 v196, v196
	v_exp_f32_e32 v197, v197
	v_exp_f32_e32 v198, v198
	v_exp_f32_e32 v199, v199
	v_med3_f32 v200, v200, s90, v170
	v_med3_f32 v201, v201, s90, v170
	v_mul_f32_e32 v200, 0xbfb8aa3b, v200
	v_mul_f32_e32 v201, 0xbfb8aa3b, v201
	v_exp_f32_e32 v200, v200
	v_exp_f32_e32 v201, v201
	v_add_f32_e32 v196, 1.0, v196
	v_add_f32_e32 v197, 1.0, v197
	v_add_f32_e32 v198, 1.0, v198
	v_add_f32_e32 v199, 1.0, v199
	v_rcp_f32_e32 v196, v196
	v_rcp_f32_e32 v197, v197
	v_rcp_f32_e32 v198, v198
	v_rcp_f32_e32 v199, v199
	v_add_f32_e32 v200, 1.0, v200
	v_add_f32_e32 v201, 1.0, v201
	v_rcp_f32_e32 v200, v200
	v_rcp_f32_e32 v201, v201
	v_fma_f32 v196, v196, v190, v181
	v_fma_f32 v197, v197, v193, v180
	v_fma_f32 v198, v198, v185, v179
	v_fma_f32 v199, v199, v192, v178
	v_log_f32_e32 v196, v196
	v_log_f32_e32 v197, v197
	v_log_f32_e32 v198, v198
	v_log_f32_e32 v199, v199
	v_max_f32_e32 v202, v104, v104
	v_fma_f32 v200, v200, v195, v177
	v_med3_f32 v202, v202, s90, v170
	v_fma_f32 v201, v201, v182, v175
	v_log_f32_e32 v200, v200
	v_mul_f32_e32 v202, 0xbfb8aa3b, v202
	v_log_f32_e32 v201, v201
	v_exp_f32_e32 v202, v202
	v_cvt_pk_bf16_f32 v196, v196, v197
	v_cvt_pk_bf16_f32 v197, v198, v199
	v_max_f32_e32 v199, v106, v106
	v_med3_f32 v199, v199, s90, v170
	v_mul_f32_e32 v199, 0xbfb8aa3b, v199
	v_cvt_pk_bf16_f32 v198, v200, v201
	v_exp_f32_e32 v200, v199
	v_max_f32_e32 v199, v107, v107
	v_add_f32_e32 v202, 1.0, v202
	v_med3_f32 v199, v199, s90, v170
	v_rcp_f32_e32 v202, v202
	v_mul_f32_e32 v199, 0xbfb8aa3b, v199
	v_exp_f32_e32 v201, v199
	v_fma_f32 v203, v203, v194, v174
	v_fma_f32 v202, v202, v191, v176
	v_log_f32_e32 v202, v202
	v_log_f32_e32 v203, v203
	v_add_f32_e32 v200, 1.0, v200
	v_add_f32_e32 v201, 1.0, v201
	v_or_b32_e32 v134, 16, v156
	v_rcp_f32_e32 v200, v200
	v_rcp_f32_e32 v201, v201
	v_ashrrev_i32_e32 v135, 31, v134
	v_lshlrev_b64 v[134:135], 12, v[134:135]
	v_lshl_add_u64 v[134:135], v[132:133], 0, v[134:135]
	v_cvt_pk_bf16_f32 v199, v202, v203
	global_store_dwordx4 v[134:135], v[196:199], off sc1
	v_max_f32_e32 v202, v100, v100
	v_max_f32_e32 v203, v101, v101
	v_fma_f32 v196, v200, v183, v173
	v_fma_f32 v197, v201, v187, v172
	v_max_f32_e32 v198, v108, v108
	v_max_f32_e32 v199, v109, v109
	v_max_f32_e32 v200, v98, v98
	v_max_f32_e32 v201, v99, v99
	v_med3_f32 v198, v198, s90, v170
	v_med3_f32 v199, v199, s90, v170
	v_med3_f32 v200, v200, s90, v170
; __device__ __forceinline__ unsigned cvt_pk_bf16(float lo, float hi) { const cvt_f2 v = {lo, hi}; return __builtin_bit_cast(unsigned, __builtin_convertvector(v, cvt_b2)); }
;     __device__ __forceinline__ void operator()(const f32x4 (&acc)[2][2][4][2], const Unit& u, int wr, int wc, int fr, int fq) const {
;     ...
;             for (int ai = 0; ai < 2; ++ai)
; #pragma unroll
;                 for (int m = 0; m < 4; ++m) { const size_t ro = (size_t)(row0 + ai * HALF + m * 16) * 2048 + col0;
; #pragma unroll
;                     for (int bj = 0; bj < 2; ++bj) { float gl[8];
; #pragma unroll
;                         for (int n = 0; n < 2; ++n)
; #pragma unroll
;                             for (int j = 0; j < 4; ++j) { const float x = fminf(fmaxf(acc[ai][bj][m][n][j], -80.f), 80.f); const float e = __expf(-x); const float sg = __builtin_amdgcn_rcpf(1.0f + e); const float l = lb[bj][4 * n + j];
;                                 const float f = l + (1.0f - l) * sg; gl[4 * n + j] = __log2f(f); }
;                         pg8::u32x4 w; w.x = cvt_pk_bf16(gl[0], gl[1]); w.y = cvt_pk_bf16(gl[2], gl[3]); w.z = cvt_pk_bf16(gl[4], gl[5]); w.w = cvt_pk_bf16(gl[6], gl[7]);
;                         *(pg8::u32x4*)(G + ro + bj * HALF) = w;
;                         } }
	v_med3_f32 v201, v201, s90, v170
	v_med3_f32 v202, v202, s90, v170
	v_med3_f32 v203, v203, s90, v170
	v_mul_f32_e32 v198, 0xbfb8aa3b, v198
	v_mul_f32_e32 v199, 0xbfb8aa3b, v199
	v_mul_f32_e32 v200, 0xbfb8aa3b, v200
	v_mul_f32_e32 v201, 0xbfb8aa3b, v201
	v_mul_f32_e32 v202, 0xbfb8aa3b, v202
	v_mul_f32_e32 v203, 0xbfb8aa3b, v203
	v_exp_f32_e32 v198, v198
	v_exp_f32_e32 v199, v199
	v_exp_f32_e32 v200, v200
	v_exp_f32_e32 v201, v201
	v_exp_f32_e32 v202, v202
	v_exp_f32_e32 v203, v203
	v_add_f32_e32 v198, 1.0, v198
	v_add_f32_e32 v199, 1.0, v199
	v_add_f32_e32 v200, 1.0, v200
	v_add_f32_e32 v201, 1.0, v201
	v_add_f32_e32 v202, 1.0, v202
	v_add_f32_e32 v203, 1.0, v203
	v_rcp_f32_e32 v198, v198
	v_rcp_f32_e32 v199, v199
	v_rcp_f32_e32 v200, v200
	v_rcp_f32_e32 v201, v201
	v_rcp_f32_e32 v202, v202
	v_rcp_f32_e32 v203, v203
	v_fma_f32 v198, v198, v157, v161
	v_fma_f32 v199, v199, v186, v160
	v_fma_f32 v200, v200, v189, v159
	v_fma_f32 v201, v201, v146, v136
	v_fma_f32 v202, v202, v184, v137
	v_fma_f32 v203, v203, v188, v158
	v_log_f32_e32 v196, v196
	v_log_f32_e32 v197, v197
	v_log_f32_e32 v198, v198
	v_log_f32_e32 v199, v199
	v_log_f32_e32 v200, v200
	v_log_f32_e32 v201, v201
	v_log_f32_e32 v202, v202
	v_log_f32_e32 v203, v203
	v_cvt_pk_bf16_f32 v196, v196, v197
	v_cvt_pk_bf16_f32 v197, v198, v199
	v_cvt_pk_bf16_f32 v198, v200, v201
	v_cvt_pk_bf16_f32 v199, v202, v203
	global_store_dwordx4 v[134:135], v[196:199], off offset:256 sc1
	v_max_f32_e32 v200, v86, v86
	v_max_f32_e32 v201, v87, v87
	v_max_f32_e32 v196, v94, v94
	v_max_f32_e32 v197, v95, v95
	v_max_f32_e32 v198, v96, v96
	v_max_f32_e32 v199, v97, v97
	v_med3_f32 v196, v196, s90, v170
	v_med3_f32 v197, v197, s90, v170
	v_med3_f32 v198, v198, s90, v170
	v_med3_f32 v199, v199, s90, v170
	v_mul_f32_e32 v196, 0xbfb8aa3b, v196
	v_mul_f32_e32 v197, 0xbfb8aa3b, v197
	v_mul_f32_e32 v198, 0xbfb8aa3b, v198
	v_mul_f32_e32 v199, 0xbfb8aa3b, v199
	v_exp_f32_e32 v196, v196
	v_exp_f32_e32 v197, v197
	v_exp_f32_e32 v198, v198
	v_exp_f32_e32 v199, v199
	v_med3_f32 v200, v200, s90, v170
	v_med3_f32 v201, v201, s90, v170
	v_mul_f32_e32 v200, 0xbfb8aa3b, v200
	v_mul_f32_e32 v201, 0xbfb8aa3b, v201
	v_exp_f32_e32 v200, v200
	v_exp_f32_e32 v201, v201
	v_add_f32_e32 v196, 1.0, v196
	v_add_f32_e32 v197, 1.0, v197
	v_add_f32_e32 v198, 1.0, v198
	v_add_f32_e32 v199, 1.0, v199
	v_rcp_f32_e32 v196, v196
	v_rcp_f32_e32 v197, v197
	v_rcp_f32_e32 v198, v198
	v_rcp_f32_e32 v199, v199
	v_add_f32_e32 v200, 1.0, v200
	v_add_f32_e32 v201, 1.0, v201
	v_rcp_f32_e32 v200, v200
	v_rcp_f32_e32 v201, v201
	v_fma_f32 v196, v196, v190, v181
	v_fma_f32 v197, v197, v193, v180
	v_fma_f32 v198, v198, v185, v179
	v_fma_f32 v199, v199, v192, v178
	v_log_f32_e32 v196, v196
	v_log_f32_e32 v197, v197
	v_log_f32_e32 v198, v198
	v_log_f32_e32 v199, v199
	v_max_f32_e32 v202, v88, v88
	v_max_f32_e32 v203, v89, v89
	v_fma_f32 v200, v200, v195, v177
	v_med3_f32 v202, v202, s90, v170
	v_med3_f32 v203, v203, s90, v170
	v_fma_f32 v201, v201, v182, v175
	v_log_f32_e32 v200, v200
	v_mul_f32_e32 v202, 0xbfb8aa3b, v202
	v_mul_f32_e32 v203, 0xbfb8aa3b, v203
	v_log_f32_e32 v201, v201
	v_exp_f32_e32 v202, v202
	v_exp_f32_e32 v203, v203
	v_cvt_pk_bf16_f32 v196, v196, v197
	v_cvt_pk_bf16_f32 v197, v198, v199
	v_max_f32_e32 v199, v90, v90
	v_med3_f32 v199, v199, s90, v170
	v_mul_f32_e32 v199, 0xbfb8aa3b, v199
	v_cvt_pk_bf16_f32 v198, v200, v201
	v_exp_f32_e32 v200, v199
	v_max_f32_e32 v199, v91, v91
	v_add_f32_e32 v202, 1.0, v202
	v_add_f32_e32 v203, 1.0, v203
	v_med3_f32 v199, v199, s90, v170
	v_rcp_f32_e32 v202, v202
	v_rcp_f32_e32 v203, v203
	v_mul_f32_e32 v199, 0xbfb8aa3b, v199
	v_exp_f32_e32 v201, v199
	v_fma_f32 v202, v202, v191, v176
	v_fma_f32 v203, v203, v194, v174
	v_log_f32_e32 v202, v202
	v_log_f32_e32 v203, v203
	v_add_f32_e32 v200, 1.0, v200
	v_add_f32_e32 v201, 1.0, v201
	v_or_b32_e32 v134, 32, v156
	v_rcp_f32_e32 v200, v200
	v_rcp_f32_e32 v201, v201
	v_ashrrev_i32_e32 v135, 31, v134
	v_lshlrev_b64 v[134:135], 12, v[134:135]
	v_lshl_add_u64 v[134:135], v[132:133], 0, v[134:135]
	v_cvt_pk_bf16_f32 v199, v202, v203
	global_store_dwordx4 v[134:135], v[196:199], off sc1
	v_max_f32_e32 v202, v84, v84
	v_max_f32_e32 v203, v85, v85
	v_fma_f32 v196, v200, v183, v173
	v_fma_f32 v197, v201, v187, v172
	v_max_f32_e32 v198, v92, v92
	v_max_f32_e32 v199, v93, v93
	v_max_f32_e32 v200, v82, v82
	v_max_f32_e32 v201, v83, v83
	v_med3_f32 v198, v198, s90, v170
	v_med3_f32 v199, v199, s90, v170
	v_med3_f32 v200, v200, s90, v170
	v_med3_f32 v201, v201, s90, v170
	v_med3_f32 v202, v202, s90, v170
	v_med3_f32 v203, v203, s90, v170
	v_mul_f32_e32 v198, 0xbfb8aa3b, v198
	v_mul_f32_e32 v199, 0xbfb8aa3b, v199
	v_mul_f32_e32 v200, 0xbfb8aa3b, v200
	v_mul_f32_e32 v201, 0xbfb8aa3b, v201
	v_mul_f32_e32 v202, 0xbfb8aa3b, v202
	v_mul_f32_e32 v203, 0xbfb8aa3b, v203
	v_exp_f32_e32 v198, v198
	v_exp_f32_e32 v199, v199
	v_exp_f32_e32 v200, v200
	v_exp_f32_e32 v201, v201
	v_exp_f32_e32 v202, v202
	v_exp_f32_e32 v203, v203
	v_add_f32_e32 v198, 1.0, v198
	v_add_f32_e32 v199, 1.0, v199
	v_add_f32_e32 v200, 1.0, v200
	v_add_f32_e32 v201, 1.0, v201
	v_add_f32_e32 v202, 1.0, v202
	v_add_f32_e32 v203, 1.0, v203
	v_rcp_f32_e32 v198, v198
	v_rcp_f32_e32 v199, v199
	v_rcp_f32_e32 v200, v200
	v_rcp_f32_e32 v201, v201
	v_rcp_f32_e32 v202, v202
	v_rcp_f32_e32 v203, v203
	v_fma_f32 v198, v198, v157, v161
	v_fma_f32 v199, v199, v186, v160
	v_fma_f32 v200, v200, v189, v159
	v_fma_f32 v201, v201, v146, v136
	v_fma_f32 v202, v202, v184, v137
	v_fma_f32 v203, v203, v188, v158
	v_log_f32_e32 v196, v196
	v_log_f32_e32 v197, v197
	v_log_f32_e32 v198, v198
	v_log_f32_e32 v199, v199
	v_log_f32_e32 v200, v200
; __device__ __forceinline__ unsigned cvt_pk_bf16(float lo, float hi) { const cvt_f2 v = {lo, hi}; return __builtin_bit_cast(unsigned, __builtin_convertvector(v, cvt_b2)); }
;     __device__ __forceinline__ void operator()(const f32x4 (&acc)[2][2][4][2], const Unit& u, int wr, int wc, int fr, int fq) const {
;     ...
;             for (int ai = 0; ai < 2; ++ai)
; #pragma unroll
;                 for (int m = 0; m < 4; ++m) { const size_t ro = (size_t)(row0 + ai * HALF + m * 16) * 2048 + col0;
; #pragma unroll
;                     for (int bj = 0; bj < 2; ++bj) { float gl[8];
; #pragma unroll
;                         for (int n = 0; n < 2; ++n)
; #pragma unroll
;                             for (int j = 0; j < 4; ++j) { const float x = fminf(fmaxf(acc[ai][bj][m][n][j], -80.f), 80.f); const float e = __expf(-x); const float sg = __builtin_amdgcn_rcpf(1.0f + e); const float l = lb[bj][4 * n + j];
;                                 const float f = l + (1.0f - l) * sg; gl[4 * n + j] = __log2f(f); }
;                         pg8::u32x4 w; w.x = cvt_pk_bf16(gl[0], gl[1]); w.y = cvt_pk_bf16(gl[2], gl[3]); w.z = cvt_pk_bf16(gl[4], gl[5]); w.w = cvt_pk_bf16(gl[6], gl[7]);
;                         *(pg8::u32x4*)(G + ro + bj * HALF) = w;
;                         } }
	v_log_f32_e32 v201, v201
	v_log_f32_e32 v202, v202
	v_log_f32_e32 v203, v203
	v_cvt_pk_bf16_f32 v196, v196, v197
	v_cvt_pk_bf16_f32 v197, v198, v199
	v_cvt_pk_bf16_f32 v198, v200, v201
	v_cvt_pk_bf16_f32 v199, v202, v203
	global_store_dwordx4 v[134:135], v[196:199], off offset:256 sc1
	v_or_b32_e32 v134, 48, v156
	v_ashrrev_i32_e32 v135, 31, v134
	v_max_f32_e32 v196, v78, v78
	v_med3_f32 v196, v196, s90, v170
	v_max_f32_e32 v197, v79, v79
	v_mul_f32_e32 v196, 0xbfb8aa3b, v196
	v_med3_f32 v197, v197, s90, v170
	v_exp_f32_e32 v196, v196
	v_mul_f32_e32 v197, 0xbfb8aa3b, v197
	v_exp_f32_e32 v197, v197
	v_lshlrev_b64 v[134:135], 12, v[134:135]
	v_add_f32_e32 v196, 1.0, v196
	v_rcp_f32_e32 v196, v196
	v_add_f32_e32 v197, 1.0, v197
	v_rcp_f32_e32 v197, v197
	v_lshl_add_u64 v[132:133], v[132:133], 0, v[134:135]
	v_fma_f32 v134, v196, v190, v181
	v_max_f32_e32 v196, v80, v80
	v_fma_f32 v135, v197, v193, v180
	v_med3_f32 v196, v196, s90, v170
	v_max_f32_e32 v197, v81, v81
	v_mul_f32_e32 v196, 0xbfb8aa3b, v196
	v_med3_f32 v197, v197, s90, v170
	v_exp_f32_e32 v196, v196
	v_mul_f32_e32 v197, 0xbfb8aa3b, v197
	v_exp_f32_e32 v197, v197
	v_max_f32_e32 v198, v70, v70
	v_add_f32_e32 v196, 1.0, v196
	v_med3_f32 v198, v198, s90, v170
	v_rcp_f32_e32 v196, v196
	v_add_f32_e32 v197, 1.0, v197
	v_mul_f32_e32 v198, 0xbfb8aa3b, v198
	v_rcp_f32_e32 v197, v197
	v_exp_f32_e32 v198, v198
	v_fma_f32 v196, v196, v185, v179
	v_log_f32_e32 v199, v196
	v_fma_f32 v196, v197, v192, v178
	v_add_f32_e32 v197, 1.0, v198
	v_max_f32_e32 v198, v71, v71
	v_med3_f32 v198, v198, s90, v170
	v_rcp_f32_e32 v197, v197
	v_mul_f32_e32 v198, 0xbfb8aa3b, v198
	v_exp_f32_e32 v198, v198
	v_log_f32_e32 v200, v196
	v_fma_f32 v196, v197, v195, v177
	v_max_f32_e32 v197, v72, v72
	v_log_f32_e32 v201, v196
	v_add_f32_e32 v196, 1.0, v198
	v_med3_f32 v197, v197, s90, v170
	v_max_f32_e32 v198, v73, v73
	v_mul_f32_e32 v197, 0xbfb8aa3b, v197
	v_med3_f32 v198, v198, s90, v170
	v_exp_f32_e32 v197, v197
	v_mul_f32_e32 v198, 0xbfb8aa3b, v198
	v_exp_f32_e32 v198, v198
	v_rcp_f32_e32 v196, v196
	v_add_f32_e32 v197, 1.0, v197
	v_rcp_f32_e32 v197, v197
	v_add_f32_e32 v198, 1.0, v198
	v_rcp_f32_e32 v198, v198
	v_fma_f32 v196, v196, v182, v175
	v_log_f32_e32 v202, v196
	v_fma_f32 v196, v197, v191, v176
	v_log_f32_e32 v203, v196
	v_fma_f32 v196, v198, v194, v174
	v_log_f32_e32 v134, v134
	v_log_f32_e32 v135, v135
	v_log_f32_e32 v204, v196
	v_cvt_pk_bf16_f32 v197, v199, v200
	v_cvt_pk_bf16_f32 v198, v201, v202
	v_cvt_pk_bf16_f32 v196, v134, v135
	v_cvt_pk_bf16_f32 v199, v203, v204
	global_store_dwordx4 v[132:133], v[196:199], off sc1
	v_max_f32_e32 v134, v74, v74
	v_max_f32_e32 v135, v75, v75
	v_max_f32_e32 v196, v76, v76
	v_med3_f32 v196, v196, s90, v170
	v_max_f32_e32 v197, v77, v77
	v_mul_f32_e32 v196, 0xbfb8aa3b, v196
	v_med3_f32 v197, v197, s90, v170
	v_exp_f32_e32 v196, v196
	v_mul_f32_e32 v197, 0xbfb8aa3b, v197
	v_exp_f32_e32 v197, v197
	v_max_f32_e32 v198, v66, v66
	v_add_f32_e32 v196, 1.0, v196
	v_med3_f32 v198, v198, s90, v170
	v_rcp_f32_e32 v196, v196
	v_add_f32_e32 v197, 1.0, v197
	v_mul_f32_e32 v198, 0xbfb8aa3b, v198
	v_rcp_f32_e32 v197, v197
	v_exp_f32_e32 v198, v198
	v_fma_f32 v196, v196, v157, v161
	v_log_f32_e32 v199, v196
	v_fma_f32 v196, v197, v186, v160
	v_add_f32_e32 v197, 1.0, v198
	v_max_f32_e32 v198, v67, v67
	v_med3_f32 v198, v198, s90, v170
	v_rcp_f32_e32 v197, v197
	v_mul_f32_e32 v198, 0xbfb8aa3b, v198
	v_exp_f32_e32 v198, v198
	v_log_f32_e32 v200, v196
	v_fma_f32 v196, v197, v189, v159
	v_max_f32_e32 v197, v68, v68
	v_log_f32_e32 v201, v196
	v_add_f32_e32 v196, 1.0, v198
	v_med3_f32 v197, v197, s90, v170
	v_max_f32_e32 v198, v69, v69
	v_med3_f32 v134, v134, s90, v170
	v_med3_f32 v135, v135, s90, v170
	v_mul_f32_e32 v197, 0xbfb8aa3b, v197
	v_med3_f32 v198, v198, s90, v170
	v_mul_f32_e32 v134, 0xbfb8aa3b, v134
	v_mul_f32_e32 v135, 0xbfb8aa3b, v135
	v_exp_f32_e32 v197, v197
	v_mul_f32_e32 v198, 0xbfb8aa3b, v198
	v_exp_f32_e32 v134, v134
	v_exp_f32_e32 v135, v135
	v_exp_f32_e32 v198, v198
	v_rcp_f32_e32 v196, v196
	v_add_f32_e32 v197, 1.0, v197
	v_add_f32_e32 v134, 1.0, v134
	v_add_f32_e32 v135, 1.0, v135
	v_rcp_f32_e32 v197, v197
	v_add_f32_e32 v198, 1.0, v198
	v_rcp_f32_e32 v134, v134
	v_rcp_f32_e32 v135, v135
	v_rcp_f32_e32 v198, v198
	v_fma_f32 v196, v196, v146, v136
	v_log_f32_e32 v202, v196
	v_fma_f32 v196, v197, v184, v137
	v_fma_f32 v134, v134, v183, v173
	v_fma_f32 v135, v135, v187, v172
	v_log_f32_e32 v203, v196
	v_fma_f32 v196, v198, v188, v158
	v_log_f32_e32 v134, v134
	v_log_f32_e32 v135, v135
	v_log_f32_e32 v204, v196
	v_cvt_pk_bf16_f32 v197, v199, v200
	v_cvt_pk_bf16_f32 v198, v201, v202
	v_cvt_pk_bf16_f32 v196, v134, v135
	v_cvt_pk_bf16_f32 v199, v203, v204
	global_store_dwordx4 v[132:133], v[196:199], off offset:256 sc1
	v_max_f32_e32 v132, v62, v62
	v_med3_f32 v132, v132, s90, v170
	v_max_f32_e32 v196, v64, v64
	v_med3_f32 v196, v196, s90, v170
	v_max_f32_e32 v197, v65, v65
	v_mul_f32_e32 v196, 0xbfb8aa3b, v196
	v_med3_f32 v197, v197, s90, v170
	v_exp_f32_e32 v196, v196
	v_mul_f32_e32 v197, 0xbfb8aa3b, v197
	v_exp_f32_e32 v197, v197
	v_max_f32_e32 v198, v54, v54
	v_add_f32_e32 v196, 1.0, v196
	v_med3_f32 v198, v198, s90, v170
	v_rcp_f32_e32 v196, v196
	v_add_f32_e32 v197, 1.0, v197
	v_mul_f32_e32 v198, 0xbfb8aa3b, v198
	v_rcp_f32_e32 v197, v197
	v_exp_f32_e32 v198, v198
	v_fma_f32 v196, v196, v185, v179
	v_log_f32_e32 v199, v196
	v_fma_f32 v196, v197, v192, v178
	v_add_f32_e32 v197, 1.0, v198
	v_max_f32_e32 v198, v55, v55
	v_med3_f32 v198, v198, s90, v170
	v_rcp_f32_e32 v197, v197
	v_mul_f32_e32 v198, 0xbfb8aa3b, v198
	v_max_f32_e32 v133, v63, v63
	v_exp_f32_e32 v198, v198
; __device__ __forceinline__ unsigned cvt_pk_bf16(float lo, float hi) { const cvt_f2 v = {lo, hi}; return __builtin_bit_cast(unsigned, __builtin_convertvector(v, cvt_b2)); }
;     __device__ __forceinline__ void operator()(const f32x4 (&acc)[2][2][4][2], const Unit& u, int wr, int wc, int fr, int fq) const {
;     ...
;             for (int ai = 0; ai < 2; ++ai)
; #pragma unroll
;                 for (int m = 0; m < 4; ++m) { const size_t ro = (size_t)(row0 + ai * HALF + m * 16) * 2048 + col0;
; #pragma unroll
;                     for (int bj = 0; bj < 2; ++bj) { float gl[8];
; #pragma unroll
;                         for (int n = 0; n < 2; ++n)
; #pragma unroll
;                             for (int j = 0; j < 4; ++j) { const float x = fminf(fmaxf(acc[ai][bj][m][n][j], -80.f), 80.f); const float e = __expf(-x); const float sg = __builtin_amdgcn_rcpf(1.0f + e); const float l = lb[bj][4 * n + j];
;                                 const float f = l + (1.0f - l) * sg; gl[4 * n + j] = __log2f(f); }
;                         pg8::u32x4 w; w.x = cvt_pk_bf16(gl[0], gl[1]); w.y = cvt_pk_bf16(gl[2], gl[3]); w.z = cvt_pk_bf16(gl[4], gl[5]); w.w = cvt_pk_bf16(gl[6], gl[7]);
;                         *(pg8::u32x4*)(G + ro + bj * HALF) = w;
;                         } }
	v_mul_f32_e32 v132, 0xbfb8aa3b, v132
	v_med3_f32 v133, v133, s90, v170
	v_exp_f32_e32 v132, v132
	v_mul_f32_e32 v133, 0xbfb8aa3b, v133
	v_exp_f32_e32 v133, v133
	v_log_f32_e32 v200, v196
	v_fma_f32 v196, v197, v195, v177
	v_max_f32_e32 v197, v56, v56
	v_log_f32_e32 v201, v196
	v_add_f32_e32 v196, 1.0, v198
	v_med3_f32 v197, v197, s90, v170
	v_max_f32_e32 v198, v57, v57
	v_mul_f32_e32 v197, 0xbfb8aa3b, v197
	v_med3_f32 v198, v198, s90, v170
	v_add_f32_e32 v132, 1.0, v132
	v_exp_f32_e32 v197, v197
	v_mul_f32_e32 v198, 0xbfb8aa3b, v198
	v_rcp_f32_e32 v134, v132
	v_add_f32_e32 v132, 1.0, v133
	v_exp_f32_e32 v198, v198
	v_rcp_f32_e32 v135, v132
	v_rcp_f32_e32 v196, v196
	v_add_f32_e32 v197, 1.0, v197
	v_rcp_f32_e32 v197, v197
	v_add_f32_e32 v198, 1.0, v198
	v_fma_f32 v134, v134, v190, v181
	v_fma_f32 v135, v135, v193, v180
	v_rcp_f32_e32 v198, v198
	v_log_f32_e32 v134, v134
	v_log_f32_e32 v135, v135
	v_fma_f32 v196, v196, v182, v175
	v_log_f32_e32 v202, v196
	v_fma_f32 v196, v197, v191, v176
	v_log_f32_e32 v203, v196
	v_fma_f32 v196, v198, v194, v174
	v_log_f32_e32 v204, v196
	v_cvt_pk_bf16_f32 v196, v134, v135
	v_max_f32_e32 v134, v58, v58
	v_med3_f32 v134, v134, s90, v170
	v_mul_f32_e32 v134, 0xbfb8aa3b, v134
	v_cvt_pk_bf16_f32 v197, v199, v200
	v_exp_f32_e32 v200, v134
	v_max_f32_e32 v134, v59, v59
	v_med3_f32 v134, v134, s90, v170
	v_lshl_add_u64 v[132:133], v[130:131], 0, s[0:1]
	s_mov_b32 s0, 0x80000
	v_mul_f32_e32 v134, 0xbfb8aa3b, v134
	v_cvt_pk_bf16_f32 v198, v201, v202
	v_exp_f32_e32 v201, v134
	v_add_co_u32_e32 v134, vcc, s0, v130
	v_cvt_pk_bf16_f32 v199, v203, v204
	s_nop 0
	v_addc_co_u32_e32 v135, vcc, 0, v131, vcc
	global_store_dwordx4 v[134:135], v[196:199], off sc1
	v_add_f32_e32 v200, 1.0, v200
	v_rcp_f32_e32 v200, v200
	v_max_f32_e32 v196, v60, v60
	v_med3_f32 v196, v196, s90, v170
	v_max_f32_e32 v197, v61, v61
	v_mul_f32_e32 v196, 0xbfb8aa3b, v196
	v_med3_f32 v197, v197, s90, v170
	v_exp_f32_e32 v196, v196
	v_mul_f32_e32 v197, 0xbfb8aa3b, v197
	v_exp_f32_e32 v197, v197
	v_max_f32_e32 v198, v50, v50
	v_add_f32_e32 v196, 1.0, v196
	v_med3_f32 v198, v198, s90, v170
	v_rcp_f32_e32 v196, v196
	v_add_f32_e32 v197, 1.0, v197
	v_mul_f32_e32 v198, 0xbfb8aa3b, v198
	v_rcp_f32_e32 v197, v197
	v_exp_f32_e32 v198, v198
	v_fma_f32 v196, v196, v157, v161
	v_log_f32_e32 v199, v196
	v_fma_f32 v196, v197, v186, v160
	v_add_f32_e32 v197, 1.0, v198
	v_max_f32_e32 v198, v51, v51
	v_med3_f32 v198, v198, s90, v170
	v_add_f32_e32 v201, 1.0, v201
	v_rcp_f32_e32 v197, v197
	v_mul_f32_e32 v198, 0xbfb8aa3b, v198
	v_rcp_f32_e32 v201, v201
	v_exp_f32_e32 v198, v198
	v_fma_f32 v134, v200, v183, v173
	v_log_f32_e32 v200, v196
	v_fma_f32 v196, v197, v189, v159
	v_max_f32_e32 v197, v52, v52
	v_fma_f32 v135, v201, v187, v172
	v_log_f32_e32 v201, v196
	v_add_f32_e32 v196, 1.0, v198
	v_med3_f32 v197, v197, s90, v170
	v_max_f32_e32 v198, v53, v53
	v_mul_f32_e32 v197, 0xbfb8aa3b, v197
	v_med3_f32 v198, v198, s90, v170
	v_exp_f32_e32 v197, v197
	v_mul_f32_e32 v198, 0xbfb8aa3b, v198
	v_exp_f32_e32 v198, v198
	v_rcp_f32_e32 v196, v196
	v_add_f32_e32 v197, 1.0, v197
	v_rcp_f32_e32 v197, v197
	v_add_f32_e32 v198, 1.0, v198
	v_rcp_f32_e32 v198, v198
	v_fma_f32 v196, v196, v146, v136
	v_log_f32_e32 v202, v196
	v_fma_f32 v196, v197, v184, v137
	v_log_f32_e32 v203, v196
	v_fma_f32 v196, v198, v188, v158
	v_log_f32_e32 v134, v134
	v_log_f32_e32 v135, v135
	v_log_f32_e32 v204, v196
	v_cvt_pk_bf16_f32 v197, v199, v200
	v_cvt_pk_bf16_f32 v198, v201, v202
	v_cvt_pk_bf16_f32 v196, v134, v135
	v_cvt_pk_bf16_f32 v199, v203, v204
	global_store_dwordx4 v[132:133], v[196:199], off offset:256 sc1
	v_max_f32_e32 v132, v46, v46
	v_med3_f32 v132, v132, s90, v170
	v_max_f32_e32 v196, v48, v48
	v_med3_f32 v196, v196, s90, v170
	v_max_f32_e32 v197, v49, v49
	v_mul_f32_e32 v196, 0xbfb8aa3b, v196
	v_med3_f32 v197, v197, s90, v170
	v_exp_f32_e32 v196, v196
	v_mul_f32_e32 v197, 0xbfb8aa3b, v197
	v_exp_f32_e32 v197, v197
	v_max_f32_e32 v198, v38, v38
	v_add_f32_e32 v196, 1.0, v196
	v_med3_f32 v198, v198, s90, v170
	v_rcp_f32_e32 v196, v196
	v_add_f32_e32 v197, 1.0, v197
	v_mul_f32_e32 v198, 0xbfb8aa3b, v198
	v_rcp_f32_e32 v197, v197
	v_exp_f32_e32 v198, v198
	v_fma_f32 v196, v196, v185, v179
	v_log_f32_e32 v199, v196
	v_fma_f32 v196, v197, v192, v178
	v_add_f32_e32 v197, 1.0, v198
	v_max_f32_e32 v198, v39, v39
	v_med3_f32 v198, v198, s90, v170
	v_rcp_f32_e32 v197, v197
	v_mul_f32_e32 v198, 0xbfb8aa3b, v198
	v_max_f32_e32 v133, v47, v47
	v_exp_f32_e32 v198, v198
	v_mul_f32_e32 v132, 0xbfb8aa3b, v132
	v_med3_f32 v133, v133, s90, v170
	v_exp_f32_e32 v132, v132
	v_mul_f32_e32 v133, 0xbfb8aa3b, v133
	v_exp_f32_e32 v133, v133
	v_log_f32_e32 v200, v196
	v_fma_f32 v196, v197, v195, v177
	v_max_f32_e32 v197, v40, v40
	v_log_f32_e32 v201, v196
	v_add_f32_e32 v196, 1.0, v198
	v_med3_f32 v197, v197, s90, v170
	v_max_f32_e32 v198, v41, v41
	v_mul_f32_e32 v197, 0xbfb8aa3b, v197
	v_med3_f32 v198, v198, s90, v170
	v_add_f32_e32 v132, 1.0, v132
	v_exp_f32_e32 v197, v197
	v_mul_f32_e32 v198, 0xbfb8aa3b, v198
	v_rcp_f32_e32 v134, v132
	v_add_f32_e32 v132, 1.0, v133
	v_exp_f32_e32 v198, v198
	v_rcp_f32_e32 v135, v132
	v_rcp_f32_e32 v196, v196
	v_add_f32_e32 v197, 1.0, v197
	v_rcp_f32_e32 v197, v197
	v_add_f32_e32 v198, 1.0, v198
	v_fma_f32 v134, v134, v190, v181
	v_fma_f32 v135, v135, v193, v180
	v_rcp_f32_e32 v198, v198
	v_log_f32_e32 v134, v134
	v_log_f32_e32 v135, v135
	v_fma_f32 v196, v196, v182, v175
	v_log_f32_e32 v202, v196
	v_fma_f32 v196, v197, v191, v176
	v_log_f32_e32 v203, v196
	v_fma_f32 v196, v198, v194, v174
	v_log_f32_e32 v204, v196
	v_cvt_pk_bf16_f32 v196, v134, v135
	v_max_f32_e32 v134, v42, v42
; __device__ __forceinline__ unsigned cvt_pk_bf16(float lo, float hi) { const cvt_f2 v = {lo, hi}; return __builtin_bit_cast(unsigned, __builtin_convertvector(v, cvt_b2)); }
;     __device__ __forceinline__ void operator()(const f32x4 (&acc)[2][2][4][2], const Unit& u, int wr, int wc, int fr, int fq) const {
;     ...
;             for (int ai = 0; ai < 2; ++ai)
; #pragma unroll
;                 for (int m = 0; m < 4; ++m) { const size_t ro = (size_t)(row0 + ai * HALF + m * 16) * 2048 + col0;
; #pragma unroll
;                     for (int bj = 0; bj < 2; ++bj) { float gl[8];
; #pragma unroll
;                         for (int n = 0; n < 2; ++n)
; #pragma unroll
;                             for (int j = 0; j < 4; ++j) { const float x = fminf(fmaxf(acc[ai][bj][m][n][j], -80.f), 80.f); const float e = __expf(-x); const float sg = __builtin_amdgcn_rcpf(1.0f + e); const float l = lb[bj][4 * n + j];
;                                 const float f = l + (1.0f - l) * sg; gl[4 * n + j] = __log2f(f); }
;                         pg8::u32x4 w; w.x = cvt_pk_bf16(gl[0], gl[1]); w.y = cvt_pk_bf16(gl[2], gl[3]); w.z = cvt_pk_bf16(gl[4], gl[5]); w.w = cvt_pk_bf16(gl[6], gl[7]);
;                         *(pg8::u32x4*)(G + ro + bj * HALF) = w;
;                         } }
	v_med3_f32 v134, v134, s90, v170
	v_mul_f32_e32 v134, 0xbfb8aa3b, v134
	v_cvt_pk_bf16_f32 v197, v199, v200
	v_exp_f32_e32 v200, v134
	v_max_f32_e32 v134, v43, v43
	s_mov_b64 s[0:1], 0x90000
	v_med3_f32 v134, v134, s90, v170
	v_lshl_add_u64 v[132:133], v[130:131], 0, s[0:1]
	s_mov_b32 s0, 0x90000
	v_mul_f32_e32 v134, 0xbfb8aa3b, v134
	v_cvt_pk_bf16_f32 v198, v201, v202
	v_exp_f32_e32 v201, v134
	v_add_co_u32_e32 v134, vcc, s0, v130
	v_cvt_pk_bf16_f32 v199, v203, v204
	s_nop 0
	v_addc_co_u32_e32 v135, vcc, 0, v131, vcc
	global_store_dwordx4 v[134:135], v[196:199], off sc1
	v_add_f32_e32 v200, 1.0, v200
	v_rcp_f32_e32 v200, v200
	v_max_f32_e32 v196, v44, v44
	v_med3_f32 v196, v196, s90, v170
	v_max_f32_e32 v197, v45, v45
	v_mul_f32_e32 v196, 0xbfb8aa3b, v196
	v_med3_f32 v197, v197, s90, v170
	v_exp_f32_e32 v196, v196
	v_mul_f32_e32 v197, 0xbfb8aa3b, v197
	v_exp_f32_e32 v197, v197
	v_max_f32_e32 v198, v34, v34
	v_add_f32_e32 v196, 1.0, v196
	v_med3_f32 v198, v198, s90, v170
	v_rcp_f32_e32 v196, v196
	v_add_f32_e32 v197, 1.0, v197
	v_mul_f32_e32 v198, 0xbfb8aa3b, v198
	v_rcp_f32_e32 v197, v197
	v_exp_f32_e32 v198, v198
	v_fma_f32 v196, v196, v157, v161
	v_log_f32_e32 v199, v196
	v_fma_f32 v196, v197, v186, v160
	v_add_f32_e32 v197, 1.0, v198
	v_max_f32_e32 v198, v35, v35
	v_med3_f32 v198, v198, s90, v170
	v_add_f32_e32 v201, 1.0, v201
	v_rcp_f32_e32 v197, v197
	v_mul_f32_e32 v198, 0xbfb8aa3b, v198
	v_rcp_f32_e32 v201, v201
	v_exp_f32_e32 v198, v198
	v_fma_f32 v134, v200, v183, v173
	v_log_f32_e32 v200, v196
	v_fma_f32 v196, v197, v189, v159
	v_max_f32_e32 v197, v36, v36
	v_fma_f32 v135, v201, v187, v172
	v_log_f32_e32 v201, v196
	v_add_f32_e32 v196, 1.0, v198
	v_med3_f32 v197, v197, s90, v170
	v_max_f32_e32 v198, v37, v37
	v_mul_f32_e32 v197, 0xbfb8aa3b, v197
	v_med3_f32 v198, v198, s90, v170
	v_exp_f32_e32 v197, v197
	v_mul_f32_e32 v198, 0xbfb8aa3b, v198
	v_exp_f32_e32 v198, v198
	v_rcp_f32_e32 v196, v196
	v_add_f32_e32 v197, 1.0, v197
	v_rcp_f32_e32 v197, v197
	v_add_f32_e32 v198, 1.0, v198
	v_rcp_f32_e32 v198, v198
	v_fma_f32 v196, v196, v146, v136
	v_log_f32_e32 v202, v196
	v_fma_f32 v196, v197, v184, v137
	v_log_f32_e32 v203, v196
	v_fma_f32 v196, v198, v188, v158
	v_log_f32_e32 v134, v134
	v_log_f32_e32 v135, v135
	v_log_f32_e32 v204, v196
	v_cvt_pk_bf16_f32 v197, v199, v200
	v_cvt_pk_bf16_f32 v198, v201, v202
	v_cvt_pk_bf16_f32 v196, v134, v135
	v_cvt_pk_bf16_f32 v199, v203, v204
	global_store_dwordx4 v[132:133], v[196:199], off offset:256 sc1
	v_max_f32_e32 v132, v30, v30
	v_med3_f32 v132, v132, s90, v170
	v_max_f32_e32 v196, v32, v32
	v_med3_f32 v196, v196, s90, v170
	v_max_f32_e32 v197, v33, v33
	v_mul_f32_e32 v196, 0xbfb8aa3b, v196
	v_med3_f32 v197, v197, s90, v170
	v_exp_f32_e32 v196, v196
	v_mul_f32_e32 v197, 0xbfb8aa3b, v197
	v_exp_f32_e32 v197, v197
	v_max_f32_e32 v198, v22, v22
	v_add_f32_e32 v196, 1.0, v196
	v_med3_f32 v198, v198, s90, v170
	v_rcp_f32_e32 v196, v196
	v_add_f32_e32 v197, 1.0, v197
	v_mul_f32_e32 v198, 0xbfb8aa3b, v198
	v_rcp_f32_e32 v197, v197
	v_exp_f32_e32 v198, v198
	v_fma_f32 v196, v196, v185, v179
	v_log_f32_e32 v199, v196
	v_fma_f32 v196, v197, v192, v178
	v_add_f32_e32 v197, 1.0, v198
	v_max_f32_e32 v198, v23, v23
	v_med3_f32 v198, v198, s90, v170
	v_rcp_f32_e32 v197, v197
	v_mul_f32_e32 v198, 0xbfb8aa3b, v198
	v_max_f32_e32 v133, v31, v31
	v_exp_f32_e32 v198, v198
	v_mul_f32_e32 v132, 0xbfb8aa3b, v132
	v_med3_f32 v133, v133, s90, v170
	v_exp_f32_e32 v132, v132
	v_mul_f32_e32 v133, 0xbfb8aa3b, v133
	v_exp_f32_e32 v133, v133
	v_log_f32_e32 v200, v196
	v_fma_f32 v196, v197, v195, v177
	v_max_f32_e32 v197, v24, v24
	v_log_f32_e32 v201, v196
	v_add_f32_e32 v196, 1.0, v198
	v_med3_f32 v197, v197, s90, v170
	v_max_f32_e32 v198, v25, v25
	v_mul_f32_e32 v197, 0xbfb8aa3b, v197
	v_med3_f32 v198, v198, s90, v170
	v_add_f32_e32 v132, 1.0, v132
	v_exp_f32_e32 v197, v197
	v_mul_f32_e32 v198, 0xbfb8aa3b, v198
	v_rcp_f32_e32 v134, v132
	v_add_f32_e32 v132, 1.0, v133
	v_exp_f32_e32 v198, v198
	v_rcp_f32_e32 v135, v132
	v_rcp_f32_e32 v196, v196
	v_add_f32_e32 v197, 1.0, v197
	v_rcp_f32_e32 v197, v197
	v_add_f32_e32 v198, 1.0, v198
	v_fma_f32 v134, v134, v190, v181
	v_fma_f32 v135, v135, v193, v180
	v_rcp_f32_e32 v198, v198
	v_log_f32_e32 v134, v134
	v_log_f32_e32 v135, v135
	v_fma_f32 v196, v196, v182, v175
	v_log_f32_e32 v202, v196
	v_fma_f32 v196, v197, v191, v176
	v_log_f32_e32 v203, v196
	v_fma_f32 v196, v198, v194, v174
	v_log_f32_e32 v204, v196
	v_cvt_pk_bf16_f32 v196, v134, v135
	v_max_f32_e32 v134, v26, v26
	v_med3_f32 v134, v134, s90, v170
	v_mul_f32_e32 v134, 0xbfb8aa3b, v134
	v_cvt_pk_bf16_f32 v197, v199, v200
	v_exp_f32_e32 v200, v134
	v_max_f32_e32 v134, v27, v27
	s_mov_b64 s[0:1], 0xa0000
	v_med3_f32 v134, v134, s90, v170
	v_lshl_add_u64 v[132:133], v[130:131], 0, s[0:1]
	s_mov_b32 s0, 0xa0000
	v_mul_f32_e32 v134, 0xbfb8aa3b, v134
	v_cvt_pk_bf16_f32 v198, v201, v202
	v_exp_f32_e32 v201, v134
	v_add_co_u32_e32 v134, vcc, s0, v130
	v_cvt_pk_bf16_f32 v199, v203, v204
	s_nop 0
	v_addc_co_u32_e32 v135, vcc, 0, v131, vcc
	global_store_dwordx4 v[134:135], v[196:199], off sc1
	v_add_f32_e32 v200, 1.0, v200
	v_rcp_f32_e32 v200, v200
	v_max_f32_e32 v196, v28, v28
	v_med3_f32 v196, v196, s90, v170
	v_max_f32_e32 v197, v29, v29
	v_mul_f32_e32 v196, 0xbfb8aa3b, v196
	v_med3_f32 v197, v197, s90, v170
	v_exp_f32_e32 v196, v196
	v_mul_f32_e32 v197, 0xbfb8aa3b, v197
	v_exp_f32_e32 v197, v197
	v_max_f32_e32 v198, v18, v18
	v_add_f32_e32 v196, 1.0, v196
	v_med3_f32 v198, v198, s90, v170
	v_rcp_f32_e32 v196, v196
	v_add_f32_e32 v197, 1.0, v197
	v_mul_f32_e32 v198, 0xbfb8aa3b, v198
	v_rcp_f32_e32 v197, v197
	v_exp_f32_e32 v198, v198
; __device__ __forceinline__ unsigned cvt_pk_bf16(float lo, float hi) { const cvt_f2 v = {lo, hi}; return __builtin_bit_cast(unsigned, __builtin_convertvector(v, cvt_b2)); }
;     __device__ __forceinline__ void operator()(const f32x4 (&acc)[2][2][4][2], const Unit& u, int wr, int wc, int fr, int fq) const {
;     ...
;             for (int ai = 0; ai < 2; ++ai)
; #pragma unroll
;                 for (int m = 0; m < 4; ++m) { const size_t ro = (size_t)(row0 + ai * HALF + m * 16) * 2048 + col0;
; #pragma unroll
;                     for (int bj = 0; bj < 2; ++bj) { float gl[8];
; #pragma unroll
;                         for (int n = 0; n < 2; ++n)
; #pragma unroll
;                             for (int j = 0; j < 4; ++j) { const float x = fminf(fmaxf(acc[ai][bj][m][n][j], -80.f), 80.f); const float e = __expf(-x); const float sg = __builtin_amdgcn_rcpf(1.0f + e); const float l = lb[bj][4 * n + j];
;                                 const float f = l + (1.0f - l) * sg; gl[4 * n + j] = __log2f(f); }
;                         pg8::u32x4 w; w.x = cvt_pk_bf16(gl[0], gl[1]); w.y = cvt_pk_bf16(gl[2], gl[3]); w.z = cvt_pk_bf16(gl[4], gl[5]); w.w = cvt_pk_bf16(gl[6], gl[7]);
;                         *(pg8::u32x4*)(G + ro + bj * HALF) = w;
;                         } }
	v_fma_f32 v196, v196, v157, v161
	v_log_f32_e32 v199, v196
	v_fma_f32 v196, v197, v186, v160
	v_add_f32_e32 v197, 1.0, v198
	v_max_f32_e32 v198, v19, v19
	v_med3_f32 v198, v198, s90, v170
	v_add_f32_e32 v201, 1.0, v201
	v_rcp_f32_e32 v197, v197
	v_mul_f32_e32 v198, 0xbfb8aa3b, v198
	v_rcp_f32_e32 v201, v201
	v_exp_f32_e32 v198, v198
	v_fma_f32 v134, v200, v183, v173
	v_log_f32_e32 v200, v196
	v_fma_f32 v196, v197, v189, v159
	v_max_f32_e32 v197, v20, v20
	v_fma_f32 v135, v201, v187, v172
	v_log_f32_e32 v201, v196
	v_add_f32_e32 v196, 1.0, v198
	v_med3_f32 v197, v197, s90, v170
	v_max_f32_e32 v198, v21, v21
	v_mul_f32_e32 v197, 0xbfb8aa3b, v197
	v_med3_f32 v198, v198, s90, v170
	v_exp_f32_e32 v197, v197
	v_mul_f32_e32 v198, 0xbfb8aa3b, v198
	v_exp_f32_e32 v198, v198
	v_rcp_f32_e32 v196, v196
	v_add_f32_e32 v197, 1.0, v197
	v_rcp_f32_e32 v197, v197
	v_add_f32_e32 v198, 1.0, v198
	v_rcp_f32_e32 v198, v198
	v_fma_f32 v196, v196, v146, v136
	v_log_f32_e32 v202, v196
	v_fma_f32 v196, v197, v184, v137
	v_log_f32_e32 v203, v196
	v_fma_f32 v196, v198, v188, v158
	v_log_f32_e32 v134, v134
	v_log_f32_e32 v135, v135
	v_log_f32_e32 v204, v196
	v_cvt_pk_bf16_f32 v197, v199, v200
	v_cvt_pk_bf16_f32 v198, v201, v202
	v_cvt_pk_bf16_f32 v196, v134, v135
	v_cvt_pk_bf16_f32 v199, v203, v204
	global_store_dwordx4 v[132:133], v[196:199], off offset:256 sc1
	v_max_f32_e32 v132, v14, v14
	v_med3_f32 v132, v132, s90, v170
	v_mul_f32_e32 v132, 0xbfb8aa3b, v132
	v_max_f32_e32 v133, v15, v15
	v_exp_f32_e32 v132, v132
	v_med3_f32 v133, v133, s90, v170
	v_mul_f32_e32 v133, 0xbfb8aa3b, v133
	v_exp_f32_e32 v133, v133
	v_add_f32_e32 v132, 1.0, v132
	v_rcp_f32_e32 v134, v132
	s_mov_b64 s[0:1], 0xb0000
	v_add_f32_e32 v132, 1.0, v133
	v_rcp_f32_e32 v135, v132
	v_fmac_f32_e32 v181, v134, v190
	v_log_f32_e32 v134, v181
	v_max_f32_e32 v181, v17, v17
	v_fmac_f32_e32 v180, v135, v193
	v_max_f32_e32 v135, v16, v16
	v_med3_f32 v181, v181, s90, v170
	v_med3_f32 v135, v135, s90, v170
	v_mul_f32_e32 v181, 0xbfb8aa3b, v181
	v_mul_f32_e32 v135, 0xbfb8aa3b, v135
	v_exp_f32_e32 v181, v181
	v_exp_f32_e32 v135, v135
	v_max_f32_e32 v190, v6, v6
	v_med3_f32 v190, v190, s90, v170
	v_add_f32_e32 v181, 1.0, v181
	v_add_f32_e32 v135, 1.0, v135
	v_rcp_f32_e32 v181, v181
	v_rcp_f32_e32 v135, v135
	v_mul_f32_e32 v190, 0xbfb8aa3b, v190
	v_exp_f32_e32 v190, v190
	v_fmac_f32_e32 v178, v181, v192
	v_max_f32_e32 v181, v7, v7
	v_fmac_f32_e32 v179, v135, v185
	v_med3_f32 v181, v181, s90, v170
	v_log_f32_e32 v135, v179
	v_add_f32_e32 v179, 1.0, v190
	v_mul_f32_e32 v181, 0xbfb8aa3b, v181
	v_rcp_f32_e32 v179, v179
	v_exp_f32_e32 v181, v181
	v_max_f32_e32 v185, v9, v9
	v_med3_f32 v185, v185, s90, v170
	v_fmac_f32_e32 v177, v179, v195
	v_add_f32_e32 v179, 1.0, v181
	v_max_f32_e32 v181, v8, v8
	v_med3_f32 v181, v181, s90, v170
	v_mul_f32_e32 v181, 0xbfb8aa3b, v181
	v_mul_f32_e32 v185, 0xbfb8aa3b, v185
	v_rcp_f32_e32 v179, v179
	v_exp_f32_e32 v181, v181
	v_exp_f32_e32 v185, v185
	v_log_f32_e32 v180, v180
	v_fmac_f32_e32 v175, v179, v182
	v_add_f32_e32 v179, 1.0, v181
	v_add_f32_e32 v181, 1.0, v185
	v_rcp_f32_e32 v181, v181
	v_log_f32_e32 v178, v178
	v_rcp_f32_e32 v179, v179
	v_log_f32_e32 v182, v175
	v_fmac_f32_e32 v174, v181, v194
	v_log_f32_e32 v181, v174
	v_cvt_pk_bf16_f32 v174, v134, v180
	v_max_f32_e32 v134, v10, v10
	v_med3_f32 v134, v134, s90, v170
	v_mul_f32_e32 v134, 0xbfb8aa3b, v134
	v_exp_f32_e32 v134, v134
	v_fmac_f32_e32 v176, v179, v191
	v_cvt_pk_bf16_f32 v175, v135, v178
	v_max_f32_e32 v135, v11, v11
	v_log_f32_e32 v177, v177
	v_log_f32_e32 v179, v176
	v_med3_f32 v135, v135, s90, v170
	v_mul_f32_e32 v135, 0xbfb8aa3b, v135
	v_lshl_add_u64 v[132:133], v[130:131], 0, s[0:1]
	s_mov_b32 s0, 0xb0000
	v_exp_f32_e32 v135, v135
	v_add_f32_e32 v134, 1.0, v134
	v_add_co_u32_e32 v130, vcc, s0, v130
	v_rcp_f32_e32 v134, v134
	v_cvt_pk_bf16_f32 v176, v177, v182
	v_cvt_pk_bf16_f32 v177, v179, v181
	v_addc_co_u32_e32 v131, vcc, 0, v131, vcc
	global_store_dwordx4 v[130:131], v[174:177], off sc1
	v_max_f32_e32 v131, v12, v12
	v_add_f32_e32 v135, 1.0, v135
	v_med3_f32 v131, v131, s90, v170
	v_rcp_f32_e32 v135, v135
	v_fmac_f32_e32 v173, v134, v183
	v_mul_f32_e32 v131, 0xbfb8aa3b, v131
	v_max_f32_e32 v134, v13, v13
	v_exp_f32_e32 v131, v131
	v_med3_f32 v134, v134, s90, v170
	v_mul_f32_e32 v134, 0xbfb8aa3b, v134
	v_exp_f32_e32 v134, v134
	v_fmac_f32_e32 v172, v135, v187
	v_log_f32_e32 v135, v172
	v_add_f32_e32 v131, 1.0, v131
	v_max_f32_e32 v172, v2, v2
	v_rcp_f32_e32 v131, v131
	v_med3_f32 v172, v172, s90, v170
	v_add_f32_e32 v134, 1.0, v134
	v_mul_f32_e32 v172, 0xbfb8aa3b, v172
	v_rcp_f32_e32 v134, v134
	v_exp_f32_e32 v172, v172
	v_fmac_f32_e32 v161, v131, v157
	v_max_f32_e32 v157, v3, v3
	v_med3_f32 v157, v157, s90, v170
	v_fmac_f32_e32 v160, v134, v186
	v_add_f32_e32 v134, 1.0, v172
	v_mul_f32_e32 v157, 0xbfb8aa3b, v157
	v_rcp_f32_e32 v134, v134
	v_exp_f32_e32 v157, v157
	v_log_f32_e32 v131, v161
	v_max_f32_e32 v161, v5, v5
	v_fmac_f32_e32 v159, v134, v189
	v_add_f32_e32 v134, 1.0, v157
	v_max_f32_e32 v157, v4, v4
	v_med3_f32 v157, v157, s90, v170
	v_med3_f32 v161, v161, s90, v170
	v_mul_f32_e32 v157, 0xbfb8aa3b, v157
	v_mul_f32_e32 v161, 0xbfb8aa3b, v161
	v_rcp_f32_e32 v134, v134
	v_exp_f32_e32 v157, v157
	v_exp_f32_e32 v161, v161
	v_log_f32_e32 v130, v173
	v_fmac_f32_e32 v136, v134, v146
	v_add_f32_e32 v134, 1.0, v157
	v_add_f32_e32 v146, 1.0, v161
	v_rcp_f32_e32 v134, v134
	v_rcp_f32_e32 v146, v146
	v_log_f32_e32 v160, v160
	v_log_f32_e32 v159, v159
	v_fmac_f32_e32 v137, v134, v184
	v_fmac_f32_e32 v158, v146, v188
	v_log_f32_e32 v136, v136
	v_log_f32_e32 v137, v137
	v_log_f32_e32 v146, v158
	v_cvt_pk_bf16_f32 v134, v130, v135
	v_cvt_pk_bf16_f32 v135, v131, v160
	v_cvt_pk_bf16_f32 v136, v159, v136
	v_cvt_pk_bf16_f32 v137, v137, v146
	global_store_dwordx4 v[132:133], v[134:137], off offset:256 sc1

; __device__ __forceinline__ float bf_lo(unsigned w) { return __uint_as_float(w << 16); }
; __device__ __forceinline__ float bf_hi(unsigned w) { return __uint_as_float(w & 0xffff0000u); }
; #define GAS __attribute__((address_space(1)))
; __device__ __forceinline__ unsigned pk2(float lo, float hi) { return f2bf(lo) | (f2bf(hi) << 16); }
; template <int W>
; __device__ __forceinline__ void pool_item(const bf16* Z, bf16* P, int t4, int c8) {
;     v4u rows[W + 3];
; #pragma unroll
;     for (int i = 0; i < W + 3; ++i) { const int t = t4 - (W - 1) + i; rows[i] = (t >= 0) ? *(const GAS v4u*)(Z + (size_t)t * PW + c8) : (v4u){0u, 0u, 0u, 0u}; }
;     float s[8];
; #pragma unroll
;     for (int j = 0; j < 8; ++j) s[j] = 0.f;
; #pragma unroll
;     for (int i = 0; i < W - 1; ++i) { const v4u q = rows[i];
;         s[0] += pg8::bf_lo(q.x); s[1] += pg8::bf_hi(q.x); s[2] += pg8::bf_lo(q.y); s[3] += pg8::bf_hi(q.y); s[4] += pg8::bf_lo(q.z); s[5] += pg8::bf_hi(q.z); s[6] += pg8::bf_lo(q.w); s[7] += pg8::bf_hi(q.w); }
; #pragma unroll
;     for (int r = 0; r < 4; ++r) {
;         const v4u q = rows[W - 1 + r]; const float z[8] = {pg8::bf_lo(q.x), pg8::bf_hi(q.x), pg8::bf_lo(q.y), pg8::bf_hi(q.y), pg8::bf_lo(q.z), pg8::bf_hi(q.z), pg8::bf_lo(q.w), pg8::bf_hi(q.w)};
; #pragma unroll
;         for (int j = 0; j < 8; ++j) s[j] += z[j];
;         const int t = t4 + r; const float inv = 1.0f / (float)(t + 1 < W ? t + 1 : W);
;         v4u o; o.x = pk2(s[0] * inv - z[0], s[1] * inv - z[1]); o.y = pk2(s[2] * inv - z[2], s[3] * inv - z[3]); o.z = pk2(s[4] * inv - z[4], s[5] * inv - z[5]); o.w = pk2(s[6] * inv - z[6], s[7] * inv - z[7]);
.LBB0_284:
	s_min_i32 s1, s8, 3
	s_add_i32 s1, s1, 1
	s_waitcnt vmcnt(0)
	v_lshlrev_b32_e32 v42, 16, v22
	v_and_b32_e32 v43, 0xffff0000, v22
	v_cvt_f32_i32_e32 v22, s1
	v_lshlrev_b32_e32 v44, 16, v23
	v_and_b32_e32 v45, 0xffff0000, v23
	v_lshlrev_b32_e32 v46, 16, v24
	v_div_scale_f32 v23, s[18:19], v22, v22, 1.0
	v_rcp_f32_e32 v30, v23
	v_and_b32_e32 v47, 0xffff0000, v24
	v_lshlrev_b32_e32 v36, 16, v26
	v_and_b32_e32 v37, 0xffff0000, v26
	v_fma_f32 v24, -v23, v30, 1.0
	v_fmac_f32_e32 v30, v24, v30
	v_div_scale_f32 v24, vcc, 1.0, v22, 1.0
	v_lshlrev_b32_e32 v38, 16, v27
	v_and_b32_e32 v39, 0xffff0000, v27
	v_lshlrev_b32_e32 v40, 16, v28
	v_and_b32_e32 v41, 0xffff0000, v28
	v_lshlrev_b32_e32 v26, 16, v29
	v_and_b32_e32 v27, 0xffff0000, v29
	v_lshlrev_b32_e32 v28, 16, v25
	v_and_b32_e32 v29, 0xffff0000, v25
	v_mul_f32_e32 v25, v24, v30
	s_min_i32 s1, s0, 3
	v_fma_f32 v31, -v23, v25, v24
	s_add_i32 s1, s1, 1
	v_fmac_f32_e32 v25, v31, v30
	v_cvt_f32_i32_e32 v31, s1
	v_fma_f32 v23, -v23, v25, v24
	v_div_fmas_f32 v23, v23, v30, v25
	v_div_fixup_f32 v34, v23, v22, 1.0
	v_div_scale_f32 v22, s[18:19], v31, v31, 1.0
	v_rcp_f32_e32 v23, v22
	s_min_i32 s1, s4, 3
	s_add_i32 s1, s1, 1
	s_ashr_i32 s9, s8, 31
	v_fma_f32 v30, -v22, v23, 1.0
	v_fmac_f32_e32 v23, v30, v23
	v_div_scale_f32 v30, vcc, 1.0, v31, 1.0
	v_mul_f32_e32 v32, v30, v23
	v_fma_f32 v33, -v22, v32, v30
	v_fmac_f32_e32 v32, v33, v23
	v_cvt_f32_i32_e32 v33, s1
	v_fma_f32 v22, -v22, v32, v30
	s_lshl_b64 s[8:9], s[8:9], 12
	v_div_fmas_f32 v22, v22, v23, v32
	v_lshl_add_u64 v[24:25], v[80:81], 0, s[8:9]
	v_div_fixup_f32 v48, v22, v31, 1.0
	v_div_scale_f32 v22, s[8:9], v33, v33, 1.0
	v_rcp_f32_e32 v23, v22
	v_pk_add_f32 v[62:63], v[38:39], 0 op_sel_hi:[1,0]
	v_lshlrev_b32_e32 v52, 16, v2
	v_and_b32_e32 v53, 0xffff0000, v2
	v_fma_f32 v32, -v22, v23, 1.0
	v_fmac_f32_e32 v23, v32, v23
	v_div_scale_f32 v32, vcc, 1.0, v33, 1.0
	v_mul_f32_e32 v35, v32, v23
	v_fma_f32 v49, -v22, v35, v32
	v_fmac_f32_e32 v35, v49, v23
	v_fma_f32 v22, -v22, v35, v32
	v_div_fmas_f32 v22, v22, v23, v35
	v_div_fixup_f32 v50, v22, v33, 1.0
	v_pk_add_f32 v[22:23], v[36:37], 0 op_sel_hi:[1,0]
	v_pk_add_f32 v[62:63], v[62:63], v[44:45]
	v_pk_add_f32 v[22:23], v[22:23], v[42:43]
	v_lshlrev_b32_e32 v2, 16, v3
	v_and_b32_e32 v3, 0xffff0000, v3
	v_pk_add_f32 v[22:23], v[22:23], v[52:53]
	v_lshlrev_b32_e32 v54, 16, v10
	v_and_b32_e32 v55, 0xffff0000, v10
	v_pk_add_f32 v[62:63], v[62:63], v[2:3]
	v_lshlrev_b32_e32 v10, 16, v11
	v_and_b32_e32 v11, 0xffff0000, v11
	v_pk_add_f32 v[56:57], v[22:23], v[54:55]
	v_pk_add_f32 v[62:63], v[62:63], v[10:11]
	v_pk_add_f32 v[22:23], v[56:57], v[36:37] neg_lo:[0,1] neg_hi:[0,1]
	v_mov_b32_e32 v64, v56
	v_mov_b32_e32 v67, v10
	v_mov_b32_e32 v56, v57
	v_mov_b32_e32 v57, v63
	v_mov_b32_e32 v10, v55
	v_lshlrev_b32_e32 v36, 16, v18
	v_and_b32_e32 v37, 0xffff0000, v18
	v_mov_b32_e32 v66, v54
	v_pk_fma_f32 v[54:55], v[34:35], v[56:57], v[10:11] op_sel_hi:[0,1,1] neg_lo:[0,0,1] neg_hi:[0,0,1]
	v_pk_add_f32 v[10:11], v[62:63], v[38:39] neg_lo:[0,1] neg_hi:[0,1]
	v_lshlrev_b32_e32 v18, 16, v19
	v_and_b32_e32 v19, 0xffff0000, v19
	v_pk_add_f32 v[58:59], v[22:23], v[36:37]
	v_pk_add_f32 v[38:39], v[10:11], v[18:19]
	v_mov_b32_e32 v10, v58
	v_mov_b32_e32 v11, v38
	v_mov_b32_e32 v56, v36
	v_mov_b32_e32 v57, v18
	v_pk_fma_f32 v[10:11], v[48:49], v[10:11], v[56:57] op_sel_hi:[0,1,1] neg_lo:[0,0,1] neg_hi:[0,0,1]
	v_mov_b32_e32 v56, v59
	v_mov_b32_e32 v57, v39
	v_mov_b32_e32 v18, v37
	v_pk_add_f32 v[22:23], v[58:59], v[42:43] neg_lo:[0,1] neg_hi:[0,1]
	v_lshlrev_b32_e32 v42, 16, v6
	v_and_b32_e32 v43, 0xffff0000, v6
	v_pk_fma_f32 v[18:19], v[48:49], v[56:57], v[18:19] op_sel_hi:[0,1,1] neg_lo:[0,0,1] neg_hi:[0,0,1]
	v_and_b32_sdwa v6, v11, v85 dst_sel:DWORD dst_unused:UNUSED_PAD src0_sel:WORD_1 src1_sel:DWORD
	v_add3_u32 v6, v11, v6, s22
	v_and_b32_sdwa v11, v19, v85 dst_sel:DWORD dst_unused:UNUSED_PAD src0_sel:WORD_1 src1_sel:DWORD
	v_pk_add_f32 v[60:61], v[22:23], v[42:43]
	v_lshlrev_b32_e32 v22, 16, v14
	v_and_b32_e32 v23, 0xffff0000, v14
	v_and_b32_sdwa v14, v10, v85 dst_sel:DWORD dst_unused:UNUSED_PAD src0_sel:WORD_1 src1_sel:DWORD
	v_add3_u32 v11, v19, v11, s22
	v_add3_u32 v10, v10, v14, s22
	v_and_b32_sdwa v14, v18, v85 dst_sel:DWORD dst_unused:UNUSED_PAD src0_sel:WORD_1 src1_sel:DWORD
	v_and_b32_e32 v11, 0xffff0000, v11
	v_add3_u32 v14, v18, v14, s22
	v_or_b32_sdwa v11, v11, v6 dst_sel:DWORD dst_unused:UNUSED_PAD src0_sel:DWORD src1_sel:WORD_1
	v_pk_add_f32 v[18:19], v[38:39], v[44:45] neg_lo:[0,1] neg_hi:[0,1]
	v_lshlrev_b32_e32 v6, 16, v7
	v_and_b32_e32 v7, 0xffff0000, v7
	v_pk_add_f32 v[36:37], v[18:19], v[6:7]
	v_mov_b32_e32 v18, v60
	v_mov_b32_e32 v19, v36
	v_mov_b32_e32 v38, v42
	v_mov_b32_e32 v39, v6
	v_mov_b32_e32 v65, v62
	v_and_b32_e32 v14, 0xffff0000, v14
	v_pk_fma_f32 v[18:19], v[50:51], v[18:19], v[38:39] op_sel_hi:[0,1,1] neg_lo:[0,0,1] neg_hi:[0,0,1]
	v_mov_b32_e32 v38, v61
	v_mov_b32_e32 v39, v37
	v_mov_b32_e32 v6, v43
	v_pk_fma_f32 v[64:65], v[34:35], v[64:65], v[66:67] op_sel_hi:[0,1,1] neg_lo:[0,0,1] neg_hi:[0,0,1]
	v_or_b32_sdwa v10, v14, v10 dst_sel:DWORD dst_unused:UNUSED_PAD src0_sel:DWORD src1_sel:WORD_1
	v_pk_fma_f32 v[6:7], v[50:51], v[38:39], v[6:7] op_sel_hi:[0,1,1] neg_lo:[0,0,1] neg_hi:[0,0,1]
	v_and_b32_sdwa v14, v19, v85 dst_sel:DWORD dst_unused:UNUSED_PAD src0_sel:WORD_1 src1_sel:DWORD
	v_and_b32_sdwa v35, v18, v85 dst_sel:DWORD dst_unused:UNUSED_PAD src0_sel:WORD_1 src1_sel:DWORD
	v_add3_u32 v18, v18, v35, s22
	v_add3_u32 v14, v19, v14, s22
; __device__ __forceinline__ float bf_lo(unsigned w) { return __uint_as_float(w << 16); }
; __device__ __forceinline__ float bf_hi(unsigned w) { return __uint_as_float(w & 0xffff0000u); }
; #define GAS __attribute__((address_space(1)))
; __device__ __forceinline__ unsigned pk2(float lo, float hi) { return f2bf(lo) | (f2bf(hi) << 16); }
; template <int W>
; __device__ __forceinline__ void pool_item(const bf16* Z, bf16* P, int t4, int c8) {
;     ...
;     for (int i = 0; i < W - 1; ++i) { const v4u q = rows[i];
;         s[0] += pg8::bf_lo(q.x); s[1] += pg8::bf_hi(q.x); s[2] += pg8::bf_lo(q.y); s[3] += pg8::bf_hi(q.y); s[4] += pg8::bf_lo(q.z); s[5] += pg8::bf_hi(q.z); s[6] += pg8::bf_lo(q.w); s[7] += pg8::bf_hi(q.w); }
; #pragma unroll
;     for (int r = 0; r < 4; ++r) {
;         const v4u q = rows[W - 1 + r]; const float z[8] = {pg8::bf_lo(q.x), pg8::bf_hi(q.x), pg8::bf_lo(q.y), pg8::bf_hi(q.y), pg8::bf_lo(q.z), pg8::bf_hi(q.z), pg8::bf_lo(q.w), pg8::bf_hi(q.w)};
; #pragma unroll
;         for (int j = 0; j < 8; ++j) s[j] += z[j];
;         const int t = t4 + r; const float inv = 1.0f / (float)(t + 1 < W ? t + 1 : W);
;         v4u o; o.x = pk2(s[0] * inv - z[0], s[1] * inv - z[1]); o.y = pk2(s[2] * inv - z[2], s[3] * inv - z[3]); o.z = pk2(s[4] * inv - z[4], s[5] * inv - z[5]); o.w = pk2(s[6] * inv - z[6], s[7] * inv - z[7]);
;         *(GAS v4u*)(P + (size_t)t * PW + c8) = o;
;         const v4u d = rows[r];
;         s[0] -= pg8::bf_lo(d.x); s[1] -= pg8::bf_hi(d.x); s[2] -= pg8::bf_lo(d.y); s[3] -= pg8::bf_hi(d.y); s[4] -= pg8::bf_lo(d.z); s[5] -= pg8::bf_hi(d.z); s[6] -= pg8::bf_lo(d.w); s[7] -= pg8::bf_hi(d.w);
;     }
	v_and_b32_sdwa v19, v7, v85 dst_sel:DWORD dst_unused:UNUSED_PAD src0_sel:WORD_1 src1_sel:DWORD
	v_and_b32_sdwa v35, v6, v85 dst_sel:DWORD dst_unused:UNUSED_PAD src0_sel:WORD_1 src1_sel:DWORD
	v_add3_u32 v7, v7, v19, s22
	v_add3_u32 v6, v6, v35, s22
	v_and_b32_e32 v7, 0xffff0000, v7
	v_and_b32_e32 v6, 0xffff0000, v6
	v_pk_add_f32 v[36:37], v[36:37], v[2:3] neg_lo:[0,1] neg_hi:[0,1]
	v_pk_add_f32 v[2:3], v[40:41], 0 op_sel_hi:[1,0]
	v_or_b32_sdwa v19, v7, v14 dst_sel:DWORD dst_unused:UNUSED_PAD src0_sel:DWORD src1_sel:WORD_1
	v_or_b32_sdwa v18, v6, v18 dst_sel:DWORD dst_unused:UNUSED_PAD src0_sel:DWORD src1_sel:WORD_1
	v_lshlrev_b32_e32 v6, 16, v15
	v_and_b32_e32 v7, 0xffff0000, v15
	v_pk_add_f32 v[2:3], v[2:3], v[46:47]
	v_lshlrev_b32_e32 v14, 16, v4
	v_and_b32_e32 v15, 0xffff0000, v4
	v_pk_add_f32 v[2:3], v[2:3], v[14:15]
	v_lshlrev_b32_e32 v38, 16, v12
	v_and_b32_e32 v39, 0xffff0000, v12
	v_pk_add_f32 v[42:43], v[2:3], v[38:39]
	v_lshlrev_b32_e32 v44, 16, v13
	v_pk_add_f32 v[2:3], v[42:43], v[40:41] neg_lo:[0,1] neg_hi:[0,1]
	v_lshlrev_b32_e32 v40, 16, v20
	v_and_b32_e32 v41, 0xffff0000, v20
	v_pk_add_f32 v[2:3], v[2:3], v[40:41]
	v_and_b32_e32 v45, 0xffff0000, v13
	v_pk_fma_f32 v[40:41], v[48:49], v[2:3], v[40:41] op_sel_hi:[0,1,1] neg_lo:[0,0,1] neg_hi:[0,0,1]
	v_and_b32_sdwa v4, v41, v85 dst_sel:DWORD dst_unused:UNUSED_PAD src0_sel:WORD_1 src1_sel:DWORD
	v_and_b32_sdwa v12, v40, v85 dst_sel:DWORD dst_unused:UNUSED_PAD src0_sel:WORD_1 src1_sel:DWORD
	v_add3_u32 v4, v41, v4, s22
	v_add3_u32 v12, v40, v12, s22
	v_pk_add_f32 v[2:3], v[2:3], v[46:47] neg_lo:[0,1] neg_hi:[0,1]
	v_lshlrev_b32_e32 v40, 16, v8
	v_and_b32_e32 v41, 0xffff0000, v8
	v_pk_add_f32 v[2:3], v[2:3], v[40:41]
	v_lshrrev_b32_e32 v12, 16, v12
	v_pk_fma_f32 v[40:41], v[50:51], v[2:3], v[40:41] op_sel_hi:[0,1,1] neg_lo:[0,0,1] neg_hi:[0,0,1]
	v_and_b32_sdwa v8, v40, v85 dst_sel:DWORD dst_unused:UNUSED_PAD src0_sel:WORD_1 src1_sel:DWORD
	v_and_or_b32 v12, v4, s21, v12
	v_and_b32_sdwa v4, v41, v85 dst_sel:DWORD dst_unused:UNUSED_PAD src0_sel:WORD_1 src1_sel:DWORD
	v_add3_u32 v8, v40, v8, s22
	v_add3_u32 v4, v41, v4, s22
	v_lshrrev_b32_e32 v8, 16, v8
	v_pk_add_f32 v[40:41], v[2:3], v[14:15] neg_lo:[0,1] neg_hi:[0,1]
	v_pk_add_f32 v[14:15], v[26:27], 0 op_sel_hi:[1,0]
	v_and_or_b32 v20, v4, s21, v8
	v_pk_add_f32 v[14:15], v[14:15], v[28:29]
	v_lshlrev_b32_e32 v4, 16, v5
	v_and_b32_e32 v5, 0xffff0000, v5
	v_pk_add_f32 v[14:15], v[14:15], v[4:5]
	v_mov_b32_e32 v46, v42
	v_pk_add_f32 v[14:15], v[14:15], v[44:45]
	v_mov_b32_e32 v42, v43
	v_mov_b32_e32 v47, v14
	v_mov_b32_e32 v43, v15
	v_pk_add_f32 v[14:15], v[14:15], v[26:27] neg_lo:[0,1] neg_hi:[0,1]
	v_lshlrev_b32_e32 v26, 16, v21
	v_and_b32_e32 v27, 0xffff0000, v21
	v_pk_add_f32 v[14:15], v[14:15], v[26:27]
	v_mov_b32_e32 v56, v38
	v_pk_fma_f32 v[26:27], v[48:49], v[14:15], v[26:27] op_sel_hi:[0,1,1] neg_lo:[0,0,1] neg_hi:[0,0,1]
	v_and_b32_sdwa v13, v26, v85 dst_sel:DWORD dst_unused:UNUSED_PAD src0_sel:WORD_1 src1_sel:DWORD
	v_and_b32_sdwa v8, v27, v85 dst_sel:DWORD dst_unused:UNUSED_PAD src0_sel:WORD_1 src1_sel:DWORD
	v_add3_u32 v13, v26, v13, s22
	v_add3_u32 v8, v27, v8, s22
	v_lshrrev_b32_e32 v13, 16, v13
	v_and_or_b32 v13, v8, s21, v13
	v_pk_add_f32 v[14:15], v[14:15], v[28:29] neg_lo:[0,1] neg_hi:[0,1]
	v_lshlrev_b32_e32 v8, 16, v9
	v_and_b32_e32 v9, 0xffff0000, v9
	v_pk_add_f32 v[14:15], v[14:15], v[8:9]
	v_mov_b32_e32 v57, v44
	v_pk_fma_f32 v[8:9], v[50:51], v[14:15], v[8:9] op_sel_hi:[0,1,1] neg_lo:[0,0,1] neg_hi:[0,0,1]
	v_and_b32_sdwa v21, v8, v85 dst_sel:DWORD dst_unused:UNUSED_PAD src0_sel:WORD_1 src1_sel:DWORD
	v_lshlrev_b32_e32 v2, 16, v16
	v_and_b32_e32 v3, 0xffff0000, v16
	v_pk_fma_f32 v[46:47], v[34:35], v[46:47], v[56:57] op_sel_hi:[0,1,1] neg_lo:[0,0,1] neg_hi:[0,0,1]
	v_mov_b32_e32 v44, v39
	v_and_b32_sdwa v16, v9, v85 dst_sel:DWORD dst_unused:UNUSED_PAD src0_sel:WORD_1 src1_sel:DWORD
	v_add3_u32 v8, v8, v21, s22
	v_pk_fma_f32 v[34:35], v[34:35], v[42:43], v[44:45] op_sel_hi:[0,1,1] neg_lo:[0,0,1] neg_hi:[0,0,1]
	v_add3_u32 v9, v9, v16, s22
	v_lshrrev_b32_e32 v8, 16, v8
	v_bfe_u32 v16, v64, 16, 1
	v_bfe_u32 v26, v65, 16, 1
	v_bfe_u32 v27, v46, 16, 1
	v_bfe_u32 v28, v47, 16, 1
	s_ashr_i32 s1, s0, 31
	v_and_or_b32 v21, v9, s21, v8
	v_pk_add_f32 v[4:5], v[14:15], v[4:5] neg_lo:[0,1] neg_hi:[0,1]
	v_bfe_u32 v8, v35, 16, 1
	v_bfe_u32 v9, v34, 16, 1
	v_bfe_u32 v14, v55, 16, 1
	v_bfe_u32 v15, v54, 16, 1
	v_add3_u32 v28, v47, v28, s22
	v_add3_u32 v27, v46, v27, s22
	v_add3_u32 v26, v65, v26, s22
	v_add3_u32 v16, v64, v16, s22
	s_lshl_b64 s[0:1], s[0:1], 12
	s_ashr_i32 s5, s4, 31
	v_add3_u32 v15, v54, v15, s22
	v_add3_u32 v14, v55, v14, s22
	v_add3_u32 v9, v34, v9, s22
	v_add3_u32 v8, v35, v8, s22
	v_lshrrev_b32_e32 v16, 16, v16
	v_lshrrev_b32_e32 v26, 16, v26
	v_lshrrev_b32_e32 v27, 16, v27
	v_lshrrev_b32_e32 v28, 16, v28
	v_lshl_add_u64 v[30:31], v[80:81], 0, s[0:1]
	s_lshl_b64 s[0:1], s[4:5], 12
	v_and_or_b32 v29, v8, s21, v28
	v_and_or_b32 v28, v9, s21, v27
	v_and_or_b32 v27, v14, s21, v26
	v_and_or_b32 v26, v15, s21, v16
	v_lshl_add_u64 v[32:33], v[80:81], 0, s[0:1]
	v_pk_add_f32 v[52:53], v[60:61], v[52:53] neg_lo:[0,1] neg_hi:[0,1]
	global_store_dwordx4 v[24:25], v[26:29], off sc1
	global_store_dwordx4 v[30:31], v[10:13], off sc1
	global_store_dwordx4 v[32:33], v[18:21], off sc1
	s_min_i32 s0, s6, 3
	v_pk_add_f32 v[14:15], v[36:37], v[6:7]
	v_lshlrev_b32_e32 v18, 16, v17
	v_and_b32_e32 v19, 0xffff0000, v17
	v_pk_add_f32 v[16:17], v[52:53], v[22:23]
	v_pk_add_f32 v[12:13], v[40:41], v[2:3]
	v_pk_add_f32 v[8:9], v[4:5], v[18:19]
	v_mov_b32_e32 v5, s0
	v_mov_b32_e32 v4, s6

; __device__ __forceinline__ float bf_lo(unsigned w) { return __uint_as_float(w << 16); }
; __device__ __forceinline__ float bf_hi(unsigned w) { return __uint_as_float(w & 0xffff0000u); }
; #define GAS __attribute__((address_space(1)))
; __device__ __forceinline__ unsigned pk2(float lo, float hi) { return f2bf(lo) | (f2bf(hi) << 16); }
; template <int W>
; __device__ __forceinline__ void pool_item(const bf16* Z, bf16* P, int t4, int c8) {
;     ...
;     for (int r = 0; r < 4; ++r) {
;         const v4u q = rows[W - 1 + r]; const float z[8] = {pg8::bf_lo(q.x), pg8::bf_hi(q.x), pg8::bf_lo(q.y), pg8::bf_hi(q.y), pg8::bf_lo(q.z), pg8::bf_hi(q.z), pg8::bf_lo(q.w), pg8::bf_hi(q.w)};
; #pragma unroll
;         for (int j = 0; j < 8; ++j) s[j] += z[j];
;         const int t = t4 + r; const float inv = 1.0f / (float)(t + 1 < W ? t + 1 : W);
;         v4u o; o.x = pk2(s[0] * inv - z[0], s[1] * inv - z[1]); o.y = pk2(s[2] * inv - z[2], s[3] * inv - z[3]); o.z = pk2(s[4] * inv - z[4], s[5] * inv - z[5]); o.w = pk2(s[6] * inv - z[6], s[7] * inv - z[7]);
;         *(GAS v4u*)(P + (size_t)t * PW + c8) = o;
;         const v4u d = rows[r];
;         s[0] -= pg8::bf_lo(d.x); s[1] -= pg8::bf_hi(d.x); s[2] -= pg8::bf_lo(d.y); s[3] -= pg8::bf_hi(d.y); s[4] -= pg8::bf_lo(d.z); s[5] -= pg8::bf_hi(d.z); s[6] -= pg8::bf_lo(d.w); s[7] -= pg8::bf_hi(d.w);
;     }
; __global__ void __launch_bounds__(NWAVES * 64, 2) fwd(Args args) {
;     ...
;         for (int it = gw; it < (T / 4) * 4; it += NGW) {
;             const int t4 = (it >> 2) * 4, gi = it & 3, c8 = gi * 512 + F.lane * 8;
;             if (gi == 0) pool_item<2>(Zb, Pb, t4, c8); else if (gi == 1) pool_item<4>(Zb, Pb, t4, c8); else if (gi == 2) pool_item<8>(Zb, Pb, t4, c8); else pool_item<16>(Zb, Pb, t4, c8);
;         }
.LBB0_286:
	v_add_u32_e32 v5, 1, v5
	v_cvt_f32_i32_e32 v5, v5
	v_mov_b32_e32 v18, v16
	s_add_i32 s23, s23, s82
	s_cmpk_gt_i32 s23, 0x1fff
	v_div_scale_f32 v19, s[0:1], v5, v5, 1.0
	v_rcp_f32_e32 v20, v19
	v_div_scale_f32 v16, vcc, 1.0, v5, 1.0
	v_fma_f32 v21, -v19, v20, 1.0
	v_fmac_f32_e32 v20, v21, v20
	v_mul_f32_e32 v21, v16, v20
	v_fma_f32 v24, -v19, v21, v16
	v_fmac_f32_e32 v21, v24, v20
	v_fma_f32 v16, -v19, v21, v16
	v_div_fmas_f32 v16, v16, v20, v21
	v_div_fixup_f32 v16, v16, v5, 1.0
	v_mov_b32_e32 v19, v14
	v_mov_b32_e32 v14, v17
	v_pk_fma_f32 v[10:11], v[16:17], v[14:15], v[10:11] op_sel_hi:[0,1,1] neg_lo:[0,0,1] neg_hi:[0,0,1]
	v_mov_b32_e32 v14, v12
	v_mov_b32_e32 v15, v8
	v_pk_fma_f32 v[2:3], v[16:17], v[14:15], v[2:3] op_sel_hi:[0,1,1] neg_lo:[0,0,1] neg_hi:[0,0,1]
	v_mov_b32_e32 v8, v13
	v_bfe_u32 v12, v10, 16, 1
	v_pk_fma_f32 v[6:7], v[16:17], v[8:9], v[6:7] op_sel_hi:[0,1,1] neg_lo:[0,0,1] neg_hi:[0,0,1]
	v_bfe_u32 v9, v11, 16, 1
	v_add3_u32 v10, v10, v12, s22
	v_bfe_u32 v12, v3, 16, 1
	v_pk_fma_f32 v[18:19], v[16:17], v[18:19], v[22:23] op_sel_hi:[0,1,1] neg_lo:[0,0,1] neg_hi:[0,0,1]
	v_bfe_u32 v5, v7, 16, 1
	v_bfe_u32 v8, v6, 16, 1
	v_add3_u32 v11, v11, v9, s22
	v_bfe_u32 v9, v2, 16, 1
	v_add3_u32 v3, v3, v12, s22
	v_add3_u32 v6, v6, v8, s22
	v_add3_u32 v5, v7, v5, s22
	v_bfe_u32 v7, v18, 16, 1
	v_bfe_u32 v8, v19, 16, 1
	v_add3_u32 v2, v2, v9, s22
	v_lshrrev_b32_e32 v3, 16, v3
	v_add3_u32 v8, v19, v8, s22
	v_add3_u32 v7, v18, v7, s22
	v_lshrrev_b32_e32 v2, 16, v2
	v_and_or_b32 v9, v5, s21, v3
	v_ashrrev_i32_e32 v5, 31, v4
	v_lshrrev_b32_e32 v12, 16, v7
	v_lshrrev_b32_e32 v7, 16, v8
	v_and_or_b32 v8, v6, s21, v2
	v_lshlrev_b64 v[2:3], 12, v[4:5]
	v_and_or_b32 v7, v11, s21, v7
	v_and_or_b32 v6, v10, s21, v12
	v_lshl_add_u64 v[2:3], v[80:81], 0, v[2:3]
	global_store_dwordx4 v[2:3], v[6:9], off sc1
	s_cbranch_scc1 .LBB0_387

; __device__ __forceinline__ float bf_lo(unsigned w) { return __uint_as_float(w << 16); }
; __device__ __forceinline__ float bf_hi(unsigned w) { return __uint_as_float(w & 0xffff0000u); }
; #define GAS __attribute__((address_space(1)))
; template <int W>
; __device__ __forceinline__ void pool_item(const bf16* Z, bf16* P, int t4, int c8) {
;     v4u rows[W + 3];
; #pragma unroll
;     for (int i = 0; i < W + 3; ++i) { const int t = t4 - (W - 1) + i; rows[i] = (t >= 0) ? *(const GAS v4u*)(Z + (size_t)t * PW + c8) : (v4u){0u, 0u, 0u, 0u}; }
;     float s[8];
; #pragma unroll
;     for (int j = 0; j < 8; ++j) s[j] = 0.f;
; #pragma unroll
;     for (int i = 0; i < W - 1; ++i) { const v4u q = rows[i];
;         s[0] += pg8::bf_lo(q.x); s[1] += pg8::bf_hi(q.x); s[2] += pg8::bf_lo(q.y); s[3] += pg8::bf_hi(q.y); s[4] += pg8::bf_lo(q.z); s[5] += pg8::bf_hi(q.z); s[6] += pg8::bf_lo(q.w); s[7] += pg8::bf_hi(q.w); }
; #pragma unroll
;     for (int r = 0; r < 4; ++r) {
;         const v4u q = rows[W - 1 + r]; const float z[8] = {pg8::bf_lo(q.x), pg8::bf_hi(q.x), pg8::bf_lo(q.y), pg8::bf_hi(q.y), pg8::bf_lo(q.z), pg8::bf_hi(q.z), pg8::bf_lo(q.w), pg8::bf_hi(q.w)};
; #pragma unroll
;         for (int j = 0; j < 8; ++j) s[j] += z[j];
.LBB0_330:
	s_min_i32 s1, s8, 15
	s_add_i32 s1, s1, 1
	s_waitcnt vmcnt(0)
	v_lshlrev_b32_e32 v88, 16, v66
	v_and_b32_e32 v89, 0xffff0000, v66
	v_cvt_f32_i32_e32 v66, s1
	v_lshlrev_b32_e32 v98, 16, v67
	v_and_b32_e32 v99, 0xffff0000, v67
	v_lshlrev_b32_e32 v92, 16, v68
	v_div_scale_f32 v67, s[18:19], v66, v66, 1.0
	v_and_b32_e32 v93, 0xffff0000, v68
	v_rcp_f32_e32 v68, v67
	v_lshlrev_b32_e32 v82, 16, v69
	v_and_b32_e32 v83, 0xffff0000, v69
	v_lshlrev_b32_e32 v102, 16, v70
	v_fma_f32 v69, -v67, v68, 1.0
	v_fmac_f32_e32 v68, v69, v68
	v_div_scale_f32 v69, vcc, 1.0, v66, 1.0
	v_and_b32_e32 v103, 0xffff0000, v70
	v_mul_f32_e32 v70, v69, v68
	v_lshlrev_b32_e32 v104, 16, v71
	v_and_b32_e32 v105, 0xffff0000, v71
	v_fma_f32 v71, -v67, v70, v69
	s_min_i32 s1, s0, 15
	v_fmac_f32_e32 v70, v71, v68
	s_add_i32 s1, s1, 1
	v_fma_f32 v67, -v67, v70, v69
	v_cvt_f32_i32_e32 v69, s1
	v_div_fmas_f32 v67, v67, v68, v70
	v_lshlrev_b32_e32 v90, 16, v74
	v_and_b32_e32 v91, 0xffff0000, v74
	v_div_scale_f32 v68, s[18:19], v69, v69, 1.0
	v_rcp_f32_e32 v70, v68
	v_lshlrev_b32_e32 v100, 16, v75
	v_and_b32_e32 v101, 0xffff0000, v75
	v_lshlrev_b32_e32 v74, 16, v77
	v_fma_f32 v71, -v68, v70, 1.0
	v_fmac_f32_e32 v70, v71, v70
	v_div_scale_f32 v71, vcc, 1.0, v69, 1.0
	v_and_b32_e32 v75, 0xffff0000, v77
	v_mul_f32_e32 v77, v71, v70
	v_fma_f32 v84, -v68, v77, v71
	s_min_i32 s1, s4, 15
	v_fmac_f32_e32 v77, v84, v70
	s_add_i32 s1, s1, 1
	v_fma_f32 v68, -v68, v77, v71
	v_cvt_f32_i32_e32 v71, s1
	s_ashr_i32 s9, s8, 31
	s_lshl_b64 s[18:19], s[8:9], 12
	v_lshlrev_b32_e32 v94, 16, v76
	v_and_b32_e32 v95, 0xffff0000, v76
	v_div_fixup_f32 v76, v67, v66, 1.0
	v_lshl_add_u64 v[66:67], v[80:81], 0, s[18:19]
	v_div_fmas_f32 v68, v68, v70, v77
	v_div_scale_f32 v70, s[18:19], v71, v71, 1.0
	v_rcp_f32_e32 v77, v70
	v_and_b32_e32 v107, 0xffff0000, v6
	v_lshlrev_b32_e32 v108, 16, v2
	v_and_b32_e32 v109, 0xffff0000, v2
	v_fma_f32 v86, -v70, v77, 1.0
	v_fmac_f32_e32 v77, v86, v77
	v_div_scale_f32 v86, vcc, 1.0, v71, 1.0
	v_mul_f32_e32 v87, v86, v77
	v_fma_f32 v106, -v70, v87, v86
	v_fmac_f32_e32 v87, v106, v77
	v_lshlrev_b32_e32 v106, 16, v6
	v_pk_add_f32 v[128:129], v[106:107], 0 op_sel_hi:[1,0]
	v_lshlrev_b32_e32 v110, 16, v14
	v_and_b32_e32 v111, 0xffff0000, v14
	v_pk_add_f32 v[128:129], v[128:129], v[108:109]
	v_lshlrev_b32_e32 v112, 16, v10
	v_and_b32_e32 v113, 0xffff0000, v10
	v_pk_add_f32 v[128:129], v[128:129], v[110:111]
	v_lshlrev_b32_e32 v114, 16, v22
	v_and_b32_e32 v115, 0xffff0000, v22
	v_pk_add_f32 v[112:113], v[128:129], v[112:113]
	v_lshlrev_b32_e32 v116, 16, v18
	v_and_b32_e32 v117, 0xffff0000, v18
	v_pk_add_f32 v[112:113], v[112:113], v[114:115]
	v_lshlrev_b32_e32 v118, 16, v30
	v_and_b32_e32 v119, 0xffff0000, v30
	v_pk_add_f32 v[112:113], v[112:113], v[116:117]
	v_lshlrev_b32_e32 v120, 16, v26
	v_and_b32_e32 v121, 0xffff0000, v26
	v_pk_add_f32 v[112:113], v[112:113], v[118:119]
	v_lshlrev_b32_e32 v122, 16, v38
	v_and_b32_e32 v123, 0xffff0000, v38
	v_pk_add_f32 v[112:113], v[112:113], v[120:121]
	v_lshlrev_b32_e32 v124, 16, v34
	v_and_b32_e32 v125, 0xffff0000, v34
	v_pk_add_f32 v[112:113], v[112:113], v[122:123]
	v_lshlrev_b32_e32 v126, 16, v42
	v_and_b32_e32 v127, 0xffff0000, v42
	v_pk_add_f32 v[112:113], v[112:113], v[124:125]
	v_lshlrev_b32_e32 v6, 16, v7
	v_pk_add_f32 v[112:113], v[112:113], v[126:127]
	v_and_b32_e32 v7, 0xffff0000, v7
	v_pk_add_f32 v[88:89], v[112:113], v[88:89]
	v_lshlrev_b32_e32 v2, 16, v11
	v_pk_add_f32 v[88:89], v[88:89], v[90:91]
	v_lshlrev_b32_e32 v90, 16, v46
	v_pk_add_f32 v[88:89], v[88:89], v[102:103]
	v_and_b32_e32 v91, 0xffff0000, v46
	v_pk_add_f32 v[88:89], v[88:89], v[90:91]
	v_lshlrev_b32_e32 v102, 16, v54
	v_and_b32_e32 v103, 0xffff0000, v54
	v_pk_add_f32 v[112:113], v[88:89], v[102:103]
	v_lshlrev_b32_e32 v10, 16, v23
	v_pk_add_f32 v[88:89], v[112:113], v[106:107] neg_lo:[0,1] neg_hi:[0,1]
	v_lshlrev_b32_e32 v106, 16, v62
	v_and_b32_e32 v107, 0xffff0000, v62
	v_pk_add_f32 v[114:115], v[88:89], v[106:107]
	v_lshlrev_b32_e32 v22, 16, v27
	v_pk_add_f32 v[88:89], v[114:115], v[108:109] neg_lo:[0,1] neg_hi:[0,1]
	v_lshlrev_b32_e32 v108, 16, v50
	v_and_b32_e32 v109, 0xffff0000, v50
	v_pk_add_f32 v[116:117], v[88:89], v[108:109]
	v_lshlrev_b32_e32 v26, 16, v39
	v_pk_add_f32 v[90:91], v[116:117], v[110:111] neg_lo:[0,1] neg_hi:[0,1]
	v_lshlrev_b32_e32 v110, 16, v3
	v_and_b32_e32 v111, 0xffff0000, v3
	v_and_b32_e32 v3, 0xffff0000, v11
	v_and_b32_e32 v11, 0xffff0000, v23
	v_and_b32_e32 v23, 0xffff0000, v27
	v_and_b32_e32 v27, 0xffff0000, v39
	v_pk_add_f32 v[38:39], v[6:7], 0 op_sel_hi:[1,0]
	v_lshlrev_b32_e32 v118, 16, v15
	v_and_b32_e32 v119, 0xffff0000, v15
	v_pk_add_f32 v[38:39], v[38:39], v[110:111]
	v_lshlrev_b32_e32 v14, 16, v19
	v_pk_add_f32 v[38:39], v[38:39], v[118:119]
	v_and_b32_e32 v15, 0xffff0000, v19
	v_pk_add_f32 v[2:3], v[38:39], v[2:3]
	v_lshlrev_b32_e32 v18, 16, v31
	v_pk_add_f32 v[2:3], v[2:3], v[10:11]
	v_and_b32_e32 v19, 0xffff0000, v31
	v_pk_add_f32 v[2:3], v[2:3], v[14:15]
	v_lshlrev_b32_e32 v30, 16, v35
	v_pk_add_f32 v[2:3], v[2:3], v[18:19]
	v_and_b32_e32 v31, 0xffff0000, v35
	v_pk_add_f32 v[2:3], v[2:3], v[22:23]
	v_lshlrev_b32_e32 v34, 16, v43
	v_pk_add_f32 v[2:3], v[2:3], v[26:27]
	v_and_b32_e32 v35, 0xffff0000, v43
	v_pk_add_f32 v[2:3], v[2:3], v[30:31]
	v_lshlrev_b32_e32 v10, 16, v47
	v_pk_add_f32 v[2:3], v[2:3], v[34:35]
	v_and_b32_e32 v11, 0xffff0000, v47
	v_pk_add_f32 v[2:3], v[2:3], v[98:99]
	v_mov_b32_e32 v14, v112
	v_pk_add_f32 v[2:3], v[2:3], v[100:101]
	v_mov_b32_e32 v18, v102
	v_pk_add_f32 v[2:3], v[2:3], v[104:105]
	v_div_fixup_f32 v84, v68, v69, 1.0
	v_pk_add_f32 v[2:3], v[2:3], v[10:11]
	v_lshlrev_b32_e32 v10, 16, v55
; __device__ __forceinline__ float bf_lo(unsigned w) { return __uint_as_float(w << 16); }
; __device__ __forceinline__ float bf_hi(unsigned w) { return __uint_as_float(w & 0xffff0000u); }
; __device__ __forceinline__ unsigned pk2(float lo, float hi) { return f2bf(lo) | (f2bf(hi) << 16); }
; template <int W>
; __device__ __forceinline__ void pool_item(const bf16* Z, bf16* P, int t4, int c8) {
;     ...
;     for (int i = 0; i < W - 1; ++i) { const v4u q = rows[i];
;         s[0] += pg8::bf_lo(q.x); s[1] += pg8::bf_hi(q.x); s[2] += pg8::bf_lo(q.y); s[3] += pg8::bf_hi(q.y); s[4] += pg8::bf_lo(q.z); s[5] += pg8::bf_hi(q.z); s[6] += pg8::bf_lo(q.w); s[7] += pg8::bf_hi(q.w); }
; #pragma unroll
;     for (int r = 0; r < 4; ++r) {
;         const v4u q = rows[W - 1 + r]; const float z[8] = {pg8::bf_lo(q.x), pg8::bf_hi(q.x), pg8::bf_lo(q.y), pg8::bf_hi(q.y), pg8::bf_lo(q.z), pg8::bf_hi(q.z), pg8::bf_lo(q.w), pg8::bf_hi(q.w)};
; #pragma unroll
;         for (int j = 0; j < 8; ++j) s[j] += z[j];
;         const int t = t4 + r; const float inv = 1.0f / (float)(t + 1 < W ? t + 1 : W);
;         v4u o; o.x = pk2(s[0] * inv - z[0], s[1] * inv - z[1]); o.y = pk2(s[2] * inv - z[2], s[3] * inv - z[3]); o.z = pk2(s[4] * inv - z[4], s[5] * inv - z[5]); o.w = pk2(s[6] * inv - z[6], s[7] * inv - z[7]);
	v_and_b32_e32 v11, 0xffff0000, v55
	v_pk_add_f32 v[2:3], v[2:3], v[10:11]
	v_mov_b32_e32 v19, v10
	v_mov_b32_e32 v15, v2
	v_pk_fma_f32 v[14:15], v[76:77], v[14:15], v[18:19] op_sel_hi:[0,1,1] neg_lo:[0,0,1] neg_hi:[0,0,1]
	v_mov_b32_e32 v18, v113
	v_mov_b32_e32 v19, v3
	v_mov_b32_e32 v10, v103
	v_pk_add_f32 v[2:3], v[2:3], v[6:7] neg_lo:[0,1] neg_hi:[0,1]
	v_lshlrev_b32_e32 v6, 16, v63
	v_and_b32_e32 v7, 0xffff0000, v63
	v_pk_fma_f32 v[18:19], v[76:77], v[18:19], v[10:11] op_sel_hi:[0,1,1] neg_lo:[0,0,1] neg_hi:[0,0,1]
	v_pk_add_f32 v[10:11], v[2:3], v[6:7]
	v_mov_b32_e32 v2, v114
	v_mov_b32_e32 v3, v10
	v_mov_b32_e32 v22, v106
	v_mov_b32_e32 v23, v6
	v_pk_fma_f32 v[2:3], v[84:85], v[2:3], v[22:23] op_sel_hi:[0,1,1] neg_lo:[0,0,1] neg_hi:[0,0,1]
	v_mov_b32_e32 v22, v115
	v_mov_b32_e32 v23, v11
	v_mov_b32_e32 v6, v107
	v_pk_fma_f32 v[6:7], v[84:85], v[22:23], v[6:7] op_sel_hi:[0,1,1] neg_lo:[0,0,1] neg_hi:[0,0,1]
	v_and_b32_sdwa v22, v3, v85 dst_sel:DWORD dst_unused:UNUSED_PAD src0_sel:WORD_1 src1_sel:DWORD
	v_and_b32_sdwa v23, v2, v85 dst_sel:DWORD dst_unused:UNUSED_PAD src0_sel:WORD_1 src1_sel:DWORD
	v_add3_u32 v2, v2, v23, s22
	v_add3_u32 v3, v3, v22, s22
	v_and_b32_sdwa v22, v7, v85 dst_sel:DWORD dst_unused:UNUSED_PAD src0_sel:WORD_1 src1_sel:DWORD
	v_and_b32_sdwa v23, v6, v85 dst_sel:DWORD dst_unused:UNUSED_PAD src0_sel:WORD_1 src1_sel:DWORD
	v_add3_u32 v7, v7, v22, s22
	v_add3_u32 v6, v6, v23, s22
	v_and_b32_e32 v7, 0xffff0000, v7
	v_and_b32_e32 v6, 0xffff0000, v6
	v_fma_f32 v70, -v70, v87, v86
	v_or_b32_sdwa v3, v7, v3 dst_sel:DWORD dst_unused:UNUSED_PAD src0_sel:DWORD src1_sel:WORD_1
	v_or_b32_sdwa v2, v6, v2 dst_sel:DWORD dst_unused:UNUSED_PAD src0_sel:DWORD src1_sel:WORD_1
	v_pk_add_f32 v[6:7], v[10:11], v[110:111] neg_lo:[0,1] neg_hi:[0,1]
	v_lshlrev_b32_e32 v10, 16, v51
	v_and_b32_e32 v11, 0xffff0000, v51
	v_div_fmas_f32 v70, v70, v77, v87
	v_pk_add_f32 v[22:23], v[6:7], v[10:11]
	v_div_fixup_f32 v86, v70, v71, 1.0
	v_mov_b32_e32 v6, v116
	v_mov_b32_e32 v7, v22
	v_mov_b32_e32 v26, v108
	v_mov_b32_e32 v27, v10
	v_pk_fma_f32 v[6:7], v[86:87], v[6:7], v[26:27] op_sel_hi:[0,1,1] neg_lo:[0,0,1] neg_hi:[0,0,1]
	v_mov_b32_e32 v26, v117
	v_mov_b32_e32 v27, v23
	v_mov_b32_e32 v10, v109
	v_pk_fma_f32 v[10:11], v[86:87], v[26:27], v[10:11] op_sel_hi:[0,1,1] neg_lo:[0,0,1] neg_hi:[0,0,1]
	v_and_b32_sdwa v26, v7, v85 dst_sel:DWORD dst_unused:UNUSED_PAD src0_sel:WORD_1 src1_sel:DWORD
	v_and_b32_sdwa v27, v6, v85 dst_sel:DWORD dst_unused:UNUSED_PAD src0_sel:WORD_1 src1_sel:DWORD
	v_add3_u32 v6, v6, v27, s22
	v_add3_u32 v7, v7, v26, s22
	v_and_b32_sdwa v26, v11, v85 dst_sel:DWORD dst_unused:UNUSED_PAD src0_sel:WORD_1 src1_sel:DWORD
	v_and_b32_sdwa v27, v10, v85 dst_sel:DWORD dst_unused:UNUSED_PAD src0_sel:WORD_1 src1_sel:DWORD
	v_add3_u32 v11, v11, v26, s22
	v_add3_u32 v10, v10, v27, s22
	v_lshlrev_b32_e32 v26, 16, v8
	v_and_b32_e32 v27, 0xffff0000, v8
	v_lshlrev_b32_e32 v30, 16, v4
	v_and_b32_e32 v31, 0xffff0000, v4
	v_pk_add_f32 v[100:101], v[26:27], 0 op_sel_hi:[1,0]
	v_lshlrev_b32_e32 v34, 16, v16
	v_and_b32_e32 v35, 0xffff0000, v16
	v_pk_add_f32 v[100:101], v[100:101], v[30:31]
	v_lshlrev_b32_e32 v38, 16, v12
	v_and_b32_e32 v39, 0xffff0000, v12
	v_pk_add_f32 v[100:101], v[100:101], v[34:35]
	v_lshlrev_b32_e32 v42, 16, v24
	v_and_b32_e32 v43, 0xffff0000, v24
	v_pk_add_f32 v[38:39], v[100:101], v[38:39]
	v_lshlrev_b32_e32 v46, 16, v20
	v_and_b32_e32 v47, 0xffff0000, v20
	v_pk_add_f32 v[38:39], v[38:39], v[42:43]
	v_lshlrev_b32_e32 v50, 16, v32
	v_and_b32_e32 v51, 0xffff0000, v32
	v_pk_add_f32 v[38:39], v[38:39], v[46:47]
	v_and_b32_e32 v11, 0xffff0000, v11
	v_and_b32_e32 v10, 0xffff0000, v10
	v_lshlrev_b32_e32 v54, 16, v28
	v_and_b32_e32 v55, 0xffff0000, v28
	v_pk_add_f32 v[38:39], v[38:39], v[50:51]
	v_lshlrev_b32_e32 v88, 16, v58
	v_and_b32_e32 v89, 0xffff0000, v58
	v_or_b32_sdwa v7, v11, v7 dst_sel:DWORD dst_unused:UNUSED_PAD src0_sel:DWORD src1_sel:WORD_1
	v_or_b32_sdwa v6, v10, v6 dst_sel:DWORD dst_unused:UNUSED_PAD src0_sel:DWORD src1_sel:WORD_1
	v_lshlrev_b32_e32 v10, 16, v59
	v_and_b32_e32 v11, 0xffff0000, v59
	v_lshlrev_b32_e32 v58, 16, v40
	v_and_b32_e32 v59, 0xffff0000, v40
	v_pk_add_f32 v[38:39], v[38:39], v[54:55]
	v_lshlrev_b32_e32 v62, 16, v36
	v_and_b32_e32 v63, 0xffff0000, v36
	v_pk_add_f32 v[38:39], v[38:39], v[58:59]
	v_lshlrev_b32_e32 v98, 16, v44
	v_and_b32_e32 v99, 0xffff0000, v44
	v_pk_add_f32 v[38:39], v[38:39], v[62:63]
	v_lshlrev_b32_e32 v96, 16, v72
	v_pk_add_f32 v[38:39], v[38:39], v[98:99]
	v_and_b32_e32 v97, 0xffff0000, v72
	v_pk_add_f32 v[38:39], v[38:39], v[92:93]
	v_lshlrev_b32_e32 v42, 16, v48
	v_pk_add_f32 v[38:39], v[38:39], v[94:95]
	v_and_b32_e32 v43, 0xffff0000, v48
	v_pk_add_f32 v[38:39], v[38:39], v[96:97]
	v_lshlrev_b32_e32 v46, 16, v64
	v_pk_add_f32 v[38:39], v[38:39], v[42:43]
	v_lshlrev_b32_e32 v42, 16, v56
	v_and_b32_e32 v43, 0xffff0000, v56
	v_pk_add_f32 v[38:39], v[38:39], v[42:43]
	v_and_b32_e32 v47, 0xffff0000, v64
	v_pk_add_f32 v[26:27], v[38:39], v[26:27] neg_lo:[0,1] neg_hi:[0,1]
	v_lshlrev_b32_e32 v16, 16, v17
	v_pk_add_f32 v[26:27], v[26:27], v[46:47]
	v_and_b32_e32 v17, 0xffff0000, v17
	v_pk_fma_f32 v[46:47], v[84:85], v[26:27], v[46:47] op_sel_hi:[0,1,1] neg_lo:[0,0,1] neg_hi:[0,0,1]
	v_pk_add_f32 v[26:27], v[26:27], v[30:31] neg_lo:[0,1] neg_hi:[0,1]
	v_lshlrev_b32_e32 v30, 16, v52
	v_and_b32_e32 v31, 0xffff0000, v52
	v_and_b32_sdwa v8, v46, v85 dst_sel:DWORD dst_unused:UNUSED_PAD src0_sel:WORD_1 src1_sel:DWORD
	v_pk_add_f32 v[26:27], v[26:27], v[30:31]
; __device__ __forceinline__ float bf_lo(unsigned w) { return __uint_as_float(w << 16); }
; __device__ __forceinline__ float bf_hi(unsigned w) { return __uint_as_float(w & 0xffff0000u); }
; #define GAS __attribute__((address_space(1)))
; __device__ __forceinline__ unsigned pk2(float lo, float hi) { return f2bf(lo) | (f2bf(hi) << 16); }
; template <int W>
; __device__ __forceinline__ void pool_item(const bf16* Z, bf16* P, int t4, int c8) {
;     ...
;     for (int r = 0; r < 4; ++r) {
;         const v4u q = rows[W - 1 + r]; const float z[8] = {pg8::bf_lo(q.x), pg8::bf_hi(q.x), pg8::bf_lo(q.y), pg8::bf_hi(q.y), pg8::bf_lo(q.z), pg8::bf_hi(q.z), pg8::bf_lo(q.w), pg8::bf_hi(q.w)};
; #pragma unroll
;         for (int j = 0; j < 8; ++j) s[j] += z[j];
;         const int t = t4 + r; const float inv = 1.0f / (float)(t + 1 < W ? t + 1 : W);
;         v4u o; o.x = pk2(s[0] * inv - z[0], s[1] * inv - z[1]); o.y = pk2(s[2] * inv - z[2], s[3] * inv - z[3]); o.z = pk2(s[4] * inv - z[4], s[5] * inv - z[5]); o.w = pk2(s[6] * inv - z[6], s[7] * inv - z[7]);
;         *(GAS v4u*)(P + (size_t)t * PW + c8) = o;
;         const v4u d = rows[r];
;         s[0] -= pg8::bf_lo(d.x); s[1] -= pg8::bf_hi(d.x); s[2] -= pg8::bf_lo(d.y); s[3] -= pg8::bf_hi(d.y); s[4] -= pg8::bf_lo(d.z); s[5] -= pg8::bf_hi(d.z); s[6] -= pg8::bf_lo(d.w); s[7] -= pg8::bf_hi(d.w);
;     }
	v_and_b32_sdwa v4, v47, v85 dst_sel:DWORD dst_unused:UNUSED_PAD src0_sel:WORD_1 src1_sel:DWORD
	v_add3_u32 v8, v46, v8, s22
	v_pk_fma_f32 v[30:31], v[86:87], v[26:27], v[30:31] op_sel_hi:[0,1,1] neg_lo:[0,0,1] neg_hi:[0,0,1]
	v_add3_u32 v4, v47, v4, s22
	v_lshrrev_b32_e32 v8, 16, v8
	v_and_b32_sdwa v12, v30, v85 dst_sel:DWORD dst_unused:UNUSED_PAD src0_sel:WORD_1 src1_sel:DWORD
	v_pk_add_f32 v[26:27], v[26:27], v[34:35] neg_lo:[0,1] neg_hi:[0,1]
	v_lshlrev_b32_e32 v34, 16, v9
	v_and_b32_e32 v35, 0xffff0000, v9
	v_and_or_b32 v4, v4, s21, v8
	v_and_b32_sdwa v8, v31, v85 dst_sel:DWORD dst_unused:UNUSED_PAD src0_sel:WORD_1 src1_sel:DWORD
	v_add3_u32 v12, v30, v12, s22
	v_lshlrev_b32_e32 v46, 16, v5
	v_and_b32_e32 v47, 0xffff0000, v5
	v_pk_add_f32 v[50:51], v[34:35], 0 op_sel_hi:[1,0]
	v_add3_u32 v8, v31, v8, s22
	v_lshrrev_b32_e32 v12, 16, v12
	v_pk_add_f32 v[50:51], v[50:51], v[46:47]
	v_and_or_b32 v8, v8, s21, v12
	v_lshlrev_b32_e32 v12, 16, v13
	v_and_b32_e32 v13, 0xffff0000, v13
	v_pk_add_f32 v[50:51], v[50:51], v[16:17]
	v_lshlrev_b32_e32 v24, 16, v25
	v_and_b32_e32 v25, 0xffff0000, v25
	v_pk_add_f32 v[12:13], v[50:51], v[12:13]
	v_lshlrev_b32_e32 v20, 16, v21
	v_and_b32_e32 v21, 0xffff0000, v21
	v_pk_add_f32 v[12:13], v[12:13], v[24:25]
	v_lshlrev_b32_e32 v32, 16, v33
	v_and_b32_e32 v33, 0xffff0000, v33
	v_pk_add_f32 v[12:13], v[12:13], v[20:21]
	v_lshlrev_b32_e32 v28, 16, v29
	v_and_b32_e32 v29, 0xffff0000, v29
	v_pk_add_f32 v[12:13], v[12:13], v[32:33]
	v_lshlrev_b32_e32 v40, 16, v41
	v_and_b32_e32 v41, 0xffff0000, v41
	v_pk_add_f32 v[12:13], v[12:13], v[28:29]
	v_lshlrev_b32_e32 v36, 16, v37
	v_and_b32_e32 v37, 0xffff0000, v37
	v_pk_add_f32 v[12:13], v[12:13], v[40:41]
	v_lshlrev_b32_e32 v44, 16, v45
	v_and_b32_e32 v45, 0xffff0000, v45
	v_pk_add_f32 v[12:13], v[12:13], v[36:37]
	v_lshlrev_b32_e32 v72, 16, v73
	v_pk_add_f32 v[12:13], v[12:13], v[44:45]
	v_and_b32_e32 v73, 0xffff0000, v73
	v_pk_add_f32 v[12:13], v[12:13], v[82:83]
	v_lshlrev_b32_e32 v20, 16, v49
	v_pk_add_f32 v[12:13], v[12:13], v[74:75]
	v_and_b32_e32 v21, 0xffff0000, v49
	v_pk_add_f32 v[12:13], v[12:13], v[72:73]
	v_mov_b32_e32 v24, v38
	v_pk_add_f32 v[12:13], v[12:13], v[20:21]
	v_lshlrev_b32_e32 v20, 16, v57
	v_and_b32_e32 v21, 0xffff0000, v57
	v_pk_add_f32 v[12:13], v[12:13], v[20:21]
	v_mov_b32_e32 v28, v42
	v_mov_b32_e32 v25, v12
	v_mov_b32_e32 v29, v20
	v_pk_fma_f32 v[24:25], v[76:77], v[24:25], v[28:29] op_sel_hi:[0,1,1] neg_lo:[0,0,1] neg_hi:[0,0,1]
	v_mov_b32_e32 v28, v39
	v_mov_b32_e32 v29, v13
	v_mov_b32_e32 v20, v43
	v_pk_fma_f32 v[20:21], v[76:77], v[28:29], v[20:21] op_sel_hi:[0,1,1] neg_lo:[0,0,1] neg_hi:[0,0,1]
	v_pk_add_f32 v[12:13], v[12:13], v[34:35] neg_lo:[0,1] neg_hi:[0,1]
	v_lshlrev_b32_e32 v28, 16, v65
	v_and_b32_e32 v29, 0xffff0000, v65
	v_pk_add_f32 v[12:13], v[12:13], v[28:29]
	s_ashr_i32 s1, s0, 31
	v_pk_fma_f32 v[28:29], v[84:85], v[12:13], v[28:29] op_sel_hi:[0,1,1] neg_lo:[0,0,1] neg_hi:[0,0,1]
	v_and_b32_sdwa v5, v29, v85 dst_sel:DWORD dst_unused:UNUSED_PAD src0_sel:WORD_1 src1_sel:DWORD
	v_and_b32_sdwa v9, v28, v85 dst_sel:DWORD dst_unused:UNUSED_PAD src0_sel:WORD_1 src1_sel:DWORD
	v_add3_u32 v5, v29, v5, s22
	v_add3_u32 v9, v28, v9, s22
	v_pk_add_f32 v[12:13], v[12:13], v[46:47] neg_lo:[0,1] neg_hi:[0,1]
	v_lshlrev_b32_e32 v28, 16, v53
	v_and_b32_e32 v29, 0xffff0000, v53
	v_pk_add_f32 v[12:13], v[12:13], v[28:29]
	v_lshrrev_b32_e32 v9, 16, v9
	v_pk_fma_f32 v[28:29], v[86:87], v[12:13], v[28:29] op_sel_hi:[0,1,1] neg_lo:[0,0,1] neg_hi:[0,0,1]
	v_and_b32_sdwa v32, v28, v85 dst_sel:DWORD dst_unused:UNUSED_PAD src0_sel:WORD_1 src1_sel:DWORD
	v_and_or_b32 v5, v5, s21, v9
	v_and_b32_sdwa v9, v29, v85 dst_sel:DWORD dst_unused:UNUSED_PAD src0_sel:WORD_1 src1_sel:DWORD
	v_add3_u32 v28, v28, v32, s22
	v_add3_u32 v9, v29, v9, s22
	v_lshrrev_b32_e32 v28, 16, v28
	v_and_or_b32 v9, v9, s21, v28
	v_pk_add_f32 v[28:29], v[12:13], v[16:17] neg_lo:[0,1] neg_hi:[0,1]
	v_bfe_u32 v12, v21, 16, 1
	v_bfe_u32 v13, v20, 16, 1
	v_bfe_u32 v16, v19, 16, 1
	v_bfe_u32 v17, v18, 16, 1
	v_add3_u32 v17, v18, v17, s22
	v_add3_u32 v16, v19, v16, s22
	v_add3_u32 v13, v20, v13, s22
	v_add3_u32 v12, v21, v12, s22
	v_bfe_u32 v18, v14, 16, 1
	v_bfe_u32 v19, v15, 16, 1
	v_bfe_u32 v20, v24, 16, 1
	v_bfe_u32 v21, v25, 16, 1
	v_add3_u32 v21, v25, v21, s22
	v_add3_u32 v20, v24, v20, s22
	v_add3_u32 v15, v15, v19, s22
	v_add3_u32 v14, v14, v18, s22
	s_lshl_b64 s[0:1], s[0:1], 12
	s_ashr_i32 s5, s4, 31
	v_lshrrev_b32_e32 v18, 16, v14
	v_lshrrev_b32_e32 v19, 16, v15
	v_lshrrev_b32_e32 v14, 16, v20
	v_lshrrev_b32_e32 v15, 16, v21
	v_lshl_add_u64 v[68:69], v[80:81], 0, s[0:1]
	s_lshl_b64 s[0:1], s[4:5], 12
	v_and_or_b32 v15, v12, s21, v15
	v_and_or_b32 v14, v13, s21, v14
	v_and_or_b32 v13, v16, s21, v19
	v_and_or_b32 v12, v17, s21, v18
	v_lshl_add_u64 v[70:71], v[80:81], 0, s[0:1]
	v_pk_add_f32 v[22:23], v[22:23], v[118:119] neg_lo:[0,1] neg_hi:[0,1]
	v_lshlrev_b32_e32 v30, 16, v60
	v_and_b32_e32 v31, 0xffff0000, v60
	global_store_dwordx4 v[66:67], v[12:15], off sc1
	global_store_dwordx4 v[68:69], v[2:5], off sc1
	global_store_dwordx4 v[70:71], v[6:9], off sc1
	s_min_i32 s4, s6, 15
	v_pk_add_f32 v[16:17], v[90:91], v[88:89]
	v_lshlrev_b32_e32 v6, 16, v61
	v_and_b32_e32 v7, 0xffff0000, v61
	v_pk_add_f32 v[14:15], v[22:23], v[10:11]
	v_pk_add_f32 v[12:13], v[26:27], v[30:31]
	v_pk_add_f32 v[8:9], v[28:29], v[6:7]
	s_mov_b64 s[0:1], 0
	v_mov_b32_e32 v5, s4
	v_mov_b32_e32 v4, s6
	v_mov_b32_e32 v3, v6
	v_mov_b32_e32 v2, v30
	v_mov_b32_e32 v6, v31
	v_mov_b32_e32 v23, v10
	v_mov_b32_e32 v22, v88
	v_mov_b32_e32 v10, v89

; __device__ __forceinline__ float bf_lo(unsigned w) { return __uint_as_float(w << 16); }
; __device__ __forceinline__ float bf_hi(unsigned w) { return __uint_as_float(w & 0xffff0000u); }
; #define GAS __attribute__((address_space(1)))
; template <int W>
; __device__ __forceinline__ void pool_item(const bf16* Z, bf16* P, int t4, int c8) {
;     v4u rows[W + 3];
; #pragma unroll
;     for (int i = 0; i < W + 3; ++i) { const int t = t4 - (W - 1) + i; rows[i] = (t >= 0) ? *(const GAS v4u*)(Z + (size_t)t * PW + c8) : (v4u){0u, 0u, 0u, 0u}; }
;     float s[8];
; #pragma unroll
;     for (int j = 0; j < 8; ++j) s[j] = 0.f;
; #pragma unroll
;     for (int i = 0; i < W - 1; ++i) { const v4u q = rows[i];
;         s[0] += pg8::bf_lo(q.x); s[1] += pg8::bf_hi(q.x); s[2] += pg8::bf_lo(q.y); s[3] += pg8::bf_hi(q.y); s[4] += pg8::bf_lo(q.z); s[5] += pg8::bf_hi(q.z); s[6] += pg8::bf_lo(q.w); s[7] += pg8::bf_hi(q.w); }
; #pragma unroll
;     for (int r = 0; r < 4; ++r) {
;         const v4u q = rows[W - 1 + r]; const float z[8] = {pg8::bf_lo(q.x), pg8::bf_hi(q.x), pg8::bf_lo(q.y), pg8::bf_hi(q.y), pg8::bf_lo(q.z), pg8::bf_hi(q.z), pg8::bf_lo(q.w), pg8::bf_hi(q.w)};
; #pragma unroll
;         for (int j = 0; j < 8; ++j) s[j] += z[j];
.LBB0_370:
	s_min_i32 s1, s8, 7
	s_add_i32 s1, s1, 1
	s_waitcnt vmcnt(0)
	v_lshlrev_b32_e32 v48, 16, v34
	v_and_b32_e32 v49, 0xffff0000, v34
	v_cvt_f32_i32_e32 v34, s1
	v_lshlrev_b32_e32 v62, 16, v35
	v_and_b32_e32 v63, 0xffff0000, v35
	v_lshlrev_b32_e32 v56, 16, v36
	v_div_scale_f32 v35, s[18:19], v34, v34, 1.0
	v_and_b32_e32 v57, 0xffff0000, v36
	v_rcp_f32_e32 v36, v35
	v_lshlrev_b32_e32 v46, 16, v37
	v_and_b32_e32 v47, 0xffff0000, v37
	v_lshlrev_b32_e32 v66, 16, v38
	v_fma_f32 v37, -v35, v36, 1.0
	v_fmac_f32_e32 v36, v37, v36
	v_div_scale_f32 v37, vcc, 1.0, v34, 1.0
	v_and_b32_e32 v67, 0xffff0000, v38
	v_mul_f32_e32 v38, v37, v36
	v_lshlrev_b32_e32 v68, 16, v39
	v_and_b32_e32 v69, 0xffff0000, v39
	v_fma_f32 v39, -v35, v38, v37
	s_min_i32 s1, s0, 7
	v_fmac_f32_e32 v38, v39, v36
	s_add_i32 s1, s1, 1
	v_fma_f32 v35, -v35, v38, v37
	v_cvt_f32_i32_e32 v37, s1
	v_lshlrev_b32_e32 v70, 16, v6
	v_and_b32_e32 v71, 0xffff0000, v6
	v_div_fmas_f32 v35, v35, v36, v38
	v_div_scale_f32 v36, s[18:19], v37, v37, 1.0
	v_lshlrev_b32_e32 v72, 16, v2
	v_and_b32_e32 v73, 0xffff0000, v2
	v_pk_add_f32 v[76:77], v[70:71], 0 op_sel_hi:[1,0]
	v_rcp_f32_e32 v38, v36
	v_lshlrev_b32_e32 v74, 16, v10
	v_and_b32_e32 v75, 0xffff0000, v10
	v_pk_add_f32 v[76:77], v[76:77], v[72:73]
	v_lshlrev_b32_e32 v52, 16, v42
	v_pk_add_f32 v[76:77], v[76:77], v[74:75]
	v_and_b32_e32 v53, 0xffff0000, v42
	v_pk_add_f32 v[48:49], v[76:77], v[48:49]
	v_fma_f32 v39, -v36, v38, 1.0
	v_pk_add_f32 v[48:49], v[48:49], v[52:53]
	v_lshlrev_b32_e32 v52, 16, v14
	v_pk_add_f32 v[48:49], v[48:49], v[66:67]
	v_and_b32_e32 v53, 0xffff0000, v14
	v_fmac_f32_e32 v38, v39, v38
	v_div_scale_f32 v39, vcc, 1.0, v37, 1.0
	v_pk_add_f32 v[48:49], v[48:49], v[52:53]
	v_lshlrev_b32_e32 v66, 16, v22
	v_and_b32_e32 v67, 0xffff0000, v22
	v_lshlrev_b32_e32 v64, 16, v43
	v_and_b32_e32 v65, 0xffff0000, v43
	v_lshlrev_b32_e32 v42, 16, v45
	v_and_b32_e32 v43, 0xffff0000, v45
	v_mul_f32_e32 v45, v39, v38
	v_pk_add_f32 v[76:77], v[48:49], v[66:67]
	v_fma_f32 v50, -v36, v45, v39
	s_min_i32 s1, s4, 7
	v_pk_add_f32 v[48:49], v[76:77], v[70:71] neg_lo:[0,1] neg_hi:[0,1]
	v_lshlrev_b32_e32 v70, 16, v30
	v_and_b32_e32 v71, 0xffff0000, v30
	v_fmac_f32_e32 v45, v50, v38
	s_add_i32 s1, s1, 1
	v_pk_add_f32 v[82:83], v[48:49], v[70:71]
	v_fma_f32 v36, -v36, v45, v39
	v_cvt_f32_i32_e32 v39, s1
	v_pk_add_f32 v[48:49], v[82:83], v[72:73] neg_lo:[0,1] neg_hi:[0,1]
	v_lshlrev_b32_e32 v72, 16, v18
	v_and_b32_e32 v73, 0xffff0000, v18
	v_pk_add_f32 v[86:87], v[48:49], v[72:73]
	v_lshlrev_b32_e32 v6, 16, v7
	v_and_b32_e32 v7, 0xffff0000, v7
	s_ashr_i32 s9, s8, 31
	v_pk_add_f32 v[52:53], v[86:87], v[74:75] neg_lo:[0,1] neg_hi:[0,1]
	v_lshlrev_b32_e32 v74, 16, v3
	v_and_b32_e32 v75, 0xffff0000, v3
	v_pk_add_f32 v[2:3], v[6:7], 0 op_sel_hi:[1,0]
	s_lshl_b64 s[18:19], s[8:9], 12
	v_lshlrev_b32_e32 v10, 16, v11
	v_and_b32_e32 v11, 0xffff0000, v11
	v_pk_add_f32 v[2:3], v[2:3], v[74:75]
	v_lshlrev_b32_e32 v58, 16, v44
	v_and_b32_e32 v59, 0xffff0000, v44
	v_div_fixup_f32 v44, v35, v34, 1.0
	v_lshl_add_u64 v[34:35], v[80:81], 0, s[18:19]
	v_div_fmas_f32 v36, v36, v38, v45
	v_div_scale_f32 v38, s[18:19], v39, v39, 1.0
	v_pk_add_f32 v[2:3], v[2:3], v[10:11]
	v_rcp_f32_e32 v45, v38
	v_pk_add_f32 v[2:3], v[2:3], v[62:63]
	v_lshlrev_b32_e32 v14, 16, v15
	v_pk_add_f32 v[2:3], v[2:3], v[64:65]
	v_and_b32_e32 v15, 0xffff0000, v15
	v_pk_add_f32 v[2:3], v[2:3], v[68:69]
	v_fma_f32 v51, -v38, v45, 1.0
	v_pk_add_f32 v[2:3], v[2:3], v[14:15]
	v_lshlrev_b32_e32 v14, 16, v23
	v_and_b32_e32 v15, 0xffff0000, v23
	v_pk_add_f32 v[2:3], v[2:3], v[14:15]
	v_fmac_f32_e32 v45, v51, v45
	v_mov_b32_e32 v22, v76
	v_mov_b32_e32 v23, v2
	v_mov_b32_e32 v62, v66
	v_mov_b32_e32 v63, v14
	v_pk_fma_f32 v[22:23], v[44:45], v[22:23], v[62:63] op_sel_hi:[0,1,1] neg_lo:[0,0,1] neg_hi:[0,0,1]
	v_mov_b32_e32 v63, v3
	v_pk_add_f32 v[2:3], v[2:3], v[6:7] neg_lo:[0,1] neg_hi:[0,1]
	v_lshlrev_b32_e32 v6, 16, v31
	v_and_b32_e32 v7, 0xffff0000, v31
	v_mov_b32_e32 v62, v77
	v_mov_b32_e32 v14, v67
	v_pk_add_f32 v[30:31], v[2:3], v[6:7]
	v_div_fixup_f32 v50, v36, v37, 1.0
	v_div_scale_f32 v51, vcc, 1.0, v39, 1.0
	v_pk_fma_f32 v[14:15], v[44:45], v[62:63], v[14:15] op_sel_hi:[0,1,1] neg_lo:[0,0,1] neg_hi:[0,0,1]
	v_mov_b32_e32 v2, v82
	v_mov_b32_e32 v3, v30
	v_mov_b32_e32 v62, v70
	v_mov_b32_e32 v63, v6
	v_pk_fma_f32 v[2:3], v[50:51], v[2:3], v[62:63] op_sel_hi:[0,1,1] neg_lo:[0,0,1] neg_hi:[0,0,1]
	v_mov_b32_e32 v62, v83
	v_mov_b32_e32 v63, v31
	v_mov_b32_e32 v6, v71
	v_lshlrev_b32_e32 v48, 16, v26
	v_and_b32_e32 v49, 0xffff0000, v26
	v_pk_fma_f32 v[6:7], v[50:51], v[62:63], v[6:7] op_sel_hi:[0,1,1] neg_lo:[0,0,1] neg_hi:[0,0,1]
	v_and_b32_sdwa v18, v3, v85 dst_sel:DWORD dst_unused:UNUSED_PAD src0_sel:WORD_1 src1_sel:DWORD
	v_and_b32_sdwa v26, v2, v85 dst_sel:DWORD dst_unused:UNUSED_PAD src0_sel:WORD_1 src1_sel:DWORD
	v_mul_f32_e32 v54, v51, v45
	v_add3_u32 v2, v2, v26, s22
	v_add3_u32 v3, v3, v18, s22
	v_and_b32_sdwa v18, v7, v85 dst_sel:DWORD dst_unused:UNUSED_PAD src0_sel:WORD_1 src1_sel:DWORD
	v_and_b32_sdwa v26, v6, v85 dst_sel:DWORD dst_unused:UNUSED_PAD src0_sel:WORD_1 src1_sel:DWORD
	v_fma_f32 v55, -v38, v54, v51
	v_add3_u32 v7, v7, v18, s22
	v_add3_u32 v6, v6, v26, s22
	v_fmac_f32_e32 v54, v55, v45
	v_and_b32_e32 v7, 0xffff0000, v7
	v_and_b32_e32 v6, 0xffff0000, v6
	v_fma_f32 v38, -v38, v54, v51
	v_or_b32_sdwa v3, v7, v3 dst_sel:DWORD dst_unused:UNUSED_PAD src0_sel:DWORD src1_sel:WORD_1
	v_or_b32_sdwa v2, v6, v2 dst_sel:DWORD dst_unused:UNUSED_PAD src0_sel:DWORD src1_sel:WORD_1
	v_pk_add_f32 v[6:7], v[30:31], v[74:75] neg_lo:[0,1] neg_hi:[0,1]
	v_lshlrev_b32_e32 v18, 16, v19
; __device__ __forceinline__ float bf_lo(unsigned w) { return __uint_as_float(w << 16); }
; __device__ __forceinline__ float bf_hi(unsigned w) { return __uint_as_float(w & 0xffff0000u); }
; __device__ __forceinline__ unsigned pk2(float lo, float hi) { return f2bf(lo) | (f2bf(hi) << 16); }
; template <int W>
; __device__ __forceinline__ void pool_item(const bf16* Z, bf16* P, int t4, int c8) {
;     ...
;     for (int i = 0; i < W - 1; ++i) { const v4u q = rows[i];
;         s[0] += pg8::bf_lo(q.x); s[1] += pg8::bf_hi(q.x); s[2] += pg8::bf_lo(q.y); s[3] += pg8::bf_hi(q.y); s[4] += pg8::bf_lo(q.z); s[5] += pg8::bf_hi(q.z); s[6] += pg8::bf_lo(q.w); s[7] += pg8::bf_hi(q.w); }
; #pragma unroll
;     for (int r = 0; r < 4; ++r) {
;         const v4u q = rows[W - 1 + r]; const float z[8] = {pg8::bf_lo(q.x), pg8::bf_hi(q.x), pg8::bf_lo(q.y), pg8::bf_hi(q.y), pg8::bf_lo(q.z), pg8::bf_hi(q.z), pg8::bf_lo(q.w), pg8::bf_hi(q.w)};
; #pragma unroll
;         for (int j = 0; j < 8; ++j) s[j] += z[j];
;         const int t = t4 + r; const float inv = 1.0f / (float)(t + 1 < W ? t + 1 : W);
;         v4u o; o.x = pk2(s[0] * inv - z[0], s[1] * inv - z[1]); o.y = pk2(s[2] * inv - z[2], s[3] * inv - z[3]); o.z = pk2(s[4] * inv - z[4], s[5] * inv - z[5]); o.w = pk2(s[6] * inv - z[6], s[7] * inv - z[7]);
	v_and_b32_e32 v19, 0xffff0000, v19
	v_div_fmas_f32 v38, v38, v45, v54
	v_pk_add_f32 v[30:31], v[6:7], v[18:19]
	v_div_fixup_f32 v54, v38, v39, 1.0
	v_mov_b32_e32 v6, v86
	v_mov_b32_e32 v7, v30
	v_mov_b32_e32 v62, v72
	v_mov_b32_e32 v63, v18
	v_pk_fma_f32 v[6:7], v[54:55], v[6:7], v[62:63] op_sel_hi:[0,1,1] neg_lo:[0,0,1] neg_hi:[0,0,1]
	v_mov_b32_e32 v62, v87
	v_mov_b32_e32 v63, v31
	v_mov_b32_e32 v18, v73
	v_pk_fma_f32 v[18:19], v[54:55], v[62:63], v[18:19] op_sel_hi:[0,1,1] neg_lo:[0,0,1] neg_hi:[0,0,1]
	v_and_b32_sdwa v26, v7, v85 dst_sel:DWORD dst_unused:UNUSED_PAD src0_sel:WORD_1 src1_sel:DWORD
	v_and_b32_sdwa v45, v6, v85 dst_sel:DWORD dst_unused:UNUSED_PAD src0_sel:WORD_1 src1_sel:DWORD
	v_add3_u32 v6, v6, v45, s22
	v_add3_u32 v7, v7, v26, s22
	v_and_b32_sdwa v26, v19, v85 dst_sel:DWORD dst_unused:UNUSED_PAD src0_sel:WORD_1 src1_sel:DWORD
	v_and_b32_sdwa v45, v18, v85 dst_sel:DWORD dst_unused:UNUSED_PAD src0_sel:WORD_1 src1_sel:DWORD
	v_add3_u32 v19, v19, v26, s22
	v_add3_u32 v18, v18, v45, s22
	v_and_b32_e32 v19, 0xffff0000, v19
	v_and_b32_e32 v18, 0xffff0000, v18
	v_or_b32_sdwa v7, v19, v7 dst_sel:DWORD dst_unused:UNUSED_PAD src0_sel:DWORD src1_sel:WORD_1
	v_or_b32_sdwa v6, v18, v6 dst_sel:DWORD dst_unused:UNUSED_PAD src0_sel:DWORD src1_sel:WORD_1
	v_pk_add_f32 v[18:19], v[30:31], v[10:11] neg_lo:[0,1] neg_hi:[0,1]
	v_lshlrev_b32_e32 v10, 16, v27
	v_and_b32_e32 v11, 0xffff0000, v27
	v_lshlrev_b32_e32 v26, 16, v8
	v_and_b32_e32 v27, 0xffff0000, v8
	v_lshlrev_b32_e32 v30, 16, v4
	v_and_b32_e32 v31, 0xffff0000, v4
	v_pk_add_f32 v[64:65], v[26:27], 0 op_sel_hi:[1,0]
	v_lshlrev_b32_e32 v62, 16, v12
	v_and_b32_e32 v63, 0xffff0000, v12
	v_pk_add_f32 v[64:65], v[64:65], v[30:31]
	v_lshlrev_b32_e32 v60, 16, v40
	v_pk_add_f32 v[64:65], v[64:65], v[62:63]
	v_and_b32_e32 v61, 0xffff0000, v40
	v_pk_add_f32 v[56:57], v[64:65], v[56:57]
	v_lshlrev_b32_e32 v40, 16, v41
	v_pk_add_f32 v[56:57], v[56:57], v[58:59]
	v_lshlrev_b32_e32 v58, 16, v16
	v_pk_add_f32 v[56:57], v[56:57], v[60:61]
	v_and_b32_e32 v59, 0xffff0000, v16
	v_pk_add_f32 v[56:57], v[56:57], v[58:59]
	v_lshlrev_b32_e32 v58, 16, v24
	v_and_b32_e32 v59, 0xffff0000, v24
	v_pk_add_f32 v[56:57], v[56:57], v[58:59]
	v_lshlrev_b32_e32 v60, 16, v32
	v_pk_add_f32 v[26:27], v[56:57], v[26:27] neg_lo:[0,1] neg_hi:[0,1]
	v_and_b32_e32 v61, 0xffff0000, v32
	v_pk_add_f32 v[26:27], v[26:27], v[60:61]
	v_and_b32_e32 v41, 0xffff0000, v41
	v_pk_fma_f32 v[60:61], v[50:51], v[26:27], v[60:61] op_sel_hi:[0,1,1] neg_lo:[0,0,1] neg_hi:[0,0,1]
	v_pk_add_f32 v[26:27], v[26:27], v[30:31] neg_lo:[0,1] neg_hi:[0,1]
	v_lshlrev_b32_e32 v30, 16, v20
	v_and_b32_e32 v31, 0xffff0000, v20
	v_and_b32_sdwa v8, v60, v85 dst_sel:DWORD dst_unused:UNUSED_PAD src0_sel:WORD_1 src1_sel:DWORD
	v_pk_add_f32 v[26:27], v[26:27], v[30:31]
	v_and_b32_sdwa v4, v61, v85 dst_sel:DWORD dst_unused:UNUSED_PAD src0_sel:WORD_1 src1_sel:DWORD
	v_add3_u32 v8, v60, v8, s22
	v_pk_fma_f32 v[30:31], v[54:55], v[26:27], v[30:31] op_sel_hi:[0,1,1] neg_lo:[0,0,1] neg_hi:[0,0,1]
	v_add3_u32 v4, v61, v4, s22
	v_lshrrev_b32_e32 v8, 16, v8
	v_and_b32_sdwa v12, v30, v85 dst_sel:DWORD dst_unused:UNUSED_PAD src0_sel:WORD_1 src1_sel:DWORD
	v_and_or_b32 v4, v4, s21, v8
	v_and_b32_sdwa v8, v31, v85 dst_sel:DWORD dst_unused:UNUSED_PAD src0_sel:WORD_1 src1_sel:DWORD
	v_add3_u32 v12, v30, v12, s22
	v_lshlrev_b32_e32 v60, 16, v9
	v_and_b32_e32 v61, 0xffff0000, v9
	v_add3_u32 v8, v31, v8, s22
	v_lshrrev_b32_e32 v12, 16, v12
	v_pk_add_f32 v[26:27], v[26:27], v[62:63] neg_lo:[0,1] neg_hi:[0,1]
	v_lshlrev_b32_e32 v62, 16, v5
	v_and_b32_e32 v63, 0xffff0000, v5
	v_pk_add_f32 v[64:65], v[60:61], 0 op_sel_hi:[1,0]
	v_and_or_b32 v8, v8, s21, v12
	v_lshlrev_b32_e32 v12, 16, v13
; __device__ __forceinline__ float bf_lo(unsigned w) { return __uint_as_float(w << 16); }
; __device__ __forceinline__ float bf_hi(unsigned w) { return __uint_as_float(w & 0xffff0000u); }
; #define GAS __attribute__((address_space(1)))
; __device__ __forceinline__ unsigned pk2(float lo, float hi) { return f2bf(lo) | (f2bf(hi) << 16); }
; template <int W>
; __device__ __forceinline__ void pool_item(const bf16* Z, bf16* P, int t4, int c8) {
;     ...
;     for (int r = 0; r < 4; ++r) {
;         const v4u q = rows[W - 1 + r]; const float z[8] = {pg8::bf_lo(q.x), pg8::bf_hi(q.x), pg8::bf_lo(q.y), pg8::bf_hi(q.y), pg8::bf_lo(q.z), pg8::bf_hi(q.z), pg8::bf_lo(q.w), pg8::bf_hi(q.w)};
; #pragma unroll
;         for (int j = 0; j < 8; ++j) s[j] += z[j];
;         const int t = t4 + r; const float inv = 1.0f / (float)(t + 1 < W ? t + 1 : W);
;         v4u o; o.x = pk2(s[0] * inv - z[0], s[1] * inv - z[1]); o.y = pk2(s[2] * inv - z[2], s[3] * inv - z[3]); o.z = pk2(s[4] * inv - z[4], s[5] * inv - z[5]); o.w = pk2(s[6] * inv - z[6], s[7] * inv - z[7]);
;         *(GAS v4u*)(P + (size_t)t * PW + c8) = o;
;         const v4u d = rows[r];
;         s[0] -= pg8::bf_lo(d.x); s[1] -= pg8::bf_hi(d.x); s[2] -= pg8::bf_lo(d.y); s[3] -= pg8::bf_hi(d.y); s[4] -= pg8::bf_lo(d.z); s[5] -= pg8::bf_hi(d.z); s[6] -= pg8::bf_lo(d.w); s[7] -= pg8::bf_hi(d.w);
;     }
	v_and_b32_e32 v13, 0xffff0000, v13
	v_pk_add_f32 v[64:65], v[64:65], v[62:63]
	v_lshlrev_b32_e32 v16, 16, v17
	v_pk_add_f32 v[64:65], v[64:65], v[12:13]
	v_and_b32_e32 v17, 0xffff0000, v17
	v_pk_add_f32 v[46:47], v[64:65], v[46:47]
	v_lshlrev_b32_e32 v24, 16, v25
	v_pk_add_f32 v[42:43], v[46:47], v[42:43]
	v_and_b32_e32 v25, 0xffff0000, v25
	v_pk_add_f32 v[40:41], v[42:43], v[40:41]
	v_mov_b32_e32 v42, v58
	v_pk_add_f32 v[16:17], v[40:41], v[16:17]
	v_mov_b32_e32 v40, v56
	v_pk_add_f32 v[16:17], v[16:17], v[24:25]
	v_mov_b32_e32 v43, v24
	v_mov_b32_e32 v41, v16
	v_pk_fma_f32 v[40:41], v[44:45], v[40:41], v[42:43] op_sel_hi:[0,1,1] neg_lo:[0,0,1] neg_hi:[0,0,1]
	v_mov_b32_e32 v43, v17
	v_pk_add_f32 v[16:17], v[16:17], v[60:61] neg_lo:[0,1] neg_hi:[0,1]
	v_lshlrev_b32_e32 v32, 16, v33
	v_and_b32_e32 v33, 0xffff0000, v33
	v_pk_add_f32 v[16:17], v[16:17], v[32:33]
	v_lshlrev_b32_e32 v20, 16, v21
	v_pk_fma_f32 v[32:33], v[50:51], v[16:17], v[32:33] op_sel_hi:[0,1,1] neg_lo:[0,0,1] neg_hi:[0,0,1]
	v_pk_add_f32 v[16:17], v[16:17], v[62:63] neg_lo:[0,1] neg_hi:[0,1]
	v_and_b32_e32 v21, 0xffff0000, v21
	v_and_b32_sdwa v9, v32, v85 dst_sel:DWORD dst_unused:UNUSED_PAD src0_sel:WORD_1 src1_sel:DWORD
	v_pk_add_f32 v[16:17], v[16:17], v[20:21]
	v_and_b32_sdwa v5, v33, v85 dst_sel:DWORD dst_unused:UNUSED_PAD src0_sel:WORD_1 src1_sel:DWORD
	v_add3_u32 v9, v32, v9, s22
	v_pk_fma_f32 v[20:21], v[54:55], v[16:17], v[20:21] op_sel_hi:[0,1,1] neg_lo:[0,0,1] neg_hi:[0,0,1]
	v_lshlrev_b32_e32 v30, 16, v28
	v_and_b32_e32 v31, 0xffff0000, v28
	v_add3_u32 v5, v33, v5, s22
	v_lshrrev_b32_e32 v9, 16, v9
	v_and_b32_sdwa v28, v20, v85 dst_sel:DWORD dst_unused:UNUSED_PAD src0_sel:WORD_1 src1_sel:DWORD
	v_mov_b32_e32 v42, v57
	v_mov_b32_e32 v24, v59
	v_and_or_b32 v5, v5, s21, v9
	v_and_b32_sdwa v9, v21, v85 dst_sel:DWORD dst_unused:UNUSED_PAD src0_sel:WORD_1 src1_sel:DWORD
	v_add3_u32 v20, v20, v28, s22
	v_pk_fma_f32 v[24:25], v[44:45], v[42:43], v[24:25] op_sel_hi:[0,1,1] neg_lo:[0,0,1] neg_hi:[0,0,1]
	v_add3_u32 v9, v21, v9, s22
	v_lshrrev_b32_e32 v20, 16, v20
	v_and_or_b32 v9, v9, s21, v20
	v_pk_add_f32 v[20:21], v[16:17], v[12:13] neg_lo:[0,1] neg_hi:[0,1]
	v_bfe_u32 v12, v25, 16, 1
	v_bfe_u32 v13, v24, 16, 1
	v_bfe_u32 v16, v15, 16, 1
	v_bfe_u32 v17, v14, 16, 1
	v_add3_u32 v17, v14, v17, s22
	v_add3_u32 v16, v15, v16, s22
	v_add3_u32 v13, v24, v13, s22
	v_add3_u32 v12, v25, v12, s22
	v_bfe_u32 v14, v22, 16, 1
	v_bfe_u32 v15, v23, 16, 1
	v_bfe_u32 v24, v40, 16, 1
	v_bfe_u32 v25, v41, 16, 1
	s_ashr_i32 s1, s0, 31
	v_add3_u32 v25, v41, v25, s22
	v_add3_u32 v24, v40, v24, s22
	v_add3_u32 v15, v23, v15, s22
	v_add3_u32 v14, v22, v14, s22
	s_lshl_b64 s[0:1], s[0:1], 12
	s_ashr_i32 s5, s4, 31
	v_lshrrev_b32_e32 v22, 16, v14
	v_lshrrev_b32_e32 v23, 16, v15
	v_lshrrev_b32_e32 v14, 16, v24
	v_lshrrev_b32_e32 v15, 16, v25
	v_lshl_add_u64 v[36:37], v[80:81], 0, s[0:1]
	s_lshl_b64 s[0:1], s[4:5], 12
	v_and_or_b32 v15, v12, s21, v15
	v_and_or_b32 v14, v13, s21, v14
	v_and_or_b32 v13, v16, s21, v23
	v_and_or_b32 v12, v17, s21, v22
	v_lshl_add_u64 v[38:39], v[80:81], 0, s[0:1]
	global_store_dwordx4 v[34:35], v[12:15], off sc1
	global_store_dwordx4 v[36:37], v[2:5], off sc1
	global_store_dwordx4 v[38:39], v[6:9], off sc1
	s_min_i32 s0, s6, 7
	v_pk_add_f32 v[16:17], v[52:53], v[48:49]
	v_lshlrev_b32_e32 v6, 16, v29
	v_and_b32_e32 v7, 0xffff0000, v29
	v_pk_add_f32 v[14:15], v[18:19], v[10:11]
	v_pk_add_f32 v[12:13], v[26:27], v[30:31]
	v_pk_add_f32 v[8:9], v[20:21], v[6:7]
	v_mov_b32_e32 v5, s0
	v_mov_b32_e32 v4, s6
	v_mov_b32_e32 v3, v6
	v_mov_b32_e32 v2, v30
	v_mov_b32_e32 v6, v31
	v_mov_b32_e32 v23, v10
	v_mov_b32_e32 v22, v48
	v_mov_b32_e32 v10, v49
	s_cbranch_execnz .LBB0_286
	s_branch .LBB0_350

; __device__ __forceinline__ float bf_lo(unsigned w) { return __uint_as_float(w << 16); }
; __device__ __forceinline__ float bf_hi(unsigned w) { return __uint_as_float(w & 0xffff0000u); }
; #define GAS __attribute__((address_space(1)))
; __device__ __forceinline__ unsigned pk2(float lo, float hi) { return f2bf(lo) | (f2bf(hi) << 16); }
; template <int W>
; __device__ __forceinline__ void pool_item(const bf16* Z, bf16* P, int t4, int c8) {
;     v4u rows[W + 3];
; #pragma unroll
;     for (int i = 0; i < W + 3; ++i) { const int t = t4 - (W - 1) + i; rows[i] = (t >= 0) ? *(const GAS v4u*)(Z + (size_t)t * PW + c8) : (v4u){0u, 0u, 0u, 0u}; }
;     float s[8];
; #pragma unroll
;     for (int j = 0; j < 8; ++j) s[j] = 0.f;
; #pragma unroll
;     for (int i = 0; i < W - 1; ++i) { const v4u q = rows[i];
;         s[0] += pg8::bf_lo(q.x); s[1] += pg8::bf_hi(q.x); s[2] += pg8::bf_lo(q.y); s[3] += pg8::bf_hi(q.y); s[4] += pg8::bf_lo(q.z); s[5] += pg8::bf_hi(q.z); s[6] += pg8::bf_lo(q.w); s[7] += pg8::bf_hi(q.w); }
; #pragma unroll
;     for (int r = 0; r < 4; ++r) {
;         const v4u q = rows[W - 1 + r]; const float z[8] = {pg8::bf_lo(q.x), pg8::bf_hi(q.x), pg8::bf_lo(q.y), pg8::bf_hi(q.y), pg8::bf_lo(q.z), pg8::bf_hi(q.z), pg8::bf_lo(q.w), pg8::bf_hi(q.w)};
; #pragma unroll
;         for (int j = 0; j < 8; ++j) s[j] += z[j];
;         const int t = t4 + r; const float inv = 1.0f / (float)(t + 1 < W ? t + 1 : W);
;         v4u o; o.x = pk2(s[0] * inv - z[0], s[1] * inv - z[1]); o.y = pk2(s[2] * inv - z[2], s[3] * inv - z[3]); o.z = pk2(s[4] * inv - z[4], s[5] * inv - z[5]); o.w = pk2(s[6] * inv - z[6], s[7] * inv - z[7]);
.LBB0_372:
	s_min_i32 s1, s8, 1
	s_add_i32 s1, s1, 1
	v_cvt_f32_i32_e32 v22, s1
	s_min_i32 s1, s0, 1
	s_add_i32 s1, s1, 1
	v_cvt_f32_i32_e32 v26, s1
	v_div_scale_f32 v23, s[18:19], v22, v22, 1.0
	v_rcp_f32_e32 v24, v23
	v_div_scale_f32 v25, vcc, 1.0, v22, 1.0
	s_min_i32 s1, s4, 1
	v_fma_f32 v27, -v23, v24, 1.0
	v_fmac_f32_e32 v24, v27, v24
	v_mul_f32_e32 v27, v25, v24
	v_fma_f32 v28, -v23, v27, v25
	v_fmac_f32_e32 v27, v28, v24
	v_fma_f32 v23, -v23, v27, v25
	v_div_fmas_f32 v23, v23, v24, v27
	v_div_fixup_f32 v28, v23, v22, 1.0
	v_div_scale_f32 v22, s[18:19], v26, v26, 1.0
	v_rcp_f32_e32 v23, v22
	s_add_i32 s1, s1, 1
	v_cvt_f32_i32_e32 v31, s1
	s_ashr_i32 s9, s8, 31
	v_fma_f32 v27, -v22, v23, 1.0
	v_fmac_f32_e32 v23, v27, v23
	v_div_scale_f32 v27, vcc, 1.0, v26, 1.0
	v_mul_f32_e32 v29, v27, v23
	v_fma_f32 v30, -v22, v29, v27
	v_fmac_f32_e32 v29, v30, v23
	v_fma_f32 v22, -v22, v29, v27
	s_lshl_b64 s[18:19], s[8:9], 12
	v_div_fmas_f32 v22, v22, v23, v29
	v_lshl_add_u64 v[24:25], v[80:81], 0, s[18:19]
	v_div_fixup_f32 v30, v22, v26, 1.0
	v_div_scale_f32 v22, s[18:19], v31, v31, 1.0
	v_rcp_f32_e32 v23, v22
	s_waitcnt vmcnt(0)
	v_lshlrev_b32_e32 v38, 16, v10
	v_and_b32_e32 v39, 0xffff0000, v10
	v_lshlrev_b32_e32 v40, 16, v18
	v_fma_f32 v29, -v22, v23, 1.0
	v_fmac_f32_e32 v23, v29, v23
	v_div_scale_f32 v29, vcc, 1.0, v31, 1.0
	v_mul_f32_e32 v32, v29, v23
	v_fma_f32 v33, -v22, v32, v29
	v_fmac_f32_e32 v32, v33, v23
	v_fma_f32 v22, -v22, v32, v29
	v_div_fmas_f32 v22, v22, v23, v32
	v_div_fixup_f32 v32, v22, v31, 1.0
	v_lshlrev_b32_e32 v22, 16, v2
	v_and_b32_e32 v23, 0xffff0000, v2
	v_pk_add_f32 v[36:37], v[22:23], 0 op_sel_hi:[1,0]
	v_lshlrev_b32_e32 v2, 16, v3
	v_pk_add_f32 v[36:37], v[36:37], v[38:39]
	v_and_b32_e32 v3, 0xffff0000, v3
	v_pk_add_f32 v[22:23], v[36:37], v[22:23] neg_lo:[0,1] neg_hi:[0,1]
	v_and_b32_e32 v41, 0xffff0000, v18
	v_pk_add_f32 v[50:51], v[2:3], 0 op_sel_hi:[1,0]
	v_lshlrev_b32_e32 v52, 16, v11
	v_and_b32_e32 v53, 0xffff0000, v11
	v_pk_add_f32 v[42:43], v[22:23], v[40:41]
	v_pk_add_f32 v[10:11], v[50:51], v[52:53]
	v_pk_add_f32 v[22:23], v[42:43], v[38:39] neg_lo:[0,1] neg_hi:[0,1]
	v_mov_b32_e32 v50, v36
	v_mov_b32_e32 v54, v38
	v_mov_b32_e32 v36, v37
	v_mov_b32_e32 v37, v11
	v_mov_b32_e32 v38, v39
	v_mov_b32_e32 v39, v53
	v_pk_fma_f32 v[36:37], v[28:29], v[36:37], v[38:39] op_sel_hi:[0,1,1] neg_lo:[0,0,1] neg_hi:[0,0,1]
	v_pk_add_f32 v[2:3], v[10:11], v[2:3] neg_lo:[0,1] neg_hi:[0,1]
	v_lshlrev_b32_e32 v38, 16, v19
	v_and_b32_e32 v39, 0xffff0000, v19
	v_lshlrev_b32_e32 v44, 16, v6
	v_and_b32_e32 v45, 0xffff0000, v6
	v_pk_add_f32 v[2:3], v[2:3], v[38:39]
	v_pk_add_f32 v[46:47], v[22:23], v[44:45]
	v_mov_b32_e32 v51, v10
	v_mov_b32_e32 v10, v42
	v_mov_b32_e32 v11, v2
	v_mov_b32_e32 v18, v40
	v_mov_b32_e32 v19, v38
	v_pk_add_f32 v[48:49], v[46:47], v[40:41] neg_lo:[0,1] neg_hi:[0,1]
	v_pk_fma_f32 v[10:11], v[30:31], v[10:11], v[18:19] op_sel_hi:[0,1,1] neg_lo:[0,0,1] neg_hi:[0,0,1]
	v_mov_b32_e32 v18, v43
	v_mov_b32_e32 v19, v3
	v_mov_b32_e32 v40, v41
	v_mov_b32_e32 v41, v39
	v_pk_fma_f32 v[18:19], v[30:31], v[18:19], v[40:41] op_sel_hi:[0,1,1] neg_lo:[0,0,1] neg_hi:[0,0,1]
	v_and_b32_sdwa v6, v11, v85 dst_sel:DWORD dst_unused:UNUSED_PAD src0_sel:WORD_1 src1_sel:DWORD
	v_add3_u32 v6, v11, v6, s22
	v_and_b32_sdwa v11, v19, v85 dst_sel:DWORD dst_unused:UNUSED_PAD src0_sel:WORD_1 src1_sel:DWORD
	v_add3_u32 v11, v19, v11, s22
	v_and_b32_e32 v11, 0xffff0000, v11
	v_lshlrev_b32_e32 v22, 16, v14
	v_and_b32_e32 v23, 0xffff0000, v14
	v_and_b32_sdwa v14, v10, v85 dst_sel:DWORD dst_unused:UNUSED_PAD src0_sel:WORD_1 src1_sel:DWORD
	v_or_b32_sdwa v11, v11, v6 dst_sel:DWORD dst_unused:UNUSED_PAD src0_sel:DWORD src1_sel:WORD_1
	v_pk_add_f32 v[2:3], v[2:3], v[52:53] neg_lo:[0,1] neg_hi:[0,1]
	v_lshlrev_b32_e32 v6, 16, v7
	v_and_b32_e32 v7, 0xffff0000, v7
	v_add3_u32 v10, v10, v14, s22
	v_and_b32_sdwa v14, v18, v85 dst_sel:DWORD dst_unused:UNUSED_PAD src0_sel:WORD_1 src1_sel:DWORD
	v_pk_add_f32 v[2:3], v[2:3], v[6:7]
	v_add3_u32 v14, v18, v14, s22
	v_mov_b32_e32 v18, v46
	v_mov_b32_e32 v19, v2
	v_mov_b32_e32 v40, v44
	v_mov_b32_e32 v41, v6
	v_mov_b32_e32 v55, v52
	v_and_b32_e32 v14, 0xffff0000, v14
	v_pk_fma_f32 v[18:19], v[32:33], v[18:19], v[40:41] op_sel_hi:[0,1,1] neg_lo:[0,0,1] neg_hi:[0,0,1]
	v_mov_b32_e32 v40, v47
	v_mov_b32_e32 v41, v3
	v_mov_b32_e32 v6, v45
	v_pk_fma_f32 v[50:51], v[28:29], v[50:51], v[54:55] op_sel_hi:[0,1,1] neg_lo:[0,0,1] neg_hi:[0,0,1]
	v_or_b32_sdwa v10, v14, v10 dst_sel:DWORD dst_unused:UNUSED_PAD src0_sel:DWORD src1_sel:WORD_1
	v_pk_fma_f32 v[6:7], v[32:33], v[40:41], v[6:7] op_sel_hi:[0,1,1] neg_lo:[0,0,1] neg_hi:[0,0,1]
	v_and_b32_sdwa v14, v19, v85 dst_sel:DWORD dst_unused:UNUSED_PAD src0_sel:WORD_1 src1_sel:DWORD
	v_and_b32_sdwa v29, v18, v85 dst_sel:DWORD dst_unused:UNUSED_PAD src0_sel:WORD_1 src1_sel:DWORD
	v_add3_u32 v18, v18, v29, s22
	v_add3_u32 v14, v19, v14, s22
	v_and_b32_sdwa v19, v7, v85 dst_sel:DWORD dst_unused:UNUSED_PAD src0_sel:WORD_1 src1_sel:DWORD
	v_and_b32_sdwa v29, v6, v85 dst_sel:DWORD dst_unused:UNUSED_PAD src0_sel:WORD_1 src1_sel:DWORD
	v_add3_u32 v7, v7, v19, s22
	v_add3_u32 v6, v6, v29, s22
; __device__ __forceinline__ float bf_lo(unsigned w) { return __uint_as_float(w << 16); }
; __device__ __forceinline__ float bf_hi(unsigned w) { return __uint_as_float(w & 0xffff0000u); }
; #define GAS __attribute__((address_space(1)))
; __device__ __forceinline__ unsigned pk2(float lo, float hi) { return f2bf(lo) | (f2bf(hi) << 16); }
; template <int W>
; __device__ __forceinline__ void pool_item(const bf16* Z, bf16* P, int t4, int c8) {
;     ...
;     for (int r = 0; r < 4; ++r) {
;         const v4u q = rows[W - 1 + r]; const float z[8] = {pg8::bf_lo(q.x), pg8::bf_hi(q.x), pg8::bf_lo(q.y), pg8::bf_hi(q.y), pg8::bf_lo(q.z), pg8::bf_hi(q.z), pg8::bf_lo(q.w), pg8::bf_hi(q.w)};
; #pragma unroll
;         for (int j = 0; j < 8; ++j) s[j] += z[j];
;         const int t = t4 + r; const float inv = 1.0f / (float)(t + 1 < W ? t + 1 : W);
;         v4u o; o.x = pk2(s[0] * inv - z[0], s[1] * inv - z[1]); o.y = pk2(s[2] * inv - z[2], s[3] * inv - z[3]); o.z = pk2(s[4] * inv - z[4], s[5] * inv - z[5]); o.w = pk2(s[6] * inv - z[6], s[7] * inv - z[7]);
;         *(GAS v4u*)(P + (size_t)t * PW + c8) = o;
;         const v4u d = rows[r];
;         s[0] -= pg8::bf_lo(d.x); s[1] -= pg8::bf_hi(d.x); s[2] -= pg8::bf_lo(d.y); s[3] -= pg8::bf_hi(d.y); s[4] -= pg8::bf_lo(d.z); s[5] -= pg8::bf_hi(d.z); s[6] -= pg8::bf_lo(d.w); s[7] -= pg8::bf_hi(d.w);
;     }
	v_and_b32_e32 v7, 0xffff0000, v7
	v_and_b32_e32 v6, 0xffff0000, v6
	v_pk_add_f32 v[38:39], v[2:3], v[38:39] neg_lo:[0,1] neg_hi:[0,1]
	v_lshlrev_b32_e32 v2, 16, v4
	v_and_b32_e32 v3, 0xffff0000, v4
	v_or_b32_sdwa v19, v7, v14 dst_sel:DWORD dst_unused:UNUSED_PAD src0_sel:DWORD src1_sel:WORD_1
	v_or_b32_sdwa v18, v6, v18 dst_sel:DWORD dst_unused:UNUSED_PAD src0_sel:DWORD src1_sel:WORD_1
	v_lshlrev_b32_e32 v6, 16, v15
	v_and_b32_e32 v7, 0xffff0000, v15
	v_pk_add_f32 v[14:15], v[2:3], 0 op_sel_hi:[1,0]
	v_lshlrev_b32_e32 v40, 16, v12
	v_and_b32_e32 v41, 0xffff0000, v12
	v_pk_add_f32 v[14:15], v[14:15], v[40:41]
	v_lshlrev_b32_e32 v42, 16, v20
	v_pk_add_f32 v[2:3], v[14:15], v[2:3] neg_lo:[0,1] neg_hi:[0,1]
	v_and_b32_e32 v43, 0xffff0000, v20
	v_pk_add_f32 v[2:3], v[2:3], v[42:43]
	v_lshlrev_b32_e32 v46, 16, v13
	v_pk_fma_f32 v[44:45], v[30:31], v[2:3], v[42:43] op_sel_hi:[0,1,1] neg_lo:[0,0,1] neg_hi:[0,0,1]
	v_and_b32_sdwa v4, v45, v85 dst_sel:DWORD dst_unused:UNUSED_PAD src0_sel:WORD_1 src1_sel:DWORD
	v_and_b32_sdwa v12, v44, v85 dst_sel:DWORD dst_unused:UNUSED_PAD src0_sel:WORD_1 src1_sel:DWORD
	v_add3_u32 v4, v45, v4, s22
	v_add3_u32 v12, v44, v12, s22
	v_pk_add_f32 v[2:3], v[2:3], v[40:41] neg_lo:[0,1] neg_hi:[0,1]
	v_lshlrev_b32_e32 v44, 16, v8
	v_and_b32_e32 v45, 0xffff0000, v8
	v_pk_add_f32 v[2:3], v[2:3], v[44:45]
	v_lshrrev_b32_e32 v12, 16, v12
	v_pk_fma_f32 v[44:45], v[32:33], v[2:3], v[44:45] op_sel_hi:[0,1,1] neg_lo:[0,0,1] neg_hi:[0,0,1]
	v_and_b32_sdwa v8, v44, v85 dst_sel:DWORD dst_unused:UNUSED_PAD src0_sel:WORD_1 src1_sel:DWORD
	v_and_or_b32 v12, v4, s21, v12
	v_and_b32_sdwa v4, v45, v85 dst_sel:DWORD dst_unused:UNUSED_PAD src0_sel:WORD_1 src1_sel:DWORD
	v_add3_u32 v8, v44, v8, s22
	v_add3_u32 v4, v45, v4, s22
	v_lshrrev_b32_e32 v8, 16, v8
	v_and_or_b32 v20, v4, s21, v8
	v_lshlrev_b32_e32 v4, 16, v5
	v_and_b32_e32 v5, 0xffff0000, v5
	v_pk_add_f32 v[44:45], v[4:5], 0 op_sel_hi:[1,0]
	v_and_b32_e32 v47, 0xffff0000, v13
	v_pk_add_f32 v[44:45], v[44:45], v[46:47]
	v_mov_b32_e32 v52, v14
	v_mov_b32_e32 v53, v44
	v_mov_b32_e32 v54, v40
	v_mov_b32_e32 v55, v46
	v_mov_b32_e32 v14, v15
	v_mov_b32_e32 v15, v45
	v_mov_b32_e32 v40, v41
	v_mov_b32_e32 v41, v47
	v_pk_fma_f32 v[52:53], v[28:29], v[52:53], v[54:55] op_sel_hi:[0,1,1] neg_lo:[0,0,1] neg_hi:[0,0,1]
	v_pk_fma_f32 v[14:15], v[28:29], v[14:15], v[40:41] op_sel_hi:[0,1,1] neg_lo:[0,0,1] neg_hi:[0,0,1]
	v_pk_add_f32 v[4:5], v[44:45], v[4:5] neg_lo:[0,1] neg_hi:[0,1]
	v_lshlrev_b32_e32 v28, 16, v21
	v_and_b32_e32 v29, 0xffff0000, v21
	v_pk_add_f32 v[4:5], v[4:5], v[28:29]
	v_pk_add_f32 v[42:43], v[2:3], v[42:43] neg_lo:[0,1] neg_hi:[0,1]
	v_pk_fma_f32 v[30:31], v[30:31], v[4:5], v[28:29] op_sel_hi:[0,1,1] neg_lo:[0,0,1] neg_hi:[0,0,1]
	v_and_b32_sdwa v13, v30, v85 dst_sel:DWORD dst_unused:UNUSED_PAD src0_sel:WORD_1 src1_sel:DWORD
	v_and_b32_sdwa v8, v31, v85 dst_sel:DWORD dst_unused:UNUSED_PAD src0_sel:WORD_1 src1_sel:DWORD
	v_add3_u32 v13, v30, v13, s22
	v_add3_u32 v8, v31, v8, s22
	v_lshrrev_b32_e32 v13, 16, v13
	v_and_or_b32 v13, v8, s21, v13
	v_pk_add_f32 v[4:5], v[4:5], v[46:47] neg_lo:[0,1] neg_hi:[0,1]
	v_lshlrev_b32_e32 v8, 16, v9
	v_and_b32_e32 v9, 0xffff0000, v9
	v_pk_add_f32 v[4:5], v[4:5], v[8:9]
	v_lshlrev_b32_e32 v2, 16, v16
	v_pk_fma_f32 v[8:9], v[32:33], v[4:5], v[8:9] op_sel_hi:[0,1,1] neg_lo:[0,0,1] neg_hi:[0,0,1]
	v_and_b32_sdwa v21, v8, v85 dst_sel:DWORD dst_unused:UNUSED_PAD src0_sel:WORD_1 src1_sel:DWORD
	v_and_b32_e32 v3, 0xffff0000, v16
	v_and_b32_sdwa v16, v9, v85 dst_sel:DWORD dst_unused:UNUSED_PAD src0_sel:WORD_1 src1_sel:DWORD
	v_add3_u32 v8, v8, v21, s22
	v_add3_u32 v9, v9, v16, s22
	v_lshrrev_b32_e32 v8, 16, v8
	v_and_or_b32 v21, v9, s21, v8
	v_bfe_u32 v8, v15, 16, 1
	v_bfe_u32 v9, v14, 16, 1
	v_pk_add_f32 v[4:5], v[4:5], v[28:29] neg_lo:[0,1] neg_hi:[0,1]
	v_add3_u32 v9, v14, v9, s22
	v_add3_u32 v8, v15, v8, s22
	v_bfe_u32 v14, v50, 16, 1
	v_bfe_u32 v15, v51, 16, 1
	v_bfe_u32 v29, v52, 16, 1
	v_bfe_u32 v30, v53, 16, 1
	s_ashr_i32 s1, s0, 31
	v_bfe_u32 v16, v37, 16, 1
	v_bfe_u32 v28, v36, 16, 1
	v_add3_u32 v30, v53, v30, s22
	v_add3_u32 v29, v52, v29, s22
	v_add3_u32 v15, v51, v15, s22
	v_add3_u32 v14, v50, v14, s22
	s_lshl_b64 s[0:1], s[0:1], 12
	s_ashr_i32 s5, s4, 31
	v_add3_u32 v28, v36, v28, s22
	v_add3_u32 v16, v37, v16, s22
	v_lshrrev_b32_e32 v14, 16, v14
	v_lshrrev_b32_e32 v15, 16, v15
	v_lshrrev_b32_e32 v29, 16, v29
	v_lshrrev_b32_e32 v30, 16, v30
	v_lshl_add_u64 v[26:27], v[80:81], 0, s[0:1]
	s_lshl_b64 s[0:1], s[4:5], 12
	v_and_or_b32 v31, v8, s21, v30
	v_and_or_b32 v30, v9, s21, v29
	v_and_or_b32 v29, v16, s21, v15
	v_and_or_b32 v28, v28, s21, v14
	v_lshl_add_u64 v[34:35], v[80:81], 0, s[0:1]
	global_store_dwordx4 v[24:25], v[28:31], off sc1
	global_store_dwordx4 v[26:27], v[10:13], off sc1
	global_store_dwordx4 v[34:35], v[18:21], off sc1
	s_min_i32 s4, s6, 1
	v_pk_add_f32 v[14:15], v[38:39], v[6:7]
	v_lshlrev_b32_e32 v18, 16, v17
	v_and_b32_e32 v19, 0xffff0000, v17
	v_pk_add_f32 v[16:17], v[48:49], v[22:23]
	v_pk_add_f32 v[12:13], v[42:43], v[2:3]
	v_pk_add_f32 v[8:9], v[4:5], v[18:19]
	s_mov_b64 s[0:1], 0
	v_mov_b32_e32 v5, s4
	v_mov_b32_e32 v4, s6

; #define EX2(x) __builtin_amdgcn_exp2f(x)
;     ...
;     if (!FULL) {
; #pragma unroll
;         for (int kb = 0; kb < 8; ++kb)
; #pragma unroll
;             for (int r = 0; r < 4; ++r) Ubuf[(item << 14) + (size_t)(16 * kb + 4 * q + r) * 128 + 16 * w + fr] = S[kb][r];
;         if (ro == 0) Dtot[item * 128 + k] = EX2(btot);
;     }
.LBB0_402:
	s_ashr_i32 s21, s20, 31
	s_lshl_b64 s[22:23], s[20:21], 16
	s_waitcnt vmcnt(1)
	v_lshl_add_u64 v[2:3], v[54:55], 0, s[22:23]
	v_lshl_add_u64 v[4:5], v[2:3], 0, v[56:57]
	s_waitcnt vmcnt(0)
	v_lshl_add_u64 v[6:7], v[2:3], 0, v[58:59]
	global_store_dword v[4:5], v46, off sc1
	global_store_dword v[4:5], v47, off offset:512 sc1
	global_store_dword v[4:5], v48, off offset:1024 sc1
	global_store_dword v[6:7], v49, off sc1
	v_add_co_u32_e32 v6, vcc, 0x2000, v4
	s_nop 1
	v_addc_co_u32_e32 v7, vcc, 0, v5, vcc
	global_store_dword v[6:7], v42, off sc1
	global_store_dword v[6:7], v43, off offset:512 sc1
	global_store_dword v[6:7], v44, off offset:1024 sc1
	v_lshl_add_u64 v[6:7], v[2:3], 0, v[60:61]
	global_store_dword v[6:7], v45, off sc1
	v_add_co_u32_e32 v6, vcc, 0x4000, v4
	s_nop 1
	v_addc_co_u32_e32 v7, vcc, 0, v5, vcc
	global_store_dword v[6:7], v38, off sc1
	global_store_dword v[6:7], v39, off offset:512 sc1
	global_store_dword v[6:7], v40, off offset:1024 sc1
	v_lshl_add_u64 v[6:7], v[2:3], 0, v[62:63]
	global_store_dword v[6:7], v41, off sc1
	v_add_co_u32_e32 v6, vcc, 0x6000, v4
	s_nop 1
	v_addc_co_u32_e32 v7, vcc, 0, v5, vcc
	global_store_dword v[6:7], v34, off sc1
	global_store_dword v[6:7], v35, off offset:512 sc1
	global_store_dword v[6:7], v36, off offset:1024 sc1
	v_lshl_add_u64 v[6:7], v[2:3], 0, v[64:65]
	global_store_dword v[6:7], v37, off sc1
	v_add_co_u32_e32 v6, vcc, 0x8000, v4
	s_nop 1
	v_addc_co_u32_e32 v7, vcc, 0, v5, vcc
	global_store_dword v[6:7], v30, off sc1
	global_store_dword v[6:7], v31, off offset:512 sc1
	global_store_dword v[6:7], v32, off offset:1024 sc1
	v_lshl_add_u64 v[6:7], v[2:3], 0, v[66:67]
	global_store_dword v[6:7], v33, off sc1
	v_add_co_u32_e32 v6, vcc, 0xa000, v4
	s_nop 1
	v_addc_co_u32_e32 v7, vcc, 0, v5, vcc
	global_store_dword v[6:7], v26, off sc1
	global_store_dword v[6:7], v27, off offset:512 sc1
	global_store_dword v[6:7], v28, off offset:1024 sc1
	v_lshl_add_u64 v[6:7], v[2:3], 0, v[68:69]
	global_store_dword v[6:7], v29, off sc1
	v_add_co_u32_e32 v6, vcc, 0xc000, v4
	s_nop 1
	v_addc_co_u32_e32 v7, vcc, 0, v5, vcc
	v_add_co_u32_e32 v4, vcc, 0xe000, v4
	global_store_dword v[6:7], v22, off sc1
	global_store_dword v[6:7], v23, off offset:512 sc1
	global_store_dword v[6:7], v24, off offset:1024 sc1
	v_lshl_add_u64 v[6:7], v[2:3], 0, v[70:71]
	v_addc_co_u32_e32 v5, vcc, 0, v5, vcc
	v_lshl_add_u64 v[2:3], v[2:3], 0, v[72:73]
	global_store_dword v[6:7], v25, off sc1
	global_store_dword v[4:5], v18, off sc1
	global_store_dword v[4:5], v19, off offset:512 sc1
	global_store_dword v[4:5], v20, off offset:1024 sc1
	global_store_dword v[2:3], v21, off sc1
	s_and_saveexec_b64 s[22:23], s[4:5]
	s_cbranch_execz .LBB0_389
	v_exp_f32_e32 v4, v93
	s_lshl_b64 s[28:29], s[20:21], 9
	v_lshl_add_u64 v[2:3], v[74:75], 0, s[28:29]
	global_store_dword v[2:3], v4, off sc1
	s_branch .LBB0_389

;     __device__ __forceinline__ void operator()(const f32x4 (&acc)[2][2][4][2], const Unit& u, int wr, int wc, int fr, int fq) const {
;         const int row0 = u.pm * BM + wr * 64 + fr, col0 = u.pn * BM + wc * 32 + 8 * fq;
;         f32x4 sv[2][2];
; #pragma unroll
;         for (int bj = 0; bj < 2; ++bj)
; #pragma unroll
;             for (int n = 0; n < 2; ++n) sv[bj][n] = *(const f32x4*)(scale + col0 + bj * HALF + 4 * n);
; #pragma unroll
;         for (int ai = 0; ai < 2; ++ai)
; #pragma unroll
;             for (int m = 0; m < 4; ++m) { bf16* rowp = O + (size_t)(row0 + ai * HALF + m * 16) * ldc + col0;
.LBB0_481:
	v_lshl_or_b32 v164, s76, 8, v169
	v_ashrrev_i32_e32 v165, 31, v164
	v_lshl_add_u64 v[130:131], v[164:165], 2, s[60:61]
	global_load_dwordx4 v[142:145], v[130:131], off
	global_load_dwordx4 v[138:141], v[130:131], off offset:16
	global_load_dwordx4 v[134:137], v[130:131], off offset:512
	s_nop 0
	global_load_dwordx4 v[130:133], v[130:131], off offset:528
	v_lshl_add_u32 v166, s30, 8, v163
	v_ashrrev_i32_e32 v167, 31, v166
	v_or_b32_e32 v174, 16, v166
	v_or_b32_e32 v176, 32, v166
	v_or_b32_e32 v178, 48, v166
	v_lshlrev_b64 v[166:167], 13, v[166:167]
	v_ashrrev_i32_e32 v175, 31, v174
	v_ashrrev_i32_e32 v177, 31, v176
	v_ashrrev_i32_e32 v179, 31, v178
	v_lshlrev_b64 v[180:181], 1, v[164:165]
	v_lshl_add_u64 v[164:165], s[56:57], 0, v[166:167]
	v_lshlrev_b64 v[166:167], 13, v[174:175]
	v_lshlrev_b64 v[174:175], 13, v[176:177]
	v_lshlrev_b64 v[176:177], 13, v[178:179]
	v_lshl_add_u64 v[166:167], s[56:57], 0, v[166:167]
	v_lshl_add_u64 v[174:175], s[56:57], 0, v[174:175]
	v_lshl_add_u64 v[176:177], s[56:57], 0, v[176:177]
	v_lshl_add_u64 v[164:165], v[164:165], 0, v[180:181]
	v_lshl_add_u64 v[166:167], v[166:167], 0, v[180:181]
	v_lshl_add_u64 v[174:175], v[174:175], 0, v[180:181]
	v_lshl_add_u64 v[176:177], v[176:177], 0, v[180:181]
	s_mov_b64 s[6:7], 0x100000
	s_waitcnt vmcnt(0)
; __device__ __forceinline__ unsigned cvt_pk_bf16(float lo, float hi) { const cvt_f2 v = {lo, hi}; return __builtin_bit_cast(unsigned, __builtin_convertvector(v, cvt_b2)); }
;     __device__ __forceinline__ void operator()(const f32x4 (&acc)[2][2][4][2], const Unit& u, int wr, int wc, int fr, int fq) const {
;     ...
; #pragma unroll
;         for (int ai = 0; ai < 2; ++ai)
; #pragma unroll
;             for (int m = 0; m < 4; ++m) { bf16* rowp = O + (size_t)(row0 + ai * HALF + m * 16) * ldc + col0;
; #pragma unroll
;                 for (int bj = 0; bj < 2; ++bj) { const f32x4 v0 = acc[ai][bj][m][0] * sv[bj][0], v1 = acc[ai][bj][m][1] * sv[bj][1];
;                     pg8::u32x4 w; w.x = cvt_pk_bf16(v0[0], v0[1]); w.y = cvt_pk_bf16(v0[2], v0[3]); w.z = cvt_pk_bf16(v1[0], v1[1]); w.w = cvt_pk_bf16(v1[2], v1[3]);
;                     *(pg8::u32x4*)(rowp + bj * HALF) = w; } }
	v_pk_mul_f32 v[128:129], v[128:129], v[144:145]
	v_pk_mul_f32 v[126:127], v[126:127], v[142:143]
	v_pk_mul_f32 v[124:125], v[124:125], v[140:141]
	v_pk_mul_f32 v[122:123], v[122:123], v[138:139]
	v_pk_mul_f32 v[108:109], v[108:109], v[136:137]
	v_pk_mul_f32 v[106:107], v[106:107], v[134:135]
	v_pk_mul_f32 v[100:101], v[100:101], v[132:133]
	v_pk_mul_f32 v[98:99], v[98:99], v[130:131]
	v_pk_mul_f32 v[120:121], v[120:121], v[144:145]
	v_pk_mul_f32 v[118:119], v[118:119], v[142:143]
	v_pk_mul_f32 v[116:117], v[116:117], v[140:141]
	v_pk_mul_f32 v[114:115], v[114:115], v[138:139]
	v_pk_mul_f32 v[96:97], v[96:97], v[136:137]
	v_pk_mul_f32 v[94:95], v[94:95], v[134:135]
	v_pk_mul_f32 v[92:93], v[92:93], v[132:133]
	v_pk_mul_f32 v[90:91], v[90:91], v[130:131]
	v_pk_mul_f32 v[112:113], v[112:113], v[144:145]
	v_pk_mul_f32 v[110:111], v[110:111], v[142:143]
	v_pk_mul_f32 v[104:105], v[104:105], v[140:141]
	v_pk_mul_f32 v[102:103], v[102:103], v[138:139]
	v_pk_mul_f32 v[178:179], v[88:89], v[136:137]
	v_pk_mul_f32 v[180:181], v[86:87], v[134:135]
	v_pk_mul_f32 v[182:183], v[84:85], v[132:133]
	v_pk_mul_f32 v[184:185], v[82:83], v[130:131]
	v_pk_mul_f32 v[186:187], v[80:81], v[144:145]
	v_pk_mul_f32 v[188:189], v[78:79], v[142:143]
	v_pk_mul_f32 v[190:191], v[76:77], v[140:141]
	v_pk_mul_f32 v[192:193], v[74:75], v[138:139]
	v_cvt_pk_bf16_f32 v74, v126, v127
	v_cvt_pk_bf16_f32 v75, v128, v129
	v_cvt_pk_bf16_f32 v76, v122, v123
	v_cvt_pk_bf16_f32 v77, v124, v125
	v_cvt_pk_bf16_f32 v78, v106, v107
	v_cvt_pk_bf16_f32 v79, v108, v109
	v_cvt_pk_bf16_f32 v80, v98, v99
	v_cvt_pk_bf16_f32 v81, v100, v101
	v_cvt_pk_bf16_f32 v82, v118, v119
	v_cvt_pk_bf16_f32 v83, v120, v121
	v_cvt_pk_bf16_f32 v84, v114, v115
	v_cvt_pk_bf16_f32 v85, v116, v117
	v_cvt_pk_bf16_f32 v86, v94, v95
	v_cvt_pk_bf16_f32 v87, v96, v97
	v_cvt_pk_bf16_f32 v88, v90, v91
	v_cvt_pk_bf16_f32 v89, v92, v93
	v_cvt_pk_bf16_f32 v90, v110, v111
	v_cvt_pk_bf16_f32 v91, v112, v113
	v_cvt_pk_bf16_f32 v92, v102, v103
	v_cvt_pk_bf16_f32 v93, v104, v105
	v_cvt_pk_bf16_f32 v94, v180, v181
	v_cvt_pk_bf16_f32 v95, v178, v179
	v_cvt_pk_bf16_f32 v96, v184, v185
	v_cvt_pk_bf16_f32 v97, v182, v183
	global_store_dwordx4 v[164:165], v[74:77], off sc1
	global_store_dwordx4 v[164:165], v[78:81], off offset:256 sc1
	global_store_dwordx4 v[166:167], v[82:85], off sc1
	global_store_dwordx4 v[166:167], v[86:89], off offset:256 sc1
	global_store_dwordx4 v[174:175], v[90:93], off sc1
	global_store_dwordx4 v[174:175], v[94:97], off offset:256 sc1
	v_cvt_pk_bf16_f32 v74, v188, v189
	v_cvt_pk_bf16_f32 v75, v186, v187
	v_cvt_pk_bf16_f32 v76, v192, v193
	v_cvt_pk_bf16_f32 v77, v190, v191
	global_store_dwordx4 v[176:177], v[74:77], off sc1
	v_pk_mul_f32 v[72:73], v[72:73], v[136:137]
	v_pk_mul_f32 v[70:71], v[70:71], v[134:135]
	v_pk_mul_f32 v[74:75], v[68:69], v[132:133]
	v_pk_mul_f32 v[68:69], v[66:67], v[130:131]
	v_cvt_pk_bf16_f32 v66, v70, v71
	v_cvt_pk_bf16_f32 v67, v72, v73
	v_cvt_pk_bf16_f32 v68, v68, v69
	v_cvt_pk_bf16_f32 v69, v74, v75
	global_store_dwordx4 v[176:177], v[66:69], off offset:256 sc1
	v_pk_mul_f32 v[62:63], v[62:63], v[142:143]
	v_pk_mul_f32 v[64:65], v[64:65], v[144:145]
	v_lshl_add_u64 v[66:67], v[164:165], 0, s[6:7]
	s_mov_b32 s6, 0x100000
	v_pk_mul_f32 v[68:69], v[60:61], v[140:141]
	v_pk_mul_f32 v[60:61], v[58:59], v[138:139]
	v_cvt_pk_bf16_f32 v58, v62, v63
	v_add_co_u32_e32 v62, vcc, s6, v164
	v_cvt_pk_bf16_f32 v59, v64, v65
	v_cvt_pk_bf16_f32 v60, v60, v61
	v_cvt_pk_bf16_f32 v61, v68, v69
	v_addc_co_u32_e32 v63, vcc, 0, v165, vcc
	global_store_dwordx4 v[62:63], v[58:61], off sc1
	v_pk_mul_f32 v[52:53], v[52:53], v[136:137]
	v_pk_mul_f32 v[50:51], v[50:51], v[134:135]
	v_pk_mul_f32 v[58:59], v[44:45], v[132:133]
	v_pk_mul_f32 v[44:45], v[42:43], v[130:131]
	v_cvt_pk_bf16_f32 v42, v50, v51
	v_cvt_pk_bf16_f32 v43, v52, v53
	v_cvt_pk_bf16_f32 v44, v44, v45
	v_cvt_pk_bf16_f32 v45, v58, v59
	s_mov_b64 s[6:7], 0x120000
	global_store_dwordx4 v[66:67], v[42:45], off offset:256 sc1
	v_lshl_add_u64 v[50:51], v[164:165], 0, s[6:7]
	v_pk_mul_f32 v[46:47], v[46:47], v[138:139]
	v_pk_mul_f32 v[44:45], v[56:57], v[144:145]
	v_pk_mul_f32 v[42:43], v[54:55], v[142:143]
	s_mov_b32 s6, 0x120000
	v_pk_mul_f32 v[48:49], v[48:49], v[140:141]
	v_cvt_pk_bf16_f32 v42, v42, v43
	v_cvt_pk_bf16_f32 v43, v44, v45
	v_cvt_pk_bf16_f32 v44, v46, v47
	v_add_co_u32_e32 v46, vcc, s6, v164
	v_cvt_pk_bf16_f32 v45, v48, v49
	s_nop 0
	v_addc_co_u32_e32 v47, vcc, 0, v165, vcc
	global_store_dwordx4 v[46:47], v[42:45], off sc1
	v_pk_mul_f32 v[36:37], v[36:37], v[136:137]
	v_pk_mul_f32 v[34:35], v[34:35], v[134:135]
	v_pk_mul_f32 v[42:43], v[28:29], v[132:133]
	v_pk_mul_f32 v[28:29], v[26:27], v[130:131]
	v_cvt_pk_bf16_f32 v26, v34, v35
	v_cvt_pk_bf16_f32 v27, v36, v37
	v_cvt_pk_bf16_f32 v28, v28, v29
	v_cvt_pk_bf16_f32 v29, v42, v43
	s_mov_b64 s[6:7], 0x140000
	global_store_dwordx4 v[50:51], v[26:29], off offset:256 sc1
	v_lshl_add_u64 v[34:35], v[164:165], 0, s[6:7]
	v_pk_mul_f32 v[30:31], v[30:31], v[138:139]
	v_pk_mul_f32 v[28:29], v[40:41], v[144:145]
	v_pk_mul_f32 v[26:27], v[38:39], v[142:143]
	s_mov_b32 s6, 0x140000
	v_pk_mul_f32 v[32:33], v[32:33], v[140:141]
	v_cvt_pk_bf16_f32 v26, v26, v27
	v_cvt_pk_bf16_f32 v27, v28, v29
	v_cvt_pk_bf16_f32 v28, v30, v31
	v_add_co_u32_e32 v30, vcc, s6, v164
	v_cvt_pk_bf16_f32 v29, v32, v33
	s_nop 0
	v_addc_co_u32_e32 v31, vcc, 0, v165, vcc
	global_store_dwordx4 v[30:31], v[26:29], off sc1
	v_pk_mul_f32 v[20:21], v[20:21], v[136:137]
	v_pk_mul_f32 v[18:19], v[18:19], v[134:135]
	v_pk_mul_f32 v[26:27], v[12:13], v[132:133]
	v_pk_mul_f32 v[12:13], v[10:11], v[130:131]
	v_cvt_pk_bf16_f32 v10, v18, v19
	v_cvt_pk_bf16_f32 v11, v20, v21
	v_cvt_pk_bf16_f32 v12, v12, v13
	v_cvt_pk_bf16_f32 v13, v26, v27
	s_mov_b64 s[6:7], 0x160000
	global_store_dwordx4 v[34:35], v[10:13], off offset:256 sc1
	v_lshl_add_u64 v[18:19], v[164:165], 0, s[6:7]
	v_pk_mul_f32 v[14:15], v[14:15], v[138:139]
	v_pk_mul_f32 v[12:13], v[24:25], v[144:145]
	v_pk_mul_f32 v[10:11], v[22:23], v[142:143]
	s_mov_b32 s6, 0x160000
	v_pk_mul_f32 v[16:17], v[16:17], v[140:141]
	v_cvt_pk_bf16_f32 v10, v10, v11
	v_cvt_pk_bf16_f32 v11, v12, v13
	v_cvt_pk_bf16_f32 v12, v14, v15
	v_add_co_u32_e32 v14, vcc, s6, v164
	v_cvt_pk_bf16_f32 v13, v16, v17
	s_nop 0
	v_addc_co_u32_e32 v15, vcc, 0, v165, vcc
	global_store_dwordx4 v[14:15], v[10:13], off sc1
	v_pk_mul_f32 v[8:9], v[8:9], v[136:137]
	v_pk_mul_f32 v[6:7], v[6:7], v[134:135]
	v_pk_mul_f32 v[10:11], v[4:5], v[132:133]
	v_pk_mul_f32 v[4:5], v[2:3], v[130:131]
	v_cvt_pk_bf16_f32 v2, v6, v7
	v_cvt_pk_bf16_f32 v3, v8, v9
	v_cvt_pk_bf16_f32 v4, v4, v5
	v_cvt_pk_bf16_f32 v5, v10, v11
	s_and_b64 vcc, exec, s[4:5]
	s_mov_b64 s[4:5], -1
	global_store_dwordx4 v[18:19], v[2:5], off offset:256 sc1
	s_cbranch_vccnz .LBB0_468
	s_andn2_b64 vcc, exec, s[0:1]
	s_cbranch_vccnz .LBB0_467
	s_barrier
	s_branch .LBB0_467

; __global__ void __launch_bounds__(NWAVES * 64, 2) fwd(Args args) {
;     ...
;         for (int e = gt; e < NH * HD * HD; e += NGT) {
;             const int h = e >> 14, kv = e & 16383, k = kv >> 7; float Sc = 0.f;
; #pragma unroll
;             for (int sc = 0; sc < 16; ++sc) { const size_t it = (size_t)(h * 16 + sc); HS[(it << 14) + kv] = Sc; Sc = HDt[it * 128 + k] * Sc + HU[(it << 14) + kv]; }
;         }
.LBB0_487:
	v_ashrrev_i32_e32 v9, 10, v8
	v_lshrrev_b32_e32 v2, 5, v8
	v_and_b32_e32 v6, -16, v9
	v_lshlrev_b32_e32 v10, 2, v8
	v_and_b32_e32 v2, 0x1fc, v2
	v_ashrrev_i32_e32 v7, 31, v6
	v_lshl_add_u64 v[4:5], s[14:15], 0, v[2:3]
	v_and_b32_e32 v2, 0xfffc, v10
	v_lshlrev_b64 v[10:11], 16, v[6:7]
	v_or_b32_e32 v10, v10, v2
	v_lshlrev_b64 v[12:13], 9, v[6:7]
	v_lshl_add_u64 v[14:15], s[8:9], 0, v[10:11]
	v_lshl_add_u64 v[12:13], v[4:5], 0, v[12:13]
	global_store_dword v[14:15], v3, off sc1
	v_lshl_add_u64 v[10:11], s[12:13], 0, v[10:11]
	global_load_dword v7, v[12:13], off
	global_load_dword v16, v[10:11], off
	v_or_b32_e32 v10, 1, v6
	v_ashrrev_i32_e32 v11, 31, v10
	v_lshlrev_b64 v[12:13], 16, v[10:11]
	v_or_b32_e32 v12, v12, v2
	v_lshlrev_b64 v[10:11], 9, v[10:11]
	v_lshl_add_u64 v[14:15], s[8:9], 0, v[12:13]
	v_lshl_add_u64 v[10:11], v[4:5], 0, v[10:11]
	v_lshl_add_u64 v[12:13], s[12:13], 0, v[12:13]
	global_load_dword v17, v[12:13], off
	v_add_u32_e32 v8, s81, v8
	v_cmp_lt_i32_e32 vcc, s6, v8
	s_or_b64 s[4:5], vcc, s[4:5]
	s_waitcnt vmcnt(0)
	v_fmac_f32_e32 v16, 0, v7
	global_store_dword v[14:15], v16, off sc1
	global_load_dword v7, v[10:11], off
	v_or_b32_e32 v10, 2, v6
	v_ashrrev_i32_e32 v11, 31, v10
	v_lshlrev_b64 v[12:13], 16, v[10:11]
	v_or_b32_e32 v12, v12, v2
	v_lshlrev_b64 v[10:11], 9, v[10:11]
	v_lshl_add_u64 v[14:15], s[8:9], 0, v[12:13]
	v_lshl_add_u64 v[10:11], v[4:5], 0, v[10:11]
	v_lshl_add_u64 v[12:13], s[12:13], 0, v[12:13]
	global_load_dword v18, v[12:13], off
	s_waitcnt vmcnt(1)
	v_fmac_f32_e32 v17, v16, v7
	global_store_dword v[14:15], v17, off sc1
	global_load_dword v7, v[10:11], off
	v_or_b32_e32 v10, 3, v6
	v_ashrrev_i32_e32 v11, 31, v10
	v_lshlrev_b64 v[12:13], 16, v[10:11]
	v_or_b32_e32 v12, v12, v2
	v_lshlrev_b64 v[10:11], 9, v[10:11]
	v_lshl_add_u64 v[14:15], s[8:9], 0, v[12:13]
	v_lshl_add_u64 v[10:11], v[4:5], 0, v[10:11]
	v_lshl_add_u64 v[12:13], s[12:13], 0, v[12:13]
	global_load_dword v16, v[12:13], off
	s_waitcnt vmcnt(1)
	v_fmac_f32_e32 v18, v17, v7
	global_store_dword v[14:15], v18, off sc1
	global_load_dword v7, v[10:11], off
	v_or_b32_e32 v10, 4, v6
	v_ashrrev_i32_e32 v11, 31, v10
	v_lshlrev_b64 v[12:13], 16, v[10:11]
	v_or_b32_e32 v12, v12, v2
	v_lshlrev_b64 v[10:11], 9, v[10:11]
	v_lshl_add_u64 v[14:15], s[8:9], 0, v[12:13]
	v_lshl_add_u64 v[10:11], v[4:5], 0, v[10:11]
	v_lshl_add_u64 v[12:13], s[12:13], 0, v[12:13]
	global_load_dword v17, v[12:13], off
	s_waitcnt vmcnt(1)
	v_fmac_f32_e32 v16, v18, v7
	global_store_dword v[14:15], v16, off sc1
	global_load_dword v7, v[10:11], off
	v_or_b32_e32 v10, 5, v6
	v_ashrrev_i32_e32 v11, 31, v10
	v_lshlrev_b64 v[12:13], 16, v[10:11]
	v_or_b32_e32 v12, v12, v2
	v_lshlrev_b64 v[10:11], 9, v[10:11]
	v_lshl_add_u64 v[14:15], s[8:9], 0, v[12:13]
	v_lshl_add_u64 v[10:11], v[4:5], 0, v[10:11]
	v_lshl_add_u64 v[12:13], s[12:13], 0, v[12:13]
	global_load_dword v18, v[12:13], off
	s_waitcnt vmcnt(1)
	v_fmac_f32_e32 v17, v16, v7
	global_store_dword v[14:15], v17, off sc1
	global_load_dword v7, v[10:11], off
	v_or_b32_e32 v10, 6, v6
	v_ashrrev_i32_e32 v11, 31, v10
	v_lshlrev_b64 v[12:13], 16, v[10:11]
	v_or_b32_e32 v12, v12, v2
	v_lshlrev_b64 v[10:11], 9, v[10:11]
	v_lshl_add_u64 v[14:15], s[8:9], 0, v[12:13]
	v_lshl_add_u64 v[10:11], v[4:5], 0, v[10:11]
	v_lshl_add_u64 v[12:13], s[12:13], 0, v[12:13]
	global_load_dword v16, v[12:13], off
	s_waitcnt vmcnt(1)
	v_fmac_f32_e32 v18, v17, v7
	global_store_dword v[14:15], v18, off sc1
	global_load_dword v7, v[10:11], off
	v_or_b32_e32 v10, 7, v6
	v_ashrrev_i32_e32 v11, 31, v10
	v_lshlrev_b64 v[12:13], 16, v[10:11]
	v_or_b32_e32 v12, v12, v2
	v_lshlrev_b64 v[10:11], 9, v[10:11]
	v_lshl_add_u64 v[14:15], s[8:9], 0, v[12:13]
	v_lshl_add_u64 v[10:11], v[4:5], 0, v[10:11]
	v_lshl_add_u64 v[12:13], s[12:13], 0, v[12:13]
	global_load_dword v17, v[12:13], off
	s_waitcnt vmcnt(1)
; __global__ void __launch_bounds__(NWAVES * 64, 2) fwd(Args args) {
;     ...
;         for (int e = gt; e < NH * HD * HD; e += NGT) {
;             const int h = e >> 14, kv = e & 16383, k = kv >> 7; float Sc = 0.f;
; #pragma unroll
;             for (int sc = 0; sc < 16; ++sc) { const size_t it = (size_t)(h * 16 + sc); HS[(it << 14) + kv] = Sc; Sc = HDt[it * 128 + k] * Sc + HU[(it << 14) + kv]; }
;         }
	v_fmac_f32_e32 v16, v18, v7
	global_store_dword v[14:15], v16, off sc1
	global_load_dword v7, v[10:11], off
	v_or_b32_e32 v10, 8, v6
	v_ashrrev_i32_e32 v11, 31, v10
	v_lshlrev_b64 v[12:13], 16, v[10:11]
	v_or_b32_e32 v12, v12, v2
	v_lshlrev_b64 v[10:11], 9, v[10:11]
	v_lshl_add_u64 v[14:15], s[8:9], 0, v[12:13]
	v_lshl_add_u64 v[10:11], v[4:5], 0, v[10:11]
	v_lshl_add_u64 v[12:13], s[12:13], 0, v[12:13]
	global_load_dword v18, v[12:13], off
	s_waitcnt vmcnt(1)
	v_fmac_f32_e32 v17, v16, v7
	global_store_dword v[14:15], v17, off sc1
	global_load_dword v7, v[10:11], off
	v_or_b32_e32 v10, 9, v6
	v_ashrrev_i32_e32 v11, 31, v10
	v_lshlrev_b64 v[12:13], 16, v[10:11]
	v_or_b32_e32 v12, v12, v2
	v_lshlrev_b64 v[10:11], 9, v[10:11]
	v_lshl_add_u64 v[14:15], s[8:9], 0, v[12:13]
	v_lshl_add_u64 v[10:11], v[4:5], 0, v[10:11]
	v_lshl_add_u64 v[12:13], s[12:13], 0, v[12:13]
	global_load_dword v16, v[12:13], off
	s_waitcnt vmcnt(1)
	v_fmac_f32_e32 v18, v17, v7
	global_store_dword v[14:15], v18, off sc1
	global_load_dword v7, v[10:11], off
	v_or_b32_e32 v10, 10, v6
	v_ashrrev_i32_e32 v11, 31, v10
	v_lshlrev_b64 v[12:13], 16, v[10:11]
	v_or_b32_e32 v12, v12, v2
	v_lshlrev_b64 v[10:11], 9, v[10:11]
	v_lshl_add_u64 v[14:15], s[8:9], 0, v[12:13]
	v_lshl_add_u64 v[10:11], v[4:5], 0, v[10:11]
	v_lshl_add_u64 v[12:13], s[12:13], 0, v[12:13]
	global_load_dword v17, v[12:13], off
	s_waitcnt vmcnt(1)
	v_fmac_f32_e32 v16, v18, v7
	global_store_dword v[14:15], v16, off sc1
	global_load_dword v7, v[10:11], off
	v_or_b32_e32 v10, 11, v6
	v_ashrrev_i32_e32 v11, 31, v10
	v_lshlrev_b64 v[12:13], 16, v[10:11]
	v_or_b32_e32 v12, v12, v2
	v_lshlrev_b64 v[10:11], 9, v[10:11]
	v_lshl_add_u64 v[14:15], s[8:9], 0, v[12:13]
	v_lshl_add_u64 v[10:11], v[4:5], 0, v[10:11]
	v_lshl_add_u64 v[12:13], s[12:13], 0, v[12:13]
	global_load_dword v18, v[12:13], off
	s_waitcnt vmcnt(1)
	v_fmac_f32_e32 v17, v16, v7
	global_store_dword v[14:15], v17, off sc1
	global_load_dword v7, v[10:11], off
	v_or_b32_e32 v10, 12, v6
	v_ashrrev_i32_e32 v11, 31, v10
	v_lshlrev_b64 v[12:13], 16, v[10:11]
	v_or_b32_e32 v12, v12, v2
	v_lshlrev_b64 v[10:11], 9, v[10:11]
	v_lshl_add_u64 v[14:15], s[8:9], 0, v[12:13]
	v_lshl_add_u64 v[10:11], v[4:5], 0, v[10:11]
	v_lshl_add_u64 v[12:13], s[12:13], 0, v[12:13]
	global_load_dword v16, v[12:13], off
	s_waitcnt vmcnt(1)
	v_fmac_f32_e32 v18, v17, v7
	global_store_dword v[14:15], v18, off sc1
	global_load_dword v7, v[10:11], off
	v_or_b32_e32 v10, 13, v6
	v_ashrrev_i32_e32 v11, 31, v10
	v_lshlrev_b64 v[12:13], 16, v[10:11]
	v_or_b32_e32 v12, v12, v2
	v_lshlrev_b64 v[10:11], 9, v[10:11]
	v_lshl_add_u64 v[14:15], s[8:9], 0, v[12:13]
	v_lshl_add_u64 v[10:11], v[4:5], 0, v[10:11]
	v_lshl_add_u64 v[12:13], s[12:13], 0, v[12:13]
	global_load_dword v12, v[12:13], off
	v_or_b32_e32 v6, 14, v6
	s_waitcnt vmcnt(1)
	v_fmac_f32_e32 v16, v18, v7
	global_store_dword v[14:15], v16, off sc1
	global_load_dword v13, v[10:11], off
	v_ashrrev_i32_e32 v7, 31, v6
	v_lshlrev_b64 v[10:11], 16, v[6:7]
	v_lshlrev_b64 v[6:7], 9, v[6:7]
	v_or_b32_e32 v10, v10, v2
	v_lshl_add_u64 v[4:5], v[4:5], 0, v[6:7]
	v_lshl_add_u64 v[6:7], s[8:9], 0, v[10:11]
	v_lshl_add_u64 v[10:11], s[12:13], 0, v[10:11]
	global_load_dword v10, v[10:11], off
	s_waitcnt vmcnt(1)
	v_fmac_f32_e32 v12, v16, v13
	global_store_dword v[6:7], v12, off sc1
	global_load_dword v6, v[4:5], off
	v_or_b32_e32 v4, 15, v9
	v_ashrrev_i32_e32 v5, 31, v4
	v_lshlrev_b64 v[4:5], 16, v[4:5]
	v_lshl_add_u64 v[4:5], s[8:9], 0, v[4:5]
	v_lshl_add_u64 v[4:5], v[4:5], 0, v[2:3]
	s_waitcnt vmcnt(0)
	v_fmac_f32_e32 v10, v12, v6
	global_store_dword v[4:5], v10, off sc1
	s_andn2_b64 exec, exec, s[4:5]
	s_cbranch_execnz .LBB0_487

; #define GAS __attribute__((address_space(1)))
; #define LAS __attribute__((address_space(3)))
; #define EX2(x) __builtin_amdgcn_exp2f(x)
;     ...
;     if (FULL && !(VAR & 1)) { __syncthreads(); *(GAS v4u*)(YH + yoff + (size_t)(32 * 15) * D) = *(const LAS v4u*)(YT + tid * 8); }
;     if (!FULL) {
; #pragma unroll
;         for (int kb = 0; kb < 8; ++kb)
; #pragma unroll
;             for (int r = 0; r < 4; ++r) Ubuf[(item << 14) + (size_t)(16 * kb + 4 * q + r) * 128 + 16 * w + fr] = S[kb][r];
;         if (ro == 0) Dtot[item * 128 + k] = EX2(btot);
;     }
;     __syncthreads();
.LBB0_545:
	s_waitcnt lgkmcnt(0)
	s_barrier
	s_waitcnt vmcnt(4)
	ds_read_b128 v[2:5], v185
	s_waitcnt vmcnt(3)
	v_add_co_u32_e32 v6, vcc, 0x3c0000, v132
	s_add_i32 s88, s88, s74
	s_add_i32 s75, s75, s81
	s_add_i32 s33, s33, s82
	v_addc_co_u32_e32 v7, vcc, 0, v133, vcc
	s_cmpk_gt_i32 s88, 0xff
	s_mov_b64 s[92:93], s[22:23]
	s_waitcnt lgkmcnt(0)
	global_store_dwordx4 v[6:7], v[2:5], off sc1
	s_barrier
	s_cbranch_scc1 .LBB0_655

; #define GAS __attribute__((address_space(1)))
; #define LAS __attribute__((address_space(3)))
; __device__ __forceinline__ float bf2f(unsigned short b) { return __uint_as_float(((unsigned)b) << 16); }
;     ...
;         float c[8], gj[8]; gj[0] = bf2f(RG[(8 * ro) * 128 + k]); c[0] = gj[0];
; #pragma unroll
;         for (int j = 1; j < 8; ++j) { gj[j] = bf2f(RG[(8 * ro + j) * 128 + k]); c[j] = c[j - 1] + gj[j]; }
;         OCT[ro * 128 + k] = c[7];
;         __syncthreads();
;         if (FULL && blk > 0 && !(VAR & 1)) *(GAS v4u*)(YH + yoff + (size_t)(32 * (blk - 1)) * D) = *(const LAS v4u*)(YT + tid * 8);
.LBB0_577:
.LBB0_578:
	ds_read_u16 v66, v123
	ds_read_u16 v67, v123 offset:256
	ds_read_u16 v104, v123 offset:512
	ds_read_u16 v105, v123 offset:768
	ds_read_u16 v106, v123 offset:1024
	ds_read_u16 v107, v123 offset:1280
	ds_read_u16 v185, v123 offset:1536
	ds_read_u16 v187, v123 offset:1792
	s_waitcnt lgkmcnt(7)
	v_lshlrev_b32_e32 v116, 16, v66
	s_waitcnt lgkmcnt(6)
	v_lshlrev_b32_e32 v186, 16, v67
	v_add_f32_e32 v67, v116, v186
	s_waitcnt lgkmcnt(5)
	v_lshlrev_b32_e32 v112, 16, v104
	v_add_f32_e32 v114, v67, v112
	s_waitcnt lgkmcnt(4)
	v_lshlrev_b32_e32 v113, 16, v105
	v_add_f32_e32 v115, v114, v113
	s_waitcnt lgkmcnt(3)
	v_lshlrev_b32_e32 v108, 16, v106
	v_add_f32_e32 v110, v115, v108
	s_waitcnt lgkmcnt(2)
	v_lshlrev_b32_e32 v109, 16, v107
	v_add_f32_e32 v111, v110, v109
	s_waitcnt lgkmcnt(1)
	v_lshlrev_b32_e32 v104, 16, v185
	v_add_f32_e32 v106, v111, v104
	s_waitcnt lgkmcnt(0)
	v_lshlrev_b32_e32 v105, 16, v187
	v_add_f32_e32 v107, v106, v105
	s_cmp_eq_u32 s92, 0
	v_add_u32_e32 v185, 0x1d400, v171
	ds_write_b32 v143, v107
	s_waitcnt lgkmcnt(0)
	s_barrier
	s_cbranch_scc1 .LBB0_580
	ds_read_b128 v[188:191], v185
	s_lshl_b64 s[26:27], s[66:67], 13
	v_lshl_add_u64 v[192:193], v[132:133], 0, s[26:27]
	s_waitcnt lgkmcnt(0)
	global_store_dwordx4 v[192:193], v[188:191], off sc1

; __device__ __forceinline__ unsigned cvt_pk_bf16(float lo, float hi) { const cvt_f2 v = {lo, hi}; return __builtin_bit_cast(unsigned, __builtin_convertvector(v, cvt_b2)); }
; #define GAS __attribute__((address_space(1)))
; #define LAS __attribute__((address_space(3)))
; __device__ __forceinline__ float bf2f(unsigned short b) { return __uint_as_float(((unsigned)b) << 16); }
; #define EX2(x) __builtin_amdgcn_exp2f(x)
;     ...
;         float c[8], gj[8]; gj[0] = bf2f(RG[(8 * ro) * 128 + k]); c[0] = gj[0];
; #pragma unroll
;         for (int j = 1; j < 8; ++j) { gj[j] = bf2f(RG[(8 * ro + j) * 128 + k]); c[j] = c[j - 1] + gj[j]; }
;         OCT[ro * 128 + k] = c[7];
;         __syncthreads();
;         if (FULL && blk > 0 && !(VAR & 1)) *(GAS v4u*)(YH + yoff + (size_t)(32 * (blk - 1)) * D) = *(const LAS v4u*)(YT + tid * 8);
;         const float o0 = OCT[k], o1 = OCT[128 + k], o2 = OCT[256 + k], o3 = OCT[384 + k];
;         const float off = (ro > 0 ? o0 : 0.f) + (ro > 1 ? o1 : 0.f) + (ro > 2 ? o2 : 0.f); const float b32 = (o0 + o1) + (o2 + o3);
;         btot += b32;
;         { unsigned kdw[4], vw[4];
; #pragma unroll
;           for (int j = 0; j < 8; j += 2) {
;               const float b0 = off + c[j], b1 = off + c[j + 1]; const float k0 = 1.0f - EX2(gj[j]), k1 = 1.0f - EX2(gj[j + 1]);
;               kdw[j >> 1] = cvt_pk_bf16(k0 * EX2(b32 - b0), k1 * EX2(b32 - b1)); vw[j >> 1] = (unsigned)RV[(8 * ro + j) * 128 + k] | ((unsigned)RV[(8 * ro + j + 1) * 128 + k] << 16);
;               if (FULL && !(VAR & 8)) { const float e0 = EX2(b0), e1 = EX2(b1); const float i0 = EX2(fminf(-b0, 120.f)), i1 = EX2(fminf(-b1, 120.f));
;                   const unsigned qw = cvt_pk_bf16(bf2f(RQ[(8 * ro + j) * 128 + k]) * e0, bf2f(RQ[(8 * ro + j + 1) * 128 + k]) * e1), kw = cvt_pk_bf16(k0 * i0, k1 * i1);
;                   QA[(8 * ro + j) * 136 + k] = (bf16)qw; QA[(8 * ro + j + 1) * 136 + k] = (bf16)(qw >> 16);
;                   KA[(8 * ro + j) * 136 + k] = (bf16)kw; KA[(8 * ro + j + 1) * 136 + k] = (bf16)(kw >> 16); }
.LBB0_623:
.LBB0_624:
	ds_read_u16 v66, v123
	ds_read_u16 v67, v123 offset:256
	ds_read_u16 v104, v123 offset:512
	ds_read_u16 v105, v123 offset:768
	ds_read_u16 v106, v123 offset:1024
	ds_read_u16 v107, v123 offset:1280
	ds_read_u16 v110, v123 offset:1536
	ds_read_u16 v111, v123 offset:1792
	s_waitcnt lgkmcnt(6)
	v_lshlrev_b32_e32 v109, 16, v67
	v_lshlrev_b32_e32 v108, 16, v66
	v_mov_b32_e32 v66, v109
	s_waitcnt lgkmcnt(5)
	v_lshlrev_b32_e32 v116, 16, v104
	v_pk_add_f32 v[66:67], v[66:67], v[108:109]
	s_waitcnt lgkmcnt(4)
	v_lshlrev_b32_e32 v200, 16, v105
	v_add_f32_e32 v201, v66, v116
	s_waitcnt lgkmcnt(3)
	v_lshlrev_b32_e32 v202, 16, v106
	v_add_f32_e32 v206, v201, v200
	s_waitcnt lgkmcnt(2)
	v_lshlrev_b32_e32 v203, 16, v107
	v_add_f32_e32 v207, v206, v202
	s_waitcnt lgkmcnt(1)
	v_lshlrev_b32_e32 v204, 16, v110
	v_add_f32_e32 v208, v207, v203
	s_waitcnt lgkmcnt(0)
	v_lshlrev_b32_e32 v205, 16, v111
	v_add_f32_e32 v209, v208, v204
	v_add_f32_e32 v210, v209, v205
	ds_write_b32 v143, v210
	s_waitcnt lgkmcnt(0)
	s_barrier
	ds_read_b128 v[104:107], v185
	ds_read2st64_b32 v[110:111], v142 offset1:2
	ds_read2st64_b32 v[112:113], v142 offset0:4 offset1:6
	v_exp_f32_e32 v109, v109
	s_waitcnt lgkmcnt(2)
	global_store_dwordx4 v[136:137], v[104:107], off sc1
	s_waitcnt lgkmcnt(1)
	v_cndmask_b32_e64 v67, v110, 0, s[4:5]
	v_cndmask_b32_e64 v104, 0, v111, s[6:7]
	v_add_f32_e32 v105, v67, v104
	s_waitcnt lgkmcnt(0)
	v_cndmask_b32_e64 v107, 0, v112, s[8:9]
	v_mov_b32_e32 v106, v112
	v_mov_b32_e32 v104, v113
	v_add_f32_e32 v110, v110, v111
	v_pk_add_f32 v[106:107], v[106:107], v[104:105]
	v_mov_b32_e32 v111, v66
	v_add_f32_e32 v105, v107, v108
	v_pk_add_f32 v[66:67], v[110:111], v[106:107]
	v_exp_f32_e32 v112, v105
	v_sub_f32_e32 v104, v66, v105
	v_exp_f32_e32 v110, v104
	ds_read_u16 v104, v144
	ds_read_u16 v106, v144 offset:256
	ds_read_u16 v198, v145
	ds_read_u16 v199, v145 offset:256
	v_exp_f32_e32 v113, v67
	v_exp_f32_e32 v108, v108
	v_sub_f32_e32 v111, v66, v67
	v_min_f32_e64 v105, -v105, s87
	v_min_f32_e64 v67, -v67, s87
	v_exp_f32_e32 v111, v111
	v_exp_f32_e32 v114, v105
	v_exp_f32_e32 v115, v67
	s_waitcnt lgkmcnt(0)
	v_lshlrev_b32_e32 v199, 16, v199
	v_lshlrev_b32_e32 v198, 16, v198
	v_pk_mul_f32 v[112:113], v[112:113], v[198:199]
	v_lshl_or_b32 v104, v106, 16, v104
	v_cvt_pk_bf16_f32 v67, v112, v113
	v_pk_add_f32 v[112:113], v[108:109], 1.0 op_sel_hi:[1,0] neg_lo:[1,0] neg_hi:[1,0]
	v_add_f32_e32 v106, v206, v107
	v_pk_mul_f32 v[108:109], v[112:113], v[110:111]
	v_pk_mul_f32 v[110:111], v[112:113], v[114:115]
	v_cvt_pk_bf16_f32 v108, v108, v109
	v_cvt_pk_bf16_f32 v105, v110, v111
	ds_write_b16 v146, v67
	ds_write_b16_d16_hi v146, v67 offset:272
	ds_write_b16 v146, v105 offset:8704
	ds_write_b16_d16_hi v146, v105 offset:8976
	v_add_f32_e32 v67, v201, v107
	v_sub_f32_e32 v105, v66, v67
	v_exp_f32_e32 v110, v116
	v_exp_f32_e32 v111, v200
	v_exp_f32_e32 v112, v105
	ds_read_u16 v105, v147
	ds_read_u16 v109, v147 offset:256
	ds_read_u16 v116, v145 offset:512
	ds_read_u16 v200, v145 offset:768
	v_exp_f32_e32 v114, v67
	v_min_f32_e64 v67, -v67, s87
	v_sub_f32_e32 v113, v66, v106
	v_exp_f32_e32 v115, v106
	v_exp_f32_e32 v198, v67
	v_min_f32_e64 v67, -v106, s87
	v_exp_f32_e32 v113, v113
	v_exp_f32_e32 v199, v67
	s_waitcnt lgkmcnt(0)
	v_lshlrev_b32_e32 v201, 16, v200
	v_lshlrev_b32_e32 v200, 16, v116
	v_pk_mul_f32 v[114:115], v[114:115], v[200:201]
	v_pk_add_f32 v[110:111], v[110:111], 1.0 op_sel_hi:[1,0] neg_lo:[1,0] neg_hi:[1,0]
	v_cvt_pk_bf16_f32 v67, v114, v115
	v_pk_mul_f32 v[112:113], v[110:111], v[112:113]
	v_pk_mul_f32 v[110:111], v[110:111], v[198:199]
	v_lshl_or_b32 v105, v109, 16, v105
	v_cvt_pk_bf16_f32 v106, v110, v111
	ds_write_b16 v148, v67
	ds_write_b16_d16_hi v148, v67 offset:272
	ds_write_b16 v148, v106 offset:8704
	ds_write_b16_d16_hi v148, v106 offset:8976
	v_add_f32_e32 v67, v207, v107
	v_sub_f32_e32 v106, v66, v67
	v_cvt_pk_bf16_f32 v109, v112, v113
	v_exp_f32_e32 v112, v106
	ds_read_u16 v106, v149
	ds_read_u16 v114, v149 offset:256
	ds_read_u16 v200, v145 offset:1024
	ds_read_u16 v201, v145 offset:1280
	v_add_f32_e32 v116, v208, v107
	v_exp_f32_e32 v115, v116
	v_exp_f32_e32 v110, v202
	s_waitcnt lgkmcnt(2)
; __device__ __forceinline__ unsigned cvt_pk_bf16(float lo, float hi) { const cvt_f2 v = {lo, hi}; return __builtin_bit_cast(unsigned, __builtin_convertvector(v, cvt_b2)); }
; #define GAS __attribute__((address_space(1)))
; #define LAS __attribute__((address_space(3)))
; #define EX2(x) __builtin_amdgcn_exp2f(x)
;     ...
;           for (int j = 0; j < 8; j += 2) {
;               const float b0 = off + c[j], b1 = off + c[j + 1]; const float k0 = 1.0f - EX2(gj[j]), k1 = 1.0f - EX2(gj[j + 1]);
;               kdw[j >> 1] = cvt_pk_bf16(k0 * EX2(b32 - b0), k1 * EX2(b32 - b1)); vw[j >> 1] = (unsigned)RV[(8 * ro + j) * 128 + k] | ((unsigned)RV[(8 * ro + j + 1) * 128 + k] << 16);
;               if (FULL && !(VAR & 8)) { const float e0 = EX2(b0), e1 = EX2(b1); const float i0 = EX2(fminf(-b0, 120.f)), i1 = EX2(fminf(-b1, 120.f));
;                   const unsigned qw = cvt_pk_bf16(bf2f(RQ[(8 * ro + j) * 128 + k]) * e0, bf2f(RQ[(8 * ro + j + 1) * 128 + k]) * e1), kw = cvt_pk_bf16(k0 * i0, k1 * i1);
;                   QA[(8 * ro + j) * 136 + k] = (bf16)qw; QA[(8 * ro + j + 1) * 136 + k] = (bf16)(qw >> 16);
;                   KA[(8 * ro + j) * 136 + k] = (bf16)kw; KA[(8 * ro + j + 1) * 136 + k] = (bf16)(kw >> 16); }
;           }
;           *(LAS v4u*)(KDT + k * 40 + 8 * ro) = (v4u){kdw[0], kdw[1], kdw[2], kdw[3]};
;           *(LAS v4u*)(VT + k * 40 + 8 * ro) = (v4u){vw[0], vw[1], vw[2], vw[3]}; }
;         if (ro == 0) DEC[k] = EX2(b32);
;         unsigned short og[8];
;         if (FULL) {
; #pragma unroll
;             for (int kb = 0; kb < 8; ++kb) { v2u wv; wv.x = cvt_pk_bf16(S[kb][0], S[kb][1]); wv.y = cvt_pk_bf16(S[kb][2], S[kb][3]); *(LAS v2u*)(ST + (16 * w + fr) * 136 + 16 * kb + 4 * q) = wv; }
; #pragma unroll
;             for (int tb = 0; tb < 2; ++tb)
; #pragma unroll
;                 for (int r = 0; r < 4; ++r) og[tb * 4 + r] = RO[(16 * tb + 4 * q + r) * 128 + 16 * w + fr];
;         }
;         __syncthreads();
;         if (blk < 15) {
;             *(LAS v4u*)(RG + tid * 8) = xg; *(LAS v4u*)(RV + tid * 8) = xv; if (FULL) { *(LAS v4u*)(RQ + tid * 8) = xq; *(LAS v4u*)(RO + tid * 8) = xog; }
;             if (blk < 13) { const size_t g3 = goff + (size_t)(32 * (blk + 3)) * HW; xg = *(const GAS v4u*)(Gl + g3); xv = *(const GAS v4u*)(Vv + g3); if (FULL) { xq = *(const GAS v4u*)(QS + g3); xog = *(const GAS v4u*)(OG + g3); } }
;         }
	v_lshl_or_b32 v106, v114, 16, v106
	v_exp_f32_e32 v114, v67
	v_min_f32_e64 v67, -v67, s87
	v_exp_f32_e32 v111, v203
	v_sub_f32_e32 v113, v66, v116
	v_exp_f32_e32 v198, v67
	v_min_f32_e64 v67, -v116, s87
	v_exp_f32_e32 v113, v113
	v_exp_f32_e32 v199, v67
	s_waitcnt lgkmcnt(0)
	v_lshlrev_b32_e32 v201, 16, v201
	v_lshlrev_b32_e32 v200, 16, v200
	v_pk_mul_f32 v[114:115], v[114:115], v[200:201]
	s_nop 0
	v_cvt_pk_bf16_f32 v67, v114, v115
	v_pk_add_f32 v[114:115], v[110:111], 1.0 op_sel_hi:[1,0] neg_lo:[1,0] neg_hi:[1,0]
	s_nop 0
	v_pk_mul_f32 v[110:111], v[114:115], v[112:113]
	v_pk_mul_f32 v[112:113], v[114:115], v[198:199]
	v_cvt_pk_bf16_f32 v110, v110, v111
	v_cvt_pk_bf16_f32 v111, v112, v113
	ds_write_b16 v150, v67
	ds_write_b16_d16_hi v150, v67 offset:272
	ds_write_b16 v150, v111 offset:8704
	ds_write_b16_d16_hi v150, v111 offset:8976
	v_add_f32_e32 v67, v209, v107
	v_add_f32_e32 v111, v210, v107
	v_sub_f32_e32 v107, v66, v67
	v_exp_f32_e32 v114, v107
	ds_read_u16 v107, v151
	ds_read_u16 v116, v151 offset:256
	ds_read_u16 v202, v145 offset:1536
	ds_read_u16 v203, v145 offset:1792
	v_exp_f32_e32 v198, v67
	v_min_f32_e64 v67, -v67, s87
	v_exp_f32_e32 v112, v204
	v_exp_f32_e32 v113, v205
	v_sub_f32_e32 v115, v66, v111
	v_exp_f32_e32 v199, v111
	v_exp_f32_e32 v200, v67
	v_min_f32_e64 v67, -v111, s87
	v_exp_f32_e32 v115, v115
	v_exp_f32_e32 v201, v67
	s_waitcnt lgkmcnt(0)
	v_lshlrev_b32_e32 v203, 16, v203
	v_lshlrev_b32_e32 v202, 16, v202
	v_pk_mul_f32 v[198:199], v[198:199], v[202:203]
	v_pk_add_f32 v[112:113], v[112:113], 1.0 op_sel_hi:[1,0] neg_lo:[1,0] neg_hi:[1,0]
	v_cvt_pk_bf16_f32 v67, v198, v199
	v_pk_mul_f32 v[114:115], v[112:113], v[114:115]
	v_pk_mul_f32 v[112:113], v[112:113], v[200:201]
	v_lshl_or_b32 v107, v116, 16, v107
	v_cvt_pk_bf16_f32 v111, v114, v115
	v_cvt_pk_bf16_f32 v112, v112, v113
	ds_write_b16 v152, v67
	ds_write_b16_d16_hi v152, v67 offset:272
	ds_write_b16 v152, v112 offset:8704
	ds_write_b16_d16_hi v152, v112 offset:8976
	ds_write_b128 v172, v[108:111] offset:17408
	ds_write_b128 v172, v[104:107] offset:27648
	s_and_saveexec_b64 vcc, s[4:5]
	v_exp_f32_e32 v66, v66
	ds_write_b32 v159, v66
	s_or_b64 exec, exec, vcc
	v_cvt_pk_bf16_f32 v66, v34, v35
	v_cvt_pk_bf16_f32 v67, v36, v37
	v_cvt_pk_bf16_f32 v104, v38, v39
	v_cvt_pk_bf16_f32 v105, v40, v41
	ds_write2_b64 v187, v[66:67], v[104:105] offset0:128 offset1:132
	v_cvt_pk_bf16_f32 v66, v42, v43
	v_cvt_pk_bf16_f32 v67, v44, v45
	v_cvt_pk_bf16_f32 v104, v46, v47
	v_cvt_pk_bf16_f32 v105, v48, v49
	ds_write2_b64 v187, v[66:67], v[104:105] offset0:136 offset1:140
	v_cvt_pk_bf16_f32 v66, v50, v51
	v_cvt_pk_bf16_f32 v67, v52, v53
	v_cvt_pk_bf16_f32 v104, v54, v55
	v_cvt_pk_bf16_f32 v105, v56, v57
	ds_write2_b64 v187, v[66:67], v[104:105] offset0:144 offset1:148
	v_cvt_pk_bf16_f32 v66, v58, v59
	v_cvt_pk_bf16_f32 v67, v60, v61
	v_cvt_pk_bf16_f32 v104, v62, v63
	v_cvt_pk_bf16_f32 v105, v64, v65
	ds_write2_b64 v187, v[66:67], v[104:105] offset0:152 offset1:156
	ds_read_u16 v200, v173
	ds_read_u16 v201, v173 offset:256
	ds_read_u16 v198, v173 offset:512
	ds_read_u16 v199, v173 offset:768
	ds_read_u16 v116, v173 offset:4096
	ds_read_u16 v187, v173 offset:4352
	ds_read_u16 v66, v173 offset:4608
	ds_read_u16 v67, v173 offset:4864
	s_add_i32 s37, s55, 3
	s_cmp_gt_u32 s37, 14
	s_waitcnt lgkmcnt(0)
	s_barrier
	s_cbranch_scc1 .LBB0_629
	s_cmp_gt_u32 s37, 12
	s_waitcnt vmcnt(4)
	ds_write_b128 v181, v[14:17]
	s_waitcnt vmcnt(3)
	ds_write_b128 v182, v[22:25]
	s_waitcnt vmcnt(2)
	ds_write_b128 v183, v[26:29]
	s_waitcnt vmcnt(1)
	ds_write_b128 v184, v[30:33]
	s_cbranch_scc1 .LBB0_629
	v_lshl_add_u64 v[26:27], v[134:135], 0, s[92:93]
	v_add_co_u32_e32 v14, vcc, 0x25580000, v26
	s_nop 1
	v_addc_co_u32_e32 v15, vcc, 0, v27, vcc
	v_add_co_u32_e32 v22, vcc, 0x29580000, v26
	s_nop 1
	v_addc_co_u32_e32 v23, vcc, 0, v27, vcc
	v_add_co_u32_e32 v28, vcc, 0x23580000, v26
	global_load_dwordx4 v[14:17], v[14:15], off
	s_nop 0
	global_load_dwordx4 v[22:25], v[22:23], off
	v_addc_co_u32_e32 v29, vcc, 0, v27, vcc
	v_add_co_u32_e32 v30, vcc, 0x2b580000, v26
	s_nop 1
	v_addc_co_u32_e32 v31, vcc, 0, v27, vcc
	global_load_dwordx4 v[26:29], v[28:29], off
	s_nop 0
	global_load_dwordx4 v[30:33], v[30:31], off

; __device__ __forceinline__ unsigned cvt_pk_bf16(float lo, float hi) { const cvt_f2 v = {lo, hi}; return __builtin_bit_cast(unsigned, __builtin_convertvector(v, cvt_b2)); }
; __device__ __forceinline__ float bf_lo(unsigned w) { return __uint_as_float(w << 16); }
; __device__ __forceinline__ float bf_hi(unsigned w) { return __uint_as_float(w & 0xffff0000u); }
;     __device__ __forceinline__ void operator()(const f32x4 (&acc)[2][2][4][2], const Unit& u, int wr, int wc, int fr, int fq) const {
;         const int row0 = u.pm * BM + wr * 64 + fr, col0 = u.pn * BM + wc * 32 + 8 * fq;
; #pragma unroll
;         for (int ai = 0; ai < 2; ++ai)
; #pragma unroll
;             for (int m = 0; m < 4; ++m) { const size_t ro = (size_t)(row0 + ai * HALF + m * 16) * D + col0;
; #pragma unroll
;                 for (int bj = 0; bj < 2; ++bj) { const pg8::u32x4 gw = *(const pg8::u32x4*)(GBt + ro + bj * HALF);
;                     f32x4 v0 = acc[ai][bj][m][0], v1 = acc[ai][bj][m][1];
;                     v0[0] *= bf_lo(gw.x); v0[1] *= bf_hi(gw.x); v0[2] *= bf_lo(gw.y); v0[3] *= bf_hi(gw.y);
;                     v1[0] *= bf_lo(gw.z); v1[1] *= bf_hi(gw.z); v1[2] *= bf_lo(gw.w); v1[3] *= bf_hi(gw.w);
;                     pg8::u32x4 w; w.x = cvt_pk_bf16(v0[0], v0[1]); w.y = cvt_pk_bf16(v0[2], v0[3]); w.z = cvt_pk_bf16(v1[0], v1[1]); w.w = cvt_pk_bf16(v1[2], v1[3]);
;                     *(pg8::u32x4*)(O + ro + bj * HALF) = w; } }
;     }
.LBB0_732:
	v_add_u32_e32 v150, s21, v156
	v_or_b32_e32 v132, s73, v158
	v_ashrrev_i32_e32 v151, 31, v150
	v_ashrrev_i32_e32 v133, 31, v132
	v_lshlrev_b64 v[130:131], 12, v[150:151]
	v_lshl_add_u64 v[130:131], v[130:131], 0, v[132:133]
	v_lshlrev_b64 v[130:131], 1, v[130:131]
	v_lshl_add_u64 v[152:153], s[42:43], 0, v[130:131]
	global_load_dwordx4 v[164:167], v[152:153], off
	global_load_dwordx4 v[168:171], v[152:153], off offset:256
	v_or_b32_e32 v152, 16, v150
	v_ashrrev_i32_e32 v153, 31, v152
	v_lshlrev_b64 v[152:153], 12, v[152:153]
	v_lshl_add_u64 v[152:153], v[152:153], 0, v[132:133]
	v_lshl_add_u64 v[160:161], s[38:39], 0, v[130:131]
	v_lshlrev_b64 v[152:153], 1, v[152:153]
	v_lshl_add_u64 v[172:173], s[42:43], 0, v[152:153]
	s_andn2_b64 vcc, exec, s[4:5]
	s_mov_b64 s[0:1], -1
	s_waitcnt vmcnt(0)
	v_lshlrev_b32_e32 v174, 16, v164
	v_and_b32_e32 v175, 0xffff0000, v164
	v_lshlrev_b32_e32 v164, 16, v165
	v_and_b32_e32 v165, 0xffff0000, v165
	v_lshlrev_b32_e32 v176, 16, v166
	v_and_b32_e32 v177, 0xffff0000, v166
	v_lshlrev_b32_e32 v166, 16, v167
	v_and_b32_e32 v167, 0xffff0000, v167
	v_lshlrev_b32_e32 v178, 16, v168
	v_and_b32_e32 v179, 0xffff0000, v168
	v_lshlrev_b32_e32 v168, 16, v169
	v_and_b32_e32 v169, 0xffff0000, v169
	v_lshlrev_b32_e32 v180, 16, v170
	v_and_b32_e32 v181, 0xffff0000, v170
	v_lshlrev_b32_e32 v170, 16, v171
	v_and_b32_e32 v171, 0xffff0000, v171
	v_pk_mul_f32 v[126:127], v[126:127], v[174:175]
	v_pk_mul_f32 v[128:129], v[128:129], v[164:165]
	v_pk_mul_f32 v[122:123], v[122:123], v[176:177]
	v_pk_mul_f32 v[124:125], v[124:125], v[166:167]
	v_pk_mul_f32 v[118:119], v[118:119], v[178:179]
	v_pk_mul_f32 v[120:121], v[120:121], v[168:169]
	v_pk_mul_f32 v[164:165], v[114:115], v[180:181]
	v_pk_mul_f32 v[166:167], v[116:117], v[170:171]
	v_cvt_pk_bf16_f32 v114, v126, v127
	v_cvt_pk_bf16_f32 v115, v128, v129
	v_cvt_pk_bf16_f32 v116, v122, v123
	v_cvt_pk_bf16_f32 v117, v124, v125
	v_cvt_pk_bf16_f32 v118, v118, v119
	v_cvt_pk_bf16_f32 v119, v120, v121
	v_cvt_pk_bf16_f32 v120, v164, v165
	v_cvt_pk_bf16_f32 v121, v166, v167
	global_store_dwordx4 v[160:161], v[114:117], off sc1
	global_store_dwordx4 v[160:161], v[118:121], off offset:256 sc1
	global_load_dwordx4 v[114:117], v[172:173], off
	s_nop 0
	global_load_dwordx4 v[118:121], v[172:173], off offset:256
	v_or_b32_e32 v122, 32, v150
	v_ashrrev_i32_e32 v123, 31, v122
	v_lshlrev_b64 v[122:123], 12, v[122:123]
	v_lshl_add_u64 v[124:125], s[38:39], 0, v[152:153]
	v_lshl_add_u64 v[122:123], v[122:123], 0, v[132:133]
	v_lshlrev_b64 v[122:123], 1, v[122:123]
	v_lshl_add_u64 v[126:127], s[42:43], 0, v[122:123]
	s_waitcnt vmcnt(1)
	v_lshlrev_b32_e32 v128, 16, v114
	v_and_b32_e32 v129, 0xffff0000, v114
	v_lshlrev_b32_e32 v114, 16, v115
	v_and_b32_e32 v115, 0xffff0000, v115
	v_lshlrev_b32_e32 v152, 16, v116
	v_and_b32_e32 v153, 0xffff0000, v116
	v_lshlrev_b32_e32 v116, 16, v117
	v_and_b32_e32 v117, 0xffff0000, v117
	s_waitcnt vmcnt(0)
	v_lshlrev_b32_e32 v160, 16, v118
	v_and_b32_e32 v161, 0xffff0000, v118
	v_lshlrev_b32_e32 v118, 16, v119
	v_and_b32_e32 v119, 0xffff0000, v119
	v_lshlrev_b32_e32 v164, 16, v120
	v_and_b32_e32 v165, 0xffff0000, v120
	v_lshlrev_b32_e32 v120, 16, v121
	v_and_b32_e32 v121, 0xffff0000, v121
	v_pk_mul_f32 v[110:111], v[110:111], v[128:129]
	v_pk_mul_f32 v[112:113], v[112:113], v[114:115]
	v_pk_mul_f32 v[106:107], v[106:107], v[152:153]
	v_pk_mul_f32 v[108:109], v[108:109], v[116:117]
	v_pk_mul_f32 v[102:103], v[102:103], v[160:161]
	v_pk_mul_f32 v[104:105], v[104:105], v[118:119]
	v_pk_mul_f32 v[114:115], v[98:99], v[164:165]
	v_pk_mul_f32 v[116:117], v[100:101], v[120:121]
	v_cvt_pk_bf16_f32 v98, v110, v111
	v_cvt_pk_bf16_f32 v99, v112, v113
	v_cvt_pk_bf16_f32 v100, v106, v107
	v_cvt_pk_bf16_f32 v101, v108, v109
	v_cvt_pk_bf16_f32 v102, v102, v103
	v_cvt_pk_bf16_f32 v103, v104, v105
	v_cvt_pk_bf16_f32 v104, v114, v115
	v_cvt_pk_bf16_f32 v105, v116, v117
	global_store_dwordx4 v[124:125], v[98:101], off sc1
	global_store_dwordx4 v[124:125], v[102:105], off offset:256 sc1
	global_load_dwordx4 v[98:101], v[126:127], off
	s_nop 0
	global_load_dwordx4 v[102:105], v[126:127], off offset:256
	v_or_b32_e32 v106, 48, v150
	v_ashrrev_i32_e32 v107, 31, v106
	v_lshlrev_b64 v[106:107], 12, v[106:107]
	v_lshl_add_u64 v[106:107], v[106:107], 0, v[132:133]
	v_lshlrev_b64 v[106:107], 1, v[106:107]
	v_lshl_add_u64 v[108:109], s[38:39], 0, v[122:123]
	v_lshl_add_u64 v[110:111], s[42:43], 0, v[106:107]
	s_waitcnt vmcnt(1)
	v_lshlrev_b32_e32 v112, 16, v98
	v_and_b32_e32 v113, 0xffff0000, v98
	v_lshlrev_b32_e32 v98, 16, v99
	v_and_b32_e32 v99, 0xffff0000, v99
	v_lshlrev_b32_e32 v114, 16, v100
	v_and_b32_e32 v115, 0xffff0000, v100
	v_lshlrev_b32_e32 v100, 16, v101
	v_and_b32_e32 v101, 0xffff0000, v101
	s_waitcnt vmcnt(0)
	v_lshlrev_b32_e32 v116, 16, v102
	v_and_b32_e32 v117, 0xffff0000, v102
	v_lshlrev_b32_e32 v102, 16, v103
	v_and_b32_e32 v103, 0xffff0000, v103
	v_lshlrev_b32_e32 v118, 16, v104
	v_and_b32_e32 v119, 0xffff0000, v104
	v_lshlrev_b32_e32 v104, 16, v105
	v_and_b32_e32 v105, 0xffff0000, v105
	v_pk_mul_f32 v[94:95], v[94:95], v[112:113]
	v_pk_mul_f32 v[96:97], v[96:97], v[98:99]
	v_pk_mul_f32 v[90:91], v[90:91], v[114:115]
	v_pk_mul_f32 v[92:93], v[92:93], v[100:101]
	v_pk_mul_f32 v[86:87], v[86:87], v[116:117]
	v_pk_mul_f32 v[88:89], v[88:89], v[102:103]
	v_pk_mul_f32 v[98:99], v[82:83], v[118:119]
	v_pk_mul_f32 v[100:101], v[84:85], v[104:105]
	v_cvt_pk_bf16_f32 v82, v94, v95
	v_cvt_pk_bf16_f32 v83, v96, v97
	v_cvt_pk_bf16_f32 v84, v90, v91
	v_cvt_pk_bf16_f32 v85, v92, v93
	v_cvt_pk_bf16_f32 v86, v86, v87
	v_cvt_pk_bf16_f32 v87, v88, v89
	v_cvt_pk_bf16_f32 v88, v98, v99
	v_cvt_pk_bf16_f32 v89, v100, v101
	global_store_dwordx4 v[108:109], v[82:85], off sc1
	global_store_dwordx4 v[108:109], v[86:89], off offset:256 sc1
	global_load_dwordx4 v[82:85], v[110:111], off
	s_nop 0
	global_load_dwordx4 v[86:89], v[110:111], off offset:256
	v_lshl_add_u64 v[90:91], v[130:131], 0, s[6:7]
	v_lshl_add_u64 v[92:93], s[38:39], 0, v[106:107]
	v_lshl_add_u64 v[94:95], s[42:43], 0, v[90:91]
	s_waitcnt vmcnt(1)
; __device__ __forceinline__ unsigned cvt_pk_bf16(float lo, float hi) { const cvt_f2 v = {lo, hi}; return __builtin_bit_cast(unsigned, __builtin_convertvector(v, cvt_b2)); }
; __device__ __forceinline__ float bf_lo(unsigned w) { return __uint_as_float(w << 16); }
; __device__ __forceinline__ float bf_hi(unsigned w) { return __uint_as_float(w & 0xffff0000u); }
;     __device__ __forceinline__ void operator()(const f32x4 (&acc)[2][2][4][2], const Unit& u, int wr, int wc, int fr, int fq) const {
;         const int row0 = u.pm * BM + wr * 64 + fr, col0 = u.pn * BM + wc * 32 + 8 * fq;
; #pragma unroll
;         for (int ai = 0; ai < 2; ++ai)
; #pragma unroll
;             for (int m = 0; m < 4; ++m) { const size_t ro = (size_t)(row0 + ai * HALF + m * 16) * D + col0;
; #pragma unroll
;                 for (int bj = 0; bj < 2; ++bj) { const pg8::u32x4 gw = *(const pg8::u32x4*)(GBt + ro + bj * HALF);
;                     f32x4 v0 = acc[ai][bj][m][0], v1 = acc[ai][bj][m][1];
;                     v0[0] *= bf_lo(gw.x); v0[1] *= bf_hi(gw.x); v0[2] *= bf_lo(gw.y); v0[3] *= bf_hi(gw.y);
;                     v1[0] *= bf_lo(gw.z); v1[1] *= bf_hi(gw.z); v1[2] *= bf_lo(gw.w); v1[3] *= bf_hi(gw.w);
;                     pg8::u32x4 w; w.x = cvt_pk_bf16(v0[0], v0[1]); w.y = cvt_pk_bf16(v0[2], v0[3]); w.z = cvt_pk_bf16(v1[0], v1[1]); w.w = cvt_pk_bf16(v1[2], v1[3]);
;                     *(pg8::u32x4*)(O + ro + bj * HALF) = w; } }
;     }
	v_lshlrev_b32_e32 v96, 16, v82
	v_and_b32_e32 v97, 0xffff0000, v82
	v_lshlrev_b32_e32 v82, 16, v83
	v_and_b32_e32 v83, 0xffff0000, v83
	v_lshlrev_b32_e32 v98, 16, v84
	v_and_b32_e32 v99, 0xffff0000, v84
	v_lshlrev_b32_e32 v84, 16, v85
	v_and_b32_e32 v85, 0xffff0000, v85
	s_waitcnt vmcnt(0)
	v_lshlrev_b32_e32 v100, 16, v86
	v_and_b32_e32 v101, 0xffff0000, v86
	v_lshlrev_b32_e32 v86, 16, v87
	v_and_b32_e32 v87, 0xffff0000, v87
	v_lshlrev_b32_e32 v102, 16, v88
	v_and_b32_e32 v103, 0xffff0000, v88
	v_lshlrev_b32_e32 v88, 16, v89
	v_and_b32_e32 v89, 0xffff0000, v89
	v_pk_mul_f32 v[78:79], v[78:79], v[96:97]
	v_pk_mul_f32 v[80:81], v[80:81], v[82:83]
	v_pk_mul_f32 v[74:75], v[74:75], v[98:99]
	v_pk_mul_f32 v[76:77], v[76:77], v[84:85]
	v_pk_mul_f32 v[70:71], v[70:71], v[100:101]
	v_pk_mul_f32 v[72:73], v[72:73], v[86:87]
	v_pk_mul_f32 v[82:83], v[66:67], v[102:103]
	v_pk_mul_f32 v[84:85], v[68:69], v[88:89]
	v_cvt_pk_bf16_f32 v66, v78, v79
	v_cvt_pk_bf16_f32 v67, v80, v81
	v_cvt_pk_bf16_f32 v68, v74, v75
	v_cvt_pk_bf16_f32 v69, v76, v77
	v_cvt_pk_bf16_f32 v70, v70, v71
	v_cvt_pk_bf16_f32 v71, v72, v73
	v_cvt_pk_bf16_f32 v72, v82, v83
	v_cvt_pk_bf16_f32 v73, v84, v85
	global_store_dwordx4 v[92:93], v[66:69], off sc1
	global_store_dwordx4 v[92:93], v[70:73], off offset:256 sc1
	global_load_dwordx4 v[66:69], v[94:95], off
	s_nop 0
	global_load_dwordx4 v[70:73], v[94:95], off offset:256
	v_lshl_add_u64 v[74:75], v[130:131], 0, s[14:15]
	v_lshl_add_u64 v[76:77], s[38:39], 0, v[90:91]
	v_lshl_add_u64 v[78:79], s[42:43], 0, v[74:75]
	s_waitcnt vmcnt(1)
	v_lshlrev_b32_e32 v80, 16, v66
	v_and_b32_e32 v81, 0xffff0000, v66
	v_lshlrev_b32_e32 v66, 16, v67
	v_and_b32_e32 v67, 0xffff0000, v67
	v_lshlrev_b32_e32 v82, 16, v68
	v_and_b32_e32 v83, 0xffff0000, v68
	v_lshlrev_b32_e32 v68, 16, v69
	v_and_b32_e32 v69, 0xffff0000, v69
	s_waitcnt vmcnt(0)
	v_lshlrev_b32_e32 v84, 16, v70
	v_and_b32_e32 v85, 0xffff0000, v70
	v_lshlrev_b32_e32 v70, 16, v71
	v_and_b32_e32 v71, 0xffff0000, v71
	v_lshlrev_b32_e32 v86, 16, v72
	v_and_b32_e32 v87, 0xffff0000, v72
	v_lshlrev_b32_e32 v72, 16, v73
	v_and_b32_e32 v73, 0xffff0000, v73
	v_pk_mul_f32 v[62:63], v[62:63], v[80:81]
	v_pk_mul_f32 v[64:65], v[64:65], v[66:67]
	v_pk_mul_f32 v[58:59], v[58:59], v[82:83]
	v_pk_mul_f32 v[60:61], v[60:61], v[68:69]
	v_pk_mul_f32 v[54:55], v[54:55], v[84:85]
	v_pk_mul_f32 v[56:57], v[56:57], v[70:71]
	v_pk_mul_f32 v[66:67], v[50:51], v[86:87]
	v_pk_mul_f32 v[68:69], v[52:53], v[72:73]
	v_cvt_pk_bf16_f32 v50, v62, v63
	v_cvt_pk_bf16_f32 v51, v64, v65
	v_cvt_pk_bf16_f32 v52, v58, v59
	v_cvt_pk_bf16_f32 v53, v60, v61
	v_cvt_pk_bf16_f32 v54, v54, v55
	v_cvt_pk_bf16_f32 v55, v56, v57
	v_cvt_pk_bf16_f32 v56, v66, v67
	v_cvt_pk_bf16_f32 v57, v68, v69
	global_store_dwordx4 v[76:77], v[50:53], off sc1
	global_store_dwordx4 v[76:77], v[54:57], off offset:256 sc1
	global_load_dwordx4 v[50:53], v[78:79], off
	s_nop 0
	global_load_dwordx4 v[54:57], v[78:79], off offset:256
	v_lshl_add_u64 v[58:59], v[130:131], 0, s[16:17]
	v_lshl_add_u64 v[60:61], s[38:39], 0, v[74:75]
	v_lshl_add_u64 v[62:63], s[42:43], 0, v[58:59]
	s_waitcnt vmcnt(1)
	v_lshlrev_b32_e32 v64, 16, v50
	v_and_b32_e32 v65, 0xffff0000, v50
	v_lshlrev_b32_e32 v50, 16, v51
	v_and_b32_e32 v51, 0xffff0000, v51
	v_lshlrev_b32_e32 v66, 16, v52
	v_and_b32_e32 v67, 0xffff0000, v52
	v_lshlrev_b32_e32 v52, 16, v53
	v_and_b32_e32 v53, 0xffff0000, v53
	s_waitcnt vmcnt(0)
; __device__ __forceinline__ unsigned cvt_pk_bf16(float lo, float hi) { const cvt_f2 v = {lo, hi}; return __builtin_bit_cast(unsigned, __builtin_convertvector(v, cvt_b2)); }
; __device__ __forceinline__ float bf_lo(unsigned w) { return __uint_as_float(w << 16); }
; __device__ __forceinline__ float bf_hi(unsigned w) { return __uint_as_float(w & 0xffff0000u); }
;     __device__ __forceinline__ void operator()(const f32x4 (&acc)[2][2][4][2], const Unit& u, int wr, int wc, int fr, int fq) const {
;         const int row0 = u.pm * BM + wr * 64 + fr, col0 = u.pn * BM + wc * 32 + 8 * fq;
; #pragma unroll
;         for (int ai = 0; ai < 2; ++ai)
; #pragma unroll
;             for (int m = 0; m < 4; ++m) { const size_t ro = (size_t)(row0 + ai * HALF + m * 16) * D + col0;
; #pragma unroll
;                 for (int bj = 0; bj < 2; ++bj) { const pg8::u32x4 gw = *(const pg8::u32x4*)(GBt + ro + bj * HALF);
;                     f32x4 v0 = acc[ai][bj][m][0], v1 = acc[ai][bj][m][1];
;                     v0[0] *= bf_lo(gw.x); v0[1] *= bf_hi(gw.x); v0[2] *= bf_lo(gw.y); v0[3] *= bf_hi(gw.y);
;                     v1[0] *= bf_lo(gw.z); v1[1] *= bf_hi(gw.z); v1[2] *= bf_lo(gw.w); v1[3] *= bf_hi(gw.w);
;                     pg8::u32x4 w; w.x = cvt_pk_bf16(v0[0], v0[1]); w.y = cvt_pk_bf16(v0[2], v0[3]); w.z = cvt_pk_bf16(v1[0], v1[1]); w.w = cvt_pk_bf16(v1[2], v1[3]);
;                     *(pg8::u32x4*)(O + ro + bj * HALF) = w; } }
;     }
	v_lshlrev_b32_e32 v68, 16, v54
	v_and_b32_e32 v69, 0xffff0000, v54
	v_lshlrev_b32_e32 v54, 16, v55
	v_and_b32_e32 v55, 0xffff0000, v55
	v_lshlrev_b32_e32 v70, 16, v56
	v_and_b32_e32 v71, 0xffff0000, v56
	v_lshlrev_b32_e32 v56, 16, v57
	v_and_b32_e32 v57, 0xffff0000, v57
	v_pk_mul_f32 v[46:47], v[46:47], v[64:65]
	v_pk_mul_f32 v[48:49], v[48:49], v[50:51]
	v_pk_mul_f32 v[42:43], v[42:43], v[66:67]
	v_pk_mul_f32 v[44:45], v[44:45], v[52:53]
	v_pk_mul_f32 v[38:39], v[38:39], v[68:69]
	v_pk_mul_f32 v[40:41], v[40:41], v[54:55]
	v_pk_mul_f32 v[50:51], v[34:35], v[70:71]
	v_pk_mul_f32 v[52:53], v[36:37], v[56:57]
	v_cvt_pk_bf16_f32 v34, v46, v47
	v_cvt_pk_bf16_f32 v35, v48, v49
	v_cvt_pk_bf16_f32 v36, v42, v43
	v_cvt_pk_bf16_f32 v37, v44, v45
	v_cvt_pk_bf16_f32 v38, v38, v39
	v_cvt_pk_bf16_f32 v39, v40, v41
	v_cvt_pk_bf16_f32 v40, v50, v51
	v_cvt_pk_bf16_f32 v41, v52, v53
	global_store_dwordx4 v[60:61], v[34:37], off sc1
	global_store_dwordx4 v[60:61], v[38:41], off offset:256 sc1
	global_load_dwordx4 v[34:37], v[62:63], off
	s_nop 0
	global_load_dwordx4 v[38:41], v[62:63], off offset:256
	v_lshl_add_u64 v[42:43], v[130:131], 0, s[18:19]
	v_lshl_add_u64 v[44:45], s[38:39], 0, v[58:59]
	v_lshl_add_u64 v[46:47], s[42:43], 0, v[42:43]
	s_waitcnt vmcnt(1)
	v_lshlrev_b32_e32 v48, 16, v34
	v_and_b32_e32 v49, 0xffff0000, v34
	v_lshlrev_b32_e32 v34, 16, v35
	v_and_b32_e32 v35, 0xffff0000, v35
	v_lshlrev_b32_e32 v50, 16, v36
	v_and_b32_e32 v51, 0xffff0000, v36
	v_lshlrev_b32_e32 v36, 16, v37
	v_and_b32_e32 v37, 0xffff0000, v37
	s_waitcnt vmcnt(0)
	v_lshlrev_b32_e32 v52, 16, v38
	v_and_b32_e32 v53, 0xffff0000, v38
	v_lshlrev_b32_e32 v38, 16, v39
	v_and_b32_e32 v39, 0xffff0000, v39
	v_lshlrev_b32_e32 v54, 16, v40
	v_and_b32_e32 v55, 0xffff0000, v40
	v_lshlrev_b32_e32 v40, 16, v41
	v_and_b32_e32 v41, 0xffff0000, v41
	v_pk_mul_f32 v[30:31], v[30:31], v[48:49]
	v_pk_mul_f32 v[32:33], v[32:33], v[34:35]
	v_pk_mul_f32 v[26:27], v[26:27], v[50:51]
	v_pk_mul_f32 v[28:29], v[28:29], v[36:37]
	v_pk_mul_f32 v[22:23], v[22:23], v[52:53]
	v_pk_mul_f32 v[24:25], v[24:25], v[38:39]
	v_pk_mul_f32 v[34:35], v[18:19], v[54:55]
	v_pk_mul_f32 v[36:37], v[20:21], v[40:41]
	v_cvt_pk_bf16_f32 v18, v30, v31
	v_cvt_pk_bf16_f32 v19, v32, v33
	v_cvt_pk_bf16_f32 v20, v26, v27
	v_cvt_pk_bf16_f32 v21, v28, v29
	v_cvt_pk_bf16_f32 v22, v22, v23
	v_cvt_pk_bf16_f32 v23, v24, v25
	v_cvt_pk_bf16_f32 v24, v34, v35
	v_cvt_pk_bf16_f32 v25, v36, v37
	global_store_dwordx4 v[44:45], v[18:21], off sc1
	global_store_dwordx4 v[44:45], v[22:25], off offset:256 sc1
	global_load_dwordx4 v[18:21], v[46:47], off
	s_nop 0
	global_load_dwordx4 v[22:25], v[46:47], off offset:256
	v_lshl_add_u64 v[26:27], s[38:39], 0, v[42:43]
	s_waitcnt vmcnt(1)
	v_lshlrev_b32_e32 v28, 16, v18
	v_and_b32_e32 v29, 0xffff0000, v18
	v_lshlrev_b32_e32 v18, 16, v19
	v_and_b32_e32 v19, 0xffff0000, v19
	v_lshlrev_b32_e32 v30, 16, v20
	v_and_b32_e32 v31, 0xffff0000, v20
	v_lshlrev_b32_e32 v20, 16, v21
	v_and_b32_e32 v21, 0xffff0000, v21
	s_waitcnt vmcnt(0)
	v_lshlrev_b32_e32 v32, 16, v22
	v_and_b32_e32 v33, 0xffff0000, v22
	v_lshlrev_b32_e32 v22, 16, v23
	v_and_b32_e32 v23, 0xffff0000, v23
	v_lshlrev_b32_e32 v34, 16, v24
	v_and_b32_e32 v35, 0xffff0000, v24
	v_lshlrev_b32_e32 v24, 16, v25
	v_and_b32_e32 v25, 0xffff0000, v25
	v_pk_mul_f32 v[14:15], v[14:15], v[28:29]
	v_pk_mul_f32 v[16:17], v[16:17], v[18:19]
	v_pk_mul_f32 v[10:11], v[10:11], v[30:31]
	v_pk_mul_f32 v[12:13], v[12:13], v[20:21]
	v_pk_mul_f32 v[6:7], v[6:7], v[32:33]
	v_pk_mul_f32 v[8:9], v[8:9], v[22:23]
	v_pk_mul_f32 v[18:19], v[2:3], v[34:35]
	v_pk_mul_f32 v[20:21], v[4:5], v[24:25]
	v_cvt_pk_bf16_f32 v2, v14, v15
	v_cvt_pk_bf16_f32 v3, v16, v17
	v_cvt_pk_bf16_f32 v4, v10, v11
	v_cvt_pk_bf16_f32 v5, v12, v13
	v_cvt_pk_bf16_f32 v6, v6, v7
	v_cvt_pk_bf16_f32 v7, v8, v9
	v_cvt_pk_bf16_f32 v8, v18, v19
	v_cvt_pk_bf16_f32 v9, v20, v21
	global_store_dwordx4 v[26:27], v[2:5], off sc1
	global_store_dwordx4 v[26:27], v[6:9], off offset:256 sc1
	s_cbranch_vccnz .LBB0_719
	s_andn2_b64 vcc, exec, s[8:9]
	s_cbranch_vccnz .LBB0_718
	s_barrier
	s_branch .LBB0_718

; __device__ __forceinline__ unsigned cvt_pk_bf16(float lo, float hi) { const cvt_f2 v = {lo, hi}; return __builtin_bit_cast(unsigned, __builtin_convertvector(v, cvt_b2)); }
;     __device__ __forceinline__ void operator()(const f32x4 (&acc)[2][2][4][2], const Unit& u, int wr, int wc, int fr, int fq) const {
;         const int row0 = u.pm * BM + wr * 64 + fr, col0 = u.pn * BM + wc * 32 + 8 * fq;
;         float ssv[2][4];
; #pragma unroll
;         for (int ai = 0; ai < 2; ++ai)
; #pragma unroll
;             for (int m = 0; m < 4; ++m) { const size_t ro = (size_t)(row0 + ai * HALF + m * 16) * D + col0; float ss = 0.f;
; #pragma unroll
;                 for (int bj = 0; bj < 2; ++bj) {
;                     const f32x4 h0 = acc[ai][bj][m][0], h1 = acc[ai][bj][m][1];
;                     ss += (h0[0] * h0[0] + h0[1] * h0[1]) + (h0[2] * h0[2] + h0[3] * h0[3]) + (h1[0] * h1[0] + h1[1] * h1[1]) + (h1[2] * h1[2] + h1[3] * h1[3]);
;                     pg8::u32x4 w; w.x = cvt_pk_bf16(h0[0], h0[1]); w.y = cvt_pk_bf16(h0[2], h0[3]); w.z = cvt_pk_bf16(h1[0], h1[1]); w.w = cvt_pk_bf16(h1[2], h1[3]);
;                     *(pg8::u32x4*)(HB + ro + bj * HALF) = w;
;                 }
;                 ss += __shfl_xor(ss, 16); ss += __shfl_xor(ss, 32); ssv[ai][m] = ss;
;             }
;         if (fq == 0) {
; #pragma unroll
;             for (int ai = 0; ai < 2; ++ai)
; #pragma unroll
;                 for (int m = 0; m < 4; ++m) SSQ[(size_t)(u.pn * 4 + wc) * T + row0 + ai * HALF + m * 16] = ssv[ai][m];
;         }
;     }
.LBB0_813:
	v_and_b32_e32 v5, 64, v189
	v_xor_b32_e32 v3, 16, v189
	v_add_u32_e32 v5, 64, v5
	v_cmp_lt_i32_e32 vcc, v3, v5
	v_mul_f32_e32 v140, v133, v133
	v_fmac_f32_e32 v140, v132, v132
	v_cndmask_b32_e32 v3, v189, v3, vcc
	v_lshlrev_b32_e32 v138, 2, v3
	v_xor_b32_e32 v3, 32, v189
	v_cmp_lt_i32_e32 vcc, v3, v5
	v_add_u32_e32 v4, s21, v185
	v_or_b32_e32 v134, s76, v187
	v_cndmask_b32_e32 v3, v189, v3, vcc
	v_lshlrev_b32_e32 v139, 2, v3
	v_mul_f32_e32 v3, v131, v131
	v_fmac_f32_e32 v3, v130, v130
	v_add_f32_e32 v3, v3, v140
	v_mul_f32_e32 v140, v127, v127
	v_ashrrev_i32_e32 v5, 31, v4
	v_fmac_f32_e32 v140, v126, v126
	v_ashrrev_i32_e32 v135, 31, v134
	v_lshlrev_b64 v[136:137], 13, v[4:5]
	v_add_f32_e32 v3, v3, v140
	v_mul_f32_e32 v140, v129, v129
	v_fmac_f32_e32 v140, v128, v128
	v_cvt_pk_bf16_f32 v130, v130, v131
	v_cvt_pk_bf16_f32 v131, v132, v133
	v_cvt_pk_bf16_f32 v132, v126, v127
	v_cvt_pk_bf16_f32 v133, v128, v129
	v_lshl_add_u64 v[126:127], s[8:9], 0, v[136:137]
	v_lshlrev_b64 v[128:129], 1, v[134:135]
	v_lshl_add_u64 v[126:127], v[126:127], 0, v[128:129]
	global_store_dwordx4 v[126:127], v[130:133], off sc1
	s_mov_b32 s21, 0x100000
	v_add_f32_e32 v3, v140, v3
	v_mul_f32_e32 v130, v123, v123
	v_mul_f32_e32 v131, v125, v125
	v_fmac_f32_e32 v130, v122, v122
	v_fmac_f32_e32 v131, v124, v124
	v_cvt_pk_bf16_f32 v122, v122, v123
	v_cvt_pk_bf16_f32 v123, v124, v125
	v_cvt_pk_bf16_f32 v124, v118, v119
	v_cvt_pk_bf16_f32 v125, v120, v121
	v_add_f32_e32 v130, v130, v131
	v_mul_f32_e32 v131, v119, v119
	global_store_dwordx4 v[126:127], v[122:125], off offset:256 sc1
	v_mul_f32_e32 v119, v115, v115
	v_fmac_f32_e32 v131, v118, v118
	v_mul_f32_e32 v122, v117, v117
	v_fmac_f32_e32 v119, v114, v114
	v_fmac_f32_e32 v122, v116, v116
	v_add_f32_e32 v130, v130, v131
	v_mul_f32_e32 v131, v121, v121
	v_add_f32_e32 v119, v119, v122
	v_mul_f32_e32 v122, v111, v111
	v_fmac_f32_e32 v131, v120, v120
	v_or_b32_e32 v120, 16, v4
	v_fmac_f32_e32 v122, v110, v110
	v_ashrrev_i32_e32 v121, 31, v120
	v_add_f32_e32 v119, v119, v122
	v_mul_f32_e32 v122, v113, v113
	v_lshlrev_b64 v[120:121], 13, v[120:121]
	v_fmac_f32_e32 v122, v112, v112
	v_cvt_pk_bf16_f32 v114, v114, v115
	v_cvt_pk_bf16_f32 v115, v116, v117
	v_cvt_pk_bf16_f32 v117, v112, v113
	v_mul_f32_e32 v112, v107, v107
	v_mul_f32_e32 v113, v109, v109
	v_cvt_pk_bf16_f32 v116, v110, v111
	v_lshl_add_u64 v[110:111], s[8:9], 0, v[120:121]
	v_fmac_f32_e32 v112, v106, v106
	v_fmac_f32_e32 v113, v108, v108
	v_lshl_add_u64 v[110:111], v[110:111], 0, v[128:129]
	v_add_f32_e32 v112, v112, v113
	v_mul_f32_e32 v113, v103, v103
	v_cvt_pk_bf16_f32 v106, v106, v107
	v_cvt_pk_bf16_f32 v107, v108, v109
	v_cvt_pk_bf16_f32 v108, v102, v103
	v_cvt_pk_bf16_f32 v109, v104, v105
	v_fmac_f32_e32 v113, v102, v102
	global_store_dwordx4 v[110:111], v[106:109], off offset:256 sc1
	v_add_f32_e32 v112, v112, v113
	v_mul_f32_e32 v113, v105, v105
	v_mul_f32_e32 v106, v99, v99
	v_mul_f32_e32 v107, v101, v101
	v_fmac_f32_e32 v106, v98, v98
	v_fmac_f32_e32 v107, v100, v100
	v_fmac_f32_e32 v113, v104, v104
	v_or_b32_e32 v104, 32, v4
	v_add_f32_e32 v106, v106, v107
	v_mul_f32_e32 v107, v95, v95
	v_ashrrev_i32_e32 v105, 31, v104
	v_fmac_f32_e32 v107, v94, v94
	v_lshlrev_b64 v[104:105], 13, v[104:105]
	v_add_f32_e32 v106, v106, v107
	v_mul_f32_e32 v107, v97, v97
	v_fmac_f32_e32 v107, v96, v96
	v_cvt_pk_bf16_f32 v98, v98, v99
	v_cvt_pk_bf16_f32 v99, v100, v101
	v_cvt_pk_bf16_f32 v100, v94, v95
	v_cvt_pk_bf16_f32 v101, v96, v97
	v_lshl_add_u64 v[94:95], s[8:9], 0, v[104:105]
	v_mul_f32_e32 v96, v91, v91
	v_mul_f32_e32 v97, v93, v93
	v_lshl_add_u64 v[94:95], v[94:95], 0, v[128:129]
	v_fmac_f32_e32 v96, v90, v90
	v_fmac_f32_e32 v97, v92, v92
	v_cvt_pk_bf16_f32 v90, v90, v91
	v_cvt_pk_bf16_f32 v91, v92, v93
	v_cvt_pk_bf16_f32 v92, v86, v87
	v_cvt_pk_bf16_f32 v93, v88, v89
	global_store_dwordx4 v[94:95], v[90:93], off offset:256 sc1
	v_add_f32_e32 v96, v96, v97
	v_mul_f32_e32 v97, v87, v87
	v_mul_f32_e32 v90, v83, v83
	v_mul_f32_e32 v91, v85, v85
	v_fmac_f32_e32 v90, v82, v82
	v_fmac_f32_e32 v91, v84, v84
	v_add_f32_e32 v90, v90, v91
	v_mul_f32_e32 v91, v79, v79
	v_fmac_f32_e32 v91, v78, v78
	v_add_f32_e32 v90, v90, v91
	v_mul_f32_e32 v91, v81, v81
	v_fmac_f32_e32 v91, v80, v80
	v_cvt_pk_bf16_f32 v82, v82, v83
	v_cvt_pk_bf16_f32 v83, v84, v85
	v_cvt_pk_bf16_f32 v85, v80, v81
	v_mul_f32_e32 v80, v75, v75
	v_mul_f32_e32 v81, v77, v77
	v_fmac_f32_e32 v80, v74, v74
	v_fmac_f32_e32 v81, v76, v76
	v_add_f32_e32 v80, v80, v81
	v_mul_f32_e32 v81, v71, v71
	v_fmac_f32_e32 v81, v70, v70
	v_add_f32_e32 v80, v80, v81
	v_mul_f32_e32 v81, v73, v73
	v_fmac_f32_e32 v81, v72, v72
	v_cvt_pk_bf16_f32 v74, v74, v75
	v_cvt_pk_bf16_f32 v75, v76, v77
	v_cvt_pk_bf16_f32 v77, v72, v73
	v_mul_f32_e32 v72, v67, v67
	v_mul_f32_e32 v73, v69, v69
	v_fmac_f32_e32 v72, v66, v66
	v_fmac_f32_e32 v73, v68, v68
	v_add_f32_e32 v72, v72, v73
	v_mul_f32_e32 v73, v63, v63
	v_fmac_f32_e32 v73, v62, v62
	v_add_f32_e32 v72, v72, v73
	v_mul_f32_e32 v73, v65, v65
	v_fmac_f32_e32 v73, v64, v64
	v_cvt_pk_bf16_f32 v66, v66, v67
	v_cvt_pk_bf16_f32 v67, v68, v69
	v_cvt_pk_bf16_f32 v69, v64, v65
	v_add_co_u32_e32 v64, vcc, s21, v126
	v_cvt_pk_bf16_f32 v68, v62, v63
	s_nop 0
	v_addc_co_u32_e32 v65, vcc, 0, v127, vcc
	global_store_dwordx4 v[64:65], v[66:69], off sc1
	v_mul_f32_e32 v64, v59, v59
	v_mul_f32_e32 v65, v61, v61
	v_fmac_f32_e32 v64, v58, v58
	v_fmac_f32_e32 v65, v60, v60
	v_add_f32_e32 v64, v64, v65
	v_mul_f32_e32 v65, v55, v55
	v_fmac_f32_e32 v65, v54, v54
	v_add_f32_e32 v64, v64, v65
	v_mul_f32_e32 v65, v57, v57
	v_fmac_f32_e32 v65, v56, v56
	v_cvt_pk_bf16_f32 v58, v58, v59
	v_cvt_pk_bf16_f32 v59, v60, v61
; __device__ __forceinline__ unsigned cvt_pk_bf16(float lo, float hi) { const cvt_f2 v = {lo, hi}; return __builtin_bit_cast(unsigned, __builtin_convertvector(v, cvt_b2)); }
;     __device__ __forceinline__ void operator()(const f32x4 (&acc)[2][2][4][2], const Unit& u, int wr, int wc, int fr, int fq) const {
;     ...
;             for (int m = 0; m < 4; ++m) { const size_t ro = (size_t)(row0 + ai * HALF + m * 16) * D + col0; float ss = 0.f;
; #pragma unroll
;                 for (int bj = 0; bj < 2; ++bj) {
;                     const f32x4 h0 = acc[ai][bj][m][0], h1 = acc[ai][bj][m][1];
;                     ss += (h0[0] * h0[0] + h0[1] * h0[1]) + (h0[2] * h0[2] + h0[3] * h0[3]) + (h1[0] * h1[0] + h1[1] * h1[1]) + (h1[2] * h1[2] + h1[3] * h1[3]);
;                     pg8::u32x4 w; w.x = cvt_pk_bf16(h0[0], h0[1]); w.y = cvt_pk_bf16(h0[2], h0[3]); w.z = cvt_pk_bf16(h1[0], h1[1]); w.w = cvt_pk_bf16(h1[2], h1[3]);
;                     *(pg8::u32x4*)(HB + ro + bj * HALF) = w;
;                 }
;                 ss += __shfl_xor(ss, 16); ss += __shfl_xor(ss, 32); ssv[ai][m] = ss;
;             }
;         if (fq == 0) {
; #pragma unroll
;             for (int ai = 0; ai < 2; ++ai)
; #pragma unroll
;                 for (int m = 0; m < 4; ++m) SSQ[(size_t)(u.pn * 4 + wc) * T + row0 + ai * HALF + m * 16] = ssv[ai][m];
;         }
	v_cvt_pk_bf16_f32 v61, v56, v57
	v_mul_f32_e32 v56, v51, v51
	v_mul_f32_e32 v57, v53, v53
	v_fmac_f32_e32 v56, v50, v50
	v_fmac_f32_e32 v57, v52, v52
	v_add_f32_e32 v56, v56, v57
	v_mul_f32_e32 v57, v47, v47
	v_fmac_f32_e32 v57, v46, v46
	v_add_f32_e32 v56, v56, v57
	v_mul_f32_e32 v57, v49, v49
	v_fmac_f32_e32 v57, v48, v48
	v_cvt_pk_bf16_f32 v50, v50, v51
	v_cvt_pk_bf16_f32 v51, v52, v53
	v_cvt_pk_bf16_f32 v53, v48, v49
	v_add_co_u32_e32 v48, vcc, s67, v126
	v_cvt_pk_bf16_f32 v52, v46, v47
	s_nop 0
	v_addc_co_u32_e32 v49, vcc, 0, v127, vcc
	global_store_dwordx4 v[48:49], v[50:53], off sc1
	v_mul_f32_e32 v48, v43, v43
	v_mul_f32_e32 v49, v45, v45
	v_fmac_f32_e32 v48, v42, v42
	v_fmac_f32_e32 v49, v44, v44
	v_add_f32_e32 v48, v48, v49
	v_mul_f32_e32 v49, v39, v39
	v_fmac_f32_e32 v49, v38, v38
	v_add_f32_e32 v48, v48, v49
	v_mul_f32_e32 v49, v41, v41
	v_fmac_f32_e32 v49, v40, v40
	v_cvt_pk_bf16_f32 v42, v42, v43
	v_cvt_pk_bf16_f32 v43, v44, v45
	v_cvt_pk_bf16_f32 v45, v40, v41
	v_mul_f32_e32 v40, v35, v35
	v_mul_f32_e32 v41, v37, v37
	v_fmac_f32_e32 v40, v34, v34
	v_fmac_f32_e32 v41, v36, v36
	v_add_f32_e32 v40, v40, v41
	v_mul_f32_e32 v41, v31, v31
	v_fmac_f32_e32 v41, v30, v30
	v_add_f32_e32 v40, v40, v41
	v_mul_f32_e32 v41, v33, v33
	v_fmac_f32_e32 v41, v32, v32
	v_cvt_pk_bf16_f32 v34, v34, v35
	v_cvt_pk_bf16_f32 v35, v36, v37
	v_cvt_pk_bf16_f32 v37, v32, v33
	v_add_co_u32_e32 v32, vcc, s72, v126
	v_cvt_pk_bf16_f32 v36, v30, v31
	s_nop 0
	v_addc_co_u32_e32 v33, vcc, 0, v127, vcc
	global_store_dwordx4 v[32:33], v[34:37], off sc1
	v_mul_f32_e32 v32, v27, v27
	v_mul_f32_e32 v33, v29, v29
	v_fmac_f32_e32 v32, v26, v26
	v_fmac_f32_e32 v33, v28, v28
	v_add_f32_e32 v32, v32, v33
	v_mul_f32_e32 v33, v23, v23
	v_fmac_f32_e32 v33, v22, v22
	v_add_f32_e32 v32, v32, v33
	v_mul_f32_e32 v33, v25, v25
	v_fmac_f32_e32 v33, v24, v24
	v_cvt_pk_bf16_f32 v26, v26, v27
	v_cvt_pk_bf16_f32 v27, v28, v29
	v_cvt_pk_bf16_f32 v29, v24, v25
	v_mul_f32_e32 v24, v19, v19
	v_mul_f32_e32 v25, v21, v21
	v_fmac_f32_e32 v24, v18, v18
	v_fmac_f32_e32 v25, v20, v20
	v_add_f32_e32 v24, v24, v25
	v_mul_f32_e32 v25, v15, v15
	v_fmac_f32_e32 v25, v14, v14
	v_cvt_pk_bf16_f32 v18, v18, v19
	v_cvt_pk_bf16_f32 v19, v20, v21
	v_cvt_pk_bf16_f32 v20, v14, v15
	v_mul_f32_e32 v14, v11, v11
	v_mul_f32_e32 v15, v13, v13
	v_fmac_f32_e32 v14, v10, v10
	v_fmac_f32_e32 v15, v12, v12
	v_add_f32_e32 v14, v14, v15
	v_mul_f32_e32 v15, v7, v7
	v_fmac_f32_e32 v97, v86, v86
	v_fmac_f32_e32 v15, v6, v6
	v_add_f32_e32 v96, v96, v97
	v_mul_f32_e32 v97, v89, v89
	v_add_f32_e32 v24, v24, v25
	v_mul_f32_e32 v25, v17, v17
	v_add_f32_e32 v14, v14, v15
	v_mul_f32_e32 v15, v9, v9
	v_fmac_f32_e32 v97, v88, v88
	v_lshl_add_u64 v[30:31], v[126:127], 0, s[16:17]
	v_cvt_pk_bf16_f32 v28, v22, v23
	v_fmac_f32_e32 v25, v16, v16
	v_fmac_f32_e32 v15, v8, v8
	v_add_f32_e32 v130, v131, v130
	v_add_f32_e32 v119, v122, v119
	v_add_f32_e32 v112, v113, v112
	v_add_f32_e32 v106, v107, v106
	v_add_f32_e32 v96, v97, v96
	v_add_f32_e32 v90, v91, v90
	v_add_f32_e32 v80, v81, v80
	v_add_f32_e32 v72, v73, v72
	v_add_f32_e32 v64, v65, v64
	v_add_f32_e32 v56, v57, v56
	v_add_f32_e32 v48, v49, v48
	v_add_f32_e32 v40, v41, v40
	v_add_f32_e32 v32, v33, v32
	global_store_dwordx4 v[30:31], v[26:29], off offset:256 sc1
	v_add_f32_e32 v14, v15, v14
	v_add_f32_e32 v3, v3, v130
	v_add_f32_e32 v26, v25, v24
	v_add_f32_e32 v112, v119, v112
	v_add_f32_e32 v96, v106, v96
	v_add_f32_e32 v80, v90, v80
	v_add_f32_e32 v64, v72, v64
	v_add_f32_e32 v48, v56, v48
	v_add_f32_e32 v32, v40, v32
	v_cvt_pk_bf16_f32 v21, v16, v17
	v_add_f32_e32 v16, v26, v14
	ds_bpermute_b32 v130, v138, v3
	ds_bpermute_b32 v113, v138, v112
	ds_bpermute_b32 v97, v138, v96
	ds_bpermute_b32 v81, v138, v80
	ds_bpermute_b32 v65, v138, v64
	ds_bpermute_b32 v49, v138, v48
	ds_bpermute_b32 v33, v138, v32
	ds_bpermute_b32 v17, v138, v16
	v_add_co_u32_e32 v14, vcc, s73, v126
	s_waitcnt lgkmcnt(0)
	v_add_f32_e32 v3, v3, v130
	v_addc_co_u32_e32 v15, vcc, 0, v127, vcc
	v_add_f32_e32 v102, v112, v113
	v_add_f32_e32 v86, v96, v97
	v_cvt_pk_bf16_f32 v76, v70, v71
	v_add_f32_e32 v70, v80, v81
	v_cvt_pk_bf16_f32 v60, v54, v55
	v_add_f32_e32 v54, v64, v65
	v_cvt_pk_bf16_f32 v44, v38, v39
	v_add_f32_e32 v38, v48, v49
	v_add_f32_e32 v22, v32, v33
	global_store_dwordx4 v[14:15], v[18:21], off sc1
	v_cvt_pk_bf16_f32 v14, v10, v11
	v_add_f32_e32 v10, v16, v17
	ds_bpermute_b32 v118, v139, v3
	ds_bpermute_b32 v103, v139, v102
	ds_bpermute_b32 v87, v139, v86
	v_or_b32_e32 v88, 48, v4
	ds_bpermute_b32 v71, v139, v70
	ds_bpermute_b32 v55, v139, v54
	ds_bpermute_b32 v39, v139, v38
	ds_bpermute_b32 v23, v139, v22
	ds_bpermute_b32 v11, v139, v10
	v_ashrrev_i32_e32 v89, 31, v88
	v_lshlrev_b64 v[88:89], 13, v[88:89]
	v_cvt_pk_bf16_f32 v84, v78, v79
	v_lshl_add_u64 v[78:79], s[8:9], 0, v[88:89]
	s_mov_b64 s[28:29], 0x100000
	v_lshl_add_u64 v[78:79], v[78:79], 0, v[128:129]
	v_lshl_add_u64 v[62:63], v[126:127], 0, s[28:29]
	v_lshl_add_u64 v[46:47], v[126:127], 0, s[14:15]
	v_lshl_add_u64 v[24:25], v[126:127], 0, s[18:19]
	v_cvt_pk_bf16_f32 v15, v12, v13
	v_cvt_pk_bf16_f32 v16, v6, v7
	v_cvt_pk_bf16_f32 v17, v8, v9
	global_store_dwordx4 v[110:111], v[114:117], off sc1
	global_store_dwordx4 v[94:95], v[98:101], off sc1
	global_store_dwordx4 v[78:79], v[82:85], off sc1
	global_store_dwordx4 v[78:79], v[74:77], off offset:256 sc1
	global_store_dwordx4 v[62:63], v[58:61], off offset:256 sc1
	global_store_dwordx4 v[46:47], v[42:45], off offset:256 sc1
	global_store_dwordx4 v[24:25], v[14:17], off offset:256 sc1
	s_and_saveexec_b64 s[28:29], s[4:5]
	s_cbranch_execz .LBB0_815
	s_lshl_b32 s21, s62, 2
	s_or_b32 s30, s21, s55
	s_ashr_i32 s31, s30, 31
	s_lshl_b64 s[30:31], s[30:31], 15
	s_add_u32 s30, s58, s30
	s_addc_u32 s31, s59, s31
	s_waitcnt lgkmcnt(0)
	v_add_f32_e32 v3, v3, v118
	v_lshl_add_u64 v[4:5], v[4:5], 2, s[30:31]
	v_add_f32_e32 v6, v10, v11
	v_add_f32_e32 v7, v22, v23
	v_add_f32_e32 v8, v38, v39
	v_add_f32_e32 v9, v54, v55
	v_add_f32_e32 v10, v70, v71
	v_add_f32_e32 v11, v86, v87
	v_add_f32_e32 v12, v102, v103
	global_store_dword v[4:5], v3, off sc1
	global_store_dword v[4:5], v12, off offset:64 sc1
	global_store_dword v[4:5], v11, off offset:128 sc1
	global_store_dword v[4:5], v10, off offset:192 sc1
	global_store_dword v[4:5], v9, off offset:512 sc1
	global_store_dword v[4:5], v8, off offset:576 sc1
	global_store_dword v[4:5], v7, off offset:640 sc1
	global_store_dword v[4:5], v6, off offset:704 sc1

; #define GAS __attribute__((address_space(1)))
; #define LAS __attribute__((address_space(3)))
; #define LDS_WAIT() asm volatile("s_waitcnt lgkmcnt(0)" ::: "memory")
; __device__ __forceinline__ unsigned pk2(float lo, float hi) { return f2bf(lo) | (f2bf(hi) << 16); }
; __device__ __forceinline__ void p0_transpose_item(const float* W, int N, bf16* WT, int ldt, int rowmode, LAS float* scr, int kb, int nb, int lane, const float* kgain) {
;     const int k0 = 64 * kb, n0 = 32 * nb;
;     const int lk = lane >> 3, ln = (lane & 7) * 4;
; #pragma unroll
;     for (int i = 0; i < 8; ++i) { const int kk = 8 * i + lk; f32x4 v = __builtin_nontemporal_load((const GAS f32x4*)(W + (size_t)(k0 + kk) * N + n0 + ln)); if (kgain) v = v * kgain[k0 + kk];
;         scr[kk * 33 + ln] = v[0]; scr[kk * 33 + ln + 1] = v[1]; scr[kk * 33 + ln + 2] = v[2]; scr[kk * 33 + ln + 3] = v[3]; }
;     LDS_WAIT(); asm volatile("" ::: "memory");
;     const int c = lane & 7;
; #pragma unroll
;     for (int j = 0; j < 4; ++j) { const int n = (lane >> 3) + 8 * j; const LAS float* s = scr + (8 * c) * 33 + n;
;         v4u o; o.x = pk2(s[0 * 33], s[1 * 33]); o.y = pk2(s[2 * 33], s[3 * 33]); o.z = pk2(s[4 * 33], s[5 * 33]); o.w = pk2(s[6 * 33], s[7 * 33]);
;         const int ng = n0 + n; int row;
;         if (rowmode == 0) row = ng;
;         else if (rowmode == 3) { const int np = ng - (PW + 4 * HW); row = np < 0 ? ng : (PW + 4 * HW) + ((np & (D - 1)) >> 7) * 256 + (np >= D ? 128 : 0) + (np & 127); }
;         else row = (ng >> 7) * 256 + (rowmode == 2 ? 128 : 0) + (ng & 127);
;         *(GAS v4u*)(WT + (size_t)row * ldt + k0 + 8 * c) = o; }
;     LDS_WAIT(); asm volatile("" ::: "memory");
; }
.LBB0_880:
	s_ashr_i32 s14, s80, 31
	s_lshr_b32 s14, s14, 25
	s_add_i32 s14, s80, s14
	s_ashr_i32 s15, s14, 7
	s_lshl_b32 s14, s15, 6
	s_lshl_b32 s16, s15, 12
	s_mul_i32 s17, s15, 0xfd500000
	s_sub_i32 s16, s5, s16
	v_or_b32_e32 v32, s14, v6
	v_or_b32_e32 v34, s14, v7
	v_or_b32_e32 v36, s14, v8
	v_or_b32_e32 v38, s14, v9
	v_or_b32_e32 v40, s14, v10
	v_or_b32_e32 v42, s14, v11
	v_or_b32_e32 v44, s14, v12
	v_or_b32_e32 v46, s14, v13
	v_add_u32_e32 v48, s17, v15
	s_ashr_i32 s17, s16, 31
	v_ashrrev_i32_e32 v33, 31, v32
	s_ashr_i32 s15, s14, 31
	v_ashrrev_i32_e32 v35, 31, v34
	v_ashrrev_i32_e32 v37, 31, v36
	v_ashrrev_i32_e32 v39, 31, v38
	v_ashrrev_i32_e32 v41, 31, v40
	v_ashrrev_i32_e32 v43, 31, v42
	v_ashrrev_i32_e32 v45, 31, v44
	v_ashrrev_i32_e32 v47, 31, v46
	v_add_u32_e32 v52, 0x15800, v48
	v_add_u32_e32 v54, 0x2b000, v48
	v_add_u32_e32 v56, 0x40800, v48
	v_lshl_add_u64 v[58:59], s[16:17], 2, v[2:3]
	v_lshlrev_b64 v[32:33], 14, v[32:33]
	v_lshl_add_u64 v[50:51], s[14:15], 1, v[4:5]
	v_ashrrev_i32_e32 v49, 31, v48
	v_lshlrev_b64 v[34:35], 14, v[34:35]
	v_lshlrev_b64 v[36:37], 14, v[36:37]
	v_lshlrev_b64 v[38:39], 14, v[38:39]
	v_lshlrev_b64 v[40:41], 14, v[40:41]
	v_lshlrev_b64 v[42:43], 14, v[42:43]
	v_lshlrev_b64 v[44:45], 14, v[44:45]
	v_lshlrev_b64 v[46:47], 14, v[46:47]
	v_ashrrev_i32_e32 v53, 31, v52
	v_ashrrev_i32_e32 v55, 31, v54
	v_ashrrev_i32_e32 v57, 31, v56
	v_lshl_add_u64 v[66:67], v[58:59], 0, v[32:33]
	v_lshl_add_u64 v[64:65], v[48:49], 1, v[50:51]
	v_lshl_add_u64 v[68:69], v[58:59], 0, v[34:35]
	v_lshl_add_u64 v[70:71], v[58:59], 0, v[36:37]
	v_lshl_add_u64 v[72:73], v[58:59], 0, v[38:39]
	v_lshl_add_u64 v[74:75], v[58:59], 0, v[40:41]
	v_lshl_add_u64 v[76:77], v[58:59], 0, v[42:43]
	v_lshl_add_u64 v[78:79], v[58:59], 0, v[44:45]
	v_lshl_add_u64 v[80:81], v[58:59], 0, v[46:47]
	v_lshl_add_u64 v[82:83], v[52:53], 1, v[50:51]
	v_lshl_add_u64 v[84:85], v[54:55], 1, v[50:51]
	v_lshl_add_u64 v[86:87], v[56:57], 1, v[50:51]
	global_load_dwordx4 v[32:35], v[66:67], off nt
	global_load_dwordx4 v[36:39], v[68:69], off nt
	global_load_dwordx4 v[40:43], v[70:71], off nt
	global_load_dwordx4 v[44:47], v[72:73], off nt
	global_load_dwordx4 v[48:51], v[74:75], off nt
	global_load_dwordx4 v[52:55], v[76:77], off nt
	global_load_dwordx4 v[56:59], v[78:79], off nt
	global_load_dwordx4 v[60:63], v[80:81], off nt
	s_add_i32 s80, s80, s82
	s_add_i32 s5, s5, s7
	s_cmpk_lt_i32 s80, 0x5600
	v_add_u32_e32 v15, s4, v15
	s_waitcnt vmcnt(7)
	ds_write2_b32 v16, v32, v33 offset1:1
	ds_write2_b32 v16, v34, v35 offset0:2 offset1:3
	s_waitcnt vmcnt(6)
	ds_write2_b32 v17, v36, v37 offset1:1
	ds_write2_b32 v18, v38, v39 offset1:1
	s_waitcnt vmcnt(5)
	ds_write2_b32 v19, v40, v41 offset1:1
	ds_write2_b32 v20, v42, v43 offset1:1
	s_waitcnt vmcnt(4)
	ds_write2_b32 v21, v44, v45 offset1:1
	ds_write2_b32 v22, v46, v47 offset1:1
	s_waitcnt vmcnt(3)
	ds_write2_b32 v23, v48, v49 offset1:1
	ds_write2_b32 v24, v50, v51 offset1:1
	s_waitcnt vmcnt(2)
	ds_write2_b32 v25, v52, v53 offset1:1
	ds_write2_b32 v26, v54, v55 offset1:1
	s_waitcnt vmcnt(1)
	ds_write2_b32 v27, v56, v57 offset1:1
	ds_write2_b32 v28, v58, v59 offset1:1
	s_waitcnt vmcnt(0)
	ds_write2_b32 v29, v60, v61 offset1:1
	ds_write2_b32 v30, v62, v63 offset1:1
	s_waitcnt lgkmcnt(0)
	ds_read2_b32 v[32:33], v14 offset0:33 offset1:41
	ds_read2_b32 v[34:35], v14 offset1:8
	ds_read2_b32 v[36:37], v14 offset0:66 offset1:74
	ds_read2_b32 v[38:39], v14 offset0:99 offset1:107
	ds_read2_b32 v[40:41], v14 offset0:132 offset1:140
	ds_read2_b32 v[42:43], v14 offset0:165 offset1:173
	ds_read2_b32 v[44:45], v14 offset0:198 offset1:206
	ds_read2_b32 v[46:47], v14 offset0:231 offset1:239
	ds_read2_b32 v[48:49], v14 offset0:49 offset1:57
	ds_read2_b32 v[50:51], v14 offset0:16 offset1:24
	ds_read2_b32 v[52:53], v14 offset0:82 offset1:90
	ds_read2_b32 v[54:55], v14 offset0:115 offset1:123
	ds_read2_b32 v[56:57], v14 offset0:148 offset1:156
	ds_read2_b32 v[58:59], v14 offset0:181 offset1:189
	ds_read2_b32 v[60:61], v14 offset0:214 offset1:222
	ds_read2_b32 v[62:63], v14 offset0:247 offset1:255
	s_waitcnt lgkmcnt(14)
; #define GAS __attribute__((address_space(1)))
; #define LAS __attribute__((address_space(3)))
; __device__ __forceinline__ unsigned pk2(float lo, float hi) { return f2bf(lo) | (f2bf(hi) << 16); }
; __device__ __forceinline__ void p0_transpose_item(const float* W, int N, bf16* WT, int ldt, int rowmode, LAS float* scr, int kb, int nb, int lane, const float* kgain) {
;     ...
;     for (int j = 0; j < 4; ++j) { const int n = (lane >> 3) + 8 * j; const LAS float* s = scr + (8 * c) * 33 + n;
;         v4u o; o.x = pk2(s[0 * 33], s[1 * 33]); o.y = pk2(s[2 * 33], s[3 * 33]); o.z = pk2(s[4 * 33], s[5 * 33]); o.w = pk2(s[6 * 33], s[7 * 33]);
;         const int ng = n0 + n; int row;
;         if (rowmode == 0) row = ng;
;         else if (rowmode == 3) { const int np = ng - (PW + 4 * HW); row = np < 0 ? ng : (PW + 4 * HW) + ((np & (D - 1)) >> 7) * 256 + (np >= D ? 128 : 0) + (np & 127); }
;         else row = (ng >> 7) * 256 + (rowmode == 2 ? 128 : 0) + (ng & 127);
;         *(GAS v4u*)(WT + (size_t)row * ldt + k0 + 8 * c) = o; }
	v_bfe_u32 v31, v34, 16, 1
	s_waitcnt lgkmcnt(13)
	v_bfe_u32 v67, v36, 16, 1
	s_waitcnt lgkmcnt(12)
	v_bfe_u32 v68, v38, 16, 1
	s_waitcnt lgkmcnt(11)
	v_bfe_u32 v69, v40, 16, 1
	s_waitcnt lgkmcnt(10)
	v_bfe_u32 v70, v42, 16, 1
	s_waitcnt lgkmcnt(9)
	v_bfe_u32 v71, v44, 16, 1
	v_bfe_u32 v66, v32, 16, 1
	s_waitcnt lgkmcnt(8)
	v_bfe_u32 v72, v46, 16, 1
	v_bfe_u32 v73, v35, 16, 1
	v_bfe_u32 v74, v33, 16, 1
	v_bfe_u32 v75, v37, 16, 1
	v_bfe_u32 v76, v39, 16, 1
	v_bfe_u32 v77, v41, 16, 1
	v_bfe_u32 v78, v43, 16, 1
	v_bfe_u32 v79, v45, 16, 1
	v_bfe_u32 v80, v47, 16, 1
	s_waitcnt lgkmcnt(6)
	v_bfe_u32 v81, v50, 16, 1
	s_waitcnt lgkmcnt(5)
	v_bfe_u32 v89, v52, 16, 1
	s_waitcnt lgkmcnt(4)
	v_bfe_u32 v90, v54, 16, 1
	s_waitcnt lgkmcnt(3)
	v_bfe_u32 v91, v56, 16, 1
	s_waitcnt lgkmcnt(2)
	v_bfe_u32 v92, v58, 16, 1
	s_waitcnt lgkmcnt(1)
	v_bfe_u32 v93, v60, 16, 1
	v_bfe_u32 v96, v51, 16, 1
	v_bfe_u32 v98, v53, 16, 1
	v_bfe_u32 v100, v57, 16, 1
	v_bfe_u32 v102, v61, 16, 1
	v_add3_u32 v31, v34, v31, s12
	v_add3_u32 v34, v36, v67, s12
	v_add3_u32 v36, v38, v68, s12
	v_add3_u32 v38, v40, v69, s12
	v_add3_u32 v40, v42, v70, s12
	v_add3_u32 v42, v44, v71, s12
	v_bfe_u32 v88, v48, 16, 1
	s_waitcnt lgkmcnt(0)
	v_bfe_u32 v94, v62, 16, 1
	v_bfe_u32 v95, v49, 16, 1
	v_bfe_u32 v97, v55, 16, 1
	v_bfe_u32 v99, v59, 16, 1
	v_bfe_u32 v101, v63, 16, 1
	v_add3_u32 v32, v32, v66, s12
	v_add3_u32 v44, v46, v72, s12
	v_add3_u32 v35, v35, v73, s12
	v_add3_u32 v46, v33, v74, s12
	v_add3_u32 v33, v37, v75, s12
	v_add3_u32 v37, v39, v76, s12
	v_add3_u32 v39, v41, v77, s12
	v_add3_u32 v41, v43, v78, s12
	v_add3_u32 v43, v45, v79, s12
	v_add3_u32 v45, v47, v80, s12
	v_add3_u32 v47, v50, v81, s12
	v_add3_u32 v50, v52, v89, s12
	v_add3_u32 v52, v54, v90, s12
	v_add3_u32 v54, v56, v91, s12
	v_add3_u32 v56, v58, v92, s12
	v_add3_u32 v58, v60, v93, s12
	v_add3_u32 v51, v51, v96, s12
	v_add3_u32 v53, v53, v98, s12
	v_add3_u32 v57, v57, v100, s12
	v_add3_u32 v61, v61, v102, s12
	v_lshrrev_b32_e32 v31, 16, v31
	v_lshrrev_b32_e32 v34, 16, v34
	v_lshrrev_b32_e32 v38, 16, v38
	v_lshrrev_b32_e32 v42, 16, v42
	v_add3_u32 v48, v48, v88, s12
	v_add3_u32 v60, v62, v94, s12
	v_add3_u32 v49, v49, v95, s12
	v_add3_u32 v55, v55, v97, s12
	v_add3_u32 v59, v59, v99, s12
	v_add3_u32 v62, v63, v101, s12
	v_lshrrev_b32_e32 v63, 16, v35
	v_lshrrev_b32_e32 v66, 16, v33
	v_lshrrev_b32_e32 v39, 16, v39
	v_lshrrev_b32_e32 v43, 16, v43
	v_lshrrev_b32_e32 v47, 16, v47
	v_lshrrev_b32_e32 v50, 16, v50
	v_lshrrev_b32_e32 v54, 16, v54
	v_lshrrev_b32_e32 v58, 16, v58
	v_lshrrev_b32_e32 v51, 16, v51
	v_lshrrev_b32_e32 v53, 16, v53
	v_lshrrev_b32_e32 v57, 16, v57
	v_lshrrev_b32_e32 v61, 16, v61
	v_and_or_b32 v32, v32, s13, v31
	v_and_or_b32 v33, v36, s13, v34
	v_and_or_b32 v34, v40, s13, v38
	v_and_or_b32 v35, v44, s13, v42
	v_and_or_b32 v36, v46, s13, v63
	v_and_or_b32 v37, v37, s13, v66
	v_and_or_b32 v38, v41, s13, v39
	v_and_or_b32 v39, v45, s13, v43
	v_and_or_b32 v40, v48, s13, v47
	v_and_or_b32 v41, v52, s13, v50
	v_and_or_b32 v42, v56, s13, v54
	v_and_or_b32 v43, v60, s13, v58
	v_and_or_b32 v44, v49, s13, v51
	v_and_or_b32 v45, v55, s13, v53
	v_and_or_b32 v46, v59, s13, v57
	v_and_or_b32 v47, v62, s13, v61
	global_store_dwordx4 v[64:65], v[32:35], off sc1
	global_store_dwordx4 v[82:83], v[36:39], off sc1
	global_store_dwordx4 v[84:85], v[40:43], off sc1
	global_store_dwordx4 v[86:87], v[44:47], off sc1
	s_waitcnt lgkmcnt(0)
	s_cbranch_scc1 .LBB0_880

; #define GAS __attribute__((address_space(1)))
; #define LAS __attribute__((address_space(3)))
; #define LDS_WAIT() asm volatile("s_waitcnt lgkmcnt(0)" ::: "memory")
; __device__ __forceinline__ unsigned pk2(float lo, float hi) { return f2bf(lo) | (f2bf(hi) << 16); }
; __device__ __forceinline__ void p0_transpose_item(const float* W, int N, bf16* WT, int ldt, int rowmode, LAS float* scr, int kb, int nb, int lane, const float* kgain) {
;     const int k0 = 64 * kb, n0 = 32 * nb;
;     const int lk = lane >> 3, ln = (lane & 7) * 4;
; #pragma unroll
;     for (int i = 0; i < 8; ++i) { const int kk = 8 * i + lk; f32x4 v = __builtin_nontemporal_load((const GAS f32x4*)(W + (size_t)(k0 + kk) * N + n0 + ln)); if (kgain) v = v * kgain[k0 + kk];
;         scr[kk * 33 + ln] = v[0]; scr[kk * 33 + ln + 1] = v[1]; scr[kk * 33 + ln + 2] = v[2]; scr[kk * 33 + ln + 3] = v[3]; }
;     LDS_WAIT(); asm volatile("" ::: "memory");
;     const int c = lane & 7;
; #pragma unroll
;     for (int j = 0; j < 4; ++j) { const int n = (lane >> 3) + 8 * j; const LAS float* s = scr + (8 * c) * 33 + n;
;         v4u o; o.x = pk2(s[0 * 33], s[1 * 33]); o.y = pk2(s[2 * 33], s[3 * 33]); o.z = pk2(s[4 * 33], s[5 * 33]); o.w = pk2(s[6 * 33], s[7 * 33]);
;         const int ng = n0 + n; int row;
;         if (rowmode == 0) row = ng;
;         else if (rowmode == 3) { const int np = ng - (PW + 4 * HW); row = np < 0 ? ng : (PW + 4 * HW) + ((np & (D - 1)) >> 7) * 256 + (np >= D ? 128 : 0) + (np & 127); }
;         else row = (ng >> 7) * 256 + (rowmode == 2 ? 128 : 0) + (ng & 127);
;         *(GAS v4u*)(WT + (size_t)row * ldt + k0 + 8 * c) = o; }
;     LDS_WAIT(); asm volatile("" ::: "memory");
; }
.LBB0_885:
	s_ashr_i32 s15, s4, 31
	s_lshr_b32 s15, s15, 25
	s_add_i32 s15, s4, s15
	s_ashr_i32 s15, s15, 7
	s_lshl_b32 s16, s15, 6
	s_lshl_b32 s17, s15, 12
	s_mul_i32 s15, s15, 0xfd500000
	s_sub_i32 s18, s12, s17
	v_or_b32_e32 v32, s16, v6
	v_or_b32_e32 v34, s16, v7
	v_or_b32_e32 v36, s16, v8
	v_or_b32_e32 v38, s16, v9
	v_or_b32_e32 v40, s16, v10
	v_or_b32_e32 v42, s16, v11
	v_or_b32_e32 v44, s16, v12
	v_or_b32_e32 v46, s16, v13
	v_add_u32_e32 v48, s15, v15
	s_ashr_i32 s19, s18, 31
	v_ashrrev_i32_e32 v33, 31, v32
	s_ashr_i32 s17, s16, 31
	v_ashrrev_i32_e32 v35, 31, v34
	v_ashrrev_i32_e32 v37, 31, v36
	v_ashrrev_i32_e32 v39, 31, v38
	v_ashrrev_i32_e32 v41, 31, v40
	v_ashrrev_i32_e32 v43, 31, v42
	v_ashrrev_i32_e32 v45, 31, v44
	v_ashrrev_i32_e32 v47, 31, v46
	v_add_u32_e32 v52, 0x15800, v48
	v_add_u32_e32 v54, 0x2b000, v48
	v_add_u32_e32 v56, 0x40800, v48
	v_lshl_add_u64 v[58:59], s[18:19], 2, v[2:3]
	v_lshlrev_b64 v[32:33], 14, v[32:33]
	v_lshl_add_u64 v[50:51], s[16:17], 1, v[4:5]
	v_ashrrev_i32_e32 v49, 31, v48
	v_lshlrev_b64 v[34:35], 14, v[34:35]
	v_lshlrev_b64 v[36:37], 14, v[36:37]
	v_lshlrev_b64 v[38:39], 14, v[38:39]
	v_lshlrev_b64 v[40:41], 14, v[40:41]
	v_lshlrev_b64 v[42:43], 14, v[42:43]
	v_lshlrev_b64 v[44:45], 14, v[44:45]
	v_lshlrev_b64 v[46:47], 14, v[46:47]
	v_ashrrev_i32_e32 v53, 31, v52
	v_ashrrev_i32_e32 v55, 31, v54
	v_ashrrev_i32_e32 v57, 31, v56
	v_lshl_add_u64 v[66:67], v[58:59], 0, v[32:33]
	v_lshl_add_u64 v[64:65], v[48:49], 1, v[50:51]
	v_lshl_add_u64 v[68:69], v[58:59], 0, v[34:35]
	v_lshl_add_u64 v[70:71], v[58:59], 0, v[36:37]
	v_lshl_add_u64 v[72:73], v[58:59], 0, v[38:39]
	v_lshl_add_u64 v[74:75], v[58:59], 0, v[40:41]
	v_lshl_add_u64 v[76:77], v[58:59], 0, v[42:43]
	v_lshl_add_u64 v[78:79], v[58:59], 0, v[44:45]
	v_lshl_add_u64 v[80:81], v[58:59], 0, v[46:47]
	v_lshl_add_u64 v[82:83], v[52:53], 1, v[50:51]
	v_lshl_add_u64 v[84:85], v[54:55], 1, v[50:51]
	v_lshl_add_u64 v[86:87], v[56:57], 1, v[50:51]
	global_load_dwordx4 v[32:35], v[66:67], off nt
	global_load_dwordx4 v[36:39], v[68:69], off nt
	global_load_dwordx4 v[40:43], v[70:71], off nt
	global_load_dwordx4 v[44:47], v[72:73], off nt
	global_load_dwordx4 v[48:51], v[74:75], off nt
	global_load_dwordx4 v[52:55], v[76:77], off nt
	global_load_dwordx4 v[56:59], v[78:79], off nt
	global_load_dwordx4 v[60:63], v[80:81], off nt
	s_add_i32 s4, s4, s5
	s_add_i32 s12, s12, s6
	s_cmpk_gt_i32 s4, 0x55ff
	v_add_u32_e32 v15, s7, v15
	s_waitcnt vmcnt(7)
	ds_write2_b32 v16, v32, v33 offset1:1
	ds_write2_b32 v16, v34, v35 offset0:2 offset1:3
	s_waitcnt vmcnt(6)
	ds_write2_b32 v17, v36, v37 offset1:1
	ds_write2_b32 v18, v38, v39 offset1:1
	s_waitcnt vmcnt(5)
	ds_write2_b32 v19, v40, v41 offset1:1
	ds_write2_b32 v20, v42, v43 offset1:1
	s_waitcnt vmcnt(4)
	ds_write2_b32 v21, v44, v45 offset1:1
	ds_write2_b32 v22, v46, v47 offset1:1
	s_waitcnt vmcnt(3)
	ds_write2_b32 v23, v48, v49 offset1:1
	ds_write2_b32 v24, v50, v51 offset1:1
	s_waitcnt vmcnt(2)
	ds_write2_b32 v25, v52, v53 offset1:1
	ds_write2_b32 v26, v54, v55 offset1:1
	s_waitcnt vmcnt(1)
	ds_write2_b32 v27, v56, v57 offset1:1
	ds_write2_b32 v28, v58, v59 offset1:1
	s_waitcnt vmcnt(0)
	ds_write2_b32 v29, v60, v61 offset1:1
	ds_write2_b32 v30, v62, v63 offset1:1
	s_waitcnt lgkmcnt(0)
	ds_read2_b32 v[32:33], v14 offset0:33 offset1:41
	ds_read2_b32 v[34:35], v14 offset1:8
	ds_read2_b32 v[36:37], v14 offset0:66 offset1:74
	ds_read2_b32 v[38:39], v14 offset0:99 offset1:107
	ds_read2_b32 v[40:41], v14 offset0:132 offset1:140
	ds_read2_b32 v[42:43], v14 offset0:165 offset1:173
	ds_read2_b32 v[44:45], v14 offset0:198 offset1:206
	ds_read2_b32 v[46:47], v14 offset0:231 offset1:239
	ds_read2_b32 v[48:49], v14 offset0:49 offset1:57
	ds_read2_b32 v[50:51], v14 offset0:16 offset1:24
	ds_read2_b32 v[52:53], v14 offset0:82 offset1:90
	ds_read2_b32 v[54:55], v14 offset0:115 offset1:123
	ds_read2_b32 v[56:57], v14 offset0:148 offset1:156
	ds_read2_b32 v[58:59], v14 offset0:181 offset1:189
	ds_read2_b32 v[60:61], v14 offset0:214 offset1:222
	ds_read2_b32 v[62:63], v14 offset0:247 offset1:255
	s_waitcnt lgkmcnt(14)
; #define GAS __attribute__((address_space(1)))
; #define LAS __attribute__((address_space(3)))
; __device__ __forceinline__ unsigned pk2(float lo, float hi) { return f2bf(lo) | (f2bf(hi) << 16); }
; __device__ __forceinline__ void p0_transpose_item(const float* W, int N, bf16* WT, int ldt, int rowmode, LAS float* scr, int kb, int nb, int lane, const float* kgain) {
;     ...
;     for (int j = 0; j < 4; ++j) { const int n = (lane >> 3) + 8 * j; const LAS float* s = scr + (8 * c) * 33 + n;
;         v4u o; o.x = pk2(s[0 * 33], s[1 * 33]); o.y = pk2(s[2 * 33], s[3 * 33]); o.z = pk2(s[4 * 33], s[5 * 33]); o.w = pk2(s[6 * 33], s[7 * 33]);
;         const int ng = n0 + n; int row;
;         if (rowmode == 0) row = ng;
;         else if (rowmode == 3) { const int np = ng - (PW + 4 * HW); row = np < 0 ? ng : (PW + 4 * HW) + ((np & (D - 1)) >> 7) * 256 + (np >= D ? 128 : 0) + (np & 127); }
;         else row = (ng >> 7) * 256 + (rowmode == 2 ? 128 : 0) + (ng & 127);
;         *(GAS v4u*)(WT + (size_t)row * ldt + k0 + 8 * c) = o; }
	v_bfe_u32 v31, v34, 16, 1
	s_waitcnt lgkmcnt(13)
	v_bfe_u32 v67, v36, 16, 1
	s_waitcnt lgkmcnt(12)
	v_bfe_u32 v68, v38, 16, 1
	s_waitcnt lgkmcnt(11)
	v_bfe_u32 v69, v40, 16, 1
	s_waitcnt lgkmcnt(10)
	v_bfe_u32 v70, v42, 16, 1
	s_waitcnt lgkmcnt(9)
	v_bfe_u32 v71, v44, 16, 1
	v_bfe_u32 v66, v32, 16, 1
	s_waitcnt lgkmcnt(8)
	v_bfe_u32 v72, v46, 16, 1
	v_bfe_u32 v73, v35, 16, 1
	v_bfe_u32 v74, v33, 16, 1
	v_bfe_u32 v75, v37, 16, 1
	v_bfe_u32 v76, v39, 16, 1
	v_bfe_u32 v77, v41, 16, 1
	v_bfe_u32 v78, v43, 16, 1
	v_bfe_u32 v79, v45, 16, 1
	v_bfe_u32 v80, v47, 16, 1
	s_waitcnt lgkmcnt(6)
	v_bfe_u32 v81, v50, 16, 1
	s_waitcnt lgkmcnt(5)
	v_bfe_u32 v89, v52, 16, 1
	s_waitcnt lgkmcnt(4)
	v_bfe_u32 v90, v54, 16, 1
	s_waitcnt lgkmcnt(3)
	v_bfe_u32 v91, v56, 16, 1
	s_waitcnt lgkmcnt(2)
	v_bfe_u32 v92, v58, 16, 1
	s_waitcnt lgkmcnt(1)
	v_bfe_u32 v93, v60, 16, 1
	v_bfe_u32 v96, v51, 16, 1
	v_bfe_u32 v98, v53, 16, 1
	v_bfe_u32 v100, v57, 16, 1
	v_bfe_u32 v102, v61, 16, 1
	v_add3_u32 v31, v34, v31, s13
	v_add3_u32 v34, v36, v67, s13
	v_add3_u32 v36, v38, v68, s13
	v_add3_u32 v38, v40, v69, s13
	v_add3_u32 v40, v42, v70, s13
	v_add3_u32 v42, v44, v71, s13
	v_bfe_u32 v88, v48, 16, 1
	s_waitcnt lgkmcnt(0)
	v_bfe_u32 v94, v62, 16, 1
	v_bfe_u32 v95, v49, 16, 1
	v_bfe_u32 v97, v55, 16, 1
	v_bfe_u32 v99, v59, 16, 1
	v_bfe_u32 v101, v63, 16, 1
	v_add3_u32 v32, v32, v66, s13
	v_add3_u32 v44, v46, v72, s13
	v_add3_u32 v35, v35, v73, s13
	v_add3_u32 v46, v33, v74, s13
	v_add3_u32 v33, v37, v75, s13
	v_add3_u32 v37, v39, v76, s13
	v_add3_u32 v39, v41, v77, s13
	v_add3_u32 v41, v43, v78, s13
	v_add3_u32 v43, v45, v79, s13
	v_add3_u32 v45, v47, v80, s13
	v_add3_u32 v47, v50, v81, s13
	v_add3_u32 v50, v52, v89, s13
	v_add3_u32 v52, v54, v90, s13
	v_add3_u32 v54, v56, v91, s13
	v_add3_u32 v56, v58, v92, s13
	v_add3_u32 v58, v60, v93, s13
	v_add3_u32 v51, v51, v96, s13
	v_add3_u32 v53, v53, v98, s13
	v_add3_u32 v57, v57, v100, s13
	v_add3_u32 v61, v61, v102, s13
	v_lshrrev_b32_e32 v31, 16, v31
	v_lshrrev_b32_e32 v34, 16, v34
	v_lshrrev_b32_e32 v38, 16, v38
	v_lshrrev_b32_e32 v42, 16, v42
	v_add3_u32 v48, v48, v88, s13
	v_add3_u32 v60, v62, v94, s13
	v_add3_u32 v49, v49, v95, s13
	v_add3_u32 v55, v55, v97, s13
	v_add3_u32 v59, v59, v99, s13
	v_add3_u32 v62, v63, v101, s13
	v_lshrrev_b32_e32 v63, 16, v35
	v_lshrrev_b32_e32 v66, 16, v33
	v_lshrrev_b32_e32 v39, 16, v39
	v_lshrrev_b32_e32 v43, 16, v43
	v_lshrrev_b32_e32 v47, 16, v47
	v_lshrrev_b32_e32 v50, 16, v50
	v_lshrrev_b32_e32 v54, 16, v54
	v_lshrrev_b32_e32 v58, 16, v58
	v_lshrrev_b32_e32 v51, 16, v51
	v_lshrrev_b32_e32 v53, 16, v53
	v_lshrrev_b32_e32 v57, 16, v57
	v_lshrrev_b32_e32 v61, 16, v61
	v_and_or_b32 v32, v32, s14, v31
	v_and_or_b32 v33, v36, s14, v34
	v_and_or_b32 v34, v40, s14, v38
	v_and_or_b32 v35, v44, s14, v42
	v_and_or_b32 v36, v46, s14, v63
	v_and_or_b32 v37, v37, s14, v66
	v_and_or_b32 v38, v41, s14, v39
	v_and_or_b32 v39, v45, s14, v43
	v_and_or_b32 v40, v48, s14, v47
	v_and_or_b32 v41, v52, s14, v50
	v_and_or_b32 v42, v56, s14, v54
	v_and_or_b32 v43, v60, s14, v58
	v_and_or_b32 v44, v49, s14, v51
	v_and_or_b32 v45, v55, s14, v53
	v_and_or_b32 v46, v59, s14, v57
	v_and_or_b32 v47, v62, s14, v61
	global_store_dwordx4 v[64:65], v[32:35], off sc1
	global_store_dwordx4 v[82:83], v[36:39], off sc1
	global_store_dwordx4 v[84:85], v[40:43], off sc1
	global_store_dwordx4 v[86:87], v[44:47], off sc1
	s_waitcnt lgkmcnt(0)
	s_cbranch_scc0 .LBB0_885

; __device__ __forceinline__ unsigned cvt_pk_bf16(float lo, float hi) { const cvt_f2 v = {lo, hi}; return __builtin_bit_cast(unsigned, __builtin_convertvector(v, cvt_b2)); }
; __device__ __forceinline__ float fsilu(float x) { return x * fsigmoid(x); }
;     __device__ __forceinline__ void operator()(const f32x4 (&acc)[2][2][4][2], const Unit& u, int wr, int wc, int fr, int fq) const {
;         const int row0 = u.pm * BM + wr * 64 + fr, col0 = u.pn * HALF + wc * 32 + 8 * fq;
; #pragma unroll
;         for (int ai = 0; ai < 2; ++ai)
; #pragma unroll
;             for (int m = 0; m < 4; ++m) { const int row = row0 + ai * HALF + m * 16; const float r = RS[row - pm_lo * BM];
;                 float o[8];
; #pragma unroll
;                 for (int n = 0; n < 2; ++n)
; #pragma unroll
;                     for (int j = 0; j < 4; ++j) { const float gt = acc[ai][0][m][n][j] * r, up = acc[ai][1][m][n][j] * r; o[4 * n + j] = fsilu(gt) * up; }
;                 pg8::u32x4 w; w.x = cvt_pk_bf16(o[0], o[1]); w.y = cvt_pk_bf16(o[2], o[3]); w.z = cvt_pk_bf16(o[4], o[5]); w.w = cvt_pk_bf16(o[6], o[7]);
;                 *(pg8::u32x4*)(O + (size_t)row * DFF + col0) = w; }
;     }
.LBB0_911:
	v_lshl_add_u32 v158, s22, 8, v149
	v_add_u32_e32 v165, 0x90, v158
	v_or_b32_e32 v159, 16, v158
	v_or_b32_e32 v160, 32, v158
	v_or_b32_e32 v161, 48, v158
	v_add_u32_e32 v163, 0x80, v158
	v_subrev_u32_e32 v164, s41, v165
	v_add_u32_e32 v169, 0xa0, v158
	v_subrev_u32_e32 v147, s41, v158
	v_subrev_u32_e32 v148, s41, v159
	v_subrev_u32_e32 v150, s41, v160
	v_subrev_u32_e32 v152, s41, v161
	v_subrev_u32_e32 v154, s41, v163
	v_lshl_add_u32 v167, v164, 2, s44
	v_subrev_u32_e32 v164, s41, v169
	v_add_u32_e32 v176, 0xb0, v158
	v_lshl_add_u32 v147, v147, 2, s44
	v_lshl_add_u32 v148, v148, 2, s44
	v_lshl_add_u32 v150, v150, 2, s44
	v_lshl_add_u32 v152, v152, 2, s44
	v_lshl_add_u32 v154, v154, 2, s44
	v_lshl_add_u32 v171, v164, 2, s44
	v_subrev_u32_e32 v164, s41, v176
	v_lshl_add_u32 v172, v164, 2, s44
	ds_read_b32 v164, v147
	ds_read_b32 v166, v148
	ds_read_b32 v168, v150
	ds_read_b32 v170, v152
	ds_read_b32 v154, v154
	ds_read_b32 v152, v167
	ds_read_b32 v150, v171
	ds_read_b32 v148, v172
	s_waitcnt lgkmcnt(0)
	v_pk_mul_f32 v[126:127], v[126:127], v[164:165] op_sel_hi:[1,0]
	v_pk_mul_f32 v[128:129], v[128:129], v[164:165] op_sel_hi:[1,0]
	v_mul_f32_e32 v147, 0xbfb8aa3b, v126
	v_exp_f32_e32 v167, v147
	v_mul_f32_e32 v171, 0xbfb8aa3b, v127
	v_exp_f32_e32 v171, v171
	v_mul_f32_e32 v173, 0xbfb8aa3b, v129
	v_add_f32_e32 v167, 1.0, v167
	v_rcp_f32_e32 v172, v167
	v_add_f32_e32 v167, 1.0, v171
	v_mul_f32_e32 v171, 0xbfb8aa3b, v128
	v_exp_f32_e32 v171, v171
	v_exp_f32_e32 v175, v173
	v_rcp_f32_e32 v173, v167
	v_pk_mul_f32 v[118:119], v[118:119], v[164:165] op_sel_hi:[1,0]
	v_add_f32_e32 v167, 1.0, v171
	v_rcp_f32_e32 v174, v167
	v_add_f32_e32 v167, 1.0, v175
	v_rcp_f32_e32 v175, v167
	v_pk_mul_f32 v[126:127], v[126:127], v[172:173]
	v_pk_mul_f32 v[122:123], v[122:123], v[164:165] op_sel_hi:[1,0]
	v_pk_mul_f32 v[118:119], v[118:119], v[126:127]
	v_pk_mul_f32 v[126:127], v[128:129], v[174:175]
	v_mul_f32_e32 v128, 0xbfb8aa3b, v122
	v_exp_f32_e32 v128, v128
	v_pk_mul_f32 v[120:121], v[120:121], v[164:165] op_sel_hi:[1,0]
	v_pk_mul_f32 v[124:125], v[124:125], v[164:165] op_sel_hi:[1,0]
	v_pk_mul_f32 v[120:121], v[120:121], v[126:127]
	v_mul_f32_e32 v126, 0xbfb8aa3b, v123
	v_exp_f32_e32 v127, v126
	v_add_f32_e32 v126, 1.0, v128
	v_mul_f32_e32 v128, 0xbfb8aa3b, v124
	v_mul_f32_e32 v129, 0xbfb8aa3b, v125
	v_exp_f32_e32 v128, v128
	v_exp_f32_e32 v129, v129
	v_add_f32_e32 v127, 1.0, v127
	v_rcp_f32_e32 v126, v126
	v_rcp_f32_e32 v127, v127
	v_add_f32_e32 v128, 1.0, v128
	v_add_f32_e32 v129, 1.0, v129
	v_rcp_f32_e32 v128, v128
	v_rcp_f32_e32 v129, v129
	v_pk_mul_f32 v[110:111], v[110:111], v[164:165] op_sel_hi:[1,0]
	v_pk_mul_f32 v[122:123], v[122:123], v[126:127]
	v_lshl_or_b32 v146, s46, 7, v153
	v_pk_mul_f32 v[110:111], v[110:111], v[122:123]
	v_pk_mul_f32 v[112:113], v[112:113], v[164:165] op_sel_hi:[1,0]
	v_pk_mul_f32 v[122:123], v[124:125], v[128:129]
	v_ashrrev_i32_e32 v147, 31, v146
	v_pk_mul_f32 v[112:113], v[112:113], v[122:123]
	v_cvt_pk_bf16_f32 v118, v118, v119
	v_cvt_pk_bf16_f32 v119, v120, v121
	v_cvt_pk_bf16_f32 v120, v110, v111
	v_mov_b64_e32 v[110:111], s[62:63]
	v_cvt_pk_bf16_f32 v121, v112, v113
	v_mad_i64_i32 v[122:123], s[24:25], v158, s45, v[110:111]
	v_lshlrev_b64 v[112:113], 1, v[146:147]
	v_lshl_add_u64 v[122:123], v[122:123], 0, v[112:113]
	v_pk_mul_f32 v[114:115], v[114:115], v[166:167] op_sel_hi:[1,0]
	global_store_dwordx4 v[122:123], v[118:121], off sc1
	v_mul_f32_e32 v124, 0xbfb8aa3b, v114
	v_pk_mul_f32 v[116:117], v[116:117], v[166:167] op_sel_hi:[1,0]
	v_mul_f32_e32 v118, 0xbfb8aa3b, v115
	v_exp_f32_e32 v124, v124
	v_exp_f32_e32 v119, v118
	v_mul_f32_e32 v120, 0xbfb8aa3b, v116
	v_mul_f32_e32 v121, 0xbfb8aa3b, v117
	v_exp_f32_e32 v120, v120
	v_exp_f32_e32 v121, v121
	v_add_f32_e32 v118, 1.0, v124
	v_add_f32_e32 v119, 1.0, v119
	v_rcp_f32_e32 v118, v118
	v_rcp_f32_e32 v119, v119
	v_add_f32_e32 v120, 1.0, v120
	v_add_f32_e32 v121, 1.0, v121
	v_rcp_f32_e32 v120, v120
	v_rcp_f32_e32 v121, v121
	v_pk_mul_f32 v[102:103], v[102:103], v[166:167] op_sel_hi:[1,0]
	v_pk_mul_f32 v[114:115], v[114:115], v[118:119]
	v_pk_mul_f32 v[106:107], v[106:107], v[166:167] op_sel_hi:[1,0]
	v_pk_mul_f32 v[102:103], v[102:103], v[114:115]
	v_pk_mul_f32 v[114:115], v[116:117], v[120:121]
	v_mul_f32_e32 v116, 0xbfb8aa3b, v106
	v_exp_f32_e32 v116, v116
	v_pk_mul_f32 v[104:105], v[104:105], v[166:167] op_sel_hi:[1,0]
	v_pk_mul_f32 v[108:109], v[108:109], v[166:167] op_sel_hi:[1,0]
	v_pk_mul_f32 v[104:105], v[104:105], v[114:115]
	v_mul_f32_e32 v114, 0xbfb8aa3b, v107
	v_exp_f32_e32 v115, v114
	v_add_f32_e32 v114, 1.0, v116
	v_mul_f32_e32 v116, 0xbfb8aa3b, v108
	v_mul_f32_e32 v117, 0xbfb8aa3b, v109
	v_exp_f32_e32 v116, v116
	v_exp_f32_e32 v117, v117
	v_add_f32_e32 v115, 1.0, v115
	v_rcp_f32_e32 v114, v114
	v_rcp_f32_e32 v115, v115
	v_add_f32_e32 v116, 1.0, v116
	v_add_f32_e32 v117, 1.0, v117
	v_rcp_f32_e32 v116, v116
	v_rcp_f32_e32 v117, v117
	v_pk_mul_f32 v[94:95], v[94:95], v[166:167] op_sel_hi:[1,0]
	v_pk_mul_f32 v[106:107], v[106:107], v[114:115]
	v_pk_mul_f32 v[98:99], v[98:99], v[168:169] op_sel_hi:[1,0]
	v_pk_mul_f32 v[106:107], v[94:95], v[106:107]
	v_pk_mul_f32 v[94:95], v[96:97], v[166:167] op_sel_hi:[1,0]
	v_pk_mul_f32 v[96:97], v[108:109], v[116:117]
	v_pk_mul_f32 v[86:87], v[86:87], v[168:169] op_sel_hi:[1,0]
	v_pk_mul_f32 v[108:109], v[94:95], v[96:97]
	v_cvt_pk_bf16_f32 v94, v102, v103
	v_mad_i64_i32 v[102:103], s[24:25], v159, s45, v[110:111]
	v_cvt_pk_bf16_f32 v95, v104, v105
	v_cvt_pk_bf16_f32 v96, v106, v107
	v_cvt_pk_bf16_f32 v97, v108, v109
	v_lshl_add_u64 v[102:103], v[102:103], 0, v[112:113]
	v_mul_f32_e32 v104, 0xbfb8aa3b, v98
; __device__ __forceinline__ unsigned cvt_pk_bf16(float lo, float hi) { const cvt_f2 v = {lo, hi}; return __builtin_bit_cast(unsigned, __builtin_convertvector(v, cvt_b2)); }
; __device__ __forceinline__ float fsilu(float x) { return x * fsigmoid(x); }
;     __device__ __forceinline__ void operator()(const f32x4 (&acc)[2][2][4][2], const Unit& u, int wr, int wc, int fr, int fq) const {
;         const int row0 = u.pm * BM + wr * 64 + fr, col0 = u.pn * HALF + wc * 32 + 8 * fq;
; #pragma unroll
;         for (int ai = 0; ai < 2; ++ai)
; #pragma unroll
;             for (int m = 0; m < 4; ++m) { const int row = row0 + ai * HALF + m * 16; const float r = RS[row - pm_lo * BM];
;                 float o[8];
; #pragma unroll
;                 for (int n = 0; n < 2; ++n)
; #pragma unroll
;                     for (int j = 0; j < 4; ++j) { const float gt = acc[ai][0][m][n][j] * r, up = acc[ai][1][m][n][j] * r; o[4 * n + j] = fsilu(gt) * up; }
;                 pg8::u32x4 w; w.x = cvt_pk_bf16(o[0], o[1]); w.y = cvt_pk_bf16(o[2], o[3]); w.z = cvt_pk_bf16(o[4], o[5]); w.w = cvt_pk_bf16(o[6], o[7]);
;                 *(pg8::u32x4*)(O + (size_t)row * DFF + col0) = w; }
;     }
	global_store_dwordx4 v[102:103], v[94:97], off sc1
	v_exp_f32_e32 v104, v104
	v_pk_mul_f32 v[90:91], v[90:91], v[168:169] op_sel_hi:[1,0]
	v_mul_f32_e32 v94, 0xbfb8aa3b, v99
	v_pk_mul_f32 v[96:97], v[100:101], v[168:169] op_sel_hi:[1,0]
	v_exp_f32_e32 v95, v94
	v_mul_f32_e32 v100, 0xbfb8aa3b, v96
	v_mul_f32_e32 v101, 0xbfb8aa3b, v97
	v_exp_f32_e32 v100, v100
	v_exp_f32_e32 v101, v101
	v_add_f32_e32 v94, 1.0, v104
	v_add_f32_e32 v95, 1.0, v95
	v_rcp_f32_e32 v94, v94
	v_rcp_f32_e32 v95, v95
	v_add_f32_e32 v100, 1.0, v100
	v_add_f32_e32 v101, 1.0, v101
	v_rcp_f32_e32 v100, v100
	v_rcp_f32_e32 v101, v101
	v_pk_mul_f32 v[94:95], v[98:99], v[94:95]
	v_pk_mul_f32 v[88:89], v[88:89], v[168:169] op_sel_hi:[1,0]
	v_pk_mul_f32 v[86:87], v[86:87], v[94:95]
	v_pk_mul_f32 v[94:95], v[96:97], v[100:101]
	v_mul_f32_e32 v96, 0xbfb8aa3b, v90
	v_exp_f32_e32 v96, v96
	v_pk_mul_f32 v[88:89], v[88:89], v[94:95]
	v_mul_f32_e32 v94, 0xbfb8aa3b, v91
	v_pk_mul_f32 v[92:93], v[92:93], v[168:169] op_sel_hi:[1,0]
	v_exp_f32_e32 v95, v94
	v_add_f32_e32 v94, 1.0, v96
	v_mul_f32_e32 v96, 0xbfb8aa3b, v92
	v_mul_f32_e32 v97, 0xbfb8aa3b, v93
	v_exp_f32_e32 v96, v96
	v_exp_f32_e32 v97, v97
	v_add_f32_e32 v95, 1.0, v95
	v_rcp_f32_e32 v94, v94
	v_rcp_f32_e32 v95, v95
	v_add_f32_e32 v96, 1.0, v96
	v_add_f32_e32 v97, 1.0, v97
	v_rcp_f32_e32 v96, v96
	v_rcp_f32_e32 v97, v97
	v_pk_mul_f32 v[78:79], v[78:79], v[168:169] op_sel_hi:[1,0]
	v_pk_mul_f32 v[90:91], v[90:91], v[94:95]
	v_pk_mul_f32 v[82:83], v[82:83], v[170:171] op_sel_hi:[1,0]
	v_pk_mul_f32 v[90:91], v[78:79], v[90:91]
	v_pk_mul_f32 v[78:79], v[80:81], v[168:169] op_sel_hi:[1,0]
	v_pk_mul_f32 v[80:81], v[92:93], v[96:97]
	v_pk_mul_f32 v[70:71], v[70:71], v[170:171] op_sel_hi:[1,0]
	v_pk_mul_f32 v[92:93], v[78:79], v[80:81]
	v_cvt_pk_bf16_f32 v78, v86, v87
	v_mad_i64_i32 v[86:87], s[24:25], v160, s45, v[110:111]
	v_cvt_pk_bf16_f32 v79, v88, v89
	v_cvt_pk_bf16_f32 v80, v90, v91
	v_cvt_pk_bf16_f32 v81, v92, v93
	v_lshl_add_u64 v[86:87], v[86:87], 0, v[112:113]
	v_mul_f32_e32 v88, 0xbfb8aa3b, v82
	global_store_dwordx4 v[86:87], v[78:81], off sc1
	v_exp_f32_e32 v88, v88
	v_pk_mul_f32 v[74:75], v[74:75], v[170:171] op_sel_hi:[1,0]
	v_mul_f32_e32 v78, 0xbfb8aa3b, v83
	v_pk_mul_f32 v[80:81], v[84:85], v[170:171] op_sel_hi:[1,0]
	v_exp_f32_e32 v79, v78
	v_mul_f32_e32 v84, 0xbfb8aa3b, v80
	v_mul_f32_e32 v85, 0xbfb8aa3b, v81
	v_exp_f32_e32 v84, v84
	v_exp_f32_e32 v85, v85
	v_add_f32_e32 v78, 1.0, v88
	v_add_f32_e32 v79, 1.0, v79
	v_rcp_f32_e32 v78, v78
	v_rcp_f32_e32 v79, v79
	v_add_f32_e32 v84, 1.0, v84
	v_add_f32_e32 v85, 1.0, v85
	v_rcp_f32_e32 v84, v84
	v_rcp_f32_e32 v85, v85
	v_pk_mul_f32 v[78:79], v[82:83], v[78:79]
	v_pk_mul_f32 v[72:73], v[72:73], v[170:171] op_sel_hi:[1,0]
	v_pk_mul_f32 v[70:71], v[70:71], v[78:79]
	v_pk_mul_f32 v[78:79], v[80:81], v[84:85]
	v_mul_f32_e32 v80, 0xbfb8aa3b, v74
	v_exp_f32_e32 v80, v80
	v_pk_mul_f32 v[72:73], v[72:73], v[78:79]
	v_mul_f32_e32 v78, 0xbfb8aa3b, v75
	v_pk_mul_f32 v[76:77], v[76:77], v[170:171] op_sel_hi:[1,0]
	v_exp_f32_e32 v79, v78
	v_add_f32_e32 v78, 1.0, v80
	v_mul_f32_e32 v80, 0xbfb8aa3b, v76
	v_mul_f32_e32 v81, 0xbfb8aa3b, v77
	v_exp_f32_e32 v80, v80
	v_exp_f32_e32 v81, v81
	v_add_f32_e32 v79, 1.0, v79
	v_rcp_f32_e32 v78, v78
	v_rcp_f32_e32 v79, v79
	v_add_f32_e32 v80, 1.0, v80
	v_add_f32_e32 v81, 1.0, v81
	v_rcp_f32_e32 v80, v80
	v_rcp_f32_e32 v81, v81
	v_pk_mul_f32 v[66:67], v[66:67], v[170:171] op_sel_hi:[1,0]
	v_pk_mul_f32 v[74:75], v[74:75], v[78:79]
	v_pk_mul_f32 v[62:63], v[62:63], v[154:155] op_sel_hi:[1,0]
	v_pk_mul_f32 v[74:75], v[66:67], v[74:75]
	v_pk_mul_f32 v[66:67], v[68:69], v[170:171] op_sel_hi:[1,0]
	v_pk_mul_f32 v[68:69], v[76:77], v[80:81]
	v_pk_mul_f32 v[64:65], v[64:65], v[154:155] op_sel_hi:[1,0]
	v_pk_mul_f32 v[76:77], v[66:67], v[68:69]
	v_cvt_pk_bf16_f32 v66, v70, v71
	v_mad_i64_i32 v[70:71], s[24:25], v161, s45, v[110:111]
	v_cvt_pk_bf16_f32 v67, v72, v73
	v_cvt_pk_bf16_f32 v68, v74, v75
	v_cvt_pk_bf16_f32 v69, v76, v77
	v_lshl_add_u64 v[70:71], v[70:71], 0, v[112:113]
	v_mul_f32_e32 v72, 0xbfb8aa3b, v62
	global_store_dwordx4 v[70:71], v[66:69], off sc1
	v_exp_f32_e32 v72, v72
	v_pk_mul_f32 v[54:55], v[54:55], v[154:155] op_sel_hi:[1,0]
	v_mul_f32_e32 v66, 0xbfb8aa3b, v63
	v_exp_f32_e32 v67, v66
	v_mul_f32_e32 v68, 0xbfb8aa3b, v64
	v_mul_f32_e32 v69, 0xbfb8aa3b, v65
	v_exp_f32_e32 v68, v68
	v_exp_f32_e32 v69, v69
	v_add_f32_e32 v66, 1.0, v72
	v_add_f32_e32 v67, 1.0, v67
	v_rcp_f32_e32 v66, v66
	v_rcp_f32_e32 v67, v67
	v_add_f32_e32 v68, 1.0, v68
	v_add_f32_e32 v69, 1.0, v69
	v_rcp_f32_e32 v68, v68
	v_rcp_f32_e32 v69, v69
	v_pk_mul_f32 v[62:63], v[62:63], v[66:67]
	v_pk_mul_f32 v[58:59], v[58:59], v[154:155] op_sel_hi:[1,0]
	v_pk_mul_f32 v[54:55], v[54:55], v[62:63]
	v_pk_mul_f32 v[62:63], v[64:65], v[68:69]
	v_mul_f32_e32 v64, 0xbfb8aa3b, v58
	v_exp_f32_e32 v64, v64
	v_pk_mul_f32 v[56:57], v[56:57], v[154:155] op_sel_hi:[1,0]
	v_pk_mul_f32 v[60:61], v[60:61], v[154:155] op_sel_hi:[1,0]
	v_pk_mul_f32 v[56:57], v[56:57], v[62:63]
	v_mul_f32_e32 v62, 0xbfb8aa3b, v59
	v_exp_f32_e32 v63, v62
	v_add_f32_e32 v62, 1.0, v64
	v_mul_f32_e32 v64, 0xbfb8aa3b, v60
	v_mul_f32_e32 v65, 0xbfb8aa3b, v61
	v_exp_f32_e32 v64, v64
	v_exp_f32_e32 v65, v65
	v_add_f32_e32 v63, 1.0, v63
	v_rcp_f32_e32 v62, v62
	v_rcp_f32_e32 v63, v63
	v_add_f32_e32 v64, 1.0, v64
	v_add_f32_e32 v65, 1.0, v65
	v_rcp_f32_e32 v64, v64
	v_rcp_f32_e32 v65, v65
	v_pk_mul_f32 v[46:47], v[46:47], v[154:155] op_sel_hi:[1,0]
	v_pk_mul_f32 v[58:59], v[58:59], v[62:63]
	v_pk_mul_f32 v[50:51], v[50:51], v[152:153] op_sel_hi:[1,0]
	v_pk_mul_f32 v[58:59], v[46:47], v[58:59]
; __device__ __forceinline__ unsigned cvt_pk_bf16(float lo, float hi) { const cvt_f2 v = {lo, hi}; return __builtin_bit_cast(unsigned, __builtin_convertvector(v, cvt_b2)); }
; __device__ __forceinline__ float fsilu(float x) { return x * fsigmoid(x); }
;     __device__ __forceinline__ void operator()(const f32x4 (&acc)[2][2][4][2], const Unit& u, int wr, int wc, int fr, int fq) const {
;         const int row0 = u.pm * BM + wr * 64 + fr, col0 = u.pn * HALF + wc * 32 + 8 * fq;
; #pragma unroll
;         for (int ai = 0; ai < 2; ++ai)
; #pragma unroll
;             for (int m = 0; m < 4; ++m) { const int row = row0 + ai * HALF + m * 16; const float r = RS[row - pm_lo * BM];
;                 float o[8];
; #pragma unroll
;                 for (int n = 0; n < 2; ++n)
; #pragma unroll
;                     for (int j = 0; j < 4; ++j) { const float gt = acc[ai][0][m][n][j] * r, up = acc[ai][1][m][n][j] * r; o[4 * n + j] = fsilu(gt) * up; }
;                 pg8::u32x4 w; w.x = cvt_pk_bf16(o[0], o[1]); w.y = cvt_pk_bf16(o[2], o[3]); w.z = cvt_pk_bf16(o[4], o[5]); w.w = cvt_pk_bf16(o[6], o[7]);
;                 *(pg8::u32x4*)(O + (size_t)row * DFF + col0) = w; }
;     }
	v_pk_mul_f32 v[46:47], v[48:49], v[154:155] op_sel_hi:[1,0]
	v_pk_mul_f32 v[48:49], v[60:61], v[64:65]
	v_pk_mul_f32 v[38:39], v[38:39], v[152:153] op_sel_hi:[1,0]
	v_pk_mul_f32 v[60:61], v[46:47], v[48:49]
	v_cvt_pk_bf16_f32 v46, v54, v55
	v_mad_i64_i32 v[54:55], s[24:25], v163, s45, v[110:111]
	v_cvt_pk_bf16_f32 v47, v56, v57
	v_cvt_pk_bf16_f32 v48, v58, v59
	v_cvt_pk_bf16_f32 v49, v60, v61
	v_lshl_add_u64 v[54:55], v[54:55], 0, v[112:113]
	v_mul_f32_e32 v56, 0xbfb8aa3b, v50
	global_store_dwordx4 v[54:55], v[46:49], off sc1
	v_exp_f32_e32 v56, v56
	v_pk_mul_f32 v[42:43], v[42:43], v[152:153] op_sel_hi:[1,0]
	v_mul_f32_e32 v46, 0xbfb8aa3b, v51
	v_pk_mul_f32 v[48:49], v[52:53], v[152:153] op_sel_hi:[1,0]
	v_exp_f32_e32 v47, v46
	v_mul_f32_e32 v52, 0xbfb8aa3b, v48
	v_mul_f32_e32 v53, 0xbfb8aa3b, v49
	v_exp_f32_e32 v52, v52
	v_exp_f32_e32 v53, v53
	v_add_f32_e32 v46, 1.0, v56
	v_add_f32_e32 v47, 1.0, v47
	v_rcp_f32_e32 v46, v46
	v_rcp_f32_e32 v47, v47
	v_add_f32_e32 v52, 1.0, v52
	v_add_f32_e32 v53, 1.0, v53
	v_rcp_f32_e32 v52, v52
	v_rcp_f32_e32 v53, v53
	v_pk_mul_f32 v[46:47], v[50:51], v[46:47]
	v_pk_mul_f32 v[40:41], v[40:41], v[152:153] op_sel_hi:[1,0]
	v_pk_mul_f32 v[38:39], v[38:39], v[46:47]
	v_pk_mul_f32 v[46:47], v[48:49], v[52:53]
	v_mul_f32_e32 v48, 0xbfb8aa3b, v42
	v_exp_f32_e32 v48, v48
	v_pk_mul_f32 v[40:41], v[40:41], v[46:47]
	v_mul_f32_e32 v46, 0xbfb8aa3b, v43
	v_pk_mul_f32 v[44:45], v[44:45], v[152:153] op_sel_hi:[1,0]
	v_exp_f32_e32 v47, v46
	v_add_f32_e32 v46, 1.0, v48
	v_mul_f32_e32 v48, 0xbfb8aa3b, v44
	v_mul_f32_e32 v49, 0xbfb8aa3b, v45
	v_exp_f32_e32 v48, v48
	v_exp_f32_e32 v49, v49
	v_add_f32_e32 v47, 1.0, v47
	v_rcp_f32_e32 v46, v46
	v_rcp_f32_e32 v47, v47
	v_add_f32_e32 v48, 1.0, v48
	v_add_f32_e32 v49, 1.0, v49
	v_rcp_f32_e32 v48, v48
	v_rcp_f32_e32 v49, v49
	v_pk_mul_f32 v[30:31], v[30:31], v[152:153] op_sel_hi:[1,0]
	v_pk_mul_f32 v[42:43], v[42:43], v[46:47]
	v_pk_mul_f32 v[34:35], v[34:35], v[150:151] op_sel_hi:[1,0]
	v_pk_mul_f32 v[42:43], v[30:31], v[42:43]
	v_pk_mul_f32 v[30:31], v[32:33], v[152:153] op_sel_hi:[1,0]
	v_pk_mul_f32 v[32:33], v[44:45], v[48:49]
	v_pk_mul_f32 v[22:23], v[22:23], v[150:151] op_sel_hi:[1,0]
	v_pk_mul_f32 v[44:45], v[30:31], v[32:33]
	v_cvt_pk_bf16_f32 v30, v38, v39
	v_mad_i64_i32 v[38:39], s[24:25], v165, s45, v[110:111]
	v_cvt_pk_bf16_f32 v31, v40, v41
	v_cvt_pk_bf16_f32 v32, v42, v43
	v_cvt_pk_bf16_f32 v33, v44, v45
	v_lshl_add_u64 v[38:39], v[38:39], 0, v[112:113]
	v_mul_f32_e32 v40, 0xbfb8aa3b, v34
	global_store_dwordx4 v[38:39], v[30:33], off sc1
	v_exp_f32_e32 v40, v40
	v_pk_mul_f32 v[26:27], v[26:27], v[150:151] op_sel_hi:[1,0]
	v_mul_f32_e32 v30, 0xbfb8aa3b, v35
	v_pk_mul_f32 v[32:33], v[36:37], v[150:151] op_sel_hi:[1,0]
	v_exp_f32_e32 v31, v30
	v_mul_f32_e32 v36, 0xbfb8aa3b, v32
	v_mul_f32_e32 v37, 0xbfb8aa3b, v33
	v_exp_f32_e32 v36, v36
	v_exp_f32_e32 v37, v37
	v_add_f32_e32 v30, 1.0, v40
	v_add_f32_e32 v31, 1.0, v31
	v_rcp_f32_e32 v30, v30
	v_rcp_f32_e32 v31, v31
	v_add_f32_e32 v36, 1.0, v36
	v_add_f32_e32 v37, 1.0, v37
	v_rcp_f32_e32 v36, v36
	v_rcp_f32_e32 v37, v37
	v_pk_mul_f32 v[30:31], v[34:35], v[30:31]
	v_pk_mul_f32 v[24:25], v[24:25], v[150:151] op_sel_hi:[1,0]
	v_pk_mul_f32 v[22:23], v[22:23], v[30:31]
	v_pk_mul_f32 v[30:31], v[32:33], v[36:37]
	v_mul_f32_e32 v32, 0xbfb8aa3b, v26
	v_exp_f32_e32 v32, v32
	v_pk_mul_f32 v[24:25], v[24:25], v[30:31]
	v_mul_f32_e32 v30, 0xbfb8aa3b, v27
	v_pk_mul_f32 v[28:29], v[28:29], v[150:151] op_sel_hi:[1,0]
	v_exp_f32_e32 v31, v30
	v_add_f32_e32 v30, 1.0, v32
	v_mul_f32_e32 v32, 0xbfb8aa3b, v28
	v_mul_f32_e32 v33, 0xbfb8aa3b, v29
	v_exp_f32_e32 v32, v32
	v_exp_f32_e32 v33, v33
	v_add_f32_e32 v31, 1.0, v31
	v_rcp_f32_e32 v30, v30
	v_rcp_f32_e32 v31, v31
	v_add_f32_e32 v32, 1.0, v32
	v_add_f32_e32 v33, 1.0, v33
	v_rcp_f32_e32 v32, v32
	v_rcp_f32_e32 v33, v33
	v_pk_mul_f32 v[18:19], v[18:19], v[150:151] op_sel_hi:[1,0]
	v_pk_mul_f32 v[26:27], v[26:27], v[30:31]
	v_pk_mul_f32 v[14:15], v[14:15], v[148:149] op_sel_hi:[1,0]
	v_pk_mul_f32 v[26:27], v[18:19], v[26:27]
	v_pk_mul_f32 v[18:19], v[20:21], v[150:151] op_sel_hi:[1,0]
	v_pk_mul_f32 v[20:21], v[28:29], v[32:33]
	v_pk_mul_f32 v[16:17], v[16:17], v[148:149] op_sel_hi:[1,0]
	v_pk_mul_f32 v[28:29], v[18:19], v[20:21]
	v_cvt_pk_bf16_f32 v18, v22, v23
	v_mad_i64_i32 v[22:23], s[24:25], v169, s45, v[110:111]
	v_cvt_pk_bf16_f32 v19, v24, v25
	v_cvt_pk_bf16_f32 v20, v26, v27
	v_cvt_pk_bf16_f32 v21, v28, v29
	v_lshl_add_u64 v[22:23], v[22:23], 0, v[112:113]
	v_mul_f32_e32 v24, 0xbfb8aa3b, v14
	global_store_dwordx4 v[22:23], v[18:21], off sc1
	v_exp_f32_e32 v24, v24
	v_pk_mul_f32 v[6:7], v[6:7], v[148:149] op_sel_hi:[1,0]
	v_mul_f32_e32 v18, 0xbfb8aa3b, v15
	v_exp_f32_e32 v19, v18
	v_mul_f32_e32 v20, 0xbfb8aa3b, v16
	v_mul_f32_e32 v21, 0xbfb8aa3b, v17
	v_exp_f32_e32 v20, v20
	v_exp_f32_e32 v21, v21
	v_add_f32_e32 v18, 1.0, v24
	v_add_f32_e32 v19, 1.0, v19
	v_rcp_f32_e32 v18, v18
	v_rcp_f32_e32 v19, v19
	v_add_f32_e32 v20, 1.0, v20
	v_add_f32_e32 v21, 1.0, v21
	v_rcp_f32_e32 v20, v20
	v_rcp_f32_e32 v21, v21
	v_pk_mul_f32 v[14:15], v[14:15], v[18:19]
	v_pk_mul_f32 v[10:11], v[10:11], v[148:149] op_sel_hi:[1,0]
	v_pk_mul_f32 v[6:7], v[6:7], v[14:15]
	v_pk_mul_f32 v[14:15], v[16:17], v[20:21]
	v_mul_f32_e32 v16, 0xbfb8aa3b, v10
	v_exp_f32_e32 v16, v16
	v_pk_mul_f32 v[8:9], v[8:9], v[148:149] op_sel_hi:[1,0]
	v_pk_mul_f32 v[12:13], v[12:13], v[148:149] op_sel_hi:[1,0]
	v_pk_mul_f32 v[8:9], v[8:9], v[14:15]
	v_mul_f32_e32 v14, 0xbfb8aa3b, v11
	v_exp_f32_e32 v15, v14
	v_add_f32_e32 v14, 1.0, v16
	v_mul_f32_e32 v16, 0xbfb8aa3b, v12
	v_mul_f32_e32 v17, 0xbfb8aa3b, v13
	v_exp_f32_e32 v16, v16
	v_exp_f32_e32 v17, v17
	v_add_f32_e32 v15, 1.0, v15
	v_rcp_f32_e32 v14, v14
	v_rcp_f32_e32 v15, v15
	v_add_f32_e32 v16, 1.0, v16
	v_add_f32_e32 v17, 1.0, v17
	v_rcp_f32_e32 v16, v16
	v_rcp_f32_e32 v17, v17
	v_pk_mul_f32 v[2:3], v[2:3], v[148:149] op_sel_hi:[1,0]
	v_pk_mul_f32 v[10:11], v[10:11], v[14:15]
	s_andn2_b64 vcc, exec, s[4:5]
	v_pk_mul_f32 v[10:11], v[2:3], v[10:11]
	v_pk_mul_f32 v[2:3], v[4:5], v[148:149] op_sel_hi:[1,0]
	v_pk_mul_f32 v[4:5], v[12:13], v[16:17]
	s_mov_b64 s[4:5], -1
	v_pk_mul_f32 v[12:13], v[2:3], v[4:5]
	v_cvt_pk_bf16_f32 v2, v6, v7
	v_mad_i64_i32 v[6:7], s[24:25], v176, s45, v[110:111]
	v_cvt_pk_bf16_f32 v3, v8, v9
	v_cvt_pk_bf16_f32 v4, v10, v11
	v_cvt_pk_bf16_f32 v5, v12, v13
	v_lshl_add_u64 v[6:7], v[6:7], 0, v[112:113]
	global_store_dwordx4 v[6:7], v[2:5], off sc1
	s_cbranch_vccnz .LBB0_904
	s_andn2_b64 vcc, exec, s[6:7]
	s_cbranch_vccnz .LBB0_903
	s_barrier
	s_branch .LBB0_903

;     __device__ __forceinline__ void fused(f32x4 (&acc)[2][2][4][2], const Unit& u, int wr, int wc, int fr, int fq, PG8_LAS unsigned char* lds, int wid, int lane) const {
;     ...
;         if (lane < 32) { const float* xr = X + (size_t)(u.pm * BM + row) * 16; float tot = 0.f;
; #pragma unroll
;             for (int t = 0; t < 16; ++t) tot += __hip_atomic_load(xr + t, __ATOMIC_RELAXED, __HIP_MEMORY_SCOPE_AGENT);
;             Sx[row] = __builtin_amdgcn_rsqf(tot * (1.0f / D) + EPS); }
;         asm volatile("s_waitcnt lgkmcnt(0)" ::: "memory"); __builtin_amdgcn_s_barrier(); asm volatile("" ::: "memory");
;         f32x4 gv[2][2];
; #pragma unroll
;         for (int bj = 0; bj < 2; ++bj)
; #pragma unroll
;             for (int n = 0; n < 2; ++n) gv[bj][n] = *(const f32x4*)(gain + col0 + bj * HALF + 4 * n);
; #pragma unroll
;         for (int ai = 0; ai < 2; ++ai)
; #pragma unroll
;             for (int m = 0; m < 4; ++m) { const int rl = ai * HALF + wr * 64 + m * 16 + fr; const float rs = Sx[rl]; const size_t ro = (size_t)(u.pm * BM + rl) * D + col0;
; #pragma unroll
;                 for (int bj = 0; bj < 2; ++bj) { *(f32x4*)(O + ro + bj * HALF) = acc[ai][bj][m][0] * rs * gv[bj][0]; *(f32x4*)(O + ro + bj * HALF + 4) = acc[ai][bj][m][1] * rs * gv[bj][1]; } }
.LBB0_1015:
	s_or_b64 exec, exec, s[16:17]
	v_lshl_or_b32 v207, v203, 3, s37
	v_or_b32_e32 v2, s38, v207
	v_ashrrev_i32_e32 v3, 31, v2
	v_lshlrev_b64 v[148:149], 2, v[2:3]
	s_waitcnt lgkmcnt(0)
	s_barrier
	v_lshl_add_u64 v[2:3], s[48:49], 0, v[148:149]
	global_load_dwordx4 v[144:147], v[2:3], off
	global_load_dwordx4 v[140:143], v[2:3], off offset:16
	global_load_dwordx4 v[136:139], v[2:3], off offset:512
	s_waitcnt lgkmcnt(0)
	global_load_dwordx4 v[132:135], v[2:3], off offset:528
	v_lshl_add_u32 v1, v208, 2, 0
	v_add_u32_e32 v1, 0x1000, v1
	ds_read2_b32 v[156:157], v1 offset1:16
	ds_read2_b32 v[158:159], v1 offset0:32 offset1:48
	v_add_u32_e32 v2, s39, v208
	v_mov_b32_e32 v3, 0
	v_add_u32_e32 v154, 32, v2
	v_mov_b32_e32 v155, v3
	v_lshlrev_b64 v[150:151], 14, v[2:3]
	v_add_u32_e32 v152, 16, v2
	v_mov_b32_e32 v153, v3
	v_lshlrev_b64 v[154:155], 14, v[154:155]
	v_lshl_add_u64 v[150:151], s[50:51], 0, v[150:151]
	v_lshlrev_b64 v[152:153], 14, v[152:153]
	v_lshl_add_u64 v[154:155], s[50:51], 0, v[154:155]
	s_waitcnt lgkmcnt(0)
	v_pk_mul_f32 v[128:129], v[128:129], v[156:157] op_sel_hi:[1,0]
	v_pk_mul_f32 v[130:131], v[130:131], v[156:157] op_sel_hi:[1,0]
	v_pk_mul_f32 v[124:125], v[124:125], v[156:157] op_sel_hi:[1,0]
	v_pk_mul_f32 v[126:127], v[126:127], v[156:157] op_sel_hi:[1,0]
	v_pk_mul_f32 v[120:121], v[120:121], v[156:157] op_sel_hi:[1,0]
	v_pk_mul_f32 v[122:123], v[122:123], v[156:157] op_sel_hi:[1,0]
	v_pk_mul_f32 v[116:117], v[116:117], v[156:157] op_sel_hi:[1,0]
	v_pk_mul_f32 v[118:119], v[118:119], v[156:157] op_sel_hi:[1,0]
	v_mov_b32_e32 v156, v157
	v_pk_mul_f32 v[84:85], v[84:85], v[158:159] op_sel_hi:[1,0]
	v_pk_mul_f32 v[86:87], v[86:87], v[158:159] op_sel_hi:[1,0]
	v_lshl_add_u64 v[152:153], s[50:51], 0, v[152:153]
	v_lshl_add_u64 v[150:151], v[150:151], 0, v[148:149]
	v_lshl_add_u64 v[154:155], v[154:155], 0, v[148:149]
	v_pk_mul_f32 v[160:161], v[112:113], v[158:159] op_sel_hi:[1,0]
	v_pk_mul_f32 v[162:163], v[114:115], v[158:159] op_sel_hi:[1,0]
	v_pk_mul_f32 v[164:165], v[108:109], v[158:159] op_sel_hi:[1,0]
	v_pk_mul_f32 v[166:167], v[110:111], v[158:159] op_sel_hi:[1,0]
	v_pk_mul_f32 v[168:169], v[104:105], v[158:159] op_sel_hi:[1,0]
	v_pk_mul_f32 v[170:171], v[106:107], v[158:159] op_sel_hi:[1,0]
	v_pk_mul_f32 v[104:105], v[100:101], v[156:157] op_sel_hi:[1,0]
	v_pk_mul_f32 v[106:107], v[102:103], v[156:157] op_sel_hi:[1,0]
	v_pk_mul_f32 v[108:109], v[96:97], v[156:157] op_sel_hi:[1,0]
	v_pk_mul_f32 v[110:111], v[98:99], v[156:157] op_sel_hi:[1,0]
	v_pk_mul_f32 v[112:113], v[92:93], v[156:157] op_sel_hi:[1,0]
	v_pk_mul_f32 v[114:115], v[94:95], v[156:157] op_sel_hi:[1,0]
	v_pk_mul_f32 v[208:209], v[88:89], v[156:157] op_sel_hi:[1,0]
	v_pk_mul_f32 v[156:157], v[90:91], v[156:157] op_sel_hi:[1,0]
	v_lshl_add_u64 v[152:153], v[152:153], 0, v[148:149]
	v_readfirstlane_b32 s56, v0
	s_lshr_b32 s57, s56, 6
	s_lshl_b32 s40, s57, 10
	s_add_i32 s58, s40, 0
	s_add_i32 m0, s58, 0x10000
	s_or_b32 s20, s36, 16
	s_lshr_b32 s18, s56, 8
	s_mul_i32 s16, s20, 0x560000
	s_waitcnt vmcnt(0)
	v_pk_mul_f32 v[90:91], v[146:147], v[130:131]
	v_pk_mul_f32 v[88:89], v[144:145], v[128:129]
	v_pk_mul_f32 v[94:95], v[142:143], v[126:127]
	v_pk_mul_f32 v[86:87], v[134:135], v[86:87]
	v_pk_mul_f32 v[84:85], v[132:133], v[84:85]
	v_pk_mul_f32 v[92:93], v[140:141], v[124:125]
	v_pk_mul_f32 v[98:99], v[138:139], v[122:123]
	v_pk_mul_f32 v[96:97], v[136:137], v[120:121]
	v_pk_mul_f32 v[102:103], v[134:135], v[118:119]
	v_pk_mul_f32 v[100:101], v[132:133], v[116:117]
	v_pk_mul_f32 v[106:107], v[146:147], v[106:107]
	v_pk_mul_f32 v[104:105], v[144:145], v[104:105]
	v_pk_mul_f32 v[110:111], v[142:143], v[110:111]
	v_pk_mul_f32 v[108:109], v[140:141], v[108:109]
	v_pk_mul_f32 v[114:115], v[138:139], v[114:115]
	v_pk_mul_f32 v[112:113], v[136:137], v[112:113]
	v_pk_mul_f32 v[118:119], v[134:135], v[156:157]
	v_pk_mul_f32 v[116:117], v[132:133], v[208:209]
	v_pk_mul_f32 v[122:123], v[146:147], v[162:163]
	v_pk_mul_f32 v[120:121], v[144:145], v[160:161]
	v_pk_mul_f32 v[126:127], v[142:143], v[166:167]
	v_pk_mul_f32 v[124:125], v[140:141], v[164:165]
	v_pk_mul_f32 v[130:131], v[138:139], v[170:171]
	v_pk_mul_f32 v[128:129], v[136:137], v[168:169]
	global_store_dwordx4 v[150:151], v[88:91], off sc1
	global_store_dwordx4 v[150:151], v[92:95], off offset:16 sc1
	global_store_dwordx4 v[150:151], v[96:99], off offset:512 sc1
	global_store_dwordx4 v[150:151], v[100:103], off offset:528 sc1
	global_store_dwordx4 v[152:153], v[104:107], off sc1
	global_store_dwordx4 v[152:153], v[108:111], off offset:16 sc1
	global_store_dwordx4 v[152:153], v[112:115], off offset:512 sc1
	global_store_dwordx4 v[152:153], v[116:119], off offset:528 sc1
	global_store_dwordx4 v[154:155], v[120:123], off sc1
	global_store_dwordx4 v[154:155], v[124:127], off offset:16 sc1
	global_store_dwordx4 v[154:155], v[128:131], off offset:512 sc1
	global_store_dwordx4 v[154:155], v[84:87], off offset:528 sc1
	s_nop 1
	v_add_u32_e32 v84, 48, v2
	v_mov_b32_e32 v85, v3
	v_mov_b32_e32 v86, v159
	v_lshlrev_b64 v[84:85], 14, v[84:85]
	v_lshl_add_u64 v[84:85], s[50:51], 0, v[84:85]
	v_pk_mul_f32 v[72:73], v[72:73], v[86:87] op_sel_hi:[1,0]
	v_pk_mul_f32 v[74:75], v[74:75], v[86:87] op_sel_hi:[1,0]
	v_lshl_add_u64 v[84:85], v[84:85], 0, v[148:149]
	v_pk_mul_f32 v[74:75], v[138:139], v[74:75]
	v_pk_mul_f32 v[72:73], v[136:137], v[72:73]
	global_store_dwordx4 v[84:85], v[72:75], off offset:512 sc1
	ds_read2_b32 v[72:73], v1 offset0:128 offset1:144
	v_pk_mul_f32 v[68:69], v[68:69], v[86:87] op_sel_hi:[1,0]
	v_pk_mul_f32 v[70:71], v[70:71], v[86:87] op_sel_hi:[1,0]
	v_pk_mul_f32 v[68:69], v[132:133], v[68:69]
	v_pk_mul_f32 v[70:71], v[134:135], v[70:71]
	global_store_dwordx4 v[84:85], v[68:71], off offset:528 sc1
	s_waitcnt lgkmcnt(0)
; #define PG8_STAGE(bufoff, gbase, voff) do { _Pragma("unroll") for (int _i = 0; _i < 2; ++_i) \
;         __builtin_amdgcn_global_load_lds((const unsigned*)((const char*)(gbase) + (voff)[_i]), (PG8_LAS unsigned*)(lds + (bufoff) + ldsw + _i * 8192), 16, 0, 0); } while (0)
; #define PG8_BAR __builtin_amdgcn_s_barrier()
; template <class Epi, class Sched, bool ALIGN_EPI = false, bool SP2 = false>
; __device__ __forceinline__ void gemm_phase(PG8_LAS unsigned char* lds, const Gemm g, const Sched& S, const Epi& E) {
;     ...
;         PG8_STAGE(PG8_SB(0, 0), cB, voffB); PG8_STAGE(PG8_SB(0, 1), cB + hstepB, voffB); PG8_STAGE(PG8_SA(0, 0), cA, voffA); PG8_STAGE(PG8_SA(0, 1), cA + hstepA, voffA);
;         if (wr == 1) PG8_BAR;
;     __device__ __forceinline__ void fused(f32x4 (&acc)[2][2][4][2], const Unit& u, int wr, int wc, int fr, int fq, PG8_LAS unsigned char* lds, int wid, int lane) const {
;     ...
;         f32x4 gv[2][2];
; #pragma unroll
;         for (int bj = 0; bj < 2; ++bj)
; #pragma unroll
;             for (int n = 0; n < 2; ++n) gv[bj][n] = *(const f32x4*)(gain + col0 + bj * HALF + 4 * n);
; #pragma unroll
;         for (int ai = 0; ai < 2; ++ai)
; #pragma unroll
;             for (int m = 0; m < 4; ++m) { const int rl = ai * HALF + wr * 64 + m * 16 + fr; const float rs = Sx[rl]; const size_t ro = (size_t)(u.pm * BM + rl) * D + col0;
; #pragma unroll
;                 for (int bj = 0; bj < 2; ++bj) { *(f32x4*)(O + ro + bj * HALF) = acc[ai][bj][m][0] * rs * gv[bj][0]; *(f32x4*)(O + ro + bj * HALF + 4) = acc[ai][bj][m][1] * rs * gv[bj][1]; } }
	v_pk_mul_f32 v[52:53], v[52:53], v[72:73] op_sel_hi:[1,0]
	v_pk_mul_f32 v[54:55], v[54:55], v[72:73] op_sel_hi:[1,0]
	v_add_u32_e32 v68, 0x80, v2
	v_mov_b32_e32 v69, v3
	v_lshlrev_b64 v[68:69], 14, v[68:69]
	v_lshl_add_u64 v[68:69], s[50:51], 0, v[68:69]
	v_lshl_add_u64 v[68:69], v[68:69], 0, v[148:149]
	v_pk_mul_f32 v[54:55], v[134:135], v[54:55]
	v_pk_mul_f32 v[52:53], v[132:133], v[52:53]
	global_store_dwordx4 v[68:69], v[52:55], off offset:528 sc1
	v_pk_mul_f32 v[80:81], v[80:81], v[86:87] op_sel_hi:[1,0]
	v_pk_mul_f32 v[82:83], v[82:83], v[86:87] op_sel_hi:[1,0]
	v_add_u32_e32 v52, 0x90, v2
	v_mov_b32_e32 v53, v3
	v_mov_b32_e32 v54, v73
	v_lshlrev_b64 v[52:53], 14, v[52:53]
	v_lshl_add_u64 v[52:53], s[50:51], 0, v[52:53]
	v_pk_mul_f32 v[40:41], v[40:41], v[54:55] op_sel_hi:[1,0]
	v_pk_mul_f32 v[42:43], v[42:43], v[54:55] op_sel_hi:[1,0]
	v_lshl_add_u64 v[52:53], v[52:53], 0, v[148:149]
	v_pk_mul_f32 v[42:43], v[138:139], v[42:43]
	v_pk_mul_f32 v[40:41], v[136:137], v[40:41]
	global_store_dwordx4 v[52:53], v[40:43], off offset:512 sc1
	ds_read2_b32 v[40:41], v1 offset0:160 offset1:176
	v_pk_mul_f32 v[36:37], v[36:37], v[54:55] op_sel_hi:[1,0]
	v_pk_mul_f32 v[38:39], v[38:39], v[54:55] op_sel_hi:[1,0]
	v_pk_mul_f32 v[36:37], v[132:133], v[36:37]
	v_pk_mul_f32 v[38:39], v[134:135], v[38:39]
	global_store_dwordx4 v[52:53], v[36:39], off offset:528 sc1
	s_waitcnt lgkmcnt(0)
	v_pk_mul_f32 v[20:21], v[20:21], v[40:41] op_sel_hi:[1,0]
	v_pk_mul_f32 v[22:23], v[22:23], v[40:41] op_sel_hi:[1,0]
	v_add_u32_e32 v36, 0xa0, v2
	v_mov_b32_e32 v37, v3
	v_lshlrev_b64 v[36:37], 14, v[36:37]
	v_lshl_add_u64 v[36:37], s[50:51], 0, v[36:37]
	v_lshl_add_u64 v[36:37], v[36:37], 0, v[148:149]
	v_pk_mul_f32 v[22:23], v[134:135], v[22:23]
	v_pk_mul_f32 v[20:21], v[132:133], v[20:21]
	v_add_u32_e32 v2, 0xb0, v2
	global_store_dwordx4 v[36:37], v[20:23], off offset:528 sc1
	v_pk_mul_f32 v[76:77], v[76:77], v[86:87] op_sel_hi:[1,0]
	v_pk_mul_f32 v[78:79], v[78:79], v[86:87] op_sel_hi:[1,0]
	v_mov_b32_e32 v20, v41
	v_lshlrev_b64 v[22:23], 14, v[2:3]
	v_pk_mul_f32 v[64:65], v[64:65], v[72:73] op_sel_hi:[1,0]
	v_pk_mul_f32 v[66:67], v[66:67], v[72:73] op_sel_hi:[1,0]
	v_pk_mul_f32 v[60:61], v[60:61], v[72:73] op_sel_hi:[1,0]
	v_pk_mul_f32 v[62:63], v[62:63], v[72:73] op_sel_hi:[1,0]
	v_pk_mul_f32 v[56:57], v[56:57], v[72:73] op_sel_hi:[1,0]
	v_pk_mul_f32 v[58:59], v[58:59], v[72:73] op_sel_hi:[1,0]
	v_pk_mul_f32 v[48:49], v[48:49], v[54:55] op_sel_hi:[1,0]
	v_pk_mul_f32 v[50:51], v[50:51], v[54:55] op_sel_hi:[1,0]
	v_pk_mul_f32 v[44:45], v[44:45], v[54:55] op_sel_hi:[1,0]
	v_pk_mul_f32 v[46:47], v[46:47], v[54:55] op_sel_hi:[1,0]
	v_pk_mul_f32 v[32:33], v[32:33], v[40:41] op_sel_hi:[1,0]
	v_pk_mul_f32 v[34:35], v[34:35], v[40:41] op_sel_hi:[1,0]
	v_pk_mul_f32 v[28:29], v[28:29], v[40:41] op_sel_hi:[1,0]
	v_pk_mul_f32 v[30:31], v[30:31], v[40:41] op_sel_hi:[1,0]
	v_pk_mul_f32 v[24:25], v[24:25], v[40:41] op_sel_hi:[1,0]
	v_pk_mul_f32 v[26:27], v[26:27], v[40:41] op_sel_hi:[1,0]
	v_pk_mul_f32 v[16:17], v[16:17], v[20:21] op_sel_hi:[1,0]
	v_pk_mul_f32 v[18:19], v[18:19], v[20:21] op_sel_hi:[1,0]
	v_lshl_add_u64 v[22:23], s[50:51], 0, v[22:23]
	v_pk_mul_f32 v[12:13], v[12:13], v[20:21] op_sel_hi:[1,0]
	v_pk_mul_f32 v[14:15], v[14:15], v[20:21] op_sel_hi:[1,0]
	v_pk_mul_f32 v[8:9], v[8:9], v[20:21] op_sel_hi:[1,0]
	v_pk_mul_f32 v[10:11], v[10:11], v[20:21] op_sel_hi:[1,0]
	v_pk_mul_f32 v[4:5], v[4:5], v[20:21] op_sel_hi:[1,0]
	v_pk_mul_f32 v[6:7], v[6:7], v[20:21] op_sel_hi:[1,0]
	v_pk_mul_f32 v[82:83], v[146:147], v[82:83]
	v_pk_mul_f32 v[80:81], v[144:145], v[80:81]
	v_pk_mul_f32 v[78:79], v[142:143], v[78:79]
	v_pk_mul_f32 v[76:77], v[140:141], v[76:77]
	v_pk_mul_f32 v[66:67], v[146:147], v[66:67]
	v_pk_mul_f32 v[64:65], v[144:145], v[64:65]
	v_pk_mul_f32 v[62:63], v[142:143], v[62:63]
	v_pk_mul_f32 v[60:61], v[140:141], v[60:61]
	v_pk_mul_f32 v[58:59], v[138:139], v[58:59]
	v_pk_mul_f32 v[56:57], v[136:137], v[56:57]
	v_pk_mul_f32 v[50:51], v[146:147], v[50:51]
	v_pk_mul_f32 v[48:49], v[144:145], v[48:49]
	v_pk_mul_f32 v[46:47], v[142:143], v[46:47]
	v_pk_mul_f32 v[44:45], v[140:141], v[44:45]
	v_pk_mul_f32 v[34:35], v[146:147], v[34:35]
	v_pk_mul_f32 v[32:33], v[144:145], v[32:33]
	v_pk_mul_f32 v[30:31], v[142:143], v[30:31]
	v_pk_mul_f32 v[28:29], v[140:141], v[28:29]
	v_pk_mul_f32 v[26:27], v[138:139], v[26:27]
	v_pk_mul_f32 v[24:25], v[136:137], v[24:25]
	v_pk_mul_f32 v[18:19], v[146:147], v[18:19]
	v_pk_mul_f32 v[16:17], v[144:145], v[16:17]
	v_lshl_add_u64 v[22:23], v[22:23], 0, v[148:149]
	v_pk_mul_f32 v[14:15], v[142:143], v[14:15]
	v_pk_mul_f32 v[12:13], v[140:141], v[12:13]
	v_pk_mul_f32 v[10:11], v[138:139], v[10:11]
	v_pk_mul_f32 v[8:9], v[136:137], v[8:9]
	v_pk_mul_f32 v[6:7], v[134:135], v[6:7]
	v_pk_mul_f32 v[4:5], v[132:133], v[4:5]
	global_store_dwordx4 v[84:85], v[80:83], off sc1
	global_store_dwordx4 v[84:85], v[76:79], off offset:16 sc1
	global_store_dwordx4 v[68:69], v[64:67], off sc1
	global_store_dwordx4 v[68:69], v[60:63], off offset:16 sc1
	global_store_dwordx4 v[68:69], v[56:59], off offset:512 sc1
	global_store_dwordx4 v[52:53], v[48:51], off sc1
	global_store_dwordx4 v[52:53], v[44:47], off offset:16 sc1
	global_store_dwordx4 v[36:37], v[32:35], off sc1
	global_store_dwordx4 v[36:37], v[28:31], off offset:16 sc1
	global_store_dwordx4 v[36:37], v[24:27], off offset:512 sc1
	global_store_dwordx4 v[22:23], v[16:19], off sc1
	global_store_dwordx4 v[22:23], v[12:15], off offset:16 sc1
	global_store_dwordx4 v[22:23], v[8:11], off offset:512 sc1
	global_store_dwordx4 v[22:23], v[4:7], off offset:528 sc1
	s_barrier
	global_load_lds_dwordx4 v[190:191], off
	s_add_i32 m0, s58, 0x12000
	s_nop 0
	global_load_lds_dwordx4 v[188:189], off
	s_add_i32 m0, s58, 0x14000
	s_nop 0
	global_load_lds_dwordx4 v[198:199], off
	s_add_i32 m0, s58, 0x16000
	s_add_u32 s16, s24, s16
	s_addc_u32 s17, s25, 0
	s_add_i32 s60, s58, 0x2000
	global_load_lds_dwordx4 v[196:197], off
	v_lshl_add_u64 v[4:5], s[16:17], 0, v[172:173]
	s_mov_b32 m0, s58
	s_add_u32 s22, s16, 0x2b0000
	global_load_lds_dwordx4 v[4:5], off
	v_lshl_add_u64 v[0:1], s[16:17], 0, v[176:177]
	s_mov_b32 m0, s60
	s_addc_u32 s23, s17, 0
	s_add_i32 s61, s58, 0x4000
	global_load_lds_dwordx4 v[0:1], off
	v_lshl_add_u64 v[6:7], s[22:23], 0, v[172:173]
	s_mov_b32 m0, s61
	s_add_i32 s62, s58, 0x6000
	global_load_lds_dwordx4 v[6:7], off
	v_lshl_add_u64 v[6:7], s[22:23], 0, v[176:177]
	s_mov_b32 m0, s62
	s_cmp_lg_u32 s18, 1
	global_load_lds_dwordx4 v[6:7], off
	s_cbranch_scc1 .LBB0_1017
	s_barrier

;     __device__ __forceinline__ void fused(f32x4 (&acc)[2][2][4][2], const Unit& u, int wr, int wc, int fr, int fq, PG8_LAS unsigned char* lds, int wid, int lane) const {
;     ...
;         f32x4 gv[2][2];
; #pragma unroll
;         for (int bj = 0; bj < 2; ++bj)
; #pragma unroll
;             for (int n = 0; n < 2; ++n) gv[bj][n] = *(const f32x4*)(gain + col0 + bj * HALF + 4 * n);
; #pragma unroll
;         for (int ai = 0; ai < 2; ++ai)
; #pragma unroll
;             for (int m = 0; m < 4; ++m) { const int rl = ai * HALF + wr * 64 + m * 16 + fr; const float rs = Sx[rl]; const size_t ro = (size_t)(u.pm * BM + rl) * D + col0;
; #pragma unroll
;                 for (int bj = 0; bj < 2; ++bj) { *(f32x4*)(O + ro + bj * HALF) = acc[ai][bj][m][0] * rs * gv[bj][0]; *(f32x4*)(O + ro + bj * HALF + 4) = acc[ai][bj][m][1] * rs * gv[bj][1]; } }
.LBB0_1058:
	s_or_b64 exec, exec, s[0:1]
	v_or_b32_e32 v0, s54, v207
	v_ashrrev_i32_e32 v1, 31, v0
	v_lshlrev_b64 v[0:1], 2, v[0:1]
	s_waitcnt lgkmcnt(0)
	s_barrier
	s_waitcnt lgkmcnt(0)
	v_lshl_add_u64 v[130:131], s[48:49], 0, v[0:1]
	global_load_dwordx4 v[142:145], v[130:131], off
	global_load_dwordx4 v[138:141], v[130:131], off offset:16
	global_load_dwordx4 v[134:137], v[130:131], off offset:512
	s_nop 0
	global_load_dwordx4 v[130:133], v[130:131], off offset:528
	v_lshl_add_u32 v148, v188, 2, 0
	v_add_u32_e32 v172, 0x1000, v148
	ds_read2_b32 v[154:155], v172 offset1:16
	ds_read2_b32 v[156:157], v172 offset0:32 offset1:48
	v_add_u32_e32 v146, s55, v188
	v_mov_b32_e32 v147, 0
	v_add_u32_e32 v152, 32, v146
	v_mov_b32_e32 v153, v147
	v_lshlrev_b64 v[148:149], 14, v[146:147]
	v_add_u32_e32 v150, 16, v146
	v_mov_b32_e32 v151, v147
	v_lshlrev_b64 v[152:153], 14, v[152:153]
	v_lshl_add_u64 v[148:149], s[50:51], 0, v[148:149]
	v_lshlrev_b64 v[150:151], 14, v[150:151]
	v_lshl_add_u64 v[152:153], s[50:51], 0, v[152:153]
	s_waitcnt lgkmcnt(0)
	v_pk_mul_f32 v[128:129], v[128:129], v[154:155] op_sel_hi:[1,0]
	v_pk_mul_f32 v[126:127], v[126:127], v[154:155] op_sel_hi:[1,0]
	v_pk_mul_f32 v[124:125], v[124:125], v[154:155] op_sel_hi:[1,0]
	v_pk_mul_f32 v[122:123], v[122:123], v[154:155] op_sel_hi:[1,0]
	v_pk_mul_f32 v[120:121], v[120:121], v[154:155] op_sel_hi:[1,0]
	v_pk_mul_f32 v[118:119], v[118:119], v[154:155] op_sel_hi:[1,0]
	v_pk_mul_f32 v[116:117], v[116:117], v[154:155] op_sel_hi:[1,0]
	v_pk_mul_f32 v[114:115], v[114:115], v[154:155] op_sel_hi:[1,0]
	v_mov_b32_e32 v154, v155
	v_pk_mul_f32 v[84:85], v[84:85], v[156:157] op_sel_hi:[1,0]
	v_pk_mul_f32 v[82:83], v[82:83], v[156:157] op_sel_hi:[1,0]
	v_lshl_add_u64 v[148:149], v[148:149], 0, v[0:1]
	v_lshl_add_u64 v[150:151], s[50:51], 0, v[150:151]
	v_lshl_add_u64 v[152:153], v[152:153], 0, v[0:1]
	v_pk_mul_f32 v[158:159], v[112:113], v[156:157] op_sel_hi:[1,0]
	v_pk_mul_f32 v[160:161], v[110:111], v[156:157] op_sel_hi:[1,0]
	v_pk_mul_f32 v[162:163], v[108:109], v[156:157] op_sel_hi:[1,0]
	v_pk_mul_f32 v[164:165], v[106:107], v[156:157] op_sel_hi:[1,0]
	v_pk_mul_f32 v[166:167], v[104:105], v[156:157] op_sel_hi:[1,0]
	v_pk_mul_f32 v[168:169], v[102:103], v[156:157] op_sel_hi:[1,0]
	v_pk_mul_f32 v[104:105], v[100:101], v[154:155] op_sel_hi:[1,0]
	v_pk_mul_f32 v[102:103], v[98:99], v[154:155] op_sel_hi:[1,0]
	v_pk_mul_f32 v[108:109], v[96:97], v[154:155] op_sel_hi:[1,0]
	v_pk_mul_f32 v[106:107], v[94:95], v[154:155] op_sel_hi:[1,0]
	v_pk_mul_f32 v[112:113], v[92:93], v[154:155] op_sel_hi:[1,0]
	v_pk_mul_f32 v[110:111], v[90:91], v[154:155] op_sel_hi:[1,0]
	v_pk_mul_f32 v[170:171], v[88:89], v[154:155] op_sel_hi:[1,0]
	v_pk_mul_f32 v[154:155], v[86:87], v[154:155] op_sel_hi:[1,0]
	v_lshl_add_u64 v[150:151], v[150:151], 0, v[0:1]
	s_waitcnt vmcnt(0)
	v_pk_mul_f32 v[86:87], v[142:143], v[126:127]
	v_pk_mul_f32 v[88:89], v[144:145], v[128:129]
	v_pk_mul_f32 v[90:91], v[138:139], v[122:123]
	v_pk_mul_f32 v[82:83], v[130:131], v[82:83]
	v_pk_mul_f32 v[84:85], v[132:133], v[84:85]
	v_pk_mul_f32 v[92:93], v[140:141], v[124:125]
	v_pk_mul_f32 v[94:95], v[134:135], v[118:119]
	v_pk_mul_f32 v[96:97], v[136:137], v[120:121]
	v_pk_mul_f32 v[98:99], v[130:131], v[114:115]
	v_pk_mul_f32 v[100:101], v[132:133], v[116:117]
	v_pk_mul_f32 v[102:103], v[142:143], v[102:103]
	v_pk_mul_f32 v[104:105], v[144:145], v[104:105]
	v_pk_mul_f32 v[106:107], v[138:139], v[106:107]
	v_pk_mul_f32 v[108:109], v[140:141], v[108:109]
	v_pk_mul_f32 v[110:111], v[134:135], v[110:111]
	v_pk_mul_f32 v[112:113], v[136:137], v[112:113]
	v_pk_mul_f32 v[114:115], v[130:131], v[154:155]
	v_pk_mul_f32 v[116:117], v[132:133], v[170:171]
	v_pk_mul_f32 v[118:119], v[142:143], v[160:161]
	v_pk_mul_f32 v[120:121], v[144:145], v[158:159]
	v_pk_mul_f32 v[122:123], v[138:139], v[164:165]
	v_pk_mul_f32 v[124:125], v[140:141], v[162:163]
	v_pk_mul_f32 v[126:127], v[134:135], v[168:169]
	v_pk_mul_f32 v[128:129], v[136:137], v[166:167]
	global_store_dwordx4 v[148:149], v[86:89], off sc1
	global_store_dwordx4 v[148:149], v[90:93], off offset:16 sc1
	global_store_dwordx4 v[148:149], v[94:97], off offset:512 sc1
	global_store_dwordx4 v[148:149], v[98:101], off offset:528 sc1
	global_store_dwordx4 v[150:151], v[102:105], off sc1
	global_store_dwordx4 v[150:151], v[106:109], off offset:16 sc1
	global_store_dwordx4 v[150:151], v[110:113], off offset:512 sc1
	global_store_dwordx4 v[150:151], v[114:117], off offset:528 sc1
	global_store_dwordx4 v[152:153], v[118:121], off sc1
	global_store_dwordx4 v[152:153], v[122:125], off offset:16 sc1
	global_store_dwordx4 v[152:153], v[126:129], off offset:512 sc1
	global_store_dwordx4 v[152:153], v[82:85], off offset:528 sc1
	s_nop 1
	v_add_u32_e32 v82, 48, v146
	v_mov_b32_e32 v83, v147
	v_mov_b32_e32 v84, v157
	v_lshlrev_b64 v[82:83], 14, v[82:83]
	v_lshl_add_u64 v[82:83], s[50:51], 0, v[82:83]
	v_pk_mul_f32 v[70:71], v[70:71], v[84:85] op_sel_hi:[1,0]
	v_pk_mul_f32 v[72:73], v[72:73], v[84:85] op_sel_hi:[1,0]
	v_lshl_add_u64 v[82:83], v[82:83], 0, v[0:1]
	v_pk_mul_f32 v[72:73], v[136:137], v[72:73]
	v_pk_mul_f32 v[70:71], v[134:135], v[70:71]
	global_store_dwordx4 v[82:83], v[70:73], off offset:512 sc1
	ds_read2_b32 v[70:71], v172 offset0:128 offset1:144
	v_pk_mul_f32 v[66:67], v[66:67], v[84:85] op_sel_hi:[1,0]
	v_pk_mul_f32 v[68:69], v[68:69], v[84:85] op_sel_hi:[1,0]
	v_pk_mul_f32 v[66:67], v[130:131], v[66:67]
	v_pk_mul_f32 v[68:69], v[132:133], v[68:69]
	global_store_dwordx4 v[82:83], v[66:69], off offset:528 sc1
	s_waitcnt lgkmcnt(0)
;     __device__ __forceinline__ void fused(f32x4 (&acc)[2][2][4][2], const Unit& u, int wr, int wc, int fr, int fq, PG8_LAS unsigned char* lds, int wid, int lane) const {
;     ...
;         f32x4 gv[2][2];
; #pragma unroll
;         for (int bj = 0; bj < 2; ++bj)
; #pragma unroll
;             for (int n = 0; n < 2; ++n) gv[bj][n] = *(const f32x4*)(gain + col0 + bj * HALF + 4 * n);
; #pragma unroll
;         for (int ai = 0; ai < 2; ++ai)
; #pragma unroll
;             for (int m = 0; m < 4; ++m) { const int rl = ai * HALF + wr * 64 + m * 16 + fr; const float rs = Sx[rl]; const size_t ro = (size_t)(u.pm * BM + rl) * D + col0;
; #pragma unroll
;                 for (int bj = 0; bj < 2; ++bj) { *(f32x4*)(O + ro + bj * HALF) = acc[ai][bj][m][0] * rs * gv[bj][0]; *(f32x4*)(O + ro + bj * HALF + 4) = acc[ai][bj][m][1] * rs * gv[bj][1]; } }
	v_pk_mul_f32 v[50:51], v[50:51], v[70:71] op_sel_hi:[1,0]
	v_pk_mul_f32 v[52:53], v[52:53], v[70:71] op_sel_hi:[1,0]
	v_add_u32_e32 v66, 0x80, v146
	v_mov_b32_e32 v67, v147
	v_lshlrev_b64 v[66:67], 14, v[66:67]
	v_lshl_add_u64 v[66:67], s[50:51], 0, v[66:67]
	v_lshl_add_u64 v[66:67], v[66:67], 0, v[0:1]
	v_pk_mul_f32 v[52:53], v[132:133], v[52:53]
	v_pk_mul_f32 v[50:51], v[130:131], v[50:51]
	global_store_dwordx4 v[66:67], v[50:53], off offset:528 sc1
	v_pk_mul_f32 v[78:79], v[78:79], v[84:85] op_sel_hi:[1,0]
	v_pk_mul_f32 v[80:81], v[80:81], v[84:85] op_sel_hi:[1,0]
	v_add_u32_e32 v50, 0x90, v146
	v_mov_b32_e32 v51, v147
	v_mov_b32_e32 v52, v71
	v_lshlrev_b64 v[50:51], 14, v[50:51]
	v_lshl_add_u64 v[50:51], s[50:51], 0, v[50:51]
	v_pk_mul_f32 v[38:39], v[38:39], v[52:53] op_sel_hi:[1,0]
	v_pk_mul_f32 v[40:41], v[40:41], v[52:53] op_sel_hi:[1,0]
	v_lshl_add_u64 v[50:51], v[50:51], 0, v[0:1]
	v_pk_mul_f32 v[40:41], v[136:137], v[40:41]
	v_pk_mul_f32 v[38:39], v[134:135], v[38:39]
	global_store_dwordx4 v[50:51], v[38:41], off offset:512 sc1
	ds_read2_b32 v[38:39], v172 offset0:160 offset1:176
	v_pk_mul_f32 v[34:35], v[34:35], v[52:53] op_sel_hi:[1,0]
	v_pk_mul_f32 v[36:37], v[36:37], v[52:53] op_sel_hi:[1,0]
	v_pk_mul_f32 v[34:35], v[130:131], v[34:35]
	v_pk_mul_f32 v[36:37], v[132:133], v[36:37]
	global_store_dwordx4 v[50:51], v[34:37], off offset:528 sc1
	s_waitcnt lgkmcnt(0)
	v_pk_mul_f32 v[18:19], v[18:19], v[38:39] op_sel_hi:[1,0]
	v_pk_mul_f32 v[20:21], v[20:21], v[38:39] op_sel_hi:[1,0]
	v_add_u32_e32 v34, 0xa0, v146
	v_mov_b32_e32 v35, v147
	v_lshlrev_b64 v[34:35], 14, v[34:35]
	v_lshl_add_u64 v[34:35], s[50:51], 0, v[34:35]
	v_lshl_add_u64 v[34:35], v[34:35], 0, v[0:1]
	v_pk_mul_f32 v[20:21], v[132:133], v[20:21]
	v_pk_mul_f32 v[18:19], v[130:131], v[18:19]
	v_add_u32_e32 v146, 0xb0, v146
	global_store_dwordx4 v[34:35], v[18:21], off offset:528 sc1
	v_pk_mul_f32 v[74:75], v[74:75], v[84:85] op_sel_hi:[1,0]
	v_pk_mul_f32 v[76:77], v[76:77], v[84:85] op_sel_hi:[1,0]
	v_lshlrev_b64 v[20:21], 14, v[146:147]
	v_mov_b32_e32 v18, v39
	v_lshl_add_u64 v[20:21], s[50:51], 0, v[20:21]
	v_lshl_add_u64 v[20:21], v[20:21], 0, v[0:1]
	v_pk_mul_f32 v[0:1], v[10:11], v[18:19] op_sel_hi:[1,0]
	v_pk_mul_f32 v[10:11], v[12:13], v[18:19] op_sel_hi:[1,0]
	v_pk_mul_f32 v[62:63], v[62:63], v[70:71] op_sel_hi:[1,0]
	v_pk_mul_f32 v[12:13], v[140:141], v[10:11]
	v_pk_mul_f32 v[10:11], v[138:139], v[0:1]
	v_pk_mul_f32 v[0:1], v[6:7], v[18:19] op_sel_hi:[1,0]
	v_pk_mul_f32 v[6:7], v[8:9], v[18:19] op_sel_hi:[1,0]
	v_pk_mul_f32 v[64:65], v[64:65], v[70:71] op_sel_hi:[1,0]
	v_pk_mul_f32 v[58:59], v[58:59], v[70:71] op_sel_hi:[1,0]
	v_pk_mul_f32 v[60:61], v[60:61], v[70:71] op_sel_hi:[1,0]
	v_pk_mul_f32 v[54:55], v[54:55], v[70:71] op_sel_hi:[1,0]
	v_pk_mul_f32 v[56:57], v[56:57], v[70:71] op_sel_hi:[1,0]
	v_pk_mul_f32 v[46:47], v[46:47], v[52:53] op_sel_hi:[1,0]
	v_pk_mul_f32 v[48:49], v[48:49], v[52:53] op_sel_hi:[1,0]
	v_pk_mul_f32 v[42:43], v[42:43], v[52:53] op_sel_hi:[1,0]
	v_pk_mul_f32 v[44:45], v[44:45], v[52:53] op_sel_hi:[1,0]
	v_pk_mul_f32 v[30:31], v[30:31], v[38:39] op_sel_hi:[1,0]
	v_pk_mul_f32 v[32:33], v[32:33], v[38:39] op_sel_hi:[1,0]
	v_pk_mul_f32 v[26:27], v[26:27], v[38:39] op_sel_hi:[1,0]
	v_pk_mul_f32 v[28:29], v[28:29], v[38:39] op_sel_hi:[1,0]
	v_pk_mul_f32 v[22:23], v[22:23], v[38:39] op_sel_hi:[1,0]
	v_pk_mul_f32 v[24:25], v[24:25], v[38:39] op_sel_hi:[1,0]
	v_pk_mul_f32 v[14:15], v[14:15], v[18:19] op_sel_hi:[1,0]
	v_pk_mul_f32 v[16:17], v[16:17], v[18:19] op_sel_hi:[1,0]
	v_pk_mul_f32 v[8:9], v[136:137], v[6:7]
	v_pk_mul_f32 v[6:7], v[134:135], v[0:1]
	v_pk_mul_f32 v[0:1], v[2:3], v[18:19] op_sel_hi:[1,0]
	v_pk_mul_f32 v[2:3], v[4:5], v[18:19] op_sel_hi:[1,0]
	v_pk_mul_f32 v[80:81], v[144:145], v[80:81]
	v_pk_mul_f32 v[78:79], v[142:143], v[78:79]
	v_pk_mul_f32 v[76:77], v[140:141], v[76:77]
	v_pk_mul_f32 v[74:75], v[138:139], v[74:75]
	v_pk_mul_f32 v[64:65], v[144:145], v[64:65]
	v_pk_mul_f32 v[62:63], v[142:143], v[62:63]
	v_pk_mul_f32 v[60:61], v[140:141], v[60:61]
	v_pk_mul_f32 v[58:59], v[138:139], v[58:59]
	v_pk_mul_f32 v[56:57], v[136:137], v[56:57]
	v_pk_mul_f32 v[54:55], v[134:135], v[54:55]
	v_pk_mul_f32 v[48:49], v[144:145], v[48:49]
	v_pk_mul_f32 v[46:47], v[142:143], v[46:47]
	v_pk_mul_f32 v[44:45], v[140:141], v[44:45]
	v_pk_mul_f32 v[42:43], v[138:139], v[42:43]
	v_pk_mul_f32 v[32:33], v[144:145], v[32:33]
	v_pk_mul_f32 v[30:31], v[142:143], v[30:31]
	v_pk_mul_f32 v[28:29], v[140:141], v[28:29]
	v_pk_mul_f32 v[26:27], v[138:139], v[26:27]
	v_pk_mul_f32 v[24:25], v[136:137], v[24:25]
	v_pk_mul_f32 v[22:23], v[134:135], v[22:23]
	v_pk_mul_f32 v[16:17], v[144:145], v[16:17]
	v_pk_mul_f32 v[14:15], v[142:143], v[14:15]
	v_pk_mul_f32 v[2:3], v[132:133], v[2:3]
	v_pk_mul_f32 v[0:1], v[130:131], v[0:1]
	global_store_dwordx4 v[82:83], v[78:81], off sc1
	global_store_dwordx4 v[82:83], v[74:77], off offset:16 sc1
	global_store_dwordx4 v[66:67], v[62:65], off sc1
	global_store_dwordx4 v[66:67], v[58:61], off offset:16 sc1
	global_store_dwordx4 v[66:67], v[54:57], off offset:512 sc1
	global_store_dwordx4 v[50:51], v[46:49], off sc1
	global_store_dwordx4 v[50:51], v[42:45], off offset:16 sc1
	global_store_dwordx4 v[34:35], v[30:33], off sc1
	global_store_dwordx4 v[34:35], v[26:29], off offset:16 sc1
	global_store_dwordx4 v[34:35], v[22:25], off offset:512 sc1
	global_store_dwordx4 v[20:21], v[14:17], off sc1
	global_store_dwordx4 v[20:21], v[10:13], off offset:16 sc1
	global_store_dwordx4 v[20:21], v[6:9], off offset:512 sc1
	global_store_dwordx4 v[20:21], v[0:3], off offset:528 sc1
